# attention: permlane max, no O copies, QK to VGPR; pipelined residual epilogues; hand-scheduled RWKV scan loops
# speedup vs baseline: 1.0530x; 1.0306x over previous
; template <int RPL>
; __device__ __forceinline__ void rwkv_item(const Params& p, int seq, int head, int dir, int slab, char* smem) {
;     ...
; #pragma unroll 4
;     for (int i = 0; i < 32; ++i) {
;       const int li = dir ? 31 - i : i;
;       const float* base = sVec + li * RV_TS + ks_ * 4;
;       const f4 w4 = *(const f4*)(base), kk4 = *(const f4*)(base + 64), b4 = *(const f4*)(base + 128),
;                kd4 = *(const f4*)(base + 192), r4 = *(const f4*)(base + 256);
;       const f2 w01 = {w4[0], w4[1]}, w23 = {w4[2], w4[3]}, kk01 = {kk4[0], kk4[1]}, kk23 = {kk4[2], kk4[3]};
;       const f2 b01 = {b4[0], b4[1]}, b23 = {b4[2], b4[3]}, kd01 = {kd4[0], kd4[1]}, kd23 = {kd4[2], kd4[3]};
;       const f2 r01 = {r4[0], r4[1]}, r23 = {r4[2], r4[3]};
;       float vv[RPL], yv[RPL];
;       if (RPL == 4) { const f4 v4 = *(const f4*)(sV + li * 64 + rbase); vv[0] = v4[0]; vv[1 % RPL] = v4[1]; vv[2 % RPL] = v4[2]; vv[3 % RPL] = v4[3]; }
;       else {
; #pragma unroll
;         for (int r = 0; r < RPL; ++r) vv[r] = sV[li * 64 + rbase + r];
;       }
; #pragma unroll
;       for (int r = 0; r < RPL; ++r) {
;         f2 t = S01[r] * kk01; t = S23[r] * kk23 + t;
;         const float sa = allred16(t[0] + t[1]);
;         const f2 nsa = {-sa, -sa}, v2 = {vv[r], vv[r]};
;         S01[r] = v2 * kd01 + (nsa * b01 + S01[r] * w01);
;         S23[r] = v2 * kd23 + (nsa * b23 + S23[r] * w23);
;         f2 u = S01[r] * r01; u = S23[r] * r23 + u;
;         yv[r] = allred16(u[0] + u[1]);
;       }
;       if (ks_ == 0) {
;         hf* yp = yout + (size_t)(s0 + t0 + li) * 1024 + head * 64 + rbase;
;         if (RPL == 4) { h4 o; o[0] = (hf)yv[0]; o[1] = (hf)yv[1 % RPL]; o[2] = (hf)yv[2 % RPL]; o[3] = (hf)yv[3 % RPL]; *(h4*)yp = o; }
;         else {
; #pragma unroll
;           for (int r = 0; r < RPL; ++r) yp[r] = (hf)yv[r];
;         }
;       }
;     }
.LBB0_763:
	s_sub_i32 s14, 31, s20
	s_and_b64 s[6:7], s[12:13], exec
	s_cselect_b32 s14, s20, s14
	s_mul_i32 s6, s14, 0x510
	v_add_u32_e32 v76, s6, v138
	ds_read_b128 v[154:157], v76 offset:256
	ds_read_b128 v[150:153], v76
	ds_read_b128 v[158:161], v76 offset:512
	v_lshl_add_u32 v77, s14, 8, v139
	ds_read_b128 v[162:165], v76 offset:768
	ds_read_b128 v[170:173], v77 offset:41472
	ds_read_b128 v[166:169], v76 offset:1024
	s_waitcnt lgkmcnt(5)
	v_pk_mul_f32 v[76:77], v[120:121], v[156:157]
	v_pk_mul_f32 v[78:79], v[118:119], v[156:157]
	v_pk_mul_f32 v[80:81], v[116:117], v[156:157]
	v_pk_mul_f32 v[82:83], v[114:115], v[156:157]
	v_pk_fma_f32 v[76:77], v[112:113], v[154:155], v[76:77]
	v_pk_fma_f32 v[78:79], v[126:127], v[154:155], v[78:79]
	v_pk_fma_f32 v[80:81], v[124:125], v[154:155], v[80:81]
	v_pk_fma_f32 v[82:83], v[122:123], v[154:155], v[82:83]
	v_add_f32_e32 v76, v76, v77
	v_add_f32_e32 v78, v78, v79
	v_add_f32_e32 v80, v80, v81
	v_add_f32_e32 v82, v82, v83
	v_add_f32_dpp v76, v76, v76 row_ror:8 row_mask:0xf bank_mask:0xf bound_ctrl:1
	v_add_f32_dpp v78, v78, v78 row_ror:8 row_mask:0xf bank_mask:0xf bound_ctrl:1
	v_add_f32_dpp v80, v80, v80 row_ror:8 row_mask:0xf bank_mask:0xf bound_ctrl:1
	v_add_f32_dpp v82, v82, v82 row_ror:8 row_mask:0xf bank_mask:0xf bound_ctrl:1
	v_add_f32_dpp v76, v76, v76 row_ror:4 row_mask:0xf bank_mask:0xf bound_ctrl:1
	v_add_f32_dpp v78, v78, v78 row_ror:4 row_mask:0xf bank_mask:0xf bound_ctrl:1
	v_add_f32_dpp v80, v80, v80 row_ror:4 row_mask:0xf bank_mask:0xf bound_ctrl:1
	v_add_f32_dpp v82, v82, v82 row_ror:4 row_mask:0xf bank_mask:0xf bound_ctrl:1
	v_add_f32_dpp v76, v76, v76 row_ror:2 row_mask:0xf bank_mask:0xf bound_ctrl:1
	v_add_f32_dpp v78, v78, v78 row_ror:2 row_mask:0xf bank_mask:0xf bound_ctrl:1
	v_add_f32_dpp v80, v80, v80 row_ror:2 row_mask:0xf bank_mask:0xf bound_ctrl:1
	v_add_f32_dpp v82, v82, v82 row_ror:2 row_mask:0xf bank_mask:0xf bound_ctrl:1
	v_add_f32_dpp v76, v76, v76 row_ror:1 row_mask:0xf bank_mask:0xf bound_ctrl:1
	v_add_f32_dpp v78, v78, v78 row_ror:1 row_mask:0xf bank_mask:0xf bound_ctrl:1
	v_add_f32_dpp v80, v80, v80 row_ror:1 row_mask:0xf bank_mask:0xf bound_ctrl:1
	v_add_f32_dpp v82, v82, v82 row_ror:1 row_mask:0xf bank_mask:0xf bound_ctrl:1
	s_waitcnt lgkmcnt(3)
	v_pk_mul_f32 v[84:85], v[160:161], v[76:77] op_sel_hi:[1,0] neg_lo:[0,1] neg_hi:[0,1]
	v_pk_mul_f32 v[86:87], v[160:161], v[78:79] op_sel_hi:[1,0] neg_lo:[0,1] neg_hi:[0,1]
	v_pk_mul_f32 v[154:155], v[160:161], v[80:81] op_sel_hi:[1,0] neg_lo:[0,1] neg_hi:[0,1]
	v_pk_mul_f32 v[156:157], v[160:161], v[82:83] op_sel_hi:[1,0] neg_lo:[0,1] neg_hi:[0,1]
	v_pk_mul_f32 v[76:77], v[158:159], v[76:77] op_sel_hi:[1,0] neg_lo:[0,1] neg_hi:[0,1]
	v_pk_mul_f32 v[78:79], v[158:159], v[78:79] op_sel_hi:[1,0] neg_lo:[0,1] neg_hi:[0,1]
	v_pk_mul_f32 v[80:81], v[158:159], v[80:81] op_sel_hi:[1,0] neg_lo:[0,1] neg_hi:[0,1]
	v_pk_mul_f32 v[82:83], v[158:159], v[82:83] op_sel_hi:[1,0] neg_lo:[0,1] neg_hi:[0,1]
	v_pk_fma_f32 v[112:113], v[112:113], v[150:151], v[76:77]
	v_pk_fma_f32 v[126:127], v[126:127], v[150:151], v[78:79]
	v_pk_fma_f32 v[124:125], v[124:125], v[150:151], v[80:81]
	v_pk_fma_f32 v[122:123], v[122:123], v[150:151], v[82:83]
	v_pk_fma_f32 v[120:121], v[120:121], v[152:153], v[84:85]
	v_pk_fma_f32 v[118:119], v[118:119], v[152:153], v[86:87]
	v_pk_fma_f32 v[116:117], v[116:117], v[152:153], v[154:155]
	v_pk_fma_f32 v[114:115], v[114:115], v[152:153], v[156:157]
	s_waitcnt lgkmcnt(1)
	v_pk_fma_f32 v[112:113], v[162:163], v[170:171], v[112:113] op_sel_hi:[1,0,1]
	v_pk_fma_f32 v[126:127], v[162:163], v[170:171], v[126:127] op_sel:[0,1,0]
	v_pk_fma_f32 v[124:125], v[162:163], v[172:173], v[124:125] op_sel_hi:[1,0,1]
	v_pk_fma_f32 v[122:123], v[162:163], v[172:173], v[122:123] op_sel:[0,1,0]
	v_pk_fma_f32 v[120:121], v[164:165], v[170:171], v[120:121] op_sel_hi:[1,0,1]
	v_pk_fma_f32 v[118:119], v[164:165], v[170:171], v[118:119] op_sel:[0,1,0]
	v_pk_fma_f32 v[116:117], v[164:165], v[172:173], v[116:117] op_sel_hi:[1,0,1]
	v_pk_fma_f32 v[114:115], v[164:165], v[172:173], v[114:115] op_sel:[0,1,0]
	s_waitcnt lgkmcnt(0)
	v_pk_mul_f32 v[76:77], v[166:167], v[112:113]
	v_pk_mul_f32 v[78:79], v[166:167], v[126:127]
	v_pk_mul_f32 v[80:81], v[166:167], v[124:125]
	v_pk_mul_f32 v[82:83], v[166:167], v[122:123]
	v_pk_fma_f32 v[76:77], v[168:169], v[120:121], v[76:77]
	v_pk_fma_f32 v[78:79], v[168:169], v[118:119], v[78:79]
	v_pk_fma_f32 v[80:81], v[168:169], v[116:117], v[80:81]
	v_pk_fma_f32 v[82:83], v[168:169], v[114:115], v[82:83]
	v_add_f32_e32 v76, v76, v77
	v_add_f32_e32 v78, v78, v79
	v_add_f32_e32 v80, v80, v81
	v_add_f32_e32 v82, v82, v83
	v_add_f32_dpp v76, v76, v76 row_ror:8 row_mask:0xf bank_mask:0xf bound_ctrl:1
	v_add_f32_dpp v78, v78, v78 row_ror:8 row_mask:0xf bank_mask:0xf bound_ctrl:1
	v_add_f32_dpp v80, v80, v80 row_ror:8 row_mask:0xf bank_mask:0xf bound_ctrl:1
	v_add_f32_dpp v82, v82, v82 row_ror:8 row_mask:0xf bank_mask:0xf bound_ctrl:1
	v_add_f32_dpp v76, v76, v76 row_ror:4 row_mask:0xf bank_mask:0xf bound_ctrl:1
	v_add_f32_dpp v78, v78, v78 row_ror:4 row_mask:0xf bank_mask:0xf bound_ctrl:1
	v_add_f32_dpp v80, v80, v80 row_ror:4 row_mask:0xf bank_mask:0xf bound_ctrl:1
	v_add_f32_dpp v82, v82, v82 row_ror:4 row_mask:0xf bank_mask:0xf bound_ctrl:1
	v_add_f32_dpp v76, v76, v76 row_ror:2 row_mask:0xf bank_mask:0xf bound_ctrl:1
	v_add_f32_dpp v78, v78, v78 row_ror:2 row_mask:0xf bank_mask:0xf bound_ctrl:1
	v_add_f32_dpp v80, v80, v80 row_ror:2 row_mask:0xf bank_mask:0xf bound_ctrl:1
	v_add_f32_dpp v82, v82, v82 row_ror:2 row_mask:0xf bank_mask:0xf bound_ctrl:1
	v_add_f32_dpp v76, v76, v76 row_ror:1 row_mask:0xf bank_mask:0xf bound_ctrl:1
	v_add_f32_dpp v78, v78, v78 row_ror:1 row_mask:0xf bank_mask:0xf bound_ctrl:1
	v_add_f32_dpp v80, v80, v80 row_ror:1 row_mask:0xf bank_mask:0xf bound_ctrl:1
	v_add_f32_dpp v82, v82, v82 row_ror:1 row_mask:0xf bank_mask:0xf bound_ctrl:1
	s_and_saveexec_b64 s[6:7], s[4:5]
	s_add_i32 s14, s8, s14
	s_lshl_b32 s14, s14, 11
	v_cvt_pk_f16_f32 v84, v76, v78
	v_cvt_pk_f16_f32 v85, v80, v82
	v_lshl_add_u64 v[86:87], v[88:89], 0, s[14:15]
	global_store_dwordx2 v[86:87], v[84:85], off
	s_or_b64 exec, exec, s[6:7]
	s_add_i32 s20, s20, 1
	s_cmp_eq_u32 s20, 32
	s_cbranch_scc0 .LBB0_763
	s_branch .LBB0_708

; template <int RPL>
; __device__ __forceinline__ void rwkv_item(const Params& p, int seq, int head, int dir, int slab, char* smem) {
;     ...
; #pragma unroll 4
;     for (int i = 0; i < 32; ++i) {
;       const int li = dir ? 31 - i : i;
;       const float* base = sVec + li * RV_TS + ks_ * 4;
;       const f4 w4 = *(const f4*)(base), kk4 = *(const f4*)(base + 64), b4 = *(const f4*)(base + 128),
;                kd4 = *(const f4*)(base + 192), r4 = *(const f4*)(base + 256);
;       const f2 w01 = {w4[0], w4[1]}, w23 = {w4[2], w4[3]}, kk01 = {kk4[0], kk4[1]}, kk23 = {kk4[2], kk4[3]};
;       const f2 b01 = {b4[0], b4[1]}, b23 = {b4[2], b4[3]}, kd01 = {kd4[0], kd4[1]}, kd23 = {kd4[2], kd4[3]};
;       const f2 r01 = {r4[0], r4[1]}, r23 = {r4[2], r4[3]};
;       float vv[RPL], yv[RPL];
;       if (RPL == 4) { const f4 v4 = *(const f4*)(sV + li * 64 + rbase); vv[0] = v4[0]; vv[1 % RPL] = v4[1]; vv[2 % RPL] = v4[2]; vv[3 % RPL] = v4[3]; }
;       else {
; #pragma unroll
;         for (int r = 0; r < RPL; ++r) vv[r] = sV[li * 64 + rbase + r];
;       }
; #pragma unroll
;       for (int r = 0; r < RPL; ++r) {
;         f2 t = S01[r] * kk01; t = S23[r] * kk23 + t;
;         const float sa = allred16(t[0] + t[1]);
;         const f2 nsa = {-sa, -sa}, v2 = {vv[r], vv[r]};
;         S01[r] = v2 * kd01 + (nsa * b01 + S01[r] * w01);
;         S23[r] = v2 * kd23 + (nsa * b23 + S23[r] * w23);
;         f2 u = S01[r] * r01; u = S23[r] * r23 + u;
;         yv[r] = allred16(u[0] + u[1]);
;       }
;       if (ks_ == 0) {
;         hf* yp = yout + (size_t)(s0 + t0 + li) * 1024 + head * 64 + rbase;
;         if (RPL == 4) { h4 o; o[0] = (hf)yv[0]; o[1] = (hf)yv[1 % RPL]; o[2] = (hf)yv[2 % RPL]; o[3] = (hf)yv[3 % RPL]; *(h4*)yp = o; }
;         else {
; #pragma unroll
;           for (int r = 0; r < RPL; ++r) yp[r] = (hf)yv[r];
;         }
;       }
;     }
.LBB0_877:
	s_and_b64 s[6:7], s[20:21], exec
	s_cselect_b32 s11, 0, 31
	s_cselect_b32 s9, 1, -1
	s_mul_i32 s72, s9, 0x800
	s_mul_i32 s9, s9, 0x510
	s_mul_i32 s6, s11, 0x510
	v_add_u32_e32 v149, s6, v134
	v_lshl_add_u32 v105, s11, 8, v135
	ds_read_b128 v[80:83], v149 offset:256
	ds_read_b128 v[76:79], v149
	ds_read_b128 v[84:87], v149 offset:512
	ds_read_b128 v[144:147], v149 offset:768
	ds_read_b32 v154, v105 offset:41472
	ds_read_b128 v[150:153], v149 offset:1024
	s_lshl_b64 s[26:27], s[18:19], 1
	s_add_i32 s6, s11, s8
	s_lshl_b32 s6, s6, 11
	s_add_u32 s26, s26, s6
	s_addc_u32 s27, s27, 0
	s_add_u32 s26, s26, s3
	s_addc_u32 s27, s27, s14
	s_ashr_i32 s6, s72, 31
	s_sub_u32 s26, s26, s72
	s_subb_u32 s27, s27, s6
	s_lshl_b32 s11, s11, 8
	s_mov_b32 s10, 0
	v_mov_b32_e32 v105, 0
.Lrw1_step:
	s_waitcnt lgkmcnt(5)
	v_pk_mul_f32 v[80:81], v[122:123], v[80:81]
	v_add_f32_dpp v105, v105, v105 row_ror:8 row_mask:0xf bank_mask:0xf bound_ctrl:1
	v_pk_fma_f32 v[80:81], v[124:125], v[82:83], v[80:81]
	v_add_u32_e32 v149, s9, v149
	v_add_f32_e32 v155, v80, v81
	v_max_i32_e32 v149, v149, v134
	v_add_f32_dpp v105, v105, v105 row_ror:4 row_mask:0xf bank_mask:0xf bound_ctrl:1
	ds_read_b128 v[80:83], v149 offset:256
	s_ashr_i32 s6, s72, 3
	v_add_f32_dpp v155, v155, v155 row_ror:8 row_mask:0xf bank_mask:0xf bound_ctrl:1
	s_add_i32 s11, s11, s6
	v_add_f32_dpp v105, v105, v105 row_ror:2 row_mask:0xf bank_mask:0xf bound_ctrl:1
	s_max_i32 s11, s11, 0
	v_add_f32_dpp v155, v155, v155 row_ror:4 row_mask:0xf bank_mask:0xf bound_ctrl:1
	s_cmp_lg_u32 s10, 0
	v_add_f32_dpp v105, v105, v105 row_ror:1 row_mask:0xf bank_mask:0xf bound_ctrl:1
	s_cselect_b64 s[6:7], s[4:5], 0
	v_add_f32_dpp v155, v155, v155 row_ror:2 row_mask:0xf bank_mask:0xf bound_ctrl:1
	s_nop 1
	v_add_f32_dpp v155, v155, v155 row_ror:1 row_mask:0xf bank_mask:0xf bound_ctrl:1
	s_waitcnt lgkmcnt(1)
	v_pk_mul_f32 v[84:85], v[84:85], v[154:155] op_sel:[0,1] op_sel_hi:[1,1] neg_lo:[0,1] neg_hi:[0,1]
	v_pk_mul_f32 v[86:87], v[86:87], v[154:155] op_sel:[0,1] op_sel_hi:[1,1] neg_lo:[0,1] neg_hi:[0,1]
	v_pk_fma_f32 v[122:123], v[122:123], v[76:77], v[84:85]
	v_pk_fma_f32 v[124:125], v[124:125], v[78:79], v[86:87]
	v_pk_fma_f32 v[122:123], v[144:145], v[154:155], v[122:123] op_sel_hi:[1,0,1]
	v_pk_fma_f32 v[124:125], v[146:147], v[154:155], v[124:125] op_sel_hi:[1,0,1]
	v_cvt_f16_f32_e32 v84, v105
	v_pk_mul_f32 v[150:151], v[150:151], v[122:123]
	v_lshl_add_u64 v[86:87], v[96:97], 1, s[26:27]
	v_pk_fma_f32 v[150:151], v[152:153], v[124:125], v[150:151]
	v_add_co_u32_e32 v86, vcc, 0xa000000, v86
	s_nop 1
	v_addc_co_u32_e32 v87, vcc, 0, v87, vcc
	s_and_b64 exec, exec, s[6:7]
	global_store_short v[86:87], v84, off
	s_mov_b64 exec, -1
	v_add_f32_e32 v105, v150, v151
	s_ashr_i32 s6, s72, 31
	s_add_u32 s26, s26, s72
	s_addc_u32 s27, s27, s6
	v_add_u32_e32 v85, s11, v135
	ds_read_b128 v[76:79], v149
	ds_read_b32 v154, v85 offset:41472
	ds_read_b128 v[84:87], v149 offset:512
	ds_read_b128 v[144:147], v149 offset:768
	ds_read_b128 v[150:153], v149 offset:1024
	s_add_i32 s10, s10, 1
	s_cmp_eq_u32 s10, 32
	s_cbranch_scc0 .Lrw1_step
	s_nop 1
	v_add_f32_dpp v105, v105, v105 row_ror:8 row_mask:0xf bank_mask:0xf bound_ctrl:1
	s_nop 1
	v_add_f32_dpp v105, v105, v105 row_ror:4 row_mask:0xf bank_mask:0xf bound_ctrl:1
	s_nop 1
	v_add_f32_dpp v105, v105, v105 row_ror:2 row_mask:0xf bank_mask:0xf bound_ctrl:1
	s_nop 1
	v_add_f32_dpp v105, v105, v105 row_ror:1 row_mask:0xf bank_mask:0xf bound_ctrl:1
	s_waitcnt lgkmcnt(0)
	v_cvt_f16_f32_e32 v84, v105
	v_lshl_add_u64 v[86:87], v[96:97], 1, s[26:27]
	v_add_co_u32_e32 v86, vcc, 0xa000000, v86
	s_nop 1
	v_addc_co_u32_e32 v87, vcc, 0, v87, vcc
	s_and_b64 exec, exec, s[4:5]
	global_store_short v[86:87], v84, off
	s_mov_b64 exec, -1
	s_branch .LBB0_806

; #define LD_AF(dst, ks_) _Pragma("unroll") for (int i = 0; i < 8; ++i) dst[i] = *(const h8*)(sA + i * 16 * G_LD + (ks_) * 32)
; #define LD_BF(dst, ks_, nh_) _Pragma("unroll") for (int i = 0; i < 4; ++i) dst[i] = *(const h8*)(sB + ((nh_) * 4 + i) * 16 * G_LD + (ks_) * 32)
; #define MMA_BLK(afx, bfx, nh_) _Pragma("unroll") for (int mi = 0; mi < 8; ++mi) _Pragma("unroll") for (int ni = 0; ni < 4; ++ni) mfma16_acc(acc[mi][(nh_) * 4 + ni], bfx[ni], afx[mi])
; template <class Epi>
; __device__ __forceinline__ void gemm_run(const GemmArgs g, Epi epi, char* smem) {
;     ...
;       h8 afA[8], afB[8], bfA[4], bfB[4];
;     ...
;       LD_AF(afA, 0); LD_BF(bfA, 0, 0);
;       if (kt + 1 < nk) {
; #pragma unroll
;         for (int i = 0; i < 8; ++i) *(u4*)(st + (lr + 32 * i) * G_LD + lcw) = ra[i];
;       }
;       __builtin_amdgcn_sched_barrier(0);
;       LD_BF(bfB, 0, 1);
;       MMA_BLK(afA, bfA, 0);
;       __builtin_amdgcn_sched_barrier(0);
;       if (kt + 1 < nk) {
; #pragma unroll
;         for (int i = 0; i < 8; ++i) *(u4*)(st + (256 + lr + 32 * i) * G_LD + lcw) = rb[i];
;       }
;       LD_AF(afB, 1); LD_BF(bfA, 1, 0);
;       MMA_BLK(afA, bfB, 1);
;       __builtin_amdgcn_sched_barrier(0);
;       if (kt + 2 < nk) {
;         const int ko = (kt + 2) * 64;
; #pragma unroll
;         for (int i = 0; i < 8; ++i) { ra[i] = __builtin_amdgcn_raw_buffer_load_b128(Ars, aoff, i * astep + ko * 2, 0); rb[i] = __builtin_amdgcn_raw_buffer_load_b128(Brs, boff, i * bstep + ko * 2, 0); }
;       }
;       LD_BF(bfB, 1, 1);
;       MMA_BLK(afB, bfA, 0);
;       __builtin_amdgcn_sched_barrier(0);
;       MMA_BLK(afB, bfB, 1);
;       __builtin_amdgcn_sched_barrier(0);
.LBB0_918:
	ds_read_b128 v[0:3], v138 offset:36864
	ds_read_b128 v[4:7], v138 offset:39168
	ds_read_b128 v[8:11], v138 offset:41472
	ds_read_b128 v[12:15], v138 offset:43776
	ds_read_b128 v[16:19], v139
	ds_read_b128 v[20:23], v139 offset:2304
	ds_read_b128 v[24:27], v139 offset:4608
	ds_read_b128 v[28:31], v139 offset:6912
	ds_read_b128 v[32:35], v139 offset:9216
	ds_read_b128 v[36:39], v139 offset:11520
	ds_read_b128 v[40:43], v139 offset:13824
	ds_read_b128 v[44:47], v139 offset:16128
	ds_read_b128 v[48:51], v138 offset:46080
	ds_read_b128 v[52:55], v138 offset:48384
	ds_read_b128 v[56:59], v138 offset:50688
	ds_read_b128 v[60:63], v138 offset:52992
	s_waitcnt lgkmcnt(11)
	v_mfma_f32_16x16x32_f16 a[208:211], v[0:3], v[16:19], a[208:211]
	v_mfma_f32_16x16x32_f16 a[200:203], v[4:7], v[16:19], a[200:203]
	v_mfma_f32_16x16x32_f16 a[196:199], v[8:11], v[16:19], a[196:199]
	v_mfma_f32_16x16x32_f16 a[192:195], v[12:15], v[16:19], a[192:195]
	s_waitcnt lgkmcnt(10)
	v_mfma_f32_16x16x32_f16 a[188:191], v[0:3], v[20:23], a[188:191]
	v_mfma_f32_16x16x32_f16 a[184:187], v[4:7], v[20:23], a[184:187]
	v_mfma_f32_16x16x32_f16 a[180:183], v[8:11], v[20:23], a[180:183]
	v_mfma_f32_16x16x32_f16 a[176:179], v[12:15], v[20:23], a[176:179]
	s_waitcnt lgkmcnt(9)
	v_mfma_f32_16x16x32_f16 a[156:159], v[0:3], v[24:27], a[156:159]
	v_mfma_f32_16x16x32_f16 a[152:155], v[4:7], v[24:27], a[152:155]
	v_mfma_f32_16x16x32_f16 a[148:151], v[8:11], v[24:27], a[148:151]
	v_mfma_f32_16x16x32_f16 a[144:147], v[12:15], v[24:27], a[144:147]
	s_waitcnt lgkmcnt(8)
	v_mfma_f32_16x16x32_f16 a[124:127], v[0:3], v[28:31], a[124:127]
	v_mfma_f32_16x16x32_f16 a[120:123], v[4:7], v[28:31], a[120:123]
	v_mfma_f32_16x16x32_f16 a[116:119], v[8:11], v[28:31], a[116:119]
	v_mfma_f32_16x16x32_f16 a[112:115], v[12:15], v[28:31], a[112:115]
	s_waitcnt lgkmcnt(7)
	v_mfma_f32_16x16x32_f16 a[92:95], v[0:3], v[32:35], a[92:95]
	v_mfma_f32_16x16x32_f16 a[88:91], v[4:7], v[32:35], a[88:91]
	v_mfma_f32_16x16x32_f16 a[84:87], v[8:11], v[32:35], a[84:87]
	v_mfma_f32_16x16x32_f16 a[80:83], v[12:15], v[32:35], a[80:83]
	s_waitcnt lgkmcnt(6)
	v_mfma_f32_16x16x32_f16 a[60:63], v[0:3], v[36:39], a[60:63]
	v_mfma_f32_16x16x32_f16 a[56:59], v[4:7], v[36:39], a[56:59]
	v_mfma_f32_16x16x32_f16 a[52:55], v[8:11], v[36:39], a[52:55]
	v_mfma_f32_16x16x32_f16 a[48:51], v[12:15], v[36:39], a[48:51]
	s_waitcnt lgkmcnt(5)
	v_mfma_f32_16x16x32_f16 a[32:35], v[0:3], v[40:43], a[32:35]
	v_mfma_f32_16x16x32_f16 a[28:31], v[4:7], v[40:43], a[28:31]
	v_mfma_f32_16x16x32_f16 a[24:27], v[8:11], v[40:43], a[24:27]
	v_mfma_f32_16x16x32_f16 a[20:23], v[12:15], v[40:43], a[20:23]
	s_waitcnt lgkmcnt(4)
	v_mfma_f32_16x16x32_f16 a[12:15], v[0:3], v[44:47], a[12:15]
	v_mfma_f32_16x16x32_f16 a[8:11], v[4:7], v[44:47], a[8:11]
	v_mfma_f32_16x16x32_f16 a[4:7], v[8:11], v[44:47], a[4:7]
	v_mfma_f32_16x16x32_f16 a[0:3], v[12:15], v[44:47], a[0:3]
	s_waitcnt lgkmcnt(3)
	v_mfma_f32_16x16x32_f16 a[172:175], v[48:51], v[28:31], a[172:175]
	s_waitcnt lgkmcnt(2)
	v_mfma_f32_16x16x32_f16 a[168:171], v[52:55], v[28:31], a[168:171]
	s_waitcnt lgkmcnt(1)
	v_mfma_f32_16x16x32_f16 a[164:167], v[56:59], v[28:31], a[164:167]
	s_waitcnt lgkmcnt(0)
	v_mfma_f32_16x16x32_f16 a[160:163], v[60:63], v[28:31], a[160:163]
	v_mfma_f32_16x16x32_f16 a[140:143], v[48:51], v[32:35], a[140:143]
	v_mfma_f32_16x16x32_f16 a[136:139], v[52:55], v[32:35], a[136:139]
	v_mfma_f32_16x16x32_f16 a[132:135], v[56:59], v[32:35], a[132:135]
	v_mfma_f32_16x16x32_f16 a[128:131], v[60:63], v[32:35], a[128:131]
	ds_read_b128 v[12:15], v138 offset:36928
	ds_read_b128 v[28:31], v138 offset:39232
	ds_read_b128 v[32:35], v138 offset:41536
	ds_read_b128 v[64:67], v138 offset:43840
	ds_read_b128 v[76:79], v139 offset:64
	ds_read_b128 v[80:83], v139 offset:2368
	s_waitcnt vmcnt(8)
	ds_read_b128 v[142:145], v139 offset:4672
	s_waitcnt vmcnt(6)
	ds_read_b128 v[146:149], v139 offset:6976
	s_waitcnt vmcnt(5)
	ds_read_b128 v[150:153], v139 offset:9280
	ds_read_b128 v[8:11], v139 offset:11584
	ds_read_b128 v[4:7], v139 offset:13888
	ds_read_b128 v[0:3], v139 offset:16192
	v_mfma_f32_16x16x32_f16 a[240:243], v[48:51], v[16:19], a[240:243]
	v_mfma_f32_16x16x32_f16 a[252:255], v[52:55], v[16:19], a[252:255]
	v_mfma_f32_16x16x32_f16 a[248:251], v[56:59], v[16:19], a[248:251]
	v_mfma_f32_16x16x32_f16 a[244:247], v[60:63], v[16:19], a[244:247]
	v_mfma_f32_16x16x32_f16 a[236:239], v[48:51], v[20:23], a[236:239]
	v_mfma_f32_16x16x32_f16 a[232:235], v[52:55], v[20:23], a[232:235]
	v_mfma_f32_16x16x32_f16 a[228:231], v[56:59], v[20:23], a[228:231]
	v_mfma_f32_16x16x32_f16 a[224:227], v[60:63], v[20:23], a[224:227]
	v_mfma_f32_16x16x32_f16 a[220:223], v[48:51], v[24:27], a[220:223]
	v_mfma_f32_16x16x32_f16 a[216:219], v[52:55], v[24:27], a[216:219]
	v_mfma_f32_16x16x32_f16 a[212:215], v[56:59], v[24:27], a[212:215]
	v_mfma_f32_16x16x32_f16 a[204:207], v[60:63], v[24:27], a[204:207]
	v_mfma_f32_16x16x32_f16 a[108:111], v[48:51], v[36:39], a[108:111]
	v_mfma_f32_16x16x32_f16 a[104:107], v[52:55], v[36:39], a[104:107]
	v_mfma_f32_16x16x32_f16 a[100:103], v[56:59], v[36:39], a[100:103]
	v_mfma_f32_16x16x32_f16 a[96:99], v[60:63], v[36:39], a[96:99]
	v_mfma_f32_16x16x32_f16 a[76:79], v[48:51], v[40:43], a[76:79]
	v_mfma_f32_16x16x32_f16 a[72:75], v[52:55], v[40:43], a[72:75]
	v_mfma_f32_16x16x32_f16 a[68:71], v[56:59], v[40:43], a[68:71]
	v_mfma_f32_16x16x32_f16 a[64:67], v[60:63], v[40:43], a[64:67]
	v_mfma_f32_16x16x32_f16 a[44:47], v[48:51], v[44:47], a[44:47]
	v_mfma_f32_16x16x32_f16 a[40:43], v[52:55], v[44:47], a[40:43]
	v_mfma_f32_16x16x32_f16 a[36:39], v[56:59], v[44:47], a[36:39]
	v_mfma_f32_16x16x32_f16 a[16:19], v[60:63], v[44:47], a[16:19]
	s_waitcnt vmcnt(3)
; #define LD_AF(dst, ks_) _Pragma("unroll") for (int i = 0; i < 8; ++i) dst[i] = *(const h8*)(sA + i * 16 * G_LD + (ks_) * 32)
; #define LD_BF(dst, ks_, nh_) _Pragma("unroll") for (int i = 0; i < 4; ++i) dst[i] = *(const h8*)(sB + ((nh_) * 4 + i) * 16 * G_LD + (ks_) * 32)
; #define MMA_BLK(afx, bfx, nh_) _Pragma("unroll") for (int mi = 0; mi < 8; ++mi) _Pragma("unroll") for (int ni = 0; ni < 4; ++ni) mfma16_acc(acc[mi][(nh_) * 4 + ni], bfx[ni], afx[mi])
; template <class Epi>
; __device__ __forceinline__ void gemm_run(const GemmArgs g, Epi epi, char* smem) {
;     ...
;       h8 afA[8], afB[8], bfA[4], bfB[4];
;     ...
;       LD_AF(afA, 0); LD_BF(bfA, 0, 0);
;       if (kt + 1 < nk) {
; #pragma unroll
;         for (int i = 0; i < 8; ++i) *(u4*)(st + (lr + 32 * i) * G_LD + lcw) = ra[i];
;       }
;       __builtin_amdgcn_sched_barrier(0);
;       LD_BF(bfB, 0, 1);
;       MMA_BLK(afA, bfA, 0);
;       __builtin_amdgcn_sched_barrier(0);
;       if (kt + 1 < nk) {
; #pragma unroll
;         for (int i = 0; i < 8; ++i) *(u4*)(st + (256 + lr + 32 * i) * G_LD + lcw) = rb[i];
;       }
;       LD_AF(afB, 1); LD_BF(bfA, 1, 0);
;       MMA_BLK(afA, bfB, 1);
;       __builtin_amdgcn_sched_barrier(0);
;       if (kt + 2 < nk) {
;         const int ko = (kt + 2) * 64;
; #pragma unroll
;         for (int i = 0; i < 8; ++i) { ra[i] = __builtin_amdgcn_raw_buffer_load_b128(Ars, aoff, i * astep + ko * 2, 0); rb[i] = __builtin_amdgcn_raw_buffer_load_b128(Brs, boff, i * bstep + ko * 2, 0); }
;       }
;       LD_BF(bfB, 1, 1);
;       MMA_BLK(afB, bfA, 0);
;       __builtin_amdgcn_sched_barrier(0);
;       MMA_BLK(afB, bfB, 1);
;       __builtin_amdgcn_sched_barrier(0);
	ds_read_b128 v[154:157], v138 offset:46144
	ds_read_b128 v[158:161], v138 offset:48448
	s_waitcnt vmcnt(1)
	ds_read_b128 v[162:165], v138 offset:50752
	ds_read_b128 v[166:169], v138 offset:53056
	s_waitcnt lgkmcnt(11)
	v_mfma_f32_16x16x32_f16 a[208:211], v[12:15], v[76:79], a[208:211]
	v_mfma_f32_16x16x32_f16 a[200:203], v[28:31], v[76:79], a[200:203]
	v_mfma_f32_16x16x32_f16 a[196:199], v[32:35], v[76:79], a[196:199]
	v_mfma_f32_16x16x32_f16 a[192:195], v[64:67], v[76:79], a[192:195]
	s_waitcnt lgkmcnt(10)
	v_mfma_f32_16x16x32_f16 a[188:191], v[12:15], v[80:83], a[188:191]
	v_mfma_f32_16x16x32_f16 a[184:187], v[28:31], v[80:83], a[184:187]
	v_mfma_f32_16x16x32_f16 a[180:183], v[32:35], v[80:83], a[180:183]
	v_mfma_f32_16x16x32_f16 a[176:179], v[64:67], v[80:83], a[176:179]
	s_waitcnt lgkmcnt(9)
	v_mfma_f32_16x16x32_f16 a[156:159], v[12:15], v[142:145], a[156:159]
	v_mfma_f32_16x16x32_f16 a[152:155], v[28:31], v[142:145], a[152:155]
	v_mfma_f32_16x16x32_f16 a[148:151], v[32:35], v[142:145], a[148:151]
	v_mfma_f32_16x16x32_f16 a[144:147], v[64:67], v[142:145], a[144:147]
	s_waitcnt lgkmcnt(8)
	v_mfma_f32_16x16x32_f16 a[124:127], v[12:15], v[146:149], a[124:127]
	v_mfma_f32_16x16x32_f16 a[120:123], v[28:31], v[146:149], a[120:123]
	v_mfma_f32_16x16x32_f16 a[116:119], v[32:35], v[146:149], a[116:119]
	v_mfma_f32_16x16x32_f16 a[112:115], v[64:67], v[146:149], a[112:115]
	s_waitcnt lgkmcnt(7)
	v_mfma_f32_16x16x32_f16 a[92:95], v[12:15], v[150:153], a[92:95]
	v_mfma_f32_16x16x32_f16 a[88:91], v[28:31], v[150:153], a[88:91]
	v_mfma_f32_16x16x32_f16 a[84:87], v[32:35], v[150:153], a[84:87]
	v_mfma_f32_16x16x32_f16 a[80:83], v[64:67], v[150:153], a[80:83]
	v_accvgpr_read_b32 v123, a211
	v_accvgpr_read_b32 v122, a210
	v_accvgpr_read_b32 v121, a203
	v_accvgpr_read_b32 v120, a202
	v_accvgpr_read_b32 v119, a199
	v_accvgpr_read_b32 v118, a198
	v_accvgpr_read_b32 v117, a195
	v_accvgpr_read_b32 v116, a194
	v_accvgpr_read_b32 v107, a191
	v_accvgpr_read_b32 v106, a190
	v_accvgpr_read_b32 v105, a187
	v_accvgpr_read_b32 v104, a186
	v_accvgpr_read_b32 v103, a183
	v_accvgpr_read_b32 v102, a182
	v_accvgpr_read_b32 v101, a179
	v_accvgpr_read_b32 v100, a178
	v_accvgpr_read_b32 v91, a159
	v_accvgpr_read_b32 v90, a158
	v_accvgpr_read_b32 v89, a155
	v_accvgpr_read_b32 v88, a154
	v_accvgpr_read_b32 v87, a151
	v_accvgpr_read_b32 v86, a150
	v_accvgpr_read_b32 v85, a147
	v_accvgpr_read_b32 v84, a146
	v_accvgpr_read_b32 v75, a127
	v_accvgpr_read_b32 v74, a126
	v_accvgpr_read_b32 v73, a123
	v_accvgpr_read_b32 v72, a122
	v_accvgpr_read_b32 v71, a119
	v_accvgpr_read_b32 v70, a118
	v_accvgpr_read_b32 v69, a115
	v_accvgpr_read_b32 v68, a114
	v_accvgpr_read_b32 v59, a95
	v_accvgpr_read_b32 v58, a94
	v_accvgpr_read_b32 v57, a91
	v_accvgpr_read_b32 v56, a90
	v_accvgpr_read_b32 v55, a87
	v_accvgpr_read_b32 v54, a86
	v_accvgpr_read_b32 v53, a83
	v_accvgpr_read_b32 v52, a82
	s_waitcnt lgkmcnt(6)
	v_mfma_f32_16x16x32_f16 a[60:63], v[12:15], v[8:11], a[60:63]
	v_mfma_f32_16x16x32_f16 a[56:59], v[28:31], v[8:11], a[56:59]
	v_mfma_f32_16x16x32_f16 a[52:55], v[32:35], v[8:11], a[52:55]
	v_mfma_f32_16x16x32_f16 a[48:51], v[64:67], v[8:11], a[48:51]
	s_waitcnt lgkmcnt(5)
	v_mfma_f32_16x16x32_f16 a[32:35], v[12:15], v[4:7], a[32:35]
	v_mfma_f32_16x16x32_f16 a[28:31], v[28:31], v[4:7], a[28:31]
	v_mfma_f32_16x16x32_f16 a[24:27], v[32:35], v[4:7], a[24:27]
	v_mfma_f32_16x16x32_f16 a[20:23], v[64:67], v[4:7], a[20:23]
	s_waitcnt lgkmcnt(4)
	v_mfma_f32_16x16x32_f16 a[12:15], v[12:15], v[0:3], a[12:15]
	v_mfma_f32_16x16x32_f16 a[8:11], v[28:31], v[0:3], a[8:11]
	v_mfma_f32_16x16x32_f16 a[4:7], v[32:35], v[0:3], a[4:7]
	v_mfma_f32_16x16x32_f16 a[0:3], v[64:67], v[0:3], a[0:3]
	v_accvgpr_read_b32 v43, a63
	v_accvgpr_read_b32 v42, a62
	v_accvgpr_read_b32 v41, a59
	v_accvgpr_read_b32 v40, a58
	v_accvgpr_read_b32 v39, a55
	v_accvgpr_read_b32 v38, a54
	v_accvgpr_read_b32 v37, a51
	v_accvgpr_read_b32 v36, a50
	v_accvgpr_read_b32 v27, a35
	v_accvgpr_read_b32 v26, a34
	v_accvgpr_read_b32 v25, a31
	v_accvgpr_read_b32 v24, a30
	v_accvgpr_read_b32 v23, a27
	v_accvgpr_read_b32 v22, a26
	v_accvgpr_read_b32 v21, a23
	v_accvgpr_read_b32 v20, a22
	v_accvgpr_read_b32 v19, a15
	v_accvgpr_read_b32 v18, a14
	v_accvgpr_read_b32 v17, a11
	v_accvgpr_read_b32 v16, a10
	v_accvgpr_read_b32 v15, a7
	v_accvgpr_read_b32 v14, a6
	v_accvgpr_read_b32 v13, a3
	v_accvgpr_read_b32 v12, a2
	s_waitcnt lgkmcnt(3)
	v_mfma_f32_16x16x32_f16 a[240:243], v[154:157], v[76:79], a[240:243]
	s_waitcnt lgkmcnt(2)
	v_mfma_f32_16x16x32_f16 a[252:255], v[158:161], v[76:79], a[252:255]
	s_waitcnt lgkmcnt(1)
	v_mfma_f32_16x16x32_f16 a[248:251], v[162:165], v[76:79], a[248:251]
	s_waitcnt lgkmcnt(0)
	v_mfma_f32_16x16x32_f16 a[244:247], v[166:169], v[76:79], a[244:247]
	v_mfma_f32_16x16x32_f16 a[236:239], v[154:157], v[80:83], a[236:239]
	v_mfma_f32_16x16x32_f16 a[232:235], v[158:161], v[80:83], a[232:235]
	v_mfma_f32_16x16x32_f16 a[228:231], v[162:165], v[80:83], a[228:231]
	v_mfma_f32_16x16x32_f16 a[224:227], v[166:169], v[80:83], a[224:227]
	v_mfma_f32_16x16x32_f16 a[220:223], v[154:157], v[142:145], a[220:223]
	v_mfma_f32_16x16x32_f16 a[216:219], v[158:161], v[142:145], a[216:219]
	v_mfma_f32_16x16x32_f16 a[212:215], v[162:165], v[142:145], a[212:215]
	v_mfma_f32_16x16x32_f16 a[204:207], v[166:169], v[142:145], a[204:207]
	v_mfma_f32_16x16x32_f16 a[172:175], v[154:157], v[146:149], a[172:175]
	v_mfma_f32_16x16x32_f16 a[168:171], v[158:161], v[146:149], a[168:171]
	v_mfma_f32_16x16x32_f16 a[164:167], v[162:165], v[146:149], a[164:167]
	v_mfma_f32_16x16x32_f16 a[160:163], v[166:169], v[146:149], a[160:163]
	v_mfma_f32_16x16x32_f16 a[140:143], v[154:157], v[150:153], a[140:143]
	v_mfma_f32_16x16x32_f16 a[136:139], v[158:161], v[150:153], a[136:139]
	v_mfma_f32_16x16x32_f16 a[132:135], v[162:165], v[150:153], a[132:135]
	v_mfma_f32_16x16x32_f16 a[128:131], v[166:169], v[150:153], a[128:131]
	s_waitcnt vmcnt(0)
; #define LD_AF(dst, ks_) _Pragma("unroll") for (int i = 0; i < 8; ++i) dst[i] = *(const h8*)(sA + i * 16 * G_LD + (ks_) * 32)
; #define LD_BF(dst, ks_, nh_) _Pragma("unroll") for (int i = 0; i < 4; ++i) dst[i] = *(const h8*)(sB + ((nh_) * 4 + i) * 16 * G_LD + (ks_) * 32)
; #define MMA_BLK(afx, bfx, nh_) _Pragma("unroll") for (int mi = 0; mi < 8; ++mi) _Pragma("unroll") for (int ni = 0; ni < 4; ++ni) mfma16_acc(acc[mi][(nh_) * 4 + ni], bfx[ni], afx[mi])
; template <class Epi>
; __device__ __forceinline__ void gemm_run(const GemmArgs g, Epi epi, char* smem) {
;     ...
;       LD_AF(afB, 1); LD_BF(bfA, 1, 0);
;       MMA_BLK(afA, bfB, 1);
;       __builtin_amdgcn_sched_barrier(0);
;       if (kt + 2 < nk) {
;         const int ko = (kt + 2) * 64;
; #pragma unroll
;         for (int i = 0; i < 8; ++i) { ra[i] = __builtin_amdgcn_raw_buffer_load_b128(Ars, aoff, i * astep + ko * 2, 0); rb[i] = __builtin_amdgcn_raw_buffer_load_b128(Brs, boff, i * bstep + ko * 2, 0); }
;       }
;       LD_BF(bfB, 1, 1);
;       MMA_BLK(afB, bfA, 0);
;       __builtin_amdgcn_sched_barrier(0);
;       MMA_BLK(afB, bfB, 1);
;       __builtin_amdgcn_sched_barrier(0);
	v_accvgpr_read_b32 v171, a243
	v_accvgpr_read_b32 v170, a242
	v_accvgpr_read_b32 v173, a255
	v_accvgpr_read_b32 v172, a254
	v_accvgpr_read_b32 v127, a251
	v_accvgpr_read_b32 v126, a250
	v_accvgpr_read_b32 v125, a247
	v_accvgpr_read_b32 v124, a246
	v_accvgpr_read_b32 v115, a239
	v_accvgpr_read_b32 v114, a238
	v_accvgpr_read_b32 v113, a235
	v_accvgpr_read_b32 v112, a234
	v_accvgpr_read_b32 v111, a231
	v_accvgpr_read_b32 v110, a230
	v_accvgpr_read_b32 v109, a227
	v_accvgpr_read_b32 v108, a226
	v_accvgpr_read_b32 v99, a223
	v_accvgpr_read_b32 v98, a222
	v_accvgpr_read_b32 v97, a219
	v_accvgpr_read_b32 v96, a218
	v_accvgpr_read_b32 v95, a215
	v_accvgpr_read_b32 v94, a214
	v_accvgpr_read_b32 v93, a207
	v_accvgpr_read_b32 v92, a206
	v_accvgpr_read_b32 v83, a175
	v_accvgpr_read_b32 v82, a174
	v_accvgpr_read_b32 v81, a171
	v_accvgpr_read_b32 v80, a170
	v_accvgpr_read_b32 v79, a167
	v_accvgpr_read_b32 v78, a166
	v_accvgpr_read_b32 v77, a163
	v_accvgpr_read_b32 v76, a162
	v_accvgpr_read_b32 v67, a143
	v_accvgpr_read_b32 v66, a142
	v_accvgpr_read_b32 v65, a139
	v_accvgpr_read_b32 v64, a138
	v_accvgpr_read_b32 v63, a135
	v_accvgpr_read_b32 v62, a134
	v_accvgpr_read_b32 v61, a131
	v_accvgpr_read_b32 v60, a130
	v_mfma_f32_16x16x32_f16 a[108:111], v[154:157], v[8:11], a[108:111]
	v_mfma_f32_16x16x32_f16 a[104:107], v[158:161], v[8:11], a[104:107]
	v_mfma_f32_16x16x32_f16 a[100:103], v[162:165], v[8:11], a[100:103]
	v_mfma_f32_16x16x32_f16 a[96:99], v[166:169], v[8:11], a[96:99]
	v_mfma_f32_16x16x32_f16 a[76:79], v[154:157], v[4:7], a[76:79]
	v_mfma_f32_16x16x32_f16 a[72:75], v[158:161], v[4:7], a[72:75]
	v_mfma_f32_16x16x32_f16 a[68:71], v[162:165], v[4:7], a[68:71]
	v_mfma_f32_16x16x32_f16 a[64:67], v[166:169], v[4:7], a[64:67]
	v_mfma_f32_16x16x32_f16 a[44:47], v[154:157], v[0:3], a[44:47]
	v_mfma_f32_16x16x32_f16 a[40:43], v[158:161], v[0:3], a[40:43]
	v_mfma_f32_16x16x32_f16 a[36:39], v[162:165], v[0:3], a[36:39]
	v_mfma_f32_16x16x32_f16 a[16:19], v[166:169], v[0:3], a[16:19]
	s_nop 0
	v_add_u32_e32 v30, s18, v130
	v_min_i32_e32 v3, 0x8000, v30
	v_or_b32_e32 v2, s20, v135
	v_ashrrev_i32_e32 v3, 13, v3
	v_mul_hi_i32_i24_e32 v143, 0xc000, v3
	v_mul_i32_i24_e32 v142, 0xc000, v3
	v_ashrrev_i32_e32 v3, 31, v2
	v_lshl_add_u64 v[142:143], s[12:13], 0, v[142:143]
	v_lshlrev_b64 v[2:3], 2, v[2:3]
	v_ashrrev_i32_e32 v31, 31, v30
	v_lshl_add_u64 v[150:151], v[142:143], 0, v[2:3]
	v_lshlrev_b64 v[142:143], 13, v[30:31]
	v_lshl_add_u64 v[142:143], s[28:29], 0, v[142:143]
	v_lshl_add_u64 v[152:153], v[142:143], 0, v[2:3]
	s_barrier
	global_load_dwordx4 v[4:7], v[150:151], off
	global_load_dwordx4 v[8:11], v[150:151], off offset:64
	global_load_dwordx4 v[12:15], v[150:151], off offset:128
	global_load_dwordx4 v[16:19], v[150:151], off offset:192
	global_load_dwordx4 v[20:23], v[150:151], off offset:256
	global_load_dwordx4 v[24:27], v[150:151], off offset:320
	global_load_dwordx4 v[32:35], v[150:151], off offset:384
	global_load_dwordx4 v[36:39], v[150:151], off offset:448
	global_load_dwordx4 v[40:43], v[152:153], off
	global_load_dwordx4 v[44:47], v[152:153], off offset:64
	global_load_dwordx4 v[48:51], v[152:153], off offset:128
	global_load_dwordx4 v[52:55], v[152:153], off offset:192
	global_load_dwordx4 v[56:59], v[152:153], off offset:256
	global_load_dwordx4 v[60:63], v[152:153], off offset:320
	global_load_dwordx4 v[64:67], v[152:153], off offset:384
	global_load_dwordx4 v[68:71], v[152:153], off offset:448
	v_mov_b32_e32 v110, 0x20000
	v_mov_b32_e32 v111, 0
	v_lshl_add_u64 v[108:109], v[152:153], 0, v[110:111]
	v_mov_b32_e32 v110, 0x40000
	global_load_dwordx4 v[72:75], v[108:109], off
	global_load_dwordx4 v[76:79], v[108:109], off offset:64
	global_load_dwordx4 v[80:83], v[108:109], off offset:128
	global_load_dwordx4 v[84:87], v[108:109], off offset:192
	global_load_dwordx4 v[88:91], v[108:109], off offset:256
	global_load_dwordx4 v[92:95], v[108:109], off offset:320
	global_load_dwordx4 v[96:99], v[108:109], off offset:384
	global_load_dwordx4 v[100:103], v[108:109], off offset:448
	v_accvgpr_read_b32 v104, a208
	v_accvgpr_read_b32 v105, a209
	v_accvgpr_read_b32 v106, a210
	v_accvgpr_read_b32 v107, a211
	s_waitcnt vmcnt(15)
	v_pk_fma_f32 v[40:41], v[104:105], v[4:5], v[40:41]
	v_pk_fma_f32 v[42:43], v[106:107], v[6:7], v[42:43]
	global_store_dwordx4 v[152:153], v[40:43], off
	v_accvgpr_read_b32 v104, a200
	v_accvgpr_read_b32 v105, a201
	v_accvgpr_read_b32 v106, a202
	v_accvgpr_read_b32 v107, a203
	s_waitcnt vmcnt(15)
	v_pk_fma_f32 v[44:45], v[104:105], v[8:9], v[44:45]
	v_pk_fma_f32 v[46:47], v[106:107], v[10:11], v[46:47]
	global_store_dwordx4 v[152:153], v[44:47], off offset:64
	v_accvgpr_read_b32 v104, a196
	v_accvgpr_read_b32 v105, a197
	v_accvgpr_read_b32 v106, a198
	v_accvgpr_read_b32 v107, a199
	s_waitcnt vmcnt(15)
	v_pk_fma_f32 v[48:49], v[104:105], v[12:13], v[48:49]
	v_pk_fma_f32 v[50:51], v[106:107], v[14:15], v[50:51]
	global_store_dwordx4 v[152:153], v[48:51], off offset:128
	v_accvgpr_read_b32 v104, a192
	v_accvgpr_read_b32 v105, a193
	v_accvgpr_read_b32 v106, a194
	v_accvgpr_read_b32 v107, a195
	s_waitcnt vmcnt(15)
	v_pk_fma_f32 v[52:53], v[104:105], v[16:17], v[52:53]
	v_pk_fma_f32 v[54:55], v[106:107], v[18:19], v[54:55]
	global_store_dwordx4 v[152:153], v[52:55], off offset:192
	v_accvgpr_read_b32 v104, a240
	v_accvgpr_read_b32 v105, a241
	v_accvgpr_read_b32 v106, a242
	v_accvgpr_read_b32 v107, a243
	s_waitcnt vmcnt(15)
	v_pk_fma_f32 v[56:57], v[104:105], v[20:21], v[56:57]
	v_pk_fma_f32 v[58:59], v[106:107], v[22:23], v[58:59]
	global_store_dwordx4 v[152:153], v[56:59], off offset:256
	v_accvgpr_read_b32 v104, a252
	v_accvgpr_read_b32 v105, a253
	v_accvgpr_read_b32 v106, a254
	v_accvgpr_read_b32 v107, a255
	s_waitcnt vmcnt(15)
	v_pk_fma_f32 v[60:61], v[104:105], v[24:25], v[60:61]
	v_pk_fma_f32 v[62:63], v[106:107], v[26:27], v[62:63]
	global_store_dwordx4 v[152:153], v[60:63], off offset:320
	v_accvgpr_read_b32 v104, a248
	v_accvgpr_read_b32 v105, a249
	v_accvgpr_read_b32 v106, a250
	v_accvgpr_read_b32 v107, a251
	s_waitcnt vmcnt(15)
	v_pk_fma_f32 v[64:65], v[104:105], v[32:33], v[64:65]
	v_pk_fma_f32 v[66:67], v[106:107], v[34:35], v[66:67]
	global_store_dwordx4 v[152:153], v[64:67], off offset:384
	v_accvgpr_read_b32 v104, a244
	v_accvgpr_read_b32 v105, a245
	v_accvgpr_read_b32 v106, a246
	v_accvgpr_read_b32 v107, a247
	s_waitcnt vmcnt(15)
	v_pk_fma_f32 v[68:69], v[104:105], v[36:37], v[68:69]
	v_pk_fma_f32 v[70:71], v[106:107], v[38:39], v[70:71]
	global_store_dwordx4 v[152:153], v[68:71], off offset:448
	v_lshl_add_u64 v[152:153], v[152:153], 0, v[110:111]
	s_nop 1
	global_load_dwordx4 v[40:43], v[152:153], off
	global_load_dwordx4 v[44:47], v[152:153], off offset:64
	global_load_dwordx4 v[48:51], v[152:153], off offset:128
	global_load_dwordx4 v[52:55], v[152:153], off offset:192
	global_load_dwordx4 v[56:59], v[152:153], off offset:256
	global_load_dwordx4 v[60:63], v[152:153], off offset:320
	global_load_dwordx4 v[64:67], v[152:153], off offset:384
	global_load_dwordx4 v[68:71], v[152:153], off offset:448
	v_accvgpr_read_b32 v104, a188
	v_accvgpr_read_b32 v105, a189
	v_accvgpr_read_b32 v106, a190
	v_accvgpr_read_b32 v107, a191
	s_waitcnt vmcnt(23)
	v_pk_fma_f32 v[72:73], v[104:105], v[4:5], v[72:73]
	v_pk_fma_f32 v[74:75], v[106:107], v[6:7], v[74:75]
	global_store_dwordx4 v[108:109], v[72:75], off
	v_accvgpr_read_b32 v104, a184
	v_accvgpr_read_b32 v105, a185
	v_accvgpr_read_b32 v106, a186
	v_accvgpr_read_b32 v107, a187
	s_waitcnt vmcnt(23)
	v_pk_fma_f32 v[76:77], v[104:105], v[8:9], v[76:77]
	v_pk_fma_f32 v[78:79], v[106:107], v[10:11], v[78:79]
	global_store_dwordx4 v[108:109], v[76:79], off offset:64
	v_accvgpr_read_b32 v104, a180
	v_accvgpr_read_b32 v105, a181
	v_accvgpr_read_b32 v106, a182
	v_accvgpr_read_b32 v107, a183
	s_waitcnt vmcnt(23)
	v_pk_fma_f32 v[80:81], v[104:105], v[12:13], v[80:81]
	v_pk_fma_f32 v[82:83], v[106:107], v[14:15], v[82:83]
	global_store_dwordx4 v[108:109], v[80:83], off offset:128
	v_accvgpr_read_b32 v104, a176
	v_accvgpr_read_b32 v105, a177
	v_accvgpr_read_b32 v106, a178
	v_accvgpr_read_b32 v107, a179
	s_waitcnt vmcnt(23)
	v_pk_fma_f32 v[84:85], v[104:105], v[16:17], v[84:85]
	v_pk_fma_f32 v[86:87], v[106:107], v[18:19], v[86:87]
	global_store_dwordx4 v[108:109], v[84:87], off offset:192
	v_accvgpr_read_b32 v104, a236
	v_accvgpr_read_b32 v105, a237
	v_accvgpr_read_b32 v106, a238
	v_accvgpr_read_b32 v107, a239
	s_waitcnt vmcnt(23)
	v_pk_fma_f32 v[88:89], v[104:105], v[20:21], v[88:89]
	v_pk_fma_f32 v[90:91], v[106:107], v[22:23], v[90:91]
	global_store_dwordx4 v[108:109], v[88:91], off offset:256
	v_accvgpr_read_b32 v104, a232
	v_accvgpr_read_b32 v105, a233
	v_accvgpr_read_b32 v106, a234
	v_accvgpr_read_b32 v107, a235
	s_waitcnt vmcnt(23)
	v_pk_fma_f32 v[92:93], v[104:105], v[24:25], v[92:93]
	v_pk_fma_f32 v[94:95], v[106:107], v[26:27], v[94:95]
	global_store_dwordx4 v[108:109], v[92:95], off offset:320
	v_accvgpr_read_b32 v104, a228
	v_accvgpr_read_b32 v105, a229
	v_accvgpr_read_b32 v106, a230
	v_accvgpr_read_b32 v107, a231
	s_waitcnt vmcnt(23)
	v_pk_fma_f32 v[96:97], v[104:105], v[32:33], v[96:97]
	v_pk_fma_f32 v[98:99], v[106:107], v[34:35], v[98:99]
	global_store_dwordx4 v[108:109], v[96:99], off offset:384
	v_accvgpr_read_b32 v104, a224
	v_accvgpr_read_b32 v105, a225
	v_accvgpr_read_b32 v106, a226
	v_accvgpr_read_b32 v107, a227
	s_waitcnt vmcnt(23)
	v_pk_fma_f32 v[100:101], v[104:105], v[36:37], v[100:101]
	v_pk_fma_f32 v[102:103], v[106:107], v[38:39], v[102:103]
	global_store_dwordx4 v[108:109], v[100:103], off offset:448
	v_lshl_add_u64 v[108:109], v[108:109], 0, v[110:111]
	s_nop 1
	global_load_dwordx4 v[72:75], v[108:109], off
	global_load_dwordx4 v[76:79], v[108:109], off offset:64
	global_load_dwordx4 v[80:83], v[108:109], off offset:128
	global_load_dwordx4 v[84:87], v[108:109], off offset:192
	global_load_dwordx4 v[88:91], v[108:109], off offset:256
	global_load_dwordx4 v[92:95], v[108:109], off offset:320
	global_load_dwordx4 v[96:99], v[108:109], off offset:384
	global_load_dwordx4 v[100:103], v[108:109], off offset:448
	v_accvgpr_read_b32 v104, a156
	v_accvgpr_read_b32 v105, a157
	v_accvgpr_read_b32 v106, a158
	v_accvgpr_read_b32 v107, a159
	s_waitcnt vmcnt(23)
	v_pk_fma_f32 v[40:41], v[104:105], v[4:5], v[40:41]
	v_pk_fma_f32 v[42:43], v[106:107], v[6:7], v[42:43]
	global_store_dwordx4 v[152:153], v[40:43], off
	v_accvgpr_read_b32 v104, a152
	v_accvgpr_read_b32 v105, a153
	v_accvgpr_read_b32 v106, a154
	v_accvgpr_read_b32 v107, a155
	s_waitcnt vmcnt(23)
	v_pk_fma_f32 v[44:45], v[104:105], v[8:9], v[44:45]
	v_pk_fma_f32 v[46:47], v[106:107], v[10:11], v[46:47]
	global_store_dwordx4 v[152:153], v[44:47], off offset:64
	v_accvgpr_read_b32 v104, a148
	v_accvgpr_read_b32 v105, a149
	v_accvgpr_read_b32 v106, a150
	v_accvgpr_read_b32 v107, a151
	s_waitcnt vmcnt(23)
	v_pk_fma_f32 v[48:49], v[104:105], v[12:13], v[48:49]
	v_pk_fma_f32 v[50:51], v[106:107], v[14:15], v[50:51]
	global_store_dwordx4 v[152:153], v[48:51], off offset:128
	v_accvgpr_read_b32 v104, a144
	v_accvgpr_read_b32 v105, a145
	v_accvgpr_read_b32 v106, a146
	v_accvgpr_read_b32 v107, a147
	s_waitcnt vmcnt(23)
	v_pk_fma_f32 v[52:53], v[104:105], v[16:17], v[52:53]
	v_pk_fma_f32 v[54:55], v[106:107], v[18:19], v[54:55]
	global_store_dwordx4 v[152:153], v[52:55], off offset:192
	v_accvgpr_read_b32 v104, a220
	v_accvgpr_read_b32 v105, a221
	v_accvgpr_read_b32 v106, a222
	v_accvgpr_read_b32 v107, a223
	s_waitcnt vmcnt(23)
	v_pk_fma_f32 v[56:57], v[104:105], v[20:21], v[56:57]
	v_pk_fma_f32 v[58:59], v[106:107], v[22:23], v[58:59]
	global_store_dwordx4 v[152:153], v[56:59], off offset:256
	v_accvgpr_read_b32 v104, a216
	v_accvgpr_read_b32 v105, a217
	v_accvgpr_read_b32 v106, a218
	v_accvgpr_read_b32 v107, a219
	s_waitcnt vmcnt(23)
	v_pk_fma_f32 v[60:61], v[104:105], v[24:25], v[60:61]
	v_pk_fma_f32 v[62:63], v[106:107], v[26:27], v[62:63]
	global_store_dwordx4 v[152:153], v[60:63], off offset:320
	v_accvgpr_read_b32 v104, a212
	v_accvgpr_read_b32 v105, a213
	v_accvgpr_read_b32 v106, a214
	v_accvgpr_read_b32 v107, a215
	s_waitcnt vmcnt(23)
	v_pk_fma_f32 v[64:65], v[104:105], v[32:33], v[64:65]
	v_pk_fma_f32 v[66:67], v[106:107], v[34:35], v[66:67]
	global_store_dwordx4 v[152:153], v[64:67], off offset:384
	v_accvgpr_read_b32 v104, a204
	v_accvgpr_read_b32 v105, a205
	v_accvgpr_read_b32 v106, a206
	v_accvgpr_read_b32 v107, a207
	s_waitcnt vmcnt(23)
	v_pk_fma_f32 v[68:69], v[104:105], v[36:37], v[68:69]
	v_pk_fma_f32 v[70:71], v[106:107], v[38:39], v[70:71]
	global_store_dwordx4 v[152:153], v[68:71], off offset:448
	v_lshl_add_u64 v[152:153], v[152:153], 0, v[110:111]
	s_nop 1
	global_load_dwordx4 v[40:43], v[152:153], off
	global_load_dwordx4 v[44:47], v[152:153], off offset:64
	global_load_dwordx4 v[48:51], v[152:153], off offset:128
	global_load_dwordx4 v[52:55], v[152:153], off offset:192
	global_load_dwordx4 v[56:59], v[152:153], off offset:256
	global_load_dwordx4 v[60:63], v[152:153], off offset:320
	global_load_dwordx4 v[64:67], v[152:153], off offset:384
	global_load_dwordx4 v[68:71], v[152:153], off offset:448
	v_accvgpr_read_b32 v104, a124
	v_accvgpr_read_b32 v105, a125
	v_accvgpr_read_b32 v106, a126
	v_accvgpr_read_b32 v107, a127
	s_waitcnt vmcnt(23)
	v_pk_fma_f32 v[72:73], v[104:105], v[4:5], v[72:73]
	v_pk_fma_f32 v[74:75], v[106:107], v[6:7], v[74:75]
	global_store_dwordx4 v[108:109], v[72:75], off
	v_accvgpr_read_b32 v104, a120
	v_accvgpr_read_b32 v105, a121
	v_accvgpr_read_b32 v106, a122
	v_accvgpr_read_b32 v107, a123
	s_waitcnt vmcnt(23)
	v_pk_fma_f32 v[76:77], v[104:105], v[8:9], v[76:77]
	v_pk_fma_f32 v[78:79], v[106:107], v[10:11], v[78:79]
	global_store_dwordx4 v[108:109], v[76:79], off offset:64
	v_accvgpr_read_b32 v104, a116
	v_accvgpr_read_b32 v105, a117
	v_accvgpr_read_b32 v106, a118
	v_accvgpr_read_b32 v107, a119
	s_waitcnt vmcnt(23)
	v_pk_fma_f32 v[80:81], v[104:105], v[12:13], v[80:81]
	v_pk_fma_f32 v[82:83], v[106:107], v[14:15], v[82:83]
	global_store_dwordx4 v[108:109], v[80:83], off offset:128
	v_accvgpr_read_b32 v104, a112
	v_accvgpr_read_b32 v105, a113
	v_accvgpr_read_b32 v106, a114
	v_accvgpr_read_b32 v107, a115
	s_waitcnt vmcnt(23)
	v_pk_fma_f32 v[84:85], v[104:105], v[16:17], v[84:85]
	v_pk_fma_f32 v[86:87], v[106:107], v[18:19], v[86:87]
	global_store_dwordx4 v[108:109], v[84:87], off offset:192
	v_accvgpr_read_b32 v104, a172
	v_accvgpr_read_b32 v105, a173
	v_accvgpr_read_b32 v106, a174
	v_accvgpr_read_b32 v107, a175
	s_waitcnt vmcnt(23)
	v_pk_fma_f32 v[88:89], v[104:105], v[20:21], v[88:89]
	v_pk_fma_f32 v[90:91], v[106:107], v[22:23], v[90:91]
	global_store_dwordx4 v[108:109], v[88:91], off offset:256
	v_accvgpr_read_b32 v104, a168
	v_accvgpr_read_b32 v105, a169
	v_accvgpr_read_b32 v106, a170
	v_accvgpr_read_b32 v107, a171
	s_waitcnt vmcnt(23)
	v_pk_fma_f32 v[92:93], v[104:105], v[24:25], v[92:93]
	v_pk_fma_f32 v[94:95], v[106:107], v[26:27], v[94:95]
	global_store_dwordx4 v[108:109], v[92:95], off offset:320
	v_accvgpr_read_b32 v104, a164
	v_accvgpr_read_b32 v105, a165
	v_accvgpr_read_b32 v106, a166
	v_accvgpr_read_b32 v107, a167
	s_waitcnt vmcnt(23)
	v_pk_fma_f32 v[96:97], v[104:105], v[32:33], v[96:97]
	v_pk_fma_f32 v[98:99], v[106:107], v[34:35], v[98:99]
	global_store_dwordx4 v[108:109], v[96:99], off offset:384
	v_accvgpr_read_b32 v104, a160
	v_accvgpr_read_b32 v105, a161
	v_accvgpr_read_b32 v106, a162
	v_accvgpr_read_b32 v107, a163
	s_waitcnt vmcnt(23)
	v_pk_fma_f32 v[100:101], v[104:105], v[36:37], v[100:101]
	v_pk_fma_f32 v[102:103], v[106:107], v[38:39], v[102:103]
	global_store_dwordx4 v[108:109], v[100:103], off offset:448
	v_lshl_add_u64 v[108:109], v[108:109], 0, v[110:111]
	s_nop 1
	global_load_dwordx4 v[72:75], v[108:109], off
	global_load_dwordx4 v[76:79], v[108:109], off offset:64
	global_load_dwordx4 v[80:83], v[108:109], off offset:128
	global_load_dwordx4 v[84:87], v[108:109], off offset:192
	global_load_dwordx4 v[88:91], v[108:109], off offset:256
	global_load_dwordx4 v[92:95], v[108:109], off offset:320
	global_load_dwordx4 v[96:99], v[108:109], off offset:384
	global_load_dwordx4 v[100:103], v[108:109], off offset:448
	v_accvgpr_read_b32 v104, a92
	v_accvgpr_read_b32 v105, a93
	v_accvgpr_read_b32 v106, a94
	v_accvgpr_read_b32 v107, a95
	s_waitcnt vmcnt(23)
	v_pk_fma_f32 v[40:41], v[104:105], v[4:5], v[40:41]
	v_pk_fma_f32 v[42:43], v[106:107], v[6:7], v[42:43]
	global_store_dwordx4 v[152:153], v[40:43], off
	v_accvgpr_read_b32 v104, a88
	v_accvgpr_read_b32 v105, a89
	v_accvgpr_read_b32 v106, a90
	v_accvgpr_read_b32 v107, a91
	s_waitcnt vmcnt(23)
	v_pk_fma_f32 v[44:45], v[104:105], v[8:9], v[44:45]
	v_pk_fma_f32 v[46:47], v[106:107], v[10:11], v[46:47]
	global_store_dwordx4 v[152:153], v[44:47], off offset:64
	v_accvgpr_read_b32 v104, a84
	v_accvgpr_read_b32 v105, a85
	v_accvgpr_read_b32 v106, a86
	v_accvgpr_read_b32 v107, a87
	s_waitcnt vmcnt(23)
	v_pk_fma_f32 v[48:49], v[104:105], v[12:13], v[48:49]
	v_pk_fma_f32 v[50:51], v[106:107], v[14:15], v[50:51]
	global_store_dwordx4 v[152:153], v[48:51], off offset:128
	v_accvgpr_read_b32 v104, a80
	v_accvgpr_read_b32 v105, a81
	v_accvgpr_read_b32 v106, a82
	v_accvgpr_read_b32 v107, a83
	s_waitcnt vmcnt(23)
	v_pk_fma_f32 v[52:53], v[104:105], v[16:17], v[52:53]
	v_pk_fma_f32 v[54:55], v[106:107], v[18:19], v[54:55]
	global_store_dwordx4 v[152:153], v[52:55], off offset:192
	v_accvgpr_read_b32 v104, a140
	v_accvgpr_read_b32 v105, a141
	v_accvgpr_read_b32 v106, a142
	v_accvgpr_read_b32 v107, a143
	s_waitcnt vmcnt(23)
	v_pk_fma_f32 v[56:57], v[104:105], v[20:21], v[56:57]
	v_pk_fma_f32 v[58:59], v[106:107], v[22:23], v[58:59]
	global_store_dwordx4 v[152:153], v[56:59], off offset:256
	v_accvgpr_read_b32 v104, a136
	v_accvgpr_read_b32 v105, a137
	v_accvgpr_read_b32 v106, a138
	v_accvgpr_read_b32 v107, a139
	s_waitcnt vmcnt(23)
	v_pk_fma_f32 v[60:61], v[104:105], v[24:25], v[60:61]
	v_pk_fma_f32 v[62:63], v[106:107], v[26:27], v[62:63]
	global_store_dwordx4 v[152:153], v[60:63], off offset:320
	v_accvgpr_read_b32 v104, a132
	v_accvgpr_read_b32 v105, a133
	v_accvgpr_read_b32 v106, a134
	v_accvgpr_read_b32 v107, a135
	s_waitcnt vmcnt(23)
	v_pk_fma_f32 v[64:65], v[104:105], v[32:33], v[64:65]
	v_pk_fma_f32 v[66:67], v[106:107], v[34:35], v[66:67]
	global_store_dwordx4 v[152:153], v[64:67], off offset:384
	v_accvgpr_read_b32 v104, a128
	v_accvgpr_read_b32 v105, a129
	v_accvgpr_read_b32 v106, a130
	v_accvgpr_read_b32 v107, a131
	s_waitcnt vmcnt(23)
	v_pk_fma_f32 v[68:69], v[104:105], v[36:37], v[68:69]
	v_pk_fma_f32 v[70:71], v[106:107], v[38:39], v[70:71]
	global_store_dwordx4 v[152:153], v[68:71], off offset:448
	v_lshl_add_u64 v[152:153], v[152:153], 0, v[110:111]
	s_nop 1
	global_load_dwordx4 v[40:43], v[152:153], off
	global_load_dwordx4 v[44:47], v[152:153], off offset:64
	global_load_dwordx4 v[48:51], v[152:153], off offset:128
	global_load_dwordx4 v[52:55], v[152:153], off offset:192
	global_load_dwordx4 v[56:59], v[152:153], off offset:256
	global_load_dwordx4 v[60:63], v[152:153], off offset:320
	global_load_dwordx4 v[64:67], v[152:153], off offset:384
	global_load_dwordx4 v[68:71], v[152:153], off offset:448
	v_accvgpr_read_b32 v104, a60
	v_accvgpr_read_b32 v105, a61
	v_accvgpr_read_b32 v106, a62
	v_accvgpr_read_b32 v107, a63
	s_waitcnt vmcnt(23)
	v_pk_fma_f32 v[72:73], v[104:105], v[4:5], v[72:73]
	v_pk_fma_f32 v[74:75], v[106:107], v[6:7], v[74:75]
	global_store_dwordx4 v[108:109], v[72:75], off
	v_accvgpr_read_b32 v104, a56
	v_accvgpr_read_b32 v105, a57
	v_accvgpr_read_b32 v106, a58
	v_accvgpr_read_b32 v107, a59
	s_waitcnt vmcnt(23)
	v_pk_fma_f32 v[76:77], v[104:105], v[8:9], v[76:77]
	v_pk_fma_f32 v[78:79], v[106:107], v[10:11], v[78:79]
	global_store_dwordx4 v[108:109], v[76:79], off offset:64
	v_accvgpr_read_b32 v104, a52
	v_accvgpr_read_b32 v105, a53
	v_accvgpr_read_b32 v106, a54
	v_accvgpr_read_b32 v107, a55
	s_waitcnt vmcnt(23)
	v_pk_fma_f32 v[80:81], v[104:105], v[12:13], v[80:81]
	v_pk_fma_f32 v[82:83], v[106:107], v[14:15], v[82:83]
	global_store_dwordx4 v[108:109], v[80:83], off offset:128
	v_accvgpr_read_b32 v104, a48
	v_accvgpr_read_b32 v105, a49
	v_accvgpr_read_b32 v106, a50
	v_accvgpr_read_b32 v107, a51
	s_waitcnt vmcnt(23)
	v_pk_fma_f32 v[84:85], v[104:105], v[16:17], v[84:85]
	v_pk_fma_f32 v[86:87], v[106:107], v[18:19], v[86:87]
	global_store_dwordx4 v[108:109], v[84:87], off offset:192
	v_accvgpr_read_b32 v104, a108
	v_accvgpr_read_b32 v105, a109
	v_accvgpr_read_b32 v106, a110
	v_accvgpr_read_b32 v107, a111
	s_waitcnt vmcnt(23)
	v_pk_fma_f32 v[88:89], v[104:105], v[20:21], v[88:89]
	v_pk_fma_f32 v[90:91], v[106:107], v[22:23], v[90:91]
	global_store_dwordx4 v[108:109], v[88:91], off offset:256
	v_accvgpr_read_b32 v104, a104
	v_accvgpr_read_b32 v105, a105
	v_accvgpr_read_b32 v106, a106
	v_accvgpr_read_b32 v107, a107
	s_waitcnt vmcnt(23)
	v_pk_fma_f32 v[92:93], v[104:105], v[24:25], v[92:93]
	v_pk_fma_f32 v[94:95], v[106:107], v[26:27], v[94:95]
	global_store_dwordx4 v[108:109], v[92:95], off offset:320
	v_accvgpr_read_b32 v104, a100
	v_accvgpr_read_b32 v105, a101
	v_accvgpr_read_b32 v106, a102
	v_accvgpr_read_b32 v107, a103
	s_waitcnt vmcnt(23)
	v_pk_fma_f32 v[96:97], v[104:105], v[32:33], v[96:97]
	v_pk_fma_f32 v[98:99], v[106:107], v[34:35], v[98:99]
	global_store_dwordx4 v[108:109], v[96:99], off offset:384
	v_accvgpr_read_b32 v104, a96
	v_accvgpr_read_b32 v105, a97
	v_accvgpr_read_b32 v106, a98
	v_accvgpr_read_b32 v107, a99
	s_waitcnt vmcnt(23)
	v_pk_fma_f32 v[100:101], v[104:105], v[36:37], v[100:101]
	v_pk_fma_f32 v[102:103], v[106:107], v[38:39], v[102:103]
	global_store_dwordx4 v[108:109], v[100:103], off offset:448
	v_lshl_add_u64 v[108:109], v[108:109], 0, v[110:111]
	s_nop 1
	global_load_dwordx4 v[72:75], v[108:109], off
	global_load_dwordx4 v[76:79], v[108:109], off offset:64
	global_load_dwordx4 v[80:83], v[108:109], off offset:128
	global_load_dwordx4 v[84:87], v[108:109], off offset:192
	global_load_dwordx4 v[88:91], v[108:109], off offset:256
	global_load_dwordx4 v[92:95], v[108:109], off offset:320
	global_load_dwordx4 v[96:99], v[108:109], off offset:384
	global_load_dwordx4 v[100:103], v[108:109], off offset:448
	v_accvgpr_read_b32 v104, a32
	v_accvgpr_read_b32 v105, a33
	v_accvgpr_read_b32 v106, a34
	v_accvgpr_read_b32 v107, a35
	s_waitcnt vmcnt(23)
; template <class Epi>
; __device__ __forceinline__ void gemm_run(const GemmArgs g, Epi epi, char* smem) {
;     ...
;   for (int tile = blockIdx.x; tile < total; tile += gridDim.x) {
	v_pk_fma_f32 v[40:41], v[104:105], v[4:5], v[40:41]
	v_pk_fma_f32 v[42:43], v[106:107], v[6:7], v[42:43]
	global_store_dwordx4 v[152:153], v[40:43], off
	v_accvgpr_read_b32 v104, a28
	v_accvgpr_read_b32 v105, a29
	v_accvgpr_read_b32 v106, a30
	v_accvgpr_read_b32 v107, a31
	s_waitcnt vmcnt(23)
	v_pk_fma_f32 v[44:45], v[104:105], v[8:9], v[44:45]
	v_pk_fma_f32 v[46:47], v[106:107], v[10:11], v[46:47]
	global_store_dwordx4 v[152:153], v[44:47], off offset:64
	v_accvgpr_read_b32 v104, a24
	v_accvgpr_read_b32 v105, a25
	v_accvgpr_read_b32 v106, a26
	v_accvgpr_read_b32 v107, a27
	s_waitcnt vmcnt(23)
	v_pk_fma_f32 v[48:49], v[104:105], v[12:13], v[48:49]
	v_pk_fma_f32 v[50:51], v[106:107], v[14:15], v[50:51]
	global_store_dwordx4 v[152:153], v[48:51], off offset:128
	v_accvgpr_read_b32 v104, a20
	v_accvgpr_read_b32 v105, a21
	v_accvgpr_read_b32 v106, a22
	v_accvgpr_read_b32 v107, a23
	s_waitcnt vmcnt(23)
	v_pk_fma_f32 v[52:53], v[104:105], v[16:17], v[52:53]
	v_pk_fma_f32 v[54:55], v[106:107], v[18:19], v[54:55]
	global_store_dwordx4 v[152:153], v[52:55], off offset:192
	v_accvgpr_read_b32 v104, a76
	v_accvgpr_read_b32 v105, a77
	v_accvgpr_read_b32 v106, a78
	v_accvgpr_read_b32 v107, a79
	s_waitcnt vmcnt(23)
	v_pk_fma_f32 v[56:57], v[104:105], v[20:21], v[56:57]
	v_pk_fma_f32 v[58:59], v[106:107], v[22:23], v[58:59]
	global_store_dwordx4 v[152:153], v[56:59], off offset:256
	v_accvgpr_read_b32 v104, a72
	v_accvgpr_read_b32 v105, a73
	v_accvgpr_read_b32 v106, a74
	v_accvgpr_read_b32 v107, a75
	s_waitcnt vmcnt(23)
	v_pk_fma_f32 v[60:61], v[104:105], v[24:25], v[60:61]
	v_pk_fma_f32 v[62:63], v[106:107], v[26:27], v[62:63]
	global_store_dwordx4 v[152:153], v[60:63], off offset:320
	v_accvgpr_read_b32 v104, a68
	v_accvgpr_read_b32 v105, a69
	v_accvgpr_read_b32 v106, a70
	v_accvgpr_read_b32 v107, a71
	s_waitcnt vmcnt(23)
	v_pk_fma_f32 v[64:65], v[104:105], v[32:33], v[64:65]
	v_pk_fma_f32 v[66:67], v[106:107], v[34:35], v[66:67]
	global_store_dwordx4 v[152:153], v[64:67], off offset:384
	v_accvgpr_read_b32 v104, a64
	v_accvgpr_read_b32 v105, a65
	v_accvgpr_read_b32 v106, a66
	v_accvgpr_read_b32 v107, a67
	s_waitcnt vmcnt(23)
	v_pk_fma_f32 v[68:69], v[104:105], v[36:37], v[68:69]
	v_pk_fma_f32 v[70:71], v[106:107], v[38:39], v[70:71]
	global_store_dwordx4 v[152:153], v[68:71], off offset:448
	v_accvgpr_read_b32 v104, a12
	v_accvgpr_read_b32 v105, a13
	v_accvgpr_read_b32 v106, a14
	v_accvgpr_read_b32 v107, a15
	s_waitcnt vmcnt(15)
	v_pk_fma_f32 v[72:73], v[104:105], v[4:5], v[72:73]
	v_pk_fma_f32 v[74:75], v[106:107], v[6:7], v[74:75]
	global_store_dwordx4 v[108:109], v[72:75], off
	v_accvgpr_read_b32 v104, a8
	v_accvgpr_read_b32 v105, a9
	v_accvgpr_read_b32 v106, a10
	v_accvgpr_read_b32 v107, a11
	s_waitcnt vmcnt(15)
	v_pk_fma_f32 v[76:77], v[104:105], v[8:9], v[76:77]
	v_pk_fma_f32 v[78:79], v[106:107], v[10:11], v[78:79]
	global_store_dwordx4 v[108:109], v[76:79], off offset:64
	v_accvgpr_read_b32 v104, a4
	v_accvgpr_read_b32 v105, a5
	v_accvgpr_read_b32 v106, a6
	v_accvgpr_read_b32 v107, a7
	s_waitcnt vmcnt(15)
	v_pk_fma_f32 v[80:81], v[104:105], v[12:13], v[80:81]
	v_pk_fma_f32 v[82:83], v[106:107], v[14:15], v[82:83]
	global_store_dwordx4 v[108:109], v[80:83], off offset:128
	v_accvgpr_read_b32 v104, a0
	v_accvgpr_read_b32 v105, a1
	v_accvgpr_read_b32 v106, a2
	v_accvgpr_read_b32 v107, a3
	s_waitcnt vmcnt(15)
	v_pk_fma_f32 v[84:85], v[104:105], v[16:17], v[84:85]
	v_pk_fma_f32 v[86:87], v[106:107], v[18:19], v[86:87]
	global_store_dwordx4 v[108:109], v[84:87], off offset:192
	v_accvgpr_read_b32 v104, a44
	v_accvgpr_read_b32 v105, a45
	v_accvgpr_read_b32 v106, a46
	v_accvgpr_read_b32 v107, a47
	s_waitcnt vmcnt(15)
	v_pk_fma_f32 v[88:89], v[104:105], v[20:21], v[88:89]
	v_pk_fma_f32 v[90:91], v[106:107], v[22:23], v[90:91]
	global_store_dwordx4 v[108:109], v[88:91], off offset:256
	v_accvgpr_read_b32 v104, a40
	v_accvgpr_read_b32 v105, a41
	v_accvgpr_read_b32 v106, a42
	v_accvgpr_read_b32 v107, a43
	s_waitcnt vmcnt(15)
	v_pk_fma_f32 v[92:93], v[104:105], v[24:25], v[92:93]
	v_pk_fma_f32 v[94:95], v[106:107], v[26:27], v[94:95]
	global_store_dwordx4 v[108:109], v[92:95], off offset:320
	v_accvgpr_read_b32 v104, a36
	v_accvgpr_read_b32 v105, a37
	v_accvgpr_read_b32 v106, a38
	v_accvgpr_read_b32 v107, a39
	s_waitcnt vmcnt(15)
	v_pk_fma_f32 v[96:97], v[104:105], v[32:33], v[96:97]
	v_pk_fma_f32 v[98:99], v[106:107], v[34:35], v[98:99]
	global_store_dwordx4 v[108:109], v[96:99], off offset:384
	v_accvgpr_read_b32 v104, a16
	v_accvgpr_read_b32 v105, a17
	v_accvgpr_read_b32 v106, a18
	v_accvgpr_read_b32 v107, a19
	s_waitcnt vmcnt(15)
	v_pk_fma_f32 v[100:101], v[104:105], v[36:37], v[100:101]
	v_pk_fma_f32 v[102:103], v[106:107], v[38:39], v[102:103]
	global_store_dwordx4 v[108:109], v[100:103], off offset:448
	v_readlane_b32 s4, v255, 22
	s_add_i32 s77, s77, s4
	s_cmpk_gt_i32 s77, 0x5ff
	s_cbranch_scc1 .LBB0_923

; #define LD_AF(dst, ks_) _Pragma("unroll") for (int i = 0; i < 8; ++i) dst[i] = *(const h8*)(sA + i * 16 * G_LD + (ks_) * 32)
; #define LD_BF(dst, ks_, nh_) _Pragma("unroll") for (int i = 0; i < 4; ++i) dst[i] = *(const h8*)(sB + ((nh_) * 4 + i) * 16 * G_LD + (ks_) * 32)
; #define MMA_BLK(afx, bfx, nh_) _Pragma("unroll") for (int mi = 0; mi < 8; ++mi) _Pragma("unroll") for (int ni = 0; ni < 4; ++ni) mfma16_acc(acc[mi][(nh_) * 4 + ni], bfx[ni], afx[mi])
; template <class Epi>
; __device__ __forceinline__ void gemm_run(const GemmArgs g, Epi epi, char* smem) {
;     ...
;       h8 afA[8], afB[8], bfA[4], bfB[4];
;     ...
;       LD_AF(afA, 0); LD_BF(bfA, 0, 0);
;       if (kt + 1 < nk) {
; #pragma unroll
;         for (int i = 0; i < 8; ++i) *(u4*)(st + (lr + 32 * i) * G_LD + lcw) = ra[i];
;       }
;       __builtin_amdgcn_sched_barrier(0);
;       LD_BF(bfB, 0, 1);
;       MMA_BLK(afA, bfA, 0);
;       __builtin_amdgcn_sched_barrier(0);
;       if (kt + 1 < nk) {
; #pragma unroll
;         for (int i = 0; i < 8; ++i) *(u4*)(st + (256 + lr + 32 * i) * G_LD + lcw) = rb[i];
;       }
;       LD_AF(afB, 1); LD_BF(bfA, 1, 0);
;       MMA_BLK(afA, bfB, 1);
;       __builtin_amdgcn_sched_barrier(0);
;       if (kt + 2 < nk) {
;         const int ko = (kt + 2) * 64;
; #pragma unroll
;         for (int i = 0; i < 8; ++i) { ra[i] = __builtin_amdgcn_raw_buffer_load_b128(Ars, aoff, i * astep + ko * 2, 0); rb[i] = __builtin_amdgcn_raw_buffer_load_b128(Brs, boff, i * bstep + ko * 2, 0); }
;       }
;       LD_BF(bfB, 1, 1);
;       MMA_BLK(afB, bfA, 0);
;       __builtin_amdgcn_sched_barrier(0);
;       MMA_BLK(afB, bfB, 1);
;       __builtin_amdgcn_sched_barrier(0);
.LBB0_999:
	ds_read_b128 v[0:3], v138 offset:36864
	ds_read_b128 v[4:7], v138 offset:39168
	ds_read_b128 v[8:11], v138 offset:41472
	ds_read_b128 v[12:15], v138 offset:43776
	ds_read_b128 v[16:19], v139
	ds_read_b128 v[20:23], v139 offset:2304
	ds_read_b128 v[24:27], v139 offset:4608
	ds_read_b128 v[28:31], v139 offset:6912
	ds_read_b128 v[32:35], v139 offset:9216
	ds_read_b128 v[36:39], v139 offset:11520
	ds_read_b128 v[40:43], v139 offset:13824
	ds_read_b128 v[44:47], v139 offset:16128
	s_waitcnt lgkmcnt(7)
	v_mfma_f32_16x16x32_f16 a[204:207], v[0:3], v[16:19], a[204:207]
	v_mfma_f32_16x16x32_f16 a[200:203], v[4:7], v[16:19], a[200:203]
	v_mfma_f32_16x16x32_f16 a[196:199], v[8:11], v[16:19], a[196:199]
	v_mfma_f32_16x16x32_f16 a[188:191], v[12:15], v[16:19], a[188:191]
	s_waitcnt lgkmcnt(6)
	v_mfma_f32_16x16x32_f16 a[192:195], v[0:3], v[20:23], a[192:195]
	v_mfma_f32_16x16x32_f16 a[184:187], v[4:7], v[20:23], a[184:187]
	v_mfma_f32_16x16x32_f16 a[180:183], v[8:11], v[20:23], a[180:183]
	v_mfma_f32_16x16x32_f16 a[176:179], v[12:15], v[20:23], a[176:179]
	s_waitcnt lgkmcnt(5)
	v_mfma_f32_16x16x32_f16 a[156:159], v[0:3], v[24:27], a[156:159]
	v_mfma_f32_16x16x32_f16 a[152:155], v[4:7], v[24:27], a[152:155]
	v_mfma_f32_16x16x32_f16 a[148:151], v[8:11], v[24:27], a[148:151]
	v_mfma_f32_16x16x32_f16 a[144:147], v[12:15], v[24:27], a[144:147]
	s_waitcnt lgkmcnt(4)
	v_mfma_f32_16x16x32_f16 a[124:127], v[0:3], v[28:31], a[124:127]
	v_mfma_f32_16x16x32_f16 a[120:123], v[4:7], v[28:31], a[120:123]
	v_mfma_f32_16x16x32_f16 a[116:119], v[8:11], v[28:31], a[116:119]
	v_mfma_f32_16x16x32_f16 a[112:115], v[12:15], v[28:31], a[112:115]
	s_waitcnt lgkmcnt(3)
	v_mfma_f32_16x16x32_f16 a[92:95], v[0:3], v[32:35], a[92:95]
	v_mfma_f32_16x16x32_f16 a[88:91], v[4:7], v[32:35], a[88:91]
	v_mfma_f32_16x16x32_f16 a[84:87], v[8:11], v[32:35], a[84:87]
	v_mfma_f32_16x16x32_f16 a[80:83], v[12:15], v[32:35], a[80:83]
	s_waitcnt lgkmcnt(2)
	v_mfma_f32_16x16x32_f16 a[60:63], v[0:3], v[36:39], a[60:63]
	v_mfma_f32_16x16x32_f16 a[56:59], v[4:7], v[36:39], a[56:59]
	v_mfma_f32_16x16x32_f16 a[52:55], v[8:11], v[36:39], a[52:55]
	v_mfma_f32_16x16x32_f16 a[48:51], v[12:15], v[36:39], a[48:51]
	s_waitcnt lgkmcnt(1)
	v_mfma_f32_16x16x32_f16 a[32:35], v[0:3], v[40:43], a[32:35]
	v_mfma_f32_16x16x32_f16 a[28:31], v[4:7], v[40:43], a[28:31]
	v_mfma_f32_16x16x32_f16 a[24:27], v[8:11], v[40:43], a[24:27]
	v_mfma_f32_16x16x32_f16 a[20:23], v[12:15], v[40:43], a[20:23]
	s_waitcnt lgkmcnt(0)
	v_mfma_f32_16x16x32_f16 a[12:15], v[0:3], v[44:47], a[12:15]
	v_mfma_f32_16x16x32_f16 a[8:11], v[4:7], v[44:47], a[8:11]
	v_mfma_f32_16x16x32_f16 a[4:7], v[8:11], v[44:47], a[4:7]
	v_mfma_f32_16x16x32_f16 a[0:3], v[12:15], v[44:47], a[0:3]
	ds_read_b128 v[0:3], v138 offset:46080
	ds_read_b128 v[4:7], v138 offset:48384
	ds_read_b128 v[8:11], v138 offset:50688
	ds_read_b128 v[12:15], v138 offset:52992
	s_waitcnt lgkmcnt(3)
	v_mfma_f32_16x16x32_f16 a[240:243], v[0:3], v[16:19], a[240:243]
	s_waitcnt lgkmcnt(2)
	v_mfma_f32_16x16x32_f16 a[252:255], v[4:7], v[16:19], a[252:255]
	s_waitcnt lgkmcnt(1)
	v_mfma_f32_16x16x32_f16 a[248:251], v[8:11], v[16:19], a[248:251]
	s_waitcnt lgkmcnt(0)
	v_mfma_f32_16x16x32_f16 a[244:247], v[12:15], v[16:19], a[244:247]
	v_mfma_f32_16x16x32_f16 a[236:239], v[0:3], v[20:23], a[236:239]
	v_mfma_f32_16x16x32_f16 a[232:235], v[4:7], v[20:23], a[232:235]
	v_mfma_f32_16x16x32_f16 a[228:231], v[8:11], v[20:23], a[228:231]
	v_mfma_f32_16x16x32_f16 a[224:227], v[12:15], v[20:23], a[224:227]
	v_mfma_f32_16x16x32_f16 a[220:223], v[0:3], v[24:27], a[220:223]
	v_mfma_f32_16x16x32_f16 a[216:219], v[4:7], v[24:27], a[216:219]
	v_mfma_f32_16x16x32_f16 a[212:215], v[8:11], v[24:27], a[212:215]
	v_mfma_f32_16x16x32_f16 a[208:211], v[12:15], v[24:27], a[208:211]
	v_mfma_f32_16x16x32_f16 a[172:175], v[0:3], v[28:31], a[172:175]
	v_mfma_f32_16x16x32_f16 a[168:171], v[4:7], v[28:31], a[168:171]
	v_mfma_f32_16x16x32_f16 a[164:167], v[8:11], v[28:31], a[164:167]
	v_mfma_f32_16x16x32_f16 a[160:163], v[12:15], v[28:31], a[160:163]
	v_mfma_f32_16x16x32_f16 a[140:143], v[0:3], v[32:35], a[140:143]
	v_mfma_f32_16x16x32_f16 a[136:139], v[4:7], v[32:35], a[136:139]
	v_mfma_f32_16x16x32_f16 a[132:135], v[8:11], v[32:35], a[132:135]
	v_mfma_f32_16x16x32_f16 a[128:131], v[12:15], v[32:35], a[128:131]
	v_mfma_f32_16x16x32_f16 a[108:111], v[0:3], v[36:39], a[108:111]
	v_mfma_f32_16x16x32_f16 a[104:107], v[4:7], v[36:39], a[104:107]
	v_mfma_f32_16x16x32_f16 a[100:103], v[8:11], v[36:39], a[100:103]
	v_mfma_f32_16x16x32_f16 a[96:99], v[12:15], v[36:39], a[96:99]
	v_mfma_f32_16x16x32_f16 a[76:79], v[0:3], v[40:43], a[76:79]
	v_mfma_f32_16x16x32_f16 a[72:75], v[4:7], v[40:43], a[72:75]
	v_mfma_f32_16x16x32_f16 a[68:71], v[8:11], v[40:43], a[68:71]
	v_mfma_f32_16x16x32_f16 a[64:67], v[12:15], v[40:43], a[64:67]
	v_mfma_f32_16x16x32_f16 a[44:47], v[0:3], v[44:47], a[44:47]
	v_mfma_f32_16x16x32_f16 a[40:43], v[4:7], v[44:47], a[40:43]
	v_mfma_f32_16x16x32_f16 a[36:39], v[8:11], v[44:47], a[36:39]
	v_mfma_f32_16x16x32_f16 a[16:19], v[12:15], v[44:47], a[16:19]
	ds_read_b128 v[20:23], v138 offset:36928
	ds_read_b128 v[44:47], v139 offset:64
	ds_read_b128 v[48:51], v138 offset:39232
	ds_read_b128 v[60:63], v138 offset:41536
	ds_read_b128 v[64:67], v138 offset:43840
	ds_read_b128 v[76:79], v139 offset:2368
	ds_read_b128 v[80:83], v139 offset:4672
	ds_read_b128 v[16:19], v139 offset:6976
	ds_read_b128 v[12:15], v139 offset:9280
	ds_read_b128 v[8:11], v139 offset:11584
	ds_read_b128 v[4:7], v139 offset:13888
	ds_read_b128 v[0:3], v139 offset:16192
	s_waitcnt vmcnt(6)
	ds_read_b128 v[142:145], v138 offset:46144
	s_waitcnt vmcnt(5)
; #define LD_AF(dst, ks_) _Pragma("unroll") for (int i = 0; i < 8; ++i) dst[i] = *(const h8*)(sA + i * 16 * G_LD + (ks_) * 32)
; #define LD_BF(dst, ks_, nh_) _Pragma("unroll") for (int i = 0; i < 4; ++i) dst[i] = *(const h8*)(sB + ((nh_) * 4 + i) * 16 * G_LD + (ks_) * 32)
; #define MMA_BLK(afx, bfx, nh_) _Pragma("unroll") for (int mi = 0; mi < 8; ++mi) _Pragma("unroll") for (int ni = 0; ni < 4; ++ni) mfma16_acc(acc[mi][(nh_) * 4 + ni], bfx[ni], afx[mi])
; template <class Epi>
; __device__ __forceinline__ void gemm_run(const GemmArgs g, Epi epi, char* smem) {
;     ...
;       h8 afA[8], afB[8], bfA[4], bfB[4];
;     ...
;       LD_AF(afA, 0); LD_BF(bfA, 0, 0);
;       if (kt + 1 < nk) {
; #pragma unroll
;         for (int i = 0; i < 8; ++i) *(u4*)(st + (lr + 32 * i) * G_LD + lcw) = ra[i];
;       }
;       __builtin_amdgcn_sched_barrier(0);
;       LD_BF(bfB, 0, 1);
;       MMA_BLK(afA, bfA, 0);
;       __builtin_amdgcn_sched_barrier(0);
;       if (kt + 1 < nk) {
; #pragma unroll
;         for (int i = 0; i < 8; ++i) *(u4*)(st + (256 + lr + 32 * i) * G_LD + lcw) = rb[i];
;       }
;       LD_AF(afB, 1); LD_BF(bfA, 1, 0);
;       MMA_BLK(afA, bfB, 1);
;       __builtin_amdgcn_sched_barrier(0);
;       if (kt + 2 < nk) {
;         const int ko = (kt + 2) * 64;
; #pragma unroll
;         for (int i = 0; i < 8; ++i) { ra[i] = __builtin_amdgcn_raw_buffer_load_b128(Ars, aoff, i * astep + ko * 2, 0); rb[i] = __builtin_amdgcn_raw_buffer_load_b128(Brs, boff, i * bstep + ko * 2, 0); }
;       }
;       LD_BF(bfB, 1, 1);
;       MMA_BLK(afB, bfA, 0);
;       __builtin_amdgcn_sched_barrier(0);
;       MMA_BLK(afB, bfB, 1);
;       __builtin_amdgcn_sched_barrier(0);
	ds_read_b128 v[146:149], v138 offset:48448
	s_waitcnt vmcnt(3)
	ds_read_b128 v[150:153], v138 offset:50752
	ds_read_b128 v[154:157], v138 offset:53056
	s_waitcnt lgkmcnt(14)
	v_mfma_f32_16x16x32_f16 a[204:207], v[20:23], v[44:47], a[204:207]
	s_waitcnt lgkmcnt(13)
	v_mfma_f32_16x16x32_f16 a[200:203], v[48:51], v[44:47], a[200:203]
	s_waitcnt lgkmcnt(12)
	v_mfma_f32_16x16x32_f16 a[196:199], v[60:63], v[44:47], a[196:199]
	s_waitcnt lgkmcnt(11)
	v_mfma_f32_16x16x32_f16 a[188:191], v[64:67], v[44:47], a[188:191]
	s_waitcnt lgkmcnt(10)
	v_mfma_f32_16x16x32_f16 a[192:195], v[20:23], v[76:79], a[192:195]
	v_mfma_f32_16x16x32_f16 a[184:187], v[48:51], v[76:79], a[184:187]
	v_mfma_f32_16x16x32_f16 a[180:183], v[60:63], v[76:79], a[180:183]
	v_mfma_f32_16x16x32_f16 a[176:179], v[64:67], v[76:79], a[176:179]
	s_waitcnt lgkmcnt(9)
	v_mfma_f32_16x16x32_f16 a[156:159], v[20:23], v[80:83], a[156:159]
	v_mfma_f32_16x16x32_f16 a[152:155], v[48:51], v[80:83], a[152:155]
	v_mfma_f32_16x16x32_f16 a[148:151], v[60:63], v[80:83], a[148:151]
	v_mfma_f32_16x16x32_f16 a[144:147], v[64:67], v[80:83], a[144:147]
	s_waitcnt lgkmcnt(8)
	v_mfma_f32_16x16x32_f16 a[124:127], v[20:23], v[16:19], a[124:127]
	v_mfma_f32_16x16x32_f16 a[120:123], v[48:51], v[16:19], a[120:123]
	v_mfma_f32_16x16x32_f16 a[116:119], v[60:63], v[16:19], a[116:119]
	v_mfma_f32_16x16x32_f16 a[112:115], v[64:67], v[16:19], a[112:115]
	s_waitcnt lgkmcnt(7)
	v_mfma_f32_16x16x32_f16 a[92:95], v[20:23], v[12:15], a[92:95]
	v_mfma_f32_16x16x32_f16 a[88:91], v[48:51], v[12:15], a[88:91]
	v_mfma_f32_16x16x32_f16 a[84:87], v[60:63], v[12:15], a[84:87]
	v_mfma_f32_16x16x32_f16 a[80:83], v[64:67], v[12:15], a[80:83]
	v_accvgpr_read_b32 v123, a207
	v_accvgpr_read_b32 v122, a206
	v_accvgpr_read_b32 v121, a203
	v_accvgpr_read_b32 v120, a202
	v_accvgpr_read_b32 v119, a199
	v_accvgpr_read_b32 v118, a198
	v_accvgpr_read_b32 v115, a191
	v_accvgpr_read_b32 v114, a190
	v_accvgpr_read_b32 v107, a195
	v_accvgpr_read_b32 v106, a194
	v_accvgpr_read_b32 v105, a187
	v_accvgpr_read_b32 v104, a186
	v_accvgpr_read_b32 v103, a183
	v_accvgpr_read_b32 v102, a182
	v_accvgpr_read_b32 v99, a179
	v_accvgpr_read_b32 v98, a178
	v_accvgpr_read_b32 v91, a159
	v_accvgpr_read_b32 v90, a158
	v_accvgpr_read_b32 v89, a155
	v_accvgpr_read_b32 v88, a154
	v_accvgpr_read_b32 v87, a151
	v_accvgpr_read_b32 v86, a150
	v_accvgpr_read_b32 v85, a147
	v_accvgpr_read_b32 v84, a146
	v_accvgpr_read_b32 v75, a127
	v_accvgpr_read_b32 v74, a126
	v_accvgpr_read_b32 v73, a123
	v_accvgpr_read_b32 v72, a122
	v_accvgpr_read_b32 v71, a119
	v_accvgpr_read_b32 v70, a118
	v_accvgpr_read_b32 v69, a115
	v_accvgpr_read_b32 v68, a114
	v_accvgpr_read_b32 v59, a95
	v_accvgpr_read_b32 v58, a94
	v_accvgpr_read_b32 v57, a91
	v_accvgpr_read_b32 v56, a90
	v_accvgpr_read_b32 v55, a87
	v_accvgpr_read_b32 v54, a86
	v_accvgpr_read_b32 v53, a83
	v_accvgpr_read_b32 v52, a82
	s_waitcnt lgkmcnt(6)
	v_mfma_f32_16x16x32_f16 a[60:63], v[20:23], v[8:11], a[60:63]
	v_mfma_f32_16x16x32_f16 a[56:59], v[48:51], v[8:11], a[56:59]
	v_mfma_f32_16x16x32_f16 a[52:55], v[60:63], v[8:11], a[52:55]
	v_mfma_f32_16x16x32_f16 a[48:51], v[64:67], v[8:11], a[48:51]
	s_waitcnt lgkmcnt(5)
	v_mfma_f32_16x16x32_f16 a[32:35], v[20:23], v[4:7], a[32:35]
	v_mfma_f32_16x16x32_f16 a[28:31], v[48:51], v[4:7], a[28:31]
	v_mfma_f32_16x16x32_f16 a[24:27], v[60:63], v[4:7], a[24:27]
	v_mfma_f32_16x16x32_f16 a[20:23], v[64:67], v[4:7], a[20:23]
	s_waitcnt lgkmcnt(4)
	v_mfma_f32_16x16x32_f16 a[12:15], v[20:23], v[0:3], a[12:15]
	v_mfma_f32_16x16x32_f16 a[8:11], v[48:51], v[0:3], a[8:11]
	v_mfma_f32_16x16x32_f16 a[4:7], v[60:63], v[0:3], a[4:7]
	v_mfma_f32_16x16x32_f16 a[0:3], v[64:67], v[0:3], a[0:3]
	v_accvgpr_read_b32 v43, a63
	v_accvgpr_read_b32 v42, a62
	v_accvgpr_read_b32 v41, a59
	v_accvgpr_read_b32 v40, a58
	v_accvgpr_read_b32 v39, a55
	v_accvgpr_read_b32 v38, a54
	v_accvgpr_read_b32 v37, a51
	v_accvgpr_read_b32 v36, a50
	v_accvgpr_read_b32 v35, a35
	v_accvgpr_read_b32 v34, a34
	v_accvgpr_read_b32 v33, a31
	v_accvgpr_read_b32 v32, a30
	v_accvgpr_read_b32 v31, a27
	v_accvgpr_read_b32 v30, a26
	v_accvgpr_read_b32 v29, a23
	v_accvgpr_read_b32 v28, a22
	v_accvgpr_read_b32 v27, a15
	v_accvgpr_read_b32 v26, a14
	v_accvgpr_read_b32 v25, a11
	v_accvgpr_read_b32 v24, a10
	v_accvgpr_read_b32 v23, a7
	v_accvgpr_read_b32 v22, a6
	v_accvgpr_read_b32 v21, a3
	v_accvgpr_read_b32 v20, a2
	s_waitcnt lgkmcnt(3)
	v_mfma_f32_16x16x32_f16 a[240:243], v[142:145], v[44:47], a[240:243]
	s_waitcnt lgkmcnt(2)
	v_mfma_f32_16x16x32_f16 a[252:255], v[146:149], v[44:47], a[252:255]
	s_waitcnt lgkmcnt(1)
	v_mfma_f32_16x16x32_f16 a[248:251], v[150:153], v[44:47], a[248:251]
	s_waitcnt lgkmcnt(0)
	v_mfma_f32_16x16x32_f16 a[244:247], v[154:157], v[44:47], a[244:247]
	v_mfma_f32_16x16x32_f16 a[236:239], v[142:145], v[76:79], a[236:239]
	v_mfma_f32_16x16x32_f16 a[232:235], v[146:149], v[76:79], a[232:235]
	v_mfma_f32_16x16x32_f16 a[228:231], v[150:153], v[76:79], a[228:231]
	v_mfma_f32_16x16x32_f16 a[224:227], v[154:157], v[76:79], a[224:227]
	v_mfma_f32_16x16x32_f16 a[220:223], v[142:145], v[80:83], a[220:223]
	v_mfma_f32_16x16x32_f16 a[216:219], v[146:149], v[80:83], a[216:219]
	v_mfma_f32_16x16x32_f16 a[212:215], v[150:153], v[80:83], a[212:215]
	v_mfma_f32_16x16x32_f16 a[208:211], v[154:157], v[80:83], a[208:211]
	v_mfma_f32_16x16x32_f16 a[172:175], v[142:145], v[16:19], a[172:175]
	v_mfma_f32_16x16x32_f16 a[168:171], v[146:149], v[16:19], a[168:171]
	v_mfma_f32_16x16x32_f16 a[164:167], v[150:153], v[16:19], a[164:167]
	v_mfma_f32_16x16x32_f16 a[160:163], v[154:157], v[16:19], a[160:163]
	v_mfma_f32_16x16x32_f16 a[140:143], v[142:145], v[12:15], a[140:143]
	v_mfma_f32_16x16x32_f16 a[136:139], v[146:149], v[12:15], a[136:139]
	v_mfma_f32_16x16x32_f16 a[132:135], v[150:153], v[12:15], a[132:135]
	v_mfma_f32_16x16x32_f16 a[128:131], v[154:157], v[12:15], a[128:131]
	s_waitcnt vmcnt(1)
; #define LD_AF(dst, ks_) _Pragma("unroll") for (int i = 0; i < 8; ++i) dst[i] = *(const h8*)(sA + i * 16 * G_LD + (ks_) * 32)
; #define LD_BF(dst, ks_, nh_) _Pragma("unroll") for (int i = 0; i < 4; ++i) dst[i] = *(const h8*)(sB + ((nh_) * 4 + i) * 16 * G_LD + (ks_) * 32)
; #define MMA_BLK(afx, bfx, nh_) _Pragma("unroll") for (int mi = 0; mi < 8; ++mi) _Pragma("unroll") for (int ni = 0; ni < 4; ++ni) mfma16_acc(acc[mi][(nh_) * 4 + ni], bfx[ni], afx[mi])
; template <class Epi>
; __device__ __forceinline__ void gemm_run(const GemmArgs g, Epi epi, char* smem) {
;     ...
;       LD_AF(afB, 1); LD_BF(bfA, 1, 0);
;       MMA_BLK(afA, bfB, 1);
;       __builtin_amdgcn_sched_barrier(0);
;       if (kt + 2 < nk) {
;         const int ko = (kt + 2) * 64;
; #pragma unroll
;         for (int i = 0; i < 8; ++i) { ra[i] = __builtin_amdgcn_raw_buffer_load_b128(Ars, aoff, i * astep + ko * 2, 0); rb[i] = __builtin_amdgcn_raw_buffer_load_b128(Brs, boff, i * bstep + ko * 2, 0); }
;       }
;       LD_BF(bfB, 1, 1);
;       MMA_BLK(afB, bfA, 0);
;       __builtin_amdgcn_sched_barrier(0);
;       MMA_BLK(afB, bfB, 1);
;       __builtin_amdgcn_sched_barrier(0);
	v_accvgpr_read_b32 v159, a243
	v_accvgpr_read_b32 v158, a242
	v_accvgpr_read_b32 v129, a255
	v_accvgpr_read_b32 v128, a254
	v_accvgpr_read_b32 v127, a251
	v_accvgpr_read_b32 v126, a250
	v_accvgpr_read_b32 v125, a247
	v_accvgpr_read_b32 v124, a246
	v_accvgpr_read_b32 v117, a239
	v_accvgpr_read_b32 v116, a238
	v_accvgpr_read_b32 v113, a235
	v_accvgpr_read_b32 v112, a234
	v_accvgpr_read_b32 v111, a231
	v_accvgpr_read_b32 v110, a230
	v_accvgpr_read_b32 v109, a227
	v_accvgpr_read_b32 v108, a226
	v_accvgpr_read_b32 v101, a223
	v_accvgpr_read_b32 v100, a222
	v_accvgpr_read_b32 v97, a219
	v_accvgpr_read_b32 v96, a218
	v_accvgpr_read_b32 v95, a215
	v_accvgpr_read_b32 v94, a214
	v_accvgpr_read_b32 v93, a211
	v_accvgpr_read_b32 v92, a210
	v_accvgpr_read_b32 v83, a175
	v_accvgpr_read_b32 v82, a174
	v_accvgpr_read_b32 v81, a171
	v_accvgpr_read_b32 v80, a170
	v_accvgpr_read_b32 v79, a167
	v_accvgpr_read_b32 v78, a166
	v_accvgpr_read_b32 v77, a163
	v_accvgpr_read_b32 v76, a162
	v_accvgpr_read_b32 v67, a143
	v_accvgpr_read_b32 v66, a142
	v_accvgpr_read_b32 v65, a139
	v_accvgpr_read_b32 v64, a138
	v_accvgpr_read_b32 v63, a135
	v_accvgpr_read_b32 v62, a134
	v_accvgpr_read_b32 v61, a131
	v_accvgpr_read_b32 v60, a130
	v_mfma_f32_16x16x32_f16 a[108:111], v[142:145], v[8:11], a[108:111]
	v_mfma_f32_16x16x32_f16 a[104:107], v[146:149], v[8:11], a[104:107]
	v_mfma_f32_16x16x32_f16 a[100:103], v[150:153], v[8:11], a[100:103]
	v_mfma_f32_16x16x32_f16 a[96:99], v[154:157], v[8:11], a[96:99]
	v_mfma_f32_16x16x32_f16 a[76:79], v[142:145], v[4:7], a[76:79]
	v_mfma_f32_16x16x32_f16 a[72:75], v[146:149], v[4:7], a[72:75]
	v_mfma_f32_16x16x32_f16 a[68:71], v[150:153], v[4:7], a[68:71]
	v_mfma_f32_16x16x32_f16 a[64:67], v[154:157], v[4:7], a[64:67]
	v_mfma_f32_16x16x32_f16 a[44:47], v[142:145], v[0:3], a[44:47]
	v_mfma_f32_16x16x32_f16 a[40:43], v[146:149], v[0:3], a[40:43]
	v_mfma_f32_16x16x32_f16 a[36:39], v[150:153], v[0:3], a[36:39]
	v_mfma_f32_16x16x32_f16 a[16:19], v[154:157], v[0:3], a[16:19]
	s_nop 0
	v_lshl_add_u32 v14, s81, 8, v132
	v_min_i32_e32 v3, 0x8000, v14
	v_or_b32_e32 v2, s83, v135
	v_ashrrev_i32_e32 v3, 13, v3
	v_ashrrev_i32_e32 v15, 31, v14
	v_mul_hi_i32_i24_e32 v143, 0xc000, v3
	v_mul_i32_i24_e32 v142, 0xc000, v3
	v_ashrrev_i32_e32 v3, 31, v2
	v_lshlrev_b64 v[146:147], 13, v[14:15]
	v_lshl_add_u64 v[142:143], s[16:17], 0, v[142:143]
	v_lshlrev_b64 v[2:3], 2, v[2:3]
	v_lshl_add_u64 v[146:147], s[28:29], 0, v[146:147]
	v_lshl_add_u64 v[150:151], v[142:143], 0, v[2:3]
	v_lshl_add_u64 v[152:153], v[146:147], 0, v[2:3]
	s_barrier
	global_load_dwordx4 v[4:7], v[150:151], off
	global_load_dwordx4 v[8:11], v[150:151], off offset:64
	global_load_dwordx4 v[16:19], v[150:151], off offset:128
	global_load_dwordx4 v[20:23], v[150:151], off offset:192
	global_load_dwordx4 v[24:27], v[150:151], off offset:256
	global_load_dwordx4 v[28:31], v[150:151], off offset:320
	global_load_dwordx4 v[32:35], v[150:151], off offset:384
	global_load_dwordx4 v[36:39], v[150:151], off offset:448
	global_load_dwordx4 v[40:43], v[152:153], off
	global_load_dwordx4 v[44:47], v[152:153], off offset:64
	global_load_dwordx4 v[48:51], v[152:153], off offset:128
	global_load_dwordx4 v[52:55], v[152:153], off offset:192
	global_load_dwordx4 v[56:59], v[152:153], off offset:256
	global_load_dwordx4 v[60:63], v[152:153], off offset:320
	global_load_dwordx4 v[64:67], v[152:153], off offset:384
	global_load_dwordx4 v[68:71], v[152:153], off offset:448
	v_mov_b32_e32 v110, 0x20000
	v_mov_b32_e32 v111, 0
	v_lshl_add_u64 v[108:109], v[152:153], 0, v[110:111]
	v_mov_b32_e32 v110, 0x40000
	global_load_dwordx4 v[72:75], v[108:109], off
	global_load_dwordx4 v[76:79], v[108:109], off offset:64
	global_load_dwordx4 v[80:83], v[108:109], off offset:128
	global_load_dwordx4 v[84:87], v[108:109], off offset:192
	global_load_dwordx4 v[88:91], v[108:109], off offset:256
	global_load_dwordx4 v[92:95], v[108:109], off offset:320
	global_load_dwordx4 v[96:99], v[108:109], off offset:384
	global_load_dwordx4 v[100:103], v[108:109], off offset:448
	v_accvgpr_read_b32 v104, a204
	v_accvgpr_read_b32 v105, a205
	v_accvgpr_read_b32 v106, a206
	v_accvgpr_read_b32 v107, a207
	s_waitcnt vmcnt(15)
	v_pk_fma_f32 v[40:41], v[104:105], v[4:5], v[40:41]
	v_pk_fma_f32 v[42:43], v[106:107], v[6:7], v[42:43]
	global_store_dwordx4 v[152:153], v[40:43], off
	v_accvgpr_read_b32 v104, a200
	v_accvgpr_read_b32 v105, a201
	v_accvgpr_read_b32 v106, a202
	v_accvgpr_read_b32 v107, a203
	s_waitcnt vmcnt(15)
	v_pk_fma_f32 v[44:45], v[104:105], v[8:9], v[44:45]
	v_pk_fma_f32 v[46:47], v[106:107], v[10:11], v[46:47]
	global_store_dwordx4 v[152:153], v[44:47], off offset:64
	v_accvgpr_read_b32 v104, a196
	v_accvgpr_read_b32 v105, a197
	v_accvgpr_read_b32 v106, a198
	v_accvgpr_read_b32 v107, a199
	s_waitcnt vmcnt(15)
	v_pk_fma_f32 v[48:49], v[104:105], v[16:17], v[48:49]
	v_pk_fma_f32 v[50:51], v[106:107], v[18:19], v[50:51]
	global_store_dwordx4 v[152:153], v[48:51], off offset:128
	v_accvgpr_read_b32 v104, a188
	v_accvgpr_read_b32 v105, a189
	v_accvgpr_read_b32 v106, a190
	v_accvgpr_read_b32 v107, a191
	s_waitcnt vmcnt(15)
	v_pk_fma_f32 v[52:53], v[104:105], v[20:21], v[52:53]
	v_pk_fma_f32 v[54:55], v[106:107], v[22:23], v[54:55]
	global_store_dwordx4 v[152:153], v[52:55], off offset:192
	v_accvgpr_read_b32 v104, a240
	v_accvgpr_read_b32 v105, a241
	v_accvgpr_read_b32 v106, a242
	v_accvgpr_read_b32 v107, a243
	s_waitcnt vmcnt(15)
	v_pk_fma_f32 v[56:57], v[104:105], v[24:25], v[56:57]
	v_pk_fma_f32 v[58:59], v[106:107], v[26:27], v[58:59]
	global_store_dwordx4 v[152:153], v[56:59], off offset:256
	v_accvgpr_read_b32 v104, a252
	v_accvgpr_read_b32 v105, a253
	v_accvgpr_read_b32 v106, a254
	v_accvgpr_read_b32 v107, a255
	s_waitcnt vmcnt(15)
	v_pk_fma_f32 v[60:61], v[104:105], v[28:29], v[60:61]
	v_pk_fma_f32 v[62:63], v[106:107], v[30:31], v[62:63]
	global_store_dwordx4 v[152:153], v[60:63], off offset:320
	v_accvgpr_read_b32 v104, a248
	v_accvgpr_read_b32 v105, a249
	v_accvgpr_read_b32 v106, a250
	v_accvgpr_read_b32 v107, a251
	s_waitcnt vmcnt(15)
	v_pk_fma_f32 v[64:65], v[104:105], v[32:33], v[64:65]
	v_pk_fma_f32 v[66:67], v[106:107], v[34:35], v[66:67]
	global_store_dwordx4 v[152:153], v[64:67], off offset:384
	v_accvgpr_read_b32 v104, a244
	v_accvgpr_read_b32 v105, a245
	v_accvgpr_read_b32 v106, a246
	v_accvgpr_read_b32 v107, a247
	s_waitcnt vmcnt(15)
	v_pk_fma_f32 v[68:69], v[104:105], v[36:37], v[68:69]
	v_pk_fma_f32 v[70:71], v[106:107], v[38:39], v[70:71]
	global_store_dwordx4 v[152:153], v[68:71], off offset:448
	v_lshl_add_u64 v[152:153], v[152:153], 0, v[110:111]
	s_nop 1
	global_load_dwordx4 v[40:43], v[152:153], off
	global_load_dwordx4 v[44:47], v[152:153], off offset:64
	global_load_dwordx4 v[48:51], v[152:153], off offset:128
	global_load_dwordx4 v[52:55], v[152:153], off offset:192
	global_load_dwordx4 v[56:59], v[152:153], off offset:256
	global_load_dwordx4 v[60:63], v[152:153], off offset:320
	global_load_dwordx4 v[64:67], v[152:153], off offset:384
	global_load_dwordx4 v[68:71], v[152:153], off offset:448
	v_accvgpr_read_b32 v104, a192
	v_accvgpr_read_b32 v105, a193
	v_accvgpr_read_b32 v106, a194
	v_accvgpr_read_b32 v107, a195
	s_waitcnt vmcnt(23)
	v_pk_fma_f32 v[72:73], v[104:105], v[4:5], v[72:73]
	v_pk_fma_f32 v[74:75], v[106:107], v[6:7], v[74:75]
	global_store_dwordx4 v[108:109], v[72:75], off
	v_accvgpr_read_b32 v104, a184
	v_accvgpr_read_b32 v105, a185
	v_accvgpr_read_b32 v106, a186
	v_accvgpr_read_b32 v107, a187
	s_waitcnt vmcnt(23)
	v_pk_fma_f32 v[76:77], v[104:105], v[8:9], v[76:77]
	v_pk_fma_f32 v[78:79], v[106:107], v[10:11], v[78:79]
	global_store_dwordx4 v[108:109], v[76:79], off offset:64
	v_accvgpr_read_b32 v104, a180
	v_accvgpr_read_b32 v105, a181
	v_accvgpr_read_b32 v106, a182
	v_accvgpr_read_b32 v107, a183
	s_waitcnt vmcnt(23)
	v_pk_fma_f32 v[80:81], v[104:105], v[16:17], v[80:81]
	v_pk_fma_f32 v[82:83], v[106:107], v[18:19], v[82:83]
	global_store_dwordx4 v[108:109], v[80:83], off offset:128
	v_accvgpr_read_b32 v104, a176
	v_accvgpr_read_b32 v105, a177
	v_accvgpr_read_b32 v106, a178
	v_accvgpr_read_b32 v107, a179
	s_waitcnt vmcnt(23)
	v_pk_fma_f32 v[84:85], v[104:105], v[20:21], v[84:85]
	v_pk_fma_f32 v[86:87], v[106:107], v[22:23], v[86:87]
	global_store_dwordx4 v[108:109], v[84:87], off offset:192
	v_accvgpr_read_b32 v104, a236
	v_accvgpr_read_b32 v105, a237
	v_accvgpr_read_b32 v106, a238
	v_accvgpr_read_b32 v107, a239
	s_waitcnt vmcnt(23)
	v_pk_fma_f32 v[88:89], v[104:105], v[24:25], v[88:89]
	v_pk_fma_f32 v[90:91], v[106:107], v[26:27], v[90:91]
	global_store_dwordx4 v[108:109], v[88:91], off offset:256
	v_accvgpr_read_b32 v104, a232
	v_accvgpr_read_b32 v105, a233
	v_accvgpr_read_b32 v106, a234
	v_accvgpr_read_b32 v107, a235
	s_waitcnt vmcnt(23)
	v_pk_fma_f32 v[92:93], v[104:105], v[28:29], v[92:93]
	v_pk_fma_f32 v[94:95], v[106:107], v[30:31], v[94:95]
	global_store_dwordx4 v[108:109], v[92:95], off offset:320
	v_accvgpr_read_b32 v104, a228
	v_accvgpr_read_b32 v105, a229
	v_accvgpr_read_b32 v106, a230
	v_accvgpr_read_b32 v107, a231
	s_waitcnt vmcnt(23)
	v_pk_fma_f32 v[96:97], v[104:105], v[32:33], v[96:97]
	v_pk_fma_f32 v[98:99], v[106:107], v[34:35], v[98:99]
	global_store_dwordx4 v[108:109], v[96:99], off offset:384
	v_accvgpr_read_b32 v104, a224
	v_accvgpr_read_b32 v105, a225
	v_accvgpr_read_b32 v106, a226
	v_accvgpr_read_b32 v107, a227
	s_waitcnt vmcnt(23)
	v_pk_fma_f32 v[100:101], v[104:105], v[36:37], v[100:101]
	v_pk_fma_f32 v[102:103], v[106:107], v[38:39], v[102:103]
	global_store_dwordx4 v[108:109], v[100:103], off offset:448
	v_lshl_add_u64 v[108:109], v[108:109], 0, v[110:111]
	s_nop 1
	global_load_dwordx4 v[72:75], v[108:109], off
	global_load_dwordx4 v[76:79], v[108:109], off offset:64
	global_load_dwordx4 v[80:83], v[108:109], off offset:128
	global_load_dwordx4 v[84:87], v[108:109], off offset:192
	global_load_dwordx4 v[88:91], v[108:109], off offset:256
	global_load_dwordx4 v[92:95], v[108:109], off offset:320
	global_load_dwordx4 v[96:99], v[108:109], off offset:384
	global_load_dwordx4 v[100:103], v[108:109], off offset:448
	v_accvgpr_read_b32 v104, a156
	v_accvgpr_read_b32 v105, a157
	v_accvgpr_read_b32 v106, a158
	v_accvgpr_read_b32 v107, a159
	s_waitcnt vmcnt(23)
	v_pk_fma_f32 v[40:41], v[104:105], v[4:5], v[40:41]
	v_pk_fma_f32 v[42:43], v[106:107], v[6:7], v[42:43]
	global_store_dwordx4 v[152:153], v[40:43], off
	v_accvgpr_read_b32 v104, a152
	v_accvgpr_read_b32 v105, a153
	v_accvgpr_read_b32 v106, a154
	v_accvgpr_read_b32 v107, a155
	s_waitcnt vmcnt(23)
	v_pk_fma_f32 v[44:45], v[104:105], v[8:9], v[44:45]
	v_pk_fma_f32 v[46:47], v[106:107], v[10:11], v[46:47]
	global_store_dwordx4 v[152:153], v[44:47], off offset:64
	v_accvgpr_read_b32 v104, a148
	v_accvgpr_read_b32 v105, a149
	v_accvgpr_read_b32 v106, a150
	v_accvgpr_read_b32 v107, a151
	s_waitcnt vmcnt(23)
	v_pk_fma_f32 v[48:49], v[104:105], v[16:17], v[48:49]
	v_pk_fma_f32 v[50:51], v[106:107], v[18:19], v[50:51]
	global_store_dwordx4 v[152:153], v[48:51], off offset:128
	v_accvgpr_read_b32 v104, a144
	v_accvgpr_read_b32 v105, a145
	v_accvgpr_read_b32 v106, a146
	v_accvgpr_read_b32 v107, a147
	s_waitcnt vmcnt(23)
	v_pk_fma_f32 v[52:53], v[104:105], v[20:21], v[52:53]
	v_pk_fma_f32 v[54:55], v[106:107], v[22:23], v[54:55]
	global_store_dwordx4 v[152:153], v[52:55], off offset:192
	v_accvgpr_read_b32 v104, a220
	v_accvgpr_read_b32 v105, a221
	v_accvgpr_read_b32 v106, a222
	v_accvgpr_read_b32 v107, a223
	s_waitcnt vmcnt(23)
	v_pk_fma_f32 v[56:57], v[104:105], v[24:25], v[56:57]
	v_pk_fma_f32 v[58:59], v[106:107], v[26:27], v[58:59]
	global_store_dwordx4 v[152:153], v[56:59], off offset:256
	v_accvgpr_read_b32 v104, a216
	v_accvgpr_read_b32 v105, a217
	v_accvgpr_read_b32 v106, a218
	v_accvgpr_read_b32 v107, a219
	s_waitcnt vmcnt(23)
	v_pk_fma_f32 v[60:61], v[104:105], v[28:29], v[60:61]
	v_pk_fma_f32 v[62:63], v[106:107], v[30:31], v[62:63]
	global_store_dwordx4 v[152:153], v[60:63], off offset:320
	v_accvgpr_read_b32 v104, a212
	v_accvgpr_read_b32 v105, a213
	v_accvgpr_read_b32 v106, a214
	v_accvgpr_read_b32 v107, a215
	s_waitcnt vmcnt(23)
	v_pk_fma_f32 v[64:65], v[104:105], v[32:33], v[64:65]
	v_pk_fma_f32 v[66:67], v[106:107], v[34:35], v[66:67]
	global_store_dwordx4 v[152:153], v[64:67], off offset:384
	v_accvgpr_read_b32 v104, a208
	v_accvgpr_read_b32 v105, a209
	v_accvgpr_read_b32 v106, a210
	v_accvgpr_read_b32 v107, a211
	s_waitcnt vmcnt(23)
	v_pk_fma_f32 v[68:69], v[104:105], v[36:37], v[68:69]
	v_pk_fma_f32 v[70:71], v[106:107], v[38:39], v[70:71]
	global_store_dwordx4 v[152:153], v[68:71], off offset:448
	v_lshl_add_u64 v[152:153], v[152:153], 0, v[110:111]
	s_nop 1
	global_load_dwordx4 v[40:43], v[152:153], off
	global_load_dwordx4 v[44:47], v[152:153], off offset:64
	global_load_dwordx4 v[48:51], v[152:153], off offset:128
	global_load_dwordx4 v[52:55], v[152:153], off offset:192
	global_load_dwordx4 v[56:59], v[152:153], off offset:256
	global_load_dwordx4 v[60:63], v[152:153], off offset:320
	global_load_dwordx4 v[64:67], v[152:153], off offset:384
	global_load_dwordx4 v[68:71], v[152:153], off offset:448
	v_accvgpr_read_b32 v104, a124
	v_accvgpr_read_b32 v105, a125
	v_accvgpr_read_b32 v106, a126
	v_accvgpr_read_b32 v107, a127
	s_waitcnt vmcnt(23)
	v_pk_fma_f32 v[72:73], v[104:105], v[4:5], v[72:73]
	v_pk_fma_f32 v[74:75], v[106:107], v[6:7], v[74:75]
	global_store_dwordx4 v[108:109], v[72:75], off
	v_accvgpr_read_b32 v104, a120
	v_accvgpr_read_b32 v105, a121
	v_accvgpr_read_b32 v106, a122
	v_accvgpr_read_b32 v107, a123
	s_waitcnt vmcnt(23)
	v_pk_fma_f32 v[76:77], v[104:105], v[8:9], v[76:77]
	v_pk_fma_f32 v[78:79], v[106:107], v[10:11], v[78:79]
	global_store_dwordx4 v[108:109], v[76:79], off offset:64
	v_accvgpr_read_b32 v104, a116
	v_accvgpr_read_b32 v105, a117
	v_accvgpr_read_b32 v106, a118
	v_accvgpr_read_b32 v107, a119
	s_waitcnt vmcnt(23)
	v_pk_fma_f32 v[80:81], v[104:105], v[16:17], v[80:81]
	v_pk_fma_f32 v[82:83], v[106:107], v[18:19], v[82:83]
	global_store_dwordx4 v[108:109], v[80:83], off offset:128
	v_accvgpr_read_b32 v104, a112
	v_accvgpr_read_b32 v105, a113
	v_accvgpr_read_b32 v106, a114
	v_accvgpr_read_b32 v107, a115
	s_waitcnt vmcnt(23)
	v_pk_fma_f32 v[84:85], v[104:105], v[20:21], v[84:85]
	v_pk_fma_f32 v[86:87], v[106:107], v[22:23], v[86:87]
	global_store_dwordx4 v[108:109], v[84:87], off offset:192
	v_accvgpr_read_b32 v104, a172
	v_accvgpr_read_b32 v105, a173
	v_accvgpr_read_b32 v106, a174
	v_accvgpr_read_b32 v107, a175
	s_waitcnt vmcnt(23)
	v_pk_fma_f32 v[88:89], v[104:105], v[24:25], v[88:89]
	v_pk_fma_f32 v[90:91], v[106:107], v[26:27], v[90:91]
	global_store_dwordx4 v[108:109], v[88:91], off offset:256
	v_accvgpr_read_b32 v104, a168
	v_accvgpr_read_b32 v105, a169
	v_accvgpr_read_b32 v106, a170
	v_accvgpr_read_b32 v107, a171
	s_waitcnt vmcnt(23)
	v_pk_fma_f32 v[92:93], v[104:105], v[28:29], v[92:93]
	v_pk_fma_f32 v[94:95], v[106:107], v[30:31], v[94:95]
	global_store_dwordx4 v[108:109], v[92:95], off offset:320
	v_accvgpr_read_b32 v104, a164
	v_accvgpr_read_b32 v105, a165
	v_accvgpr_read_b32 v106, a166
	v_accvgpr_read_b32 v107, a167
	s_waitcnt vmcnt(23)
	v_pk_fma_f32 v[96:97], v[104:105], v[32:33], v[96:97]
	v_pk_fma_f32 v[98:99], v[106:107], v[34:35], v[98:99]
	global_store_dwordx4 v[108:109], v[96:99], off offset:384
	v_accvgpr_read_b32 v104, a160
	v_accvgpr_read_b32 v105, a161
	v_accvgpr_read_b32 v106, a162
	v_accvgpr_read_b32 v107, a163
	s_waitcnt vmcnt(23)
	v_pk_fma_f32 v[100:101], v[104:105], v[36:37], v[100:101]
	v_pk_fma_f32 v[102:103], v[106:107], v[38:39], v[102:103]
	global_store_dwordx4 v[108:109], v[100:103], off offset:448
	v_lshl_add_u64 v[108:109], v[108:109], 0, v[110:111]
	s_nop 1
	global_load_dwordx4 v[72:75], v[108:109], off
	global_load_dwordx4 v[76:79], v[108:109], off offset:64
	global_load_dwordx4 v[80:83], v[108:109], off offset:128
	global_load_dwordx4 v[84:87], v[108:109], off offset:192
	global_load_dwordx4 v[88:91], v[108:109], off offset:256
	global_load_dwordx4 v[92:95], v[108:109], off offset:320
	global_load_dwordx4 v[96:99], v[108:109], off offset:384
	global_load_dwordx4 v[100:103], v[108:109], off offset:448
	v_accvgpr_read_b32 v104, a92
	v_accvgpr_read_b32 v105, a93
	v_accvgpr_read_b32 v106, a94
	v_accvgpr_read_b32 v107, a95
	s_waitcnt vmcnt(23)
	v_pk_fma_f32 v[40:41], v[104:105], v[4:5], v[40:41]
	v_pk_fma_f32 v[42:43], v[106:107], v[6:7], v[42:43]
	global_store_dwordx4 v[152:153], v[40:43], off
	v_accvgpr_read_b32 v104, a88
	v_accvgpr_read_b32 v105, a89
	v_accvgpr_read_b32 v106, a90
	v_accvgpr_read_b32 v107, a91
	s_waitcnt vmcnt(23)
	v_pk_fma_f32 v[44:45], v[104:105], v[8:9], v[44:45]
	v_pk_fma_f32 v[46:47], v[106:107], v[10:11], v[46:47]
	global_store_dwordx4 v[152:153], v[44:47], off offset:64
	v_accvgpr_read_b32 v104, a84
	v_accvgpr_read_b32 v105, a85
	v_accvgpr_read_b32 v106, a86
	v_accvgpr_read_b32 v107, a87
	s_waitcnt vmcnt(23)
	v_pk_fma_f32 v[48:49], v[104:105], v[16:17], v[48:49]
	v_pk_fma_f32 v[50:51], v[106:107], v[18:19], v[50:51]
	global_store_dwordx4 v[152:153], v[48:51], off offset:128
	v_accvgpr_read_b32 v104, a80
	v_accvgpr_read_b32 v105, a81
	v_accvgpr_read_b32 v106, a82
	v_accvgpr_read_b32 v107, a83
	s_waitcnt vmcnt(23)
	v_pk_fma_f32 v[52:53], v[104:105], v[20:21], v[52:53]
	v_pk_fma_f32 v[54:55], v[106:107], v[22:23], v[54:55]
	global_store_dwordx4 v[152:153], v[52:55], off offset:192
	v_accvgpr_read_b32 v104, a140
	v_accvgpr_read_b32 v105, a141
	v_accvgpr_read_b32 v106, a142
	v_accvgpr_read_b32 v107, a143
	s_waitcnt vmcnt(23)
	v_pk_fma_f32 v[56:57], v[104:105], v[24:25], v[56:57]
	v_pk_fma_f32 v[58:59], v[106:107], v[26:27], v[58:59]
	global_store_dwordx4 v[152:153], v[56:59], off offset:256
	v_accvgpr_read_b32 v104, a136
	v_accvgpr_read_b32 v105, a137
	v_accvgpr_read_b32 v106, a138
	v_accvgpr_read_b32 v107, a139
	s_waitcnt vmcnt(23)
	v_pk_fma_f32 v[60:61], v[104:105], v[28:29], v[60:61]
	v_pk_fma_f32 v[62:63], v[106:107], v[30:31], v[62:63]
	global_store_dwordx4 v[152:153], v[60:63], off offset:320
	v_accvgpr_read_b32 v104, a132
	v_accvgpr_read_b32 v105, a133
	v_accvgpr_read_b32 v106, a134
	v_accvgpr_read_b32 v107, a135
	s_waitcnt vmcnt(23)
	v_pk_fma_f32 v[64:65], v[104:105], v[32:33], v[64:65]
	v_pk_fma_f32 v[66:67], v[106:107], v[34:35], v[66:67]
	global_store_dwordx4 v[152:153], v[64:67], off offset:384
	v_accvgpr_read_b32 v104, a128
	v_accvgpr_read_b32 v105, a129
	v_accvgpr_read_b32 v106, a130
	v_accvgpr_read_b32 v107, a131
	s_waitcnt vmcnt(23)
	v_pk_fma_f32 v[68:69], v[104:105], v[36:37], v[68:69]
	v_pk_fma_f32 v[70:71], v[106:107], v[38:39], v[70:71]
	global_store_dwordx4 v[152:153], v[68:71], off offset:448
	v_lshl_add_u64 v[152:153], v[152:153], 0, v[110:111]
	s_nop 1
	global_load_dwordx4 v[40:43], v[152:153], off
	global_load_dwordx4 v[44:47], v[152:153], off offset:64
	global_load_dwordx4 v[48:51], v[152:153], off offset:128
	global_load_dwordx4 v[52:55], v[152:153], off offset:192
	global_load_dwordx4 v[56:59], v[152:153], off offset:256
	global_load_dwordx4 v[60:63], v[152:153], off offset:320
	global_load_dwordx4 v[64:67], v[152:153], off offset:384
	global_load_dwordx4 v[68:71], v[152:153], off offset:448
	v_accvgpr_read_b32 v104, a60
	v_accvgpr_read_b32 v105, a61
	v_accvgpr_read_b32 v106, a62
	v_accvgpr_read_b32 v107, a63
	s_waitcnt vmcnt(23)
	v_pk_fma_f32 v[72:73], v[104:105], v[4:5], v[72:73]
	v_pk_fma_f32 v[74:75], v[106:107], v[6:7], v[74:75]
	global_store_dwordx4 v[108:109], v[72:75], off
	v_accvgpr_read_b32 v104, a56
	v_accvgpr_read_b32 v105, a57
	v_accvgpr_read_b32 v106, a58
	v_accvgpr_read_b32 v107, a59
	s_waitcnt vmcnt(23)
	v_pk_fma_f32 v[76:77], v[104:105], v[8:9], v[76:77]
	v_pk_fma_f32 v[78:79], v[106:107], v[10:11], v[78:79]
	global_store_dwordx4 v[108:109], v[76:79], off offset:64
	v_accvgpr_read_b32 v104, a52
	v_accvgpr_read_b32 v105, a53
	v_accvgpr_read_b32 v106, a54
	v_accvgpr_read_b32 v107, a55
	s_waitcnt vmcnt(23)
	v_pk_fma_f32 v[80:81], v[104:105], v[16:17], v[80:81]
	v_pk_fma_f32 v[82:83], v[106:107], v[18:19], v[82:83]
	global_store_dwordx4 v[108:109], v[80:83], off offset:128
	v_accvgpr_read_b32 v104, a48
	v_accvgpr_read_b32 v105, a49
	v_accvgpr_read_b32 v106, a50
	v_accvgpr_read_b32 v107, a51
	s_waitcnt vmcnt(23)
	v_pk_fma_f32 v[84:85], v[104:105], v[20:21], v[84:85]
	v_pk_fma_f32 v[86:87], v[106:107], v[22:23], v[86:87]
	global_store_dwordx4 v[108:109], v[84:87], off offset:192
	v_accvgpr_read_b32 v104, a108
	v_accvgpr_read_b32 v105, a109
	v_accvgpr_read_b32 v106, a110
	v_accvgpr_read_b32 v107, a111
	s_waitcnt vmcnt(23)
	v_pk_fma_f32 v[88:89], v[104:105], v[24:25], v[88:89]
	v_pk_fma_f32 v[90:91], v[106:107], v[26:27], v[90:91]
	global_store_dwordx4 v[108:109], v[88:91], off offset:256
	v_accvgpr_read_b32 v104, a104
	v_accvgpr_read_b32 v105, a105
	v_accvgpr_read_b32 v106, a106
	v_accvgpr_read_b32 v107, a107
	s_waitcnt vmcnt(23)
	v_pk_fma_f32 v[92:93], v[104:105], v[28:29], v[92:93]
	v_pk_fma_f32 v[94:95], v[106:107], v[30:31], v[94:95]
	global_store_dwordx4 v[108:109], v[92:95], off offset:320
	v_accvgpr_read_b32 v104, a100
	v_accvgpr_read_b32 v105, a101
	v_accvgpr_read_b32 v106, a102
	v_accvgpr_read_b32 v107, a103
	s_waitcnt vmcnt(23)
	v_pk_fma_f32 v[96:97], v[104:105], v[32:33], v[96:97]
	v_pk_fma_f32 v[98:99], v[106:107], v[34:35], v[98:99]
	global_store_dwordx4 v[108:109], v[96:99], off offset:384
	v_accvgpr_read_b32 v104, a96
	v_accvgpr_read_b32 v105, a97
	v_accvgpr_read_b32 v106, a98
	v_accvgpr_read_b32 v107, a99
	s_waitcnt vmcnt(23)
	v_pk_fma_f32 v[100:101], v[104:105], v[36:37], v[100:101]
	v_pk_fma_f32 v[102:103], v[106:107], v[38:39], v[102:103]
	global_store_dwordx4 v[108:109], v[100:103], off offset:448
	v_lshl_add_u64 v[108:109], v[108:109], 0, v[110:111]
	s_nop 1
	global_load_dwordx4 v[72:75], v[108:109], off
	global_load_dwordx4 v[76:79], v[108:109], off offset:64
	global_load_dwordx4 v[80:83], v[108:109], off offset:128
	global_load_dwordx4 v[84:87], v[108:109], off offset:192
	global_load_dwordx4 v[88:91], v[108:109], off offset:256
	global_load_dwordx4 v[92:95], v[108:109], off offset:320
	global_load_dwordx4 v[96:99], v[108:109], off offset:384
	global_load_dwordx4 v[100:103], v[108:109], off offset:448
	v_accvgpr_read_b32 v104, a32
	v_accvgpr_read_b32 v105, a33
	v_accvgpr_read_b32 v106, a34
	v_accvgpr_read_b32 v107, a35
	s_waitcnt vmcnt(23)
; template <class Epi>
; __device__ __forceinline__ void gemm_run(const GemmArgs g, Epi epi, char* smem) {
;     ...
;   for (int tile = blockIdx.x; tile < total; tile += gridDim.x) {
	v_pk_fma_f32 v[40:41], v[104:105], v[4:5], v[40:41]
	v_pk_fma_f32 v[42:43], v[106:107], v[6:7], v[42:43]
	global_store_dwordx4 v[152:153], v[40:43], off
	v_accvgpr_read_b32 v104, a28
	v_accvgpr_read_b32 v105, a29
	v_accvgpr_read_b32 v106, a30
	v_accvgpr_read_b32 v107, a31
	s_waitcnt vmcnt(23)
	v_pk_fma_f32 v[44:45], v[104:105], v[8:9], v[44:45]
	v_pk_fma_f32 v[46:47], v[106:107], v[10:11], v[46:47]
	global_store_dwordx4 v[152:153], v[44:47], off offset:64
	v_accvgpr_read_b32 v104, a24
	v_accvgpr_read_b32 v105, a25
	v_accvgpr_read_b32 v106, a26
	v_accvgpr_read_b32 v107, a27
	s_waitcnt vmcnt(23)
	v_pk_fma_f32 v[48:49], v[104:105], v[16:17], v[48:49]
	v_pk_fma_f32 v[50:51], v[106:107], v[18:19], v[50:51]
	global_store_dwordx4 v[152:153], v[48:51], off offset:128
	v_accvgpr_read_b32 v104, a20
	v_accvgpr_read_b32 v105, a21
	v_accvgpr_read_b32 v106, a22
	v_accvgpr_read_b32 v107, a23
	s_waitcnt vmcnt(23)
	v_pk_fma_f32 v[52:53], v[104:105], v[20:21], v[52:53]
	v_pk_fma_f32 v[54:55], v[106:107], v[22:23], v[54:55]
	global_store_dwordx4 v[152:153], v[52:55], off offset:192
	v_accvgpr_read_b32 v104, a76
	v_accvgpr_read_b32 v105, a77
	v_accvgpr_read_b32 v106, a78
	v_accvgpr_read_b32 v107, a79
	s_waitcnt vmcnt(23)
	v_pk_fma_f32 v[56:57], v[104:105], v[24:25], v[56:57]
	v_pk_fma_f32 v[58:59], v[106:107], v[26:27], v[58:59]
	global_store_dwordx4 v[152:153], v[56:59], off offset:256
	v_accvgpr_read_b32 v104, a72
	v_accvgpr_read_b32 v105, a73
	v_accvgpr_read_b32 v106, a74
	v_accvgpr_read_b32 v107, a75
	s_waitcnt vmcnt(23)
	v_pk_fma_f32 v[60:61], v[104:105], v[28:29], v[60:61]
	v_pk_fma_f32 v[62:63], v[106:107], v[30:31], v[62:63]
	global_store_dwordx4 v[152:153], v[60:63], off offset:320
	v_accvgpr_read_b32 v104, a68
	v_accvgpr_read_b32 v105, a69
	v_accvgpr_read_b32 v106, a70
	v_accvgpr_read_b32 v107, a71
	s_waitcnt vmcnt(23)
	v_pk_fma_f32 v[64:65], v[104:105], v[32:33], v[64:65]
	v_pk_fma_f32 v[66:67], v[106:107], v[34:35], v[66:67]
	global_store_dwordx4 v[152:153], v[64:67], off offset:384
	v_accvgpr_read_b32 v104, a64
	v_accvgpr_read_b32 v105, a65
	v_accvgpr_read_b32 v106, a66
	v_accvgpr_read_b32 v107, a67
	s_waitcnt vmcnt(23)
	v_pk_fma_f32 v[68:69], v[104:105], v[36:37], v[68:69]
	v_pk_fma_f32 v[70:71], v[106:107], v[38:39], v[70:71]
	global_store_dwordx4 v[152:153], v[68:71], off offset:448
	v_accvgpr_read_b32 v104, a12
	v_accvgpr_read_b32 v105, a13
	v_accvgpr_read_b32 v106, a14
	v_accvgpr_read_b32 v107, a15
	s_waitcnt vmcnt(15)
	v_pk_fma_f32 v[72:73], v[104:105], v[4:5], v[72:73]
	v_pk_fma_f32 v[74:75], v[106:107], v[6:7], v[74:75]
	global_store_dwordx4 v[108:109], v[72:75], off
	v_accvgpr_read_b32 v104, a8
	v_accvgpr_read_b32 v105, a9
	v_accvgpr_read_b32 v106, a10
	v_accvgpr_read_b32 v107, a11
	s_waitcnt vmcnt(15)
	v_pk_fma_f32 v[76:77], v[104:105], v[8:9], v[76:77]
	v_pk_fma_f32 v[78:79], v[106:107], v[10:11], v[78:79]
	global_store_dwordx4 v[108:109], v[76:79], off offset:64
	v_accvgpr_read_b32 v104, a4
	v_accvgpr_read_b32 v105, a5
	v_accvgpr_read_b32 v106, a6
	v_accvgpr_read_b32 v107, a7
	s_waitcnt vmcnt(15)
	v_pk_fma_f32 v[80:81], v[104:105], v[16:17], v[80:81]
	v_pk_fma_f32 v[82:83], v[106:107], v[18:19], v[82:83]
	global_store_dwordx4 v[108:109], v[80:83], off offset:128
	v_accvgpr_read_b32 v104, a0
	v_accvgpr_read_b32 v105, a1
	v_accvgpr_read_b32 v106, a2
	v_accvgpr_read_b32 v107, a3
	s_waitcnt vmcnt(15)
	v_pk_fma_f32 v[84:85], v[104:105], v[20:21], v[84:85]
	v_pk_fma_f32 v[86:87], v[106:107], v[22:23], v[86:87]
	global_store_dwordx4 v[108:109], v[84:87], off offset:192
	v_accvgpr_read_b32 v104, a44
	v_accvgpr_read_b32 v105, a45
	v_accvgpr_read_b32 v106, a46
	v_accvgpr_read_b32 v107, a47
	s_waitcnt vmcnt(15)
	v_pk_fma_f32 v[88:89], v[104:105], v[24:25], v[88:89]
	v_pk_fma_f32 v[90:91], v[106:107], v[26:27], v[90:91]
	global_store_dwordx4 v[108:109], v[88:91], off offset:256
	v_accvgpr_read_b32 v104, a40
	v_accvgpr_read_b32 v105, a41
	v_accvgpr_read_b32 v106, a42
	v_accvgpr_read_b32 v107, a43
	s_waitcnt vmcnt(15)
	v_pk_fma_f32 v[92:93], v[104:105], v[28:29], v[92:93]
	v_pk_fma_f32 v[94:95], v[106:107], v[30:31], v[94:95]
	global_store_dwordx4 v[108:109], v[92:95], off offset:320
	v_accvgpr_read_b32 v104, a36
	v_accvgpr_read_b32 v105, a37
	v_accvgpr_read_b32 v106, a38
	v_accvgpr_read_b32 v107, a39
	s_waitcnt vmcnt(15)
	v_pk_fma_f32 v[96:97], v[104:105], v[32:33], v[96:97]
	v_pk_fma_f32 v[98:99], v[106:107], v[34:35], v[98:99]
	global_store_dwordx4 v[108:109], v[96:99], off offset:384
	v_accvgpr_read_b32 v104, a16
	v_accvgpr_read_b32 v105, a17
	v_accvgpr_read_b32 v106, a18
	v_accvgpr_read_b32 v107, a19
	s_waitcnt vmcnt(15)
	v_pk_fma_f32 v[100:101], v[104:105], v[36:37], v[100:101]
	v_pk_fma_f32 v[102:103], v[106:107], v[38:39], v[102:103]
	global_store_dwordx4 v[108:109], v[100:103], off offset:448
	s_add_i32 s80, s80, s2
	s_cmpk_gt_i32 s80, 0x1ff
	s_cbranch_scc1 .LBB0_1004

; #define LD_AF(dst, ks_) _Pragma("unroll") for (int i = 0; i < 8; ++i) dst[i] = *(const h8*)(sA + i * 16 * G_LD + (ks_) * 32)
; #define LD_BF(dst, ks_, nh_) _Pragma("unroll") for (int i = 0; i < 4; ++i) dst[i] = *(const h8*)(sB + ((nh_) * 4 + i) * 16 * G_LD + (ks_) * 32)
; #define MMA_BLK(afx, bfx, nh_) _Pragma("unroll") for (int mi = 0; mi < 8; ++mi) _Pragma("unroll") for (int ni = 0; ni < 4; ++ni) mfma16_acc(acc[mi][(nh_) * 4 + ni], bfx[ni], afx[mi])
; template <class Epi>
; __device__ __forceinline__ void gemm_run(const GemmArgs g, Epi epi, char* smem) {
;     ...
;     for (int kt = 0; kt < nk; ++kt) {
;       const hf* sA = sbase + (kt & 1) * G_STAGE + (wm * 128 + fr) * G_LD + fqs;
;       const hf* sB = sbase + (kt & 1) * G_STAGE + (256 + wn * 128 + fr) * G_LD + fqs;
;       hf* st = sbase + ((kt + 1) & 1) * G_STAGE;
;       h8 afA[8], afB[8], bfA[4], bfB[4];
;     ...
;       LD_AF(afA, 0); LD_BF(bfA, 0, 0);
;       if (kt + 1 < nk) {
; #pragma unroll
;         for (int i = 0; i < 8; ++i) *(u4*)(st + (lr + 32 * i) * G_LD + lcw) = ra[i];
;       }
;       __builtin_amdgcn_sched_barrier(0);
;       LD_BF(bfB, 0, 1);
;       MMA_BLK(afA, bfA, 0);
;       __builtin_amdgcn_sched_barrier(0);
;       if (kt + 1 < nk) {
; #pragma unroll
;         for (int i = 0; i < 8; ++i) *(u4*)(st + (256 + lr + 32 * i) * G_LD + lcw) = rb[i];
;       }
;       LD_AF(afB, 1); LD_BF(bfA, 1, 0);
;       MMA_BLK(afA, bfB, 1);
;       __builtin_amdgcn_sched_barrier(0);
;       if (kt + 2 < nk) {
;         const int ko = (kt + 2) * 64;
; #pragma unroll
;         for (int i = 0; i < 8; ++i) { ra[i] = __builtin_amdgcn_raw_buffer_load_b128(Ars, aoff, i * astep + ko * 2, 0); rb[i] = __builtin_amdgcn_raw_buffer_load_b128(Brs, boff, i * bstep + ko * 2, 0); }
;       }
;       LD_BF(bfB, 1, 1);
;       MMA_BLK(afB, bfA, 0);
;       __builtin_amdgcn_sched_barrier(0);
;       MMA_BLK(afB, bfB, 1);
;       __builtin_amdgcn_sched_barrier(0);
.LBB0_1056:
	ds_read_b128 v[0:3], v138 offset:36864
	ds_read_b128 v[4:7], v138 offset:39168
	ds_read_b128 v[8:11], v138 offset:41472
	ds_read_b128 v[12:15], v138 offset:43776
	ds_read_b128 v[16:19], v139
	ds_read_b128 v[20:23], v139 offset:2304
	ds_read_b128 v[24:27], v139 offset:4608
	ds_read_b128 v[28:31], v139 offset:6912
	ds_read_b128 v[32:35], v139 offset:9216
	ds_read_b128 v[36:39], v139 offset:11520
	ds_read_b128 v[40:43], v139 offset:13824
	ds_read_b128 v[44:47], v139 offset:16128
	s_waitcnt lgkmcnt(7)
	v_mfma_f32_16x16x32_f16 a[220:223], v[0:3], v[16:19], a[220:223]
	v_mfma_f32_16x16x32_f16 a[216:219], v[4:7], v[16:19], a[216:219]
	v_mfma_f32_16x16x32_f16 a[212:215], v[8:11], v[16:19], a[212:215]
	v_mfma_f32_16x16x32_f16 a[208:211], v[12:15], v[16:19], a[208:211]
	s_waitcnt lgkmcnt(6)
	v_mfma_f32_16x16x32_f16 a[200:203], v[0:3], v[20:23], a[200:203]
	v_mfma_f32_16x16x32_f16 a[196:199], v[4:7], v[20:23], a[196:199]
	v_mfma_f32_16x16x32_f16 a[188:191], v[8:11], v[20:23], a[188:191]
	v_mfma_f32_16x16x32_f16 a[180:183], v[12:15], v[20:23], a[180:183]
	s_waitcnt lgkmcnt(5)
	v_mfma_f32_16x16x32_f16 a[172:175], v[0:3], v[24:27], a[172:175]
	v_mfma_f32_16x16x32_f16 a[164:167], v[4:7], v[24:27], a[164:167]
	v_mfma_f32_16x16x32_f16 a[156:159], v[8:11], v[24:27], a[156:159]
	v_mfma_f32_16x16x32_f16 a[148:151], v[12:15], v[24:27], a[148:151]
	s_waitcnt lgkmcnt(4)
	v_mfma_f32_16x16x32_f16 a[140:143], v[0:3], v[28:31], a[140:143]
	v_mfma_f32_16x16x32_f16 a[132:135], v[4:7], v[28:31], a[132:135]
	v_mfma_f32_16x16x32_f16 a[124:127], v[8:11], v[28:31], a[124:127]
	v_mfma_f32_16x16x32_f16 a[116:119], v[12:15], v[28:31], a[116:119]
	s_waitcnt lgkmcnt(3)
	v_mfma_f32_16x16x32_f16 a[108:111], v[0:3], v[32:35], a[108:111]
	v_mfma_f32_16x16x32_f16 a[100:103], v[4:7], v[32:35], a[100:103]
	v_mfma_f32_16x16x32_f16 a[92:95], v[8:11], v[32:35], a[92:95]
	v_mfma_f32_16x16x32_f16 a[84:87], v[12:15], v[32:35], a[84:87]
	s_waitcnt lgkmcnt(2)
	v_mfma_f32_16x16x32_f16 a[76:79], v[0:3], v[36:39], a[76:79]
	v_mfma_f32_16x16x32_f16 a[68:71], v[4:7], v[36:39], a[68:71]
	v_mfma_f32_16x16x32_f16 a[60:63], v[8:11], v[36:39], a[60:63]
	v_mfma_f32_16x16x32_f16 a[52:55], v[12:15], v[36:39], a[52:55]
	s_waitcnt lgkmcnt(1)
	v_mfma_f32_16x16x32_f16 a[44:47], v[0:3], v[40:43], a[44:47]
	v_mfma_f32_16x16x32_f16 a[36:39], v[4:7], v[40:43], a[36:39]
	v_mfma_f32_16x16x32_f16 a[28:31], v[8:11], v[40:43], a[28:31]
	v_mfma_f32_16x16x32_f16 a[20:23], v[12:15], v[40:43], a[20:23]
	s_waitcnt lgkmcnt(0)
	v_mfma_f32_16x16x32_f16 a[12:15], v[0:3], v[44:47], a[12:15]
	v_mfma_f32_16x16x32_f16 a[8:11], v[4:7], v[44:47], a[8:11]
	v_mfma_f32_16x16x32_f16 a[4:7], v[8:11], v[44:47], a[4:7]
	v_mfma_f32_16x16x32_f16 a[0:3], v[12:15], v[44:47], a[0:3]
	ds_read_b128 v[0:3], v138 offset:46080
	ds_read_b128 v[4:7], v138 offset:48384
	ds_read_b128 v[8:11], v138 offset:50688
	ds_read_b128 v[12:15], v138 offset:52992
	s_waitcnt lgkmcnt(3)
	v_mfma_f32_16x16x32_f16 a[240:243], v[0:3], v[16:19], a[240:243]
	s_waitcnt lgkmcnt(2)
	v_mfma_f32_16x16x32_f16 a[252:255], v[4:7], v[16:19], a[252:255]
	s_waitcnt lgkmcnt(1)
	v_mfma_f32_16x16x32_f16 a[248:251], v[8:11], v[16:19], a[248:251]
	s_waitcnt lgkmcnt(0)
	v_mfma_f32_16x16x32_f16 a[244:247], v[12:15], v[16:19], a[244:247]
	v_mfma_f32_16x16x32_f16 a[236:239], v[0:3], v[20:23], a[236:239]
	v_mfma_f32_16x16x32_f16 a[232:235], v[4:7], v[20:23], a[232:235]
	v_mfma_f32_16x16x32_f16 a[228:231], v[8:11], v[20:23], a[228:231]
	v_mfma_f32_16x16x32_f16 a[224:227], v[12:15], v[20:23], a[224:227]
	v_mfma_f32_16x16x32_f16 a[204:207], v[0:3], v[24:27], a[204:207]
	v_mfma_f32_16x16x32_f16 a[192:195], v[4:7], v[24:27], a[192:195]
	v_mfma_f32_16x16x32_f16 a[184:187], v[8:11], v[24:27], a[184:187]
	v_mfma_f32_16x16x32_f16 a[176:179], v[12:15], v[24:27], a[176:179]
	v_mfma_f32_16x16x32_f16 a[168:171], v[0:3], v[28:31], a[168:171]
	v_mfma_f32_16x16x32_f16 a[160:163], v[4:7], v[28:31], a[160:163]
	v_mfma_f32_16x16x32_f16 a[152:155], v[8:11], v[28:31], a[152:155]
	v_mfma_f32_16x16x32_f16 a[144:147], v[12:15], v[28:31], a[144:147]
	v_mfma_f32_16x16x32_f16 a[136:139], v[0:3], v[32:35], a[136:139]
	v_mfma_f32_16x16x32_f16 a[128:131], v[4:7], v[32:35], a[128:131]
	v_mfma_f32_16x16x32_f16 a[120:123], v[8:11], v[32:35], a[120:123]
	v_mfma_f32_16x16x32_f16 a[112:115], v[12:15], v[32:35], a[112:115]
	v_mfma_f32_16x16x32_f16 a[104:107], v[0:3], v[36:39], a[104:107]
	v_mfma_f32_16x16x32_f16 a[96:99], v[4:7], v[36:39], a[96:99]
	v_mfma_f32_16x16x32_f16 a[88:91], v[8:11], v[36:39], a[88:91]
	v_mfma_f32_16x16x32_f16 a[80:83], v[12:15], v[36:39], a[80:83]
	v_mfma_f32_16x16x32_f16 a[72:75], v[0:3], v[40:43], a[72:75]
	v_mfma_f32_16x16x32_f16 a[64:67], v[4:7], v[40:43], a[64:67]
	v_mfma_f32_16x16x32_f16 a[56:59], v[8:11], v[40:43], a[56:59]
	v_mfma_f32_16x16x32_f16 a[48:51], v[12:15], v[40:43], a[48:51]
	v_mfma_f32_16x16x32_f16 a[40:43], v[0:3], v[44:47], a[40:43]
	v_mfma_f32_16x16x32_f16 a[32:35], v[4:7], v[44:47], a[32:35]
	v_mfma_f32_16x16x32_f16 a[24:27], v[8:11], v[44:47], a[24:27]
	v_mfma_f32_16x16x32_f16 a[16:19], v[12:15], v[44:47], a[16:19]
	ds_read_b128 v[20:23], v138 offset:36928
	ds_read_b128 v[44:47], v139 offset:64
	ds_read_b128 v[58:61], v138 offset:39232
	ds_read_b128 v[62:65], v138 offset:41536
	ds_read_b128 v[74:77], v138 offset:43840
	ds_read_b128 v[78:81], v139 offset:2368
	s_waitcnt vmcnt(6)
	ds_read_b128 v[142:145], v139 offset:4672
	ds_read_b128 v[16:19], v139 offset:6976
	ds_read_b128 v[12:15], v139 offset:9280
	ds_read_b128 v[8:11], v139 offset:11584
	ds_read_b128 v[4:7], v139 offset:13888
	ds_read_b128 v[0:3], v139 offset:16192
	s_waitcnt vmcnt(5)
; #define LD_AF(dst, ks_) _Pragma("unroll") for (int i = 0; i < 8; ++i) dst[i] = *(const h8*)(sA + i * 16 * G_LD + (ks_) * 32)
; #define LD_BF(dst, ks_, nh_) _Pragma("unroll") for (int i = 0; i < 4; ++i) dst[i] = *(const h8*)(sB + ((nh_) * 4 + i) * 16 * G_LD + (ks_) * 32)
; #define MMA_BLK(afx, bfx, nh_) _Pragma("unroll") for (int mi = 0; mi < 8; ++mi) _Pragma("unroll") for (int ni = 0; ni < 4; ++ni) mfma16_acc(acc[mi][(nh_) * 4 + ni], bfx[ni], afx[mi])
; template <class Epi>
; __device__ __forceinline__ void gemm_run(const GemmArgs g, Epi epi, char* smem) {
;     ...
;     for (int kt = 0; kt < nk; ++kt) {
;       const hf* sA = sbase + (kt & 1) * G_STAGE + (wm * 128 + fr) * G_LD + fqs;
;       const hf* sB = sbase + (kt & 1) * G_STAGE + (256 + wn * 128 + fr) * G_LD + fqs;
;       hf* st = sbase + ((kt + 1) & 1) * G_STAGE;
;       h8 afA[8], afB[8], bfA[4], bfB[4];
;     ...
;       LD_AF(afA, 0); LD_BF(bfA, 0, 0);
;       if (kt + 1 < nk) {
; #pragma unroll
;         for (int i = 0; i < 8; ++i) *(u4*)(st + (lr + 32 * i) * G_LD + lcw) = ra[i];
;       }
;       __builtin_amdgcn_sched_barrier(0);
;       LD_BF(bfB, 0, 1);
;       MMA_BLK(afA, bfA, 0);
;       __builtin_amdgcn_sched_barrier(0);
;       if (kt + 1 < nk) {
; #pragma unroll
;         for (int i = 0; i < 8; ++i) *(u4*)(st + (256 + lr + 32 * i) * G_LD + lcw) = rb[i];
;       }
;       LD_AF(afB, 1); LD_BF(bfA, 1, 0);
;       MMA_BLK(afA, bfB, 1);
;       __builtin_amdgcn_sched_barrier(0);
;       if (kt + 2 < nk) {
;         const int ko = (kt + 2) * 64;
; #pragma unroll
;         for (int i = 0; i < 8; ++i) { ra[i] = __builtin_amdgcn_raw_buffer_load_b128(Ars, aoff, i * astep + ko * 2, 0); rb[i] = __builtin_amdgcn_raw_buffer_load_b128(Brs, boff, i * bstep + ko * 2, 0); }
;       }
;       LD_BF(bfB, 1, 1);
;       MMA_BLK(afB, bfA, 0);
;       __builtin_amdgcn_sched_barrier(0);
;       MMA_BLK(afB, bfB, 1);
;       __builtin_amdgcn_sched_barrier(0);
	ds_read_b128 v[146:149], v138 offset:46144
	s_waitcnt vmcnt(3)
	ds_read_b128 v[150:153], v138 offset:48448
	ds_read_b128 v[154:157], v138 offset:50752
	s_waitcnt vmcnt(1)
	ds_read_b128 v[158:161], v138 offset:53056
	s_waitcnt lgkmcnt(14)
	v_mfma_f32_16x16x32_f16 a[220:223], v[20:23], v[44:47], a[220:223]
	s_waitcnt lgkmcnt(13)
	v_mfma_f32_16x16x32_f16 a[216:219], v[58:61], v[44:47], a[216:219]
	s_waitcnt lgkmcnt(12)
	v_mfma_f32_16x16x32_f16 a[212:215], v[62:65], v[44:47], a[212:215]
	s_waitcnt lgkmcnt(11)
	v_mfma_f32_16x16x32_f16 a[208:211], v[74:77], v[44:47], a[208:211]
	s_waitcnt lgkmcnt(10)
	v_mfma_f32_16x16x32_f16 a[200:203], v[20:23], v[78:81], a[200:203]
	v_mfma_f32_16x16x32_f16 a[196:199], v[58:61], v[78:81], a[196:199]
	v_mfma_f32_16x16x32_f16 a[188:191], v[62:65], v[78:81], a[188:191]
	v_mfma_f32_16x16x32_f16 a[180:183], v[74:77], v[78:81], a[180:183]
	s_waitcnt lgkmcnt(9)
	v_mfma_f32_16x16x32_f16 a[172:175], v[20:23], v[142:145], a[172:175]
	v_mfma_f32_16x16x32_f16 a[164:167], v[58:61], v[142:145], a[164:167]
	v_mfma_f32_16x16x32_f16 a[156:159], v[62:65], v[142:145], a[156:159]
	v_mfma_f32_16x16x32_f16 a[148:151], v[74:77], v[142:145], a[148:151]
	s_waitcnt lgkmcnt(8)
	v_mfma_f32_16x16x32_f16 a[140:143], v[20:23], v[16:19], a[140:143]
	v_mfma_f32_16x16x32_f16 a[132:135], v[58:61], v[16:19], a[132:135]
	v_mfma_f32_16x16x32_f16 a[124:127], v[62:65], v[16:19], a[124:127]
	v_mfma_f32_16x16x32_f16 a[116:119], v[74:77], v[16:19], a[116:119]
	s_waitcnt lgkmcnt(7)
	v_mfma_f32_16x16x32_f16 a[108:111], v[20:23], v[12:15], a[108:111]
	v_mfma_f32_16x16x32_f16 a[100:103], v[58:61], v[12:15], a[100:103]
	v_mfma_f32_16x16x32_f16 a[92:95], v[62:65], v[12:15], a[92:95]
	v_mfma_f32_16x16x32_f16 a[84:87], v[74:77], v[12:15], a[84:87]
	v_accvgpr_read_b32 v121, a223
	v_accvgpr_read_b32 v120, a222
	v_accvgpr_read_b32 v119, a219
	v_accvgpr_read_b32 v118, a218
	v_accvgpr_read_b32 v117, a215
	v_accvgpr_read_b32 v116, a214
	v_accvgpr_read_b32 v115, a211
	v_accvgpr_read_b32 v114, a210
	v_accvgpr_read_b32 v105, a203
	v_accvgpr_read_b32 v104, a202
	v_accvgpr_read_b32 v103, a199
	v_accvgpr_read_b32 v102, a198
	v_accvgpr_read_b32 v101, a191
	v_accvgpr_read_b32 v100, a190
	v_accvgpr_read_b32 v99, a183
	v_accvgpr_read_b32 v98, a182
	v_accvgpr_read_b32 v89, a175
	v_accvgpr_read_b32 v88, a174
	v_accvgpr_read_b32 v87, a167
	v_accvgpr_read_b32 v86, a166
	v_accvgpr_read_b32 v85, a159
	v_accvgpr_read_b32 v84, a158
	v_accvgpr_read_b32 v83, a151
	v_accvgpr_read_b32 v82, a150
	v_accvgpr_read_b32 v73, a143
	v_accvgpr_read_b32 v72, a142
	v_accvgpr_read_b32 v71, a135
	v_accvgpr_read_b32 v70, a134
	v_accvgpr_read_b32 v69, a127
	v_accvgpr_read_b32 v68, a126
	v_accvgpr_read_b32 v67, a119
	v_accvgpr_read_b32 v66, a118
	v_accvgpr_read_b32 v57, a111
	v_accvgpr_read_b32 v56, a110
	v_accvgpr_read_b32 v55, a103
	v_accvgpr_read_b32 v54, a102
	v_accvgpr_read_b32 v53, a95
	v_accvgpr_read_b32 v52, a94
	v_accvgpr_read_b32 v51, a87
	v_accvgpr_read_b32 v50, a86
	s_waitcnt lgkmcnt(6)
	v_mfma_f32_16x16x32_f16 a[76:79], v[20:23], v[8:11], a[76:79]
	v_mfma_f32_16x16x32_f16 a[68:71], v[58:61], v[8:11], a[68:71]
	v_mfma_f32_16x16x32_f16 a[60:63], v[62:65], v[8:11], a[60:63]
	v_mfma_f32_16x16x32_f16 a[52:55], v[74:77], v[8:11], a[52:55]
	s_waitcnt lgkmcnt(5)
	v_mfma_f32_16x16x32_f16 a[44:47], v[20:23], v[4:7], a[44:47]
	v_mfma_f32_16x16x32_f16 a[36:39], v[58:61], v[4:7], a[36:39]
	v_mfma_f32_16x16x32_f16 a[28:31], v[62:65], v[4:7], a[28:31]
	v_mfma_f32_16x16x32_f16 a[20:23], v[74:77], v[4:7], a[20:23]
	s_waitcnt lgkmcnt(4)
	v_mfma_f32_16x16x32_f16 a[12:15], v[20:23], v[0:3], a[12:15]
	v_mfma_f32_16x16x32_f16 a[8:11], v[58:61], v[0:3], a[8:11]
	v_mfma_f32_16x16x32_f16 a[4:7], v[62:65], v[0:3], a[4:7]
	v_mfma_f32_16x16x32_f16 a[0:3], v[74:77], v[0:3], a[0:3]
	v_accvgpr_read_b32 v43, a79
	v_accvgpr_read_b32 v42, a78
	v_accvgpr_read_b32 v41, a71
	v_accvgpr_read_b32 v40, a70
	v_accvgpr_read_b32 v39, a63
	v_accvgpr_read_b32 v38, a62
	v_accvgpr_read_b32 v37, a55
	v_accvgpr_read_b32 v36, a54
	v_accvgpr_read_b32 v35, a47
	v_accvgpr_read_b32 v34, a46
	v_accvgpr_read_b32 v33, a39
	v_accvgpr_read_b32 v32, a38
	v_accvgpr_read_b32 v31, a31
	v_accvgpr_read_b32 v30, a30
	v_accvgpr_read_b32 v29, a23
	v_accvgpr_read_b32 v28, a22
	v_accvgpr_read_b32 v27, a15
	v_accvgpr_read_b32 v26, a14
	v_accvgpr_read_b32 v25, a11
	v_accvgpr_read_b32 v24, a10
	v_accvgpr_read_b32 v23, a7
	v_accvgpr_read_b32 v22, a6
	v_accvgpr_read_b32 v21, a3
	v_accvgpr_read_b32 v20, a2
	s_waitcnt lgkmcnt(3)
	v_mfma_f32_16x16x32_f16 a[240:243], v[146:149], v[44:47], a[240:243]
	s_waitcnt lgkmcnt(2)
	v_mfma_f32_16x16x32_f16 a[252:255], v[150:153], v[44:47], a[252:255]
	s_waitcnt lgkmcnt(1)
	v_mfma_f32_16x16x32_f16 a[248:251], v[154:157], v[44:47], a[248:251]
	s_waitcnt lgkmcnt(0)
; #define LD_BF(dst, ks_, nh_) _Pragma("unroll") for (int i = 0; i < 4; ++i) dst[i] = *(const h8*)(sB + ((nh_) * 4 + i) * 16 * G_LD + (ks_) * 32)
; #define MMA_BLK(afx, bfx, nh_) _Pragma("unroll") for (int mi = 0; mi < 8; ++mi) _Pragma("unroll") for (int ni = 0; ni < 4; ++ni) mfma16_acc(acc[mi][(nh_) * 4 + ni], bfx[ni], afx[mi])
; template <class Epi>
; __device__ __forceinline__ void gemm_run(const GemmArgs g, Epi epi, char* smem) {
;     ...
;       LD_BF(bfB, 1, 1);
;       MMA_BLK(afB, bfA, 0);
;       __builtin_amdgcn_sched_barrier(0);
;       MMA_BLK(afB, bfB, 1);
;       __builtin_amdgcn_sched_barrier(0);
	v_mfma_f32_16x16x32_f16 a[244:247], v[158:161], v[44:47], a[244:247]
	v_mfma_f32_16x16x32_f16 a[236:239], v[146:149], v[78:81], a[236:239]
	v_mfma_f32_16x16x32_f16 a[232:235], v[150:153], v[78:81], a[232:235]
	v_mfma_f32_16x16x32_f16 a[228:231], v[154:157], v[78:81], a[228:231]
	v_mfma_f32_16x16x32_f16 a[224:227], v[158:161], v[78:81], a[224:227]
	v_mfma_f32_16x16x32_f16 a[204:207], v[146:149], v[142:145], a[204:207]
	v_mfma_f32_16x16x32_f16 a[192:195], v[150:153], v[142:145], a[192:195]
	v_mfma_f32_16x16x32_f16 a[184:187], v[154:157], v[142:145], a[184:187]
	v_mfma_f32_16x16x32_f16 a[176:179], v[158:161], v[142:145], a[176:179]
	v_mfma_f32_16x16x32_f16 a[168:171], v[146:149], v[16:19], a[168:171]
	v_mfma_f32_16x16x32_f16 a[160:163], v[150:153], v[16:19], a[160:163]
	v_mfma_f32_16x16x32_f16 a[152:155], v[154:157], v[16:19], a[152:155]
	v_mfma_f32_16x16x32_f16 a[144:147], v[158:161], v[16:19], a[144:147]
	v_mfma_f32_16x16x32_f16 a[136:139], v[146:149], v[12:15], a[136:139]
	v_mfma_f32_16x16x32_f16 a[128:131], v[150:153], v[12:15], a[128:131]
	v_mfma_f32_16x16x32_f16 a[120:123], v[154:157], v[12:15], a[120:123]
	v_mfma_f32_16x16x32_f16 a[112:115], v[158:161], v[12:15], a[112:115]
	v_accvgpr_read_b32 v129, a243
	v_accvgpr_read_b32 v128, a242
	v_accvgpr_read_b32 v127, a255
	v_accvgpr_read_b32 v126, a254
	v_accvgpr_read_b32 v125, a251
	v_accvgpr_read_b32 v124, a250
	v_accvgpr_read_b32 v123, a247
	v_accvgpr_read_b32 v122, a246
	v_accvgpr_read_b32 v113, a239
	v_accvgpr_read_b32 v112, a238
	v_accvgpr_read_b32 v111, a235
	v_accvgpr_read_b32 v110, a234
	v_accvgpr_read_b32 v109, a231
	v_accvgpr_read_b32 v108, a230
	v_accvgpr_read_b32 v107, a227
	v_accvgpr_read_b32 v106, a226
	v_accvgpr_read_b32 v97, a207
	v_accvgpr_read_b32 v96, a206
	v_accvgpr_read_b32 v95, a195
	v_accvgpr_read_b32 v94, a194
	v_accvgpr_read_b32 v93, a187
	v_accvgpr_read_b32 v92, a186
	v_accvgpr_read_b32 v91, a179
	v_accvgpr_read_b32 v90, a178
	v_accvgpr_read_b32 v81, a171
	v_accvgpr_read_b32 v80, a170
	v_accvgpr_read_b32 v79, a163
	v_accvgpr_read_b32 v78, a162
	v_accvgpr_read_b32 v77, a155
	v_accvgpr_read_b32 v76, a154
	v_accvgpr_read_b32 v75, a147
	v_accvgpr_read_b32 v74, a146
	v_accvgpr_read_b32 v65, a139
	v_accvgpr_read_b32 v64, a138
	v_accvgpr_read_b32 v63, a131
	v_accvgpr_read_b32 v62, a130
	v_accvgpr_read_b32 v61, a123
	v_accvgpr_read_b32 v60, a122
	v_accvgpr_read_b32 v59, a115
	v_accvgpr_read_b32 v58, a114
	v_mfma_f32_16x16x32_f16 a[104:107], v[146:149], v[8:11], a[104:107]
	v_mfma_f32_16x16x32_f16 a[96:99], v[150:153], v[8:11], a[96:99]
	v_mfma_f32_16x16x32_f16 a[88:91], v[154:157], v[8:11], a[88:91]
	v_mfma_f32_16x16x32_f16 a[80:83], v[158:161], v[8:11], a[80:83]
	v_mfma_f32_16x16x32_f16 a[72:75], v[146:149], v[4:7], a[72:75]
	v_mfma_f32_16x16x32_f16 a[64:67], v[150:153], v[4:7], a[64:67]
	v_mfma_f32_16x16x32_f16 a[56:59], v[154:157], v[4:7], a[56:59]
	v_mfma_f32_16x16x32_f16 a[48:51], v[158:161], v[4:7], a[48:51]
	v_mfma_f32_16x16x32_f16 a[40:43], v[146:149], v[0:3], a[40:43]
	v_mfma_f32_16x16x32_f16 a[32:35], v[150:153], v[0:3], a[32:35]
	v_mfma_f32_16x16x32_f16 a[24:27], v[154:157], v[0:3], a[24:27]
	v_mfma_f32_16x16x32_f16 a[16:19], v[158:161], v[0:3], a[16:19]
	s_nop 0
	v_lshl_add_u32 v142, s84, 8, v132
	v_add_u32_e32 v148, 0x4000, v142
	v_min_i32_e32 v3, 0x8000, v148
	v_or_b32_e32 v2, s85, v135
	v_ashrrev_i32_e32 v3, 13, v3
	v_ashrrev_i32_e32 v149, 31, v148
	v_mul_hi_i32_i24_e32 v145, 0xc000, v3
	v_mul_i32_i24_e32 v144, 0xc000, v3
	v_ashrrev_i32_e32 v3, 31, v2
	v_lshlrev_b64 v[148:149], 13, v[148:149]
	v_lshl_add_u64 v[144:145], s[16:17], 0, v[144:145]
	v_lshlrev_b64 v[2:3], 2, v[2:3]
	v_lshl_add_u64 v[148:149], s[28:29], 0, v[148:149]
	v_lshl_add_u64 v[152:153], v[144:145], 0, v[2:3]
	v_lshl_add_u64 v[154:155], v[148:149], 0, v[2:3]
	s_barrier
	global_load_dwordx4 v[4:7], v[152:153], off
	global_load_dwordx4 v[8:11], v[152:153], off offset:64
	global_load_dwordx4 v[12:15], v[152:153], off offset:128
	global_load_dwordx4 v[16:19], v[152:153], off offset:192
	global_load_dwordx4 v[20:23], v[152:153], off offset:256
	global_load_dwordx4 v[24:27], v[152:153], off offset:320
	global_load_dwordx4 v[28:31], v[152:153], off offset:384
	global_load_dwordx4 v[32:35], v[152:153], off offset:448
	global_load_dwordx4 v[36:39], v[154:155], off
	global_load_dwordx4 v[40:43], v[154:155], off offset:64
	global_load_dwordx4 v[44:47], v[154:155], off offset:128
	global_load_dwordx4 v[48:51], v[154:155], off offset:192
	global_load_dwordx4 v[52:55], v[154:155], off offset:256
	global_load_dwordx4 v[56:59], v[154:155], off offset:320
	global_load_dwordx4 v[60:63], v[154:155], off offset:384
	global_load_dwordx4 v[64:67], v[154:155], off offset:448
	v_mov_b32_e32 v106, 0x20000
	v_mov_b32_e32 v107, 0
	v_lshl_add_u64 v[104:105], v[154:155], 0, v[106:107]
	v_mov_b32_e32 v106, 0x40000
	global_load_dwordx4 v[68:71], v[104:105], off
	global_load_dwordx4 v[72:75], v[104:105], off offset:64
	global_load_dwordx4 v[76:79], v[104:105], off offset:128
	global_load_dwordx4 v[80:83], v[104:105], off offset:192
	global_load_dwordx4 v[84:87], v[104:105], off offset:256
	global_load_dwordx4 v[88:91], v[104:105], off offset:320
	global_load_dwordx4 v[92:95], v[104:105], off offset:384
	global_load_dwordx4 v[96:99], v[104:105], off offset:448
	v_accvgpr_read_b32 v100, a220
	v_accvgpr_read_b32 v101, a221
	v_accvgpr_read_b32 v102, a222
	v_accvgpr_read_b32 v103, a223
	s_waitcnt vmcnt(15)
	v_pk_fma_f32 v[36:37], v[100:101], v[4:5], v[36:37]
	v_pk_fma_f32 v[38:39], v[102:103], v[6:7], v[38:39]
	global_store_dwordx4 v[154:155], v[36:39], off
	v_accvgpr_read_b32 v100, a216
	v_accvgpr_read_b32 v101, a217
	v_accvgpr_read_b32 v102, a218
	v_accvgpr_read_b32 v103, a219
	s_waitcnt vmcnt(15)
	v_pk_fma_f32 v[40:41], v[100:101], v[8:9], v[40:41]
	v_pk_fma_f32 v[42:43], v[102:103], v[10:11], v[42:43]
	global_store_dwordx4 v[154:155], v[40:43], off offset:64
	v_accvgpr_read_b32 v100, a212
	v_accvgpr_read_b32 v101, a213
	v_accvgpr_read_b32 v102, a214
	v_accvgpr_read_b32 v103, a215
	s_waitcnt vmcnt(15)
	v_pk_fma_f32 v[44:45], v[100:101], v[12:13], v[44:45]
	v_pk_fma_f32 v[46:47], v[102:103], v[14:15], v[46:47]
	global_store_dwordx4 v[154:155], v[44:47], off offset:128
	v_accvgpr_read_b32 v100, a208
	v_accvgpr_read_b32 v101, a209
	v_accvgpr_read_b32 v102, a210
	v_accvgpr_read_b32 v103, a211
	s_waitcnt vmcnt(15)
	v_pk_fma_f32 v[48:49], v[100:101], v[16:17], v[48:49]
	v_pk_fma_f32 v[50:51], v[102:103], v[18:19], v[50:51]
	global_store_dwordx4 v[154:155], v[48:51], off offset:192
	v_accvgpr_read_b32 v100, a240
	v_accvgpr_read_b32 v101, a241
	v_accvgpr_read_b32 v102, a242
	v_accvgpr_read_b32 v103, a243
	s_waitcnt vmcnt(15)
	v_pk_fma_f32 v[52:53], v[100:101], v[20:21], v[52:53]
	v_pk_fma_f32 v[54:55], v[102:103], v[22:23], v[54:55]
	global_store_dwordx4 v[154:155], v[52:55], off offset:256
	v_accvgpr_read_b32 v100, a252
	v_accvgpr_read_b32 v101, a253
	v_accvgpr_read_b32 v102, a254
	v_accvgpr_read_b32 v103, a255
	s_waitcnt vmcnt(15)
	v_pk_fma_f32 v[56:57], v[100:101], v[24:25], v[56:57]
	v_pk_fma_f32 v[58:59], v[102:103], v[26:27], v[58:59]
	global_store_dwordx4 v[154:155], v[56:59], off offset:320
	v_accvgpr_read_b32 v100, a248
	v_accvgpr_read_b32 v101, a249
	v_accvgpr_read_b32 v102, a250
	v_accvgpr_read_b32 v103, a251
	s_waitcnt vmcnt(15)
	v_pk_fma_f32 v[60:61], v[100:101], v[28:29], v[60:61]
	v_pk_fma_f32 v[62:63], v[102:103], v[30:31], v[62:63]
	global_store_dwordx4 v[154:155], v[60:63], off offset:384
	v_accvgpr_read_b32 v100, a244
	v_accvgpr_read_b32 v101, a245
	v_accvgpr_read_b32 v102, a246
	v_accvgpr_read_b32 v103, a247
	s_waitcnt vmcnt(15)
	v_pk_fma_f32 v[64:65], v[100:101], v[32:33], v[64:65]
	v_pk_fma_f32 v[66:67], v[102:103], v[34:35], v[66:67]
	global_store_dwordx4 v[154:155], v[64:67], off offset:448
	v_lshl_add_u64 v[154:155], v[154:155], 0, v[106:107]
	s_nop 1
	global_load_dwordx4 v[36:39], v[154:155], off
	global_load_dwordx4 v[40:43], v[154:155], off offset:64
	global_load_dwordx4 v[44:47], v[154:155], off offset:128
	global_load_dwordx4 v[48:51], v[154:155], off offset:192
	global_load_dwordx4 v[52:55], v[154:155], off offset:256
	global_load_dwordx4 v[56:59], v[154:155], off offset:320
	global_load_dwordx4 v[60:63], v[154:155], off offset:384
	global_load_dwordx4 v[64:67], v[154:155], off offset:448
	v_accvgpr_read_b32 v100, a200
	v_accvgpr_read_b32 v101, a201
	v_accvgpr_read_b32 v102, a202
	v_accvgpr_read_b32 v103, a203
	s_waitcnt vmcnt(23)
	v_pk_fma_f32 v[68:69], v[100:101], v[4:5], v[68:69]
	v_pk_fma_f32 v[70:71], v[102:103], v[6:7], v[70:71]
	global_store_dwordx4 v[104:105], v[68:71], off
	v_accvgpr_read_b32 v100, a196
	v_accvgpr_read_b32 v101, a197
	v_accvgpr_read_b32 v102, a198
	v_accvgpr_read_b32 v103, a199
	s_waitcnt vmcnt(23)
	v_pk_fma_f32 v[72:73], v[100:101], v[8:9], v[72:73]
	v_pk_fma_f32 v[74:75], v[102:103], v[10:11], v[74:75]
	global_store_dwordx4 v[104:105], v[72:75], off offset:64
	v_accvgpr_read_b32 v100, a188
	v_accvgpr_read_b32 v101, a189
	v_accvgpr_read_b32 v102, a190
	v_accvgpr_read_b32 v103, a191
	s_waitcnt vmcnt(23)
	v_pk_fma_f32 v[76:77], v[100:101], v[12:13], v[76:77]
	v_pk_fma_f32 v[78:79], v[102:103], v[14:15], v[78:79]
	global_store_dwordx4 v[104:105], v[76:79], off offset:128
	v_accvgpr_read_b32 v100, a180
	v_accvgpr_read_b32 v101, a181
	v_accvgpr_read_b32 v102, a182
	v_accvgpr_read_b32 v103, a183
	s_waitcnt vmcnt(23)
	v_pk_fma_f32 v[80:81], v[100:101], v[16:17], v[80:81]
	v_pk_fma_f32 v[82:83], v[102:103], v[18:19], v[82:83]
	global_store_dwordx4 v[104:105], v[80:83], off offset:192
	v_accvgpr_read_b32 v100, a236
	v_accvgpr_read_b32 v101, a237
	v_accvgpr_read_b32 v102, a238
	v_accvgpr_read_b32 v103, a239
	s_waitcnt vmcnt(23)
	v_pk_fma_f32 v[84:85], v[100:101], v[20:21], v[84:85]
	v_pk_fma_f32 v[86:87], v[102:103], v[22:23], v[86:87]
	global_store_dwordx4 v[104:105], v[84:87], off offset:256
	v_accvgpr_read_b32 v100, a232
	v_accvgpr_read_b32 v101, a233
	v_accvgpr_read_b32 v102, a234
	v_accvgpr_read_b32 v103, a235
	s_waitcnt vmcnt(23)
	v_pk_fma_f32 v[88:89], v[100:101], v[24:25], v[88:89]
	v_pk_fma_f32 v[90:91], v[102:103], v[26:27], v[90:91]
	global_store_dwordx4 v[104:105], v[88:91], off offset:320
	v_accvgpr_read_b32 v100, a228
	v_accvgpr_read_b32 v101, a229
	v_accvgpr_read_b32 v102, a230
	v_accvgpr_read_b32 v103, a231
	s_waitcnt vmcnt(23)
	v_pk_fma_f32 v[92:93], v[100:101], v[28:29], v[92:93]
	v_pk_fma_f32 v[94:95], v[102:103], v[30:31], v[94:95]
	global_store_dwordx4 v[104:105], v[92:95], off offset:384
	v_accvgpr_read_b32 v100, a224
	v_accvgpr_read_b32 v101, a225
	v_accvgpr_read_b32 v102, a226
	v_accvgpr_read_b32 v103, a227
	s_waitcnt vmcnt(23)
	v_pk_fma_f32 v[96:97], v[100:101], v[32:33], v[96:97]
	v_pk_fma_f32 v[98:99], v[102:103], v[34:35], v[98:99]
	global_store_dwordx4 v[104:105], v[96:99], off offset:448
	v_lshl_add_u64 v[104:105], v[104:105], 0, v[106:107]
	s_nop 1
	global_load_dwordx4 v[68:71], v[104:105], off
	global_load_dwordx4 v[72:75], v[104:105], off offset:64
	global_load_dwordx4 v[76:79], v[104:105], off offset:128
	global_load_dwordx4 v[80:83], v[104:105], off offset:192
	global_load_dwordx4 v[84:87], v[104:105], off offset:256
	global_load_dwordx4 v[88:91], v[104:105], off offset:320
	global_load_dwordx4 v[92:95], v[104:105], off offset:384
	global_load_dwordx4 v[96:99], v[104:105], off offset:448
	v_accvgpr_read_b32 v100, a172
	v_accvgpr_read_b32 v101, a173
	v_accvgpr_read_b32 v102, a174
	v_accvgpr_read_b32 v103, a175
	s_waitcnt vmcnt(23)
	v_pk_fma_f32 v[36:37], v[100:101], v[4:5], v[36:37]
	v_pk_fma_f32 v[38:39], v[102:103], v[6:7], v[38:39]
	global_store_dwordx4 v[154:155], v[36:39], off
	v_accvgpr_read_b32 v100, a164
	v_accvgpr_read_b32 v101, a165
	v_accvgpr_read_b32 v102, a166
	v_accvgpr_read_b32 v103, a167
	s_waitcnt vmcnt(23)
	v_pk_fma_f32 v[40:41], v[100:101], v[8:9], v[40:41]
	v_pk_fma_f32 v[42:43], v[102:103], v[10:11], v[42:43]
	global_store_dwordx4 v[154:155], v[40:43], off offset:64
	v_accvgpr_read_b32 v100, a156
	v_accvgpr_read_b32 v101, a157
	v_accvgpr_read_b32 v102, a158
	v_accvgpr_read_b32 v103, a159
	s_waitcnt vmcnt(23)
	v_pk_fma_f32 v[44:45], v[100:101], v[12:13], v[44:45]
	v_pk_fma_f32 v[46:47], v[102:103], v[14:15], v[46:47]
	global_store_dwordx4 v[154:155], v[44:47], off offset:128
	v_accvgpr_read_b32 v100, a148
	v_accvgpr_read_b32 v101, a149
	v_accvgpr_read_b32 v102, a150
	v_accvgpr_read_b32 v103, a151
	s_waitcnt vmcnt(23)
	v_pk_fma_f32 v[48:49], v[100:101], v[16:17], v[48:49]
	v_pk_fma_f32 v[50:51], v[102:103], v[18:19], v[50:51]
	global_store_dwordx4 v[154:155], v[48:51], off offset:192
	v_accvgpr_read_b32 v100, a204
	v_accvgpr_read_b32 v101, a205
	v_accvgpr_read_b32 v102, a206
	v_accvgpr_read_b32 v103, a207
	s_waitcnt vmcnt(23)
	v_pk_fma_f32 v[52:53], v[100:101], v[20:21], v[52:53]
	v_pk_fma_f32 v[54:55], v[102:103], v[22:23], v[54:55]
	global_store_dwordx4 v[154:155], v[52:55], off offset:256
	v_accvgpr_read_b32 v100, a192
	v_accvgpr_read_b32 v101, a193
	v_accvgpr_read_b32 v102, a194
	v_accvgpr_read_b32 v103, a195
	s_waitcnt vmcnt(23)
	v_pk_fma_f32 v[56:57], v[100:101], v[24:25], v[56:57]
	v_pk_fma_f32 v[58:59], v[102:103], v[26:27], v[58:59]
	global_store_dwordx4 v[154:155], v[56:59], off offset:320
	v_accvgpr_read_b32 v100, a184
	v_accvgpr_read_b32 v101, a185
	v_accvgpr_read_b32 v102, a186
	v_accvgpr_read_b32 v103, a187
	s_waitcnt vmcnt(23)
	v_pk_fma_f32 v[60:61], v[100:101], v[28:29], v[60:61]
	v_pk_fma_f32 v[62:63], v[102:103], v[30:31], v[62:63]
	global_store_dwordx4 v[154:155], v[60:63], off offset:384
	v_accvgpr_read_b32 v100, a176
	v_accvgpr_read_b32 v101, a177
	v_accvgpr_read_b32 v102, a178
	v_accvgpr_read_b32 v103, a179
	s_waitcnt vmcnt(23)
	v_pk_fma_f32 v[64:65], v[100:101], v[32:33], v[64:65]
	v_pk_fma_f32 v[66:67], v[102:103], v[34:35], v[66:67]
	global_store_dwordx4 v[154:155], v[64:67], off offset:448
	v_lshl_add_u64 v[154:155], v[154:155], 0, v[106:107]
	s_nop 1
	global_load_dwordx4 v[36:39], v[154:155], off
	global_load_dwordx4 v[40:43], v[154:155], off offset:64
	global_load_dwordx4 v[44:47], v[154:155], off offset:128
	global_load_dwordx4 v[48:51], v[154:155], off offset:192
	global_load_dwordx4 v[52:55], v[154:155], off offset:256
	global_load_dwordx4 v[56:59], v[154:155], off offset:320
	global_load_dwordx4 v[60:63], v[154:155], off offset:384
	global_load_dwordx4 v[64:67], v[154:155], off offset:448
	v_accvgpr_read_b32 v100, a140
	v_accvgpr_read_b32 v101, a141
	v_accvgpr_read_b32 v102, a142
	v_accvgpr_read_b32 v103, a143
	s_waitcnt vmcnt(23)
	v_pk_fma_f32 v[68:69], v[100:101], v[4:5], v[68:69]
	v_pk_fma_f32 v[70:71], v[102:103], v[6:7], v[70:71]
	global_store_dwordx4 v[104:105], v[68:71], off
	v_accvgpr_read_b32 v100, a132
	v_accvgpr_read_b32 v101, a133
	v_accvgpr_read_b32 v102, a134
	v_accvgpr_read_b32 v103, a135
	s_waitcnt vmcnt(23)
	v_pk_fma_f32 v[72:73], v[100:101], v[8:9], v[72:73]
	v_pk_fma_f32 v[74:75], v[102:103], v[10:11], v[74:75]
	global_store_dwordx4 v[104:105], v[72:75], off offset:64
	v_accvgpr_read_b32 v100, a124
	v_accvgpr_read_b32 v101, a125
	v_accvgpr_read_b32 v102, a126
	v_accvgpr_read_b32 v103, a127
	s_waitcnt vmcnt(23)
	v_pk_fma_f32 v[76:77], v[100:101], v[12:13], v[76:77]
	v_pk_fma_f32 v[78:79], v[102:103], v[14:15], v[78:79]
	global_store_dwordx4 v[104:105], v[76:79], off offset:128
	v_accvgpr_read_b32 v100, a116
	v_accvgpr_read_b32 v101, a117
	v_accvgpr_read_b32 v102, a118
	v_accvgpr_read_b32 v103, a119
	s_waitcnt vmcnt(23)
	v_pk_fma_f32 v[80:81], v[100:101], v[16:17], v[80:81]
	v_pk_fma_f32 v[82:83], v[102:103], v[18:19], v[82:83]
	global_store_dwordx4 v[104:105], v[80:83], off offset:192
	v_accvgpr_read_b32 v100, a168
	v_accvgpr_read_b32 v101, a169
	v_accvgpr_read_b32 v102, a170
	v_accvgpr_read_b32 v103, a171
	s_waitcnt vmcnt(23)
	v_pk_fma_f32 v[84:85], v[100:101], v[20:21], v[84:85]
	v_pk_fma_f32 v[86:87], v[102:103], v[22:23], v[86:87]
	global_store_dwordx4 v[104:105], v[84:87], off offset:256
	v_accvgpr_read_b32 v100, a160
	v_accvgpr_read_b32 v101, a161
	v_accvgpr_read_b32 v102, a162
	v_accvgpr_read_b32 v103, a163
	s_waitcnt vmcnt(23)
	v_pk_fma_f32 v[88:89], v[100:101], v[24:25], v[88:89]
	v_pk_fma_f32 v[90:91], v[102:103], v[26:27], v[90:91]
	global_store_dwordx4 v[104:105], v[88:91], off offset:320
	v_accvgpr_read_b32 v100, a152
	v_accvgpr_read_b32 v101, a153
	v_accvgpr_read_b32 v102, a154
	v_accvgpr_read_b32 v103, a155
	s_waitcnt vmcnt(23)
	v_pk_fma_f32 v[92:93], v[100:101], v[28:29], v[92:93]
	v_pk_fma_f32 v[94:95], v[102:103], v[30:31], v[94:95]
	global_store_dwordx4 v[104:105], v[92:95], off offset:384
	v_accvgpr_read_b32 v100, a144
	v_accvgpr_read_b32 v101, a145
	v_accvgpr_read_b32 v102, a146
	v_accvgpr_read_b32 v103, a147
	s_waitcnt vmcnt(23)
	v_pk_fma_f32 v[96:97], v[100:101], v[32:33], v[96:97]
	v_pk_fma_f32 v[98:99], v[102:103], v[34:35], v[98:99]
	global_store_dwordx4 v[104:105], v[96:99], off offset:448
	v_lshl_add_u64 v[104:105], v[104:105], 0, v[106:107]
	s_nop 1
	global_load_dwordx4 v[68:71], v[104:105], off
	global_load_dwordx4 v[72:75], v[104:105], off offset:64
	global_load_dwordx4 v[76:79], v[104:105], off offset:128
	global_load_dwordx4 v[80:83], v[104:105], off offset:192
	global_load_dwordx4 v[84:87], v[104:105], off offset:256
	global_load_dwordx4 v[88:91], v[104:105], off offset:320
	global_load_dwordx4 v[92:95], v[104:105], off offset:384
	global_load_dwordx4 v[96:99], v[104:105], off offset:448
	v_accvgpr_read_b32 v100, a108
	v_accvgpr_read_b32 v101, a109
	v_accvgpr_read_b32 v102, a110
	v_accvgpr_read_b32 v103, a111
	s_waitcnt vmcnt(23)
	v_pk_fma_f32 v[36:37], v[100:101], v[4:5], v[36:37]
	v_pk_fma_f32 v[38:39], v[102:103], v[6:7], v[38:39]
	global_store_dwordx4 v[154:155], v[36:39], off
	v_accvgpr_read_b32 v100, a100
	v_accvgpr_read_b32 v101, a101
	v_accvgpr_read_b32 v102, a102
	v_accvgpr_read_b32 v103, a103
	s_waitcnt vmcnt(23)
	v_pk_fma_f32 v[40:41], v[100:101], v[8:9], v[40:41]
	v_pk_fma_f32 v[42:43], v[102:103], v[10:11], v[42:43]
	global_store_dwordx4 v[154:155], v[40:43], off offset:64
	v_accvgpr_read_b32 v100, a92
	v_accvgpr_read_b32 v101, a93
	v_accvgpr_read_b32 v102, a94
	v_accvgpr_read_b32 v103, a95
	s_waitcnt vmcnt(23)
	v_pk_fma_f32 v[44:45], v[100:101], v[12:13], v[44:45]
	v_pk_fma_f32 v[46:47], v[102:103], v[14:15], v[46:47]
	global_store_dwordx4 v[154:155], v[44:47], off offset:128
	v_accvgpr_read_b32 v100, a84
	v_accvgpr_read_b32 v101, a85
	v_accvgpr_read_b32 v102, a86
	v_accvgpr_read_b32 v103, a87
	s_waitcnt vmcnt(23)
	v_pk_fma_f32 v[48:49], v[100:101], v[16:17], v[48:49]
	v_pk_fma_f32 v[50:51], v[102:103], v[18:19], v[50:51]
	global_store_dwordx4 v[154:155], v[48:51], off offset:192
	v_accvgpr_read_b32 v100, a136
	v_accvgpr_read_b32 v101, a137
	v_accvgpr_read_b32 v102, a138
	v_accvgpr_read_b32 v103, a139
	s_waitcnt vmcnt(23)
	v_pk_fma_f32 v[52:53], v[100:101], v[20:21], v[52:53]
	v_pk_fma_f32 v[54:55], v[102:103], v[22:23], v[54:55]
	global_store_dwordx4 v[154:155], v[52:55], off offset:256
	v_accvgpr_read_b32 v100, a128
	v_accvgpr_read_b32 v101, a129
	v_accvgpr_read_b32 v102, a130
	v_accvgpr_read_b32 v103, a131
	s_waitcnt vmcnt(23)
	v_pk_fma_f32 v[56:57], v[100:101], v[24:25], v[56:57]
	v_pk_fma_f32 v[58:59], v[102:103], v[26:27], v[58:59]
	global_store_dwordx4 v[154:155], v[56:59], off offset:320
	v_accvgpr_read_b32 v100, a120
	v_accvgpr_read_b32 v101, a121
	v_accvgpr_read_b32 v102, a122
	v_accvgpr_read_b32 v103, a123
	s_waitcnt vmcnt(23)
	v_pk_fma_f32 v[60:61], v[100:101], v[28:29], v[60:61]
	v_pk_fma_f32 v[62:63], v[102:103], v[30:31], v[62:63]
	global_store_dwordx4 v[154:155], v[60:63], off offset:384
	v_accvgpr_read_b32 v100, a112
	v_accvgpr_read_b32 v101, a113
	v_accvgpr_read_b32 v102, a114
	v_accvgpr_read_b32 v103, a115
	s_waitcnt vmcnt(23)
	v_pk_fma_f32 v[64:65], v[100:101], v[32:33], v[64:65]
	v_pk_fma_f32 v[66:67], v[102:103], v[34:35], v[66:67]
	global_store_dwordx4 v[154:155], v[64:67], off offset:448
	v_lshl_add_u64 v[154:155], v[154:155], 0, v[106:107]
	s_nop 1
	global_load_dwordx4 v[36:39], v[154:155], off
	global_load_dwordx4 v[40:43], v[154:155], off offset:64
	global_load_dwordx4 v[44:47], v[154:155], off offset:128
	global_load_dwordx4 v[48:51], v[154:155], off offset:192
	global_load_dwordx4 v[52:55], v[154:155], off offset:256
	global_load_dwordx4 v[56:59], v[154:155], off offset:320
	global_load_dwordx4 v[60:63], v[154:155], off offset:384
	global_load_dwordx4 v[64:67], v[154:155], off offset:448
	v_accvgpr_read_b32 v100, a76
	v_accvgpr_read_b32 v101, a77
	v_accvgpr_read_b32 v102, a78
	v_accvgpr_read_b32 v103, a79
	s_waitcnt vmcnt(23)
	v_pk_fma_f32 v[68:69], v[100:101], v[4:5], v[68:69]
	v_pk_fma_f32 v[70:71], v[102:103], v[6:7], v[70:71]
	global_store_dwordx4 v[104:105], v[68:71], off
	v_accvgpr_read_b32 v100, a68
	v_accvgpr_read_b32 v101, a69
	v_accvgpr_read_b32 v102, a70
	v_accvgpr_read_b32 v103, a71
	s_waitcnt vmcnt(23)
	v_pk_fma_f32 v[72:73], v[100:101], v[8:9], v[72:73]
	v_pk_fma_f32 v[74:75], v[102:103], v[10:11], v[74:75]
	global_store_dwordx4 v[104:105], v[72:75], off offset:64
	v_accvgpr_read_b32 v100, a60
	v_accvgpr_read_b32 v101, a61
	v_accvgpr_read_b32 v102, a62
	v_accvgpr_read_b32 v103, a63
	s_waitcnt vmcnt(23)
	v_pk_fma_f32 v[76:77], v[100:101], v[12:13], v[76:77]
	v_pk_fma_f32 v[78:79], v[102:103], v[14:15], v[78:79]
	global_store_dwordx4 v[104:105], v[76:79], off offset:128
	v_accvgpr_read_b32 v100, a52
	v_accvgpr_read_b32 v101, a53
	v_accvgpr_read_b32 v102, a54
	v_accvgpr_read_b32 v103, a55
	s_waitcnt vmcnt(23)
	v_pk_fma_f32 v[80:81], v[100:101], v[16:17], v[80:81]
	v_pk_fma_f32 v[82:83], v[102:103], v[18:19], v[82:83]
	global_store_dwordx4 v[104:105], v[80:83], off offset:192
	v_accvgpr_read_b32 v100, a104
	v_accvgpr_read_b32 v101, a105
	v_accvgpr_read_b32 v102, a106
	v_accvgpr_read_b32 v103, a107
	s_waitcnt vmcnt(23)
	v_pk_fma_f32 v[84:85], v[100:101], v[20:21], v[84:85]
	v_pk_fma_f32 v[86:87], v[102:103], v[22:23], v[86:87]
	global_store_dwordx4 v[104:105], v[84:87], off offset:256
	v_accvgpr_read_b32 v100, a96
	v_accvgpr_read_b32 v101, a97
	v_accvgpr_read_b32 v102, a98
	v_accvgpr_read_b32 v103, a99
	s_waitcnt vmcnt(23)
	v_pk_fma_f32 v[88:89], v[100:101], v[24:25], v[88:89]
	v_pk_fma_f32 v[90:91], v[102:103], v[26:27], v[90:91]
	global_store_dwordx4 v[104:105], v[88:91], off offset:320
	v_accvgpr_read_b32 v100, a88
	v_accvgpr_read_b32 v101, a89
	v_accvgpr_read_b32 v102, a90
	v_accvgpr_read_b32 v103, a91
	s_waitcnt vmcnt(23)
	v_pk_fma_f32 v[92:93], v[100:101], v[28:29], v[92:93]
	v_pk_fma_f32 v[94:95], v[102:103], v[30:31], v[94:95]
	global_store_dwordx4 v[104:105], v[92:95], off offset:384
	v_accvgpr_read_b32 v100, a80
	v_accvgpr_read_b32 v101, a81
	v_accvgpr_read_b32 v102, a82
	v_accvgpr_read_b32 v103, a83
	s_waitcnt vmcnt(23)
; template <class Epi>
; __device__ __forceinline__ void gemm_run(const GemmArgs g, Epi epi, char* smem) {
;     ...
;   for (int tile = blockIdx.x; tile < total; tile += gridDim.x) {
	v_pk_fma_f32 v[96:97], v[100:101], v[32:33], v[96:97]
	v_pk_fma_f32 v[98:99], v[102:103], v[34:35], v[98:99]
	global_store_dwordx4 v[104:105], v[96:99], off offset:448
	v_lshl_add_u64 v[104:105], v[104:105], 0, v[106:107]
	s_nop 1
	global_load_dwordx4 v[68:71], v[104:105], off
	global_load_dwordx4 v[72:75], v[104:105], off offset:64
	global_load_dwordx4 v[76:79], v[104:105], off offset:128
	global_load_dwordx4 v[80:83], v[104:105], off offset:192
	global_load_dwordx4 v[84:87], v[104:105], off offset:256
	global_load_dwordx4 v[88:91], v[104:105], off offset:320
	global_load_dwordx4 v[92:95], v[104:105], off offset:384
	global_load_dwordx4 v[96:99], v[104:105], off offset:448
	v_accvgpr_read_b32 v100, a44
	v_accvgpr_read_b32 v101, a45
	v_accvgpr_read_b32 v102, a46
	v_accvgpr_read_b32 v103, a47
	s_waitcnt vmcnt(23)
	v_pk_fma_f32 v[36:37], v[100:101], v[4:5], v[36:37]
	v_pk_fma_f32 v[38:39], v[102:103], v[6:7], v[38:39]
	global_store_dwordx4 v[154:155], v[36:39], off
	v_accvgpr_read_b32 v100, a36
	v_accvgpr_read_b32 v101, a37
	v_accvgpr_read_b32 v102, a38
	v_accvgpr_read_b32 v103, a39
	s_waitcnt vmcnt(23)
	v_pk_fma_f32 v[40:41], v[100:101], v[8:9], v[40:41]
	v_pk_fma_f32 v[42:43], v[102:103], v[10:11], v[42:43]
	global_store_dwordx4 v[154:155], v[40:43], off offset:64
	v_accvgpr_read_b32 v100, a28
	v_accvgpr_read_b32 v101, a29
	v_accvgpr_read_b32 v102, a30
	v_accvgpr_read_b32 v103, a31
	s_waitcnt vmcnt(23)
	v_pk_fma_f32 v[44:45], v[100:101], v[12:13], v[44:45]
	v_pk_fma_f32 v[46:47], v[102:103], v[14:15], v[46:47]
	global_store_dwordx4 v[154:155], v[44:47], off offset:128
	v_accvgpr_read_b32 v100, a20
	v_accvgpr_read_b32 v101, a21
	v_accvgpr_read_b32 v102, a22
	v_accvgpr_read_b32 v103, a23
	s_waitcnt vmcnt(23)
	v_pk_fma_f32 v[48:49], v[100:101], v[16:17], v[48:49]
	v_pk_fma_f32 v[50:51], v[102:103], v[18:19], v[50:51]
	global_store_dwordx4 v[154:155], v[48:51], off offset:192
	v_accvgpr_read_b32 v100, a72
	v_accvgpr_read_b32 v101, a73
	v_accvgpr_read_b32 v102, a74
	v_accvgpr_read_b32 v103, a75
	s_waitcnt vmcnt(23)
	v_pk_fma_f32 v[52:53], v[100:101], v[20:21], v[52:53]
	v_pk_fma_f32 v[54:55], v[102:103], v[22:23], v[54:55]
	global_store_dwordx4 v[154:155], v[52:55], off offset:256
	v_accvgpr_read_b32 v100, a64
	v_accvgpr_read_b32 v101, a65
	v_accvgpr_read_b32 v102, a66
	v_accvgpr_read_b32 v103, a67
	s_waitcnt vmcnt(23)
	v_pk_fma_f32 v[56:57], v[100:101], v[24:25], v[56:57]
	v_pk_fma_f32 v[58:59], v[102:103], v[26:27], v[58:59]
	global_store_dwordx4 v[154:155], v[56:59], off offset:320
	v_accvgpr_read_b32 v100, a56
	v_accvgpr_read_b32 v101, a57
	v_accvgpr_read_b32 v102, a58
	v_accvgpr_read_b32 v103, a59
	s_waitcnt vmcnt(23)
	v_pk_fma_f32 v[60:61], v[100:101], v[28:29], v[60:61]
	v_pk_fma_f32 v[62:63], v[102:103], v[30:31], v[62:63]
	global_store_dwordx4 v[154:155], v[60:63], off offset:384
	v_accvgpr_read_b32 v100, a48
	v_accvgpr_read_b32 v101, a49
	v_accvgpr_read_b32 v102, a50
	v_accvgpr_read_b32 v103, a51
	s_waitcnt vmcnt(23)
	v_pk_fma_f32 v[64:65], v[100:101], v[32:33], v[64:65]
	v_pk_fma_f32 v[66:67], v[102:103], v[34:35], v[66:67]
	global_store_dwordx4 v[154:155], v[64:67], off offset:448
	v_accvgpr_read_b32 v100, a12
	v_accvgpr_read_b32 v101, a13
	v_accvgpr_read_b32 v102, a14
	v_accvgpr_read_b32 v103, a15
	s_waitcnt vmcnt(15)
	v_pk_fma_f32 v[68:69], v[100:101], v[4:5], v[68:69]
	v_pk_fma_f32 v[70:71], v[102:103], v[6:7], v[70:71]
	global_store_dwordx4 v[104:105], v[68:71], off
	v_accvgpr_read_b32 v100, a8
	v_accvgpr_read_b32 v101, a9
	v_accvgpr_read_b32 v102, a10
	v_accvgpr_read_b32 v103, a11
	s_waitcnt vmcnt(15)
	v_pk_fma_f32 v[72:73], v[100:101], v[8:9], v[72:73]
	v_pk_fma_f32 v[74:75], v[102:103], v[10:11], v[74:75]
	global_store_dwordx4 v[104:105], v[72:75], off offset:64
	v_accvgpr_read_b32 v100, a4
	v_accvgpr_read_b32 v101, a5
	v_accvgpr_read_b32 v102, a6
	v_accvgpr_read_b32 v103, a7
	s_waitcnt vmcnt(15)
	v_pk_fma_f32 v[76:77], v[100:101], v[12:13], v[76:77]
	v_pk_fma_f32 v[78:79], v[102:103], v[14:15], v[78:79]
	global_store_dwordx4 v[104:105], v[76:79], off offset:128
	v_accvgpr_read_b32 v100, a0
	v_accvgpr_read_b32 v101, a1
	v_accvgpr_read_b32 v102, a2
	v_accvgpr_read_b32 v103, a3
	s_waitcnt vmcnt(15)
	v_pk_fma_f32 v[80:81], v[100:101], v[16:17], v[80:81]
	v_pk_fma_f32 v[82:83], v[102:103], v[18:19], v[82:83]
	global_store_dwordx4 v[104:105], v[80:83], off offset:192
	v_accvgpr_read_b32 v100, a40
	v_accvgpr_read_b32 v101, a41
	v_accvgpr_read_b32 v102, a42
	v_accvgpr_read_b32 v103, a43
	s_waitcnt vmcnt(15)
	v_pk_fma_f32 v[84:85], v[100:101], v[20:21], v[84:85]
	v_pk_fma_f32 v[86:87], v[102:103], v[22:23], v[86:87]
	global_store_dwordx4 v[104:105], v[84:87], off offset:256
	v_accvgpr_read_b32 v100, a32
	v_accvgpr_read_b32 v101, a33
	v_accvgpr_read_b32 v102, a34
	v_accvgpr_read_b32 v103, a35
	s_waitcnt vmcnt(15)
	v_pk_fma_f32 v[88:89], v[100:101], v[24:25], v[88:89]
	v_pk_fma_f32 v[90:91], v[102:103], v[26:27], v[90:91]
	global_store_dwordx4 v[104:105], v[88:91], off offset:320
	v_accvgpr_read_b32 v100, a24
	v_accvgpr_read_b32 v101, a25
	v_accvgpr_read_b32 v102, a26
	v_accvgpr_read_b32 v103, a27
	s_waitcnt vmcnt(15)
	v_pk_fma_f32 v[92:93], v[100:101], v[28:29], v[92:93]
	v_pk_fma_f32 v[94:95], v[102:103], v[30:31], v[94:95]
	global_store_dwordx4 v[104:105], v[92:95], off offset:384
	v_accvgpr_read_b32 v100, a16
	v_accvgpr_read_b32 v101, a17
	v_accvgpr_read_b32 v102, a18
	v_accvgpr_read_b32 v103, a19
	s_waitcnt vmcnt(15)
	v_pk_fma_f32 v[96:97], v[100:101], v[32:33], v[96:97]
	v_pk_fma_f32 v[98:99], v[102:103], v[34:35], v[98:99]
	global_store_dwordx4 v[104:105], v[96:99], off offset:448
	s_add_i32 s83, s83, s2
	s_cmpk_lt_i32 s83, 0x200
	s_cbranch_scc0 .LBB0_1061

; #define LD_AF(dst, ks_) _Pragma("unroll") for (int i = 0; i < 8; ++i) dst[i] = *(const h8*)(sA + i * 16 * G_LD + (ks_) * 32)
; #define LD_BF(dst, ks_, nh_) _Pragma("unroll") for (int i = 0; i < 4; ++i) dst[i] = *(const h8*)(sB + ((nh_) * 4 + i) * 16 * G_LD + (ks_) * 32)
; #define MMA_BLK(afx, bfx, nh_) _Pragma("unroll") for (int mi = 0; mi < 8; ++mi) _Pragma("unroll") for (int ni = 0; ni < 4; ++ni) mfma16_acc(acc[mi][(nh_) * 4 + ni], bfx[ni], afx[mi])
; template <class Epi>
; __device__ __forceinline__ void gemm_run(const GemmArgs g, Epi epi, char* smem) {
;     ...
;     for (int kt = 0; kt < nk; ++kt) {
;       const hf* sA = sbase + (kt & 1) * G_STAGE + (wm * 128 + fr) * G_LD + fqs;
;       const hf* sB = sbase + (kt & 1) * G_STAGE + (256 + wn * 128 + fr) * G_LD + fqs;
;       hf* st = sbase + ((kt + 1) & 1) * G_STAGE;
;       h8 afA[8], afB[8], bfA[4], bfB[4];
;     ...
;       LD_AF(afA, 0); LD_BF(bfA, 0, 0);
;       if (kt + 1 < nk) {
; #pragma unroll
;         for (int i = 0; i < 8; ++i) *(u4*)(st + (lr + 32 * i) * G_LD + lcw) = ra[i];
;       }
;       __builtin_amdgcn_sched_barrier(0);
;       LD_BF(bfB, 0, 1);
;       MMA_BLK(afA, bfA, 0);
;       __builtin_amdgcn_sched_barrier(0);
;       if (kt + 1 < nk) {
; #pragma unroll
;         for (int i = 0; i < 8; ++i) *(u4*)(st + (256 + lr + 32 * i) * G_LD + lcw) = rb[i];
;       }
;       LD_AF(afB, 1); LD_BF(bfA, 1, 0);
;       MMA_BLK(afA, bfB, 1);
;       __builtin_amdgcn_sched_barrier(0);
;       if (kt + 2 < nk) {
;         const int ko = (kt + 2) * 64;
; #pragma unroll
;         for (int i = 0; i < 8; ++i) { ra[i] = __builtin_amdgcn_raw_buffer_load_b128(Ars, aoff, i * astep + ko * 2, 0); rb[i] = __builtin_amdgcn_raw_buffer_load_b128(Brs, boff, i * bstep + ko * 2, 0); }
;       }
;       LD_BF(bfB, 1, 1);
;       MMA_BLK(afB, bfA, 0);
;       __builtin_amdgcn_sched_barrier(0);
;       MMA_BLK(afB, bfB, 1);
;       __builtin_amdgcn_sched_barrier(0);
.LBB0_1114:
	ds_read_b128 v[0:3], v136 offset:36864
	ds_read_b128 v[4:7], v136 offset:39168
	ds_read_b128 v[8:11], v136 offset:41472
	ds_read_b128 v[12:15], v136 offset:43776
	ds_read_b128 v[16:19], v137
	ds_read_b128 v[20:23], v137 offset:2304
	ds_read_b128 v[24:27], v137 offset:4608
	ds_read_b128 v[28:31], v137 offset:6912
	ds_read_b128 v[32:35], v137 offset:9216
	ds_read_b128 v[36:39], v137 offset:11520
	ds_read_b128 v[40:43], v137 offset:13824
	ds_read_b128 v[44:47], v137 offset:16128
	s_waitcnt lgkmcnt(7)
	v_mfma_f32_16x16x32_f16 a[204:207], v[0:3], v[16:19], a[204:207]
	v_mfma_f32_16x16x32_f16 a[200:203], v[4:7], v[16:19], a[200:203]
	v_mfma_f32_16x16x32_f16 a[196:199], v[8:11], v[16:19], a[196:199]
	v_mfma_f32_16x16x32_f16 a[188:191], v[12:15], v[16:19], a[188:191]
	s_waitcnt lgkmcnt(6)
	v_mfma_f32_16x16x32_f16 a[192:195], v[0:3], v[20:23], a[192:195]
	v_mfma_f32_16x16x32_f16 a[184:187], v[4:7], v[20:23], a[184:187]
	v_mfma_f32_16x16x32_f16 a[180:183], v[8:11], v[20:23], a[180:183]
	v_mfma_f32_16x16x32_f16 a[176:179], v[12:15], v[20:23], a[176:179]
	s_waitcnt lgkmcnt(5)
	v_mfma_f32_16x16x32_f16 a[156:159], v[0:3], v[24:27], a[156:159]
	v_mfma_f32_16x16x32_f16 a[152:155], v[4:7], v[24:27], a[152:155]
	v_mfma_f32_16x16x32_f16 a[148:151], v[8:11], v[24:27], a[148:151]
	v_mfma_f32_16x16x32_f16 a[144:147], v[12:15], v[24:27], a[144:147]
	s_waitcnt lgkmcnt(4)
	v_mfma_f32_16x16x32_f16 a[124:127], v[0:3], v[28:31], a[124:127]
	v_mfma_f32_16x16x32_f16 a[120:123], v[4:7], v[28:31], a[120:123]
	v_mfma_f32_16x16x32_f16 a[116:119], v[8:11], v[28:31], a[116:119]
	v_mfma_f32_16x16x32_f16 a[112:115], v[12:15], v[28:31], a[112:115]
	s_waitcnt lgkmcnt(3)
	v_mfma_f32_16x16x32_f16 a[92:95], v[0:3], v[32:35], a[92:95]
	v_mfma_f32_16x16x32_f16 a[88:91], v[4:7], v[32:35], a[88:91]
	v_mfma_f32_16x16x32_f16 a[84:87], v[8:11], v[32:35], a[84:87]
	v_mfma_f32_16x16x32_f16 a[80:83], v[12:15], v[32:35], a[80:83]
	s_waitcnt lgkmcnt(2)
	v_mfma_f32_16x16x32_f16 a[60:63], v[0:3], v[36:39], a[60:63]
	v_mfma_f32_16x16x32_f16 a[56:59], v[4:7], v[36:39], a[56:59]
	v_mfma_f32_16x16x32_f16 a[52:55], v[8:11], v[36:39], a[52:55]
	v_mfma_f32_16x16x32_f16 a[48:51], v[12:15], v[36:39], a[48:51]
	s_waitcnt lgkmcnt(1)
	v_mfma_f32_16x16x32_f16 a[32:35], v[0:3], v[40:43], a[32:35]
	v_mfma_f32_16x16x32_f16 a[28:31], v[4:7], v[40:43], a[28:31]
	v_mfma_f32_16x16x32_f16 a[24:27], v[8:11], v[40:43], a[24:27]
	v_mfma_f32_16x16x32_f16 a[20:23], v[12:15], v[40:43], a[20:23]
	s_waitcnt lgkmcnt(0)
	v_mfma_f32_16x16x32_f16 a[12:15], v[0:3], v[44:47], a[12:15]
	v_mfma_f32_16x16x32_f16 a[8:11], v[4:7], v[44:47], a[8:11]
	v_mfma_f32_16x16x32_f16 a[4:7], v[8:11], v[44:47], a[4:7]
	v_mfma_f32_16x16x32_f16 a[0:3], v[12:15], v[44:47], a[0:3]
	ds_read_b128 v[0:3], v136 offset:46080
	ds_read_b128 v[4:7], v136 offset:48384
	ds_read_b128 v[8:11], v136 offset:50688
	ds_read_b128 v[12:15], v136 offset:52992
	s_waitcnt lgkmcnt(3)
	v_mfma_f32_16x16x32_f16 a[240:243], v[0:3], v[16:19], a[240:243]
	s_waitcnt lgkmcnt(2)
	v_mfma_f32_16x16x32_f16 a[252:255], v[4:7], v[16:19], a[252:255]
	s_waitcnt lgkmcnt(1)
	v_mfma_f32_16x16x32_f16 a[248:251], v[8:11], v[16:19], a[248:251]
	s_waitcnt lgkmcnt(0)
	v_mfma_f32_16x16x32_f16 a[244:247], v[12:15], v[16:19], a[244:247]
	v_mfma_f32_16x16x32_f16 a[236:239], v[0:3], v[20:23], a[236:239]
	v_mfma_f32_16x16x32_f16 a[232:235], v[4:7], v[20:23], a[232:235]
	v_mfma_f32_16x16x32_f16 a[228:231], v[8:11], v[20:23], a[228:231]
	v_mfma_f32_16x16x32_f16 a[224:227], v[12:15], v[20:23], a[224:227]
	v_mfma_f32_16x16x32_f16 a[220:223], v[0:3], v[24:27], a[220:223]
	v_mfma_f32_16x16x32_f16 a[216:219], v[4:7], v[24:27], a[216:219]
	v_mfma_f32_16x16x32_f16 a[212:215], v[8:11], v[24:27], a[212:215]
	v_mfma_f32_16x16x32_f16 a[208:211], v[12:15], v[24:27], a[208:211]
	v_mfma_f32_16x16x32_f16 a[172:175], v[0:3], v[28:31], a[172:175]
	v_mfma_f32_16x16x32_f16 a[168:171], v[4:7], v[28:31], a[168:171]
	v_mfma_f32_16x16x32_f16 a[164:167], v[8:11], v[28:31], a[164:167]
	v_mfma_f32_16x16x32_f16 a[160:163], v[12:15], v[28:31], a[160:163]
	v_mfma_f32_16x16x32_f16 a[140:143], v[0:3], v[32:35], a[140:143]
	v_mfma_f32_16x16x32_f16 a[136:139], v[4:7], v[32:35], a[136:139]
	v_mfma_f32_16x16x32_f16 a[132:135], v[8:11], v[32:35], a[132:135]
	v_mfma_f32_16x16x32_f16 a[128:131], v[12:15], v[32:35], a[128:131]
	v_mfma_f32_16x16x32_f16 a[108:111], v[0:3], v[36:39], a[108:111]
	v_mfma_f32_16x16x32_f16 a[104:107], v[4:7], v[36:39], a[104:107]
	v_mfma_f32_16x16x32_f16 a[100:103], v[8:11], v[36:39], a[100:103]
	v_mfma_f32_16x16x32_f16 a[96:99], v[12:15], v[36:39], a[96:99]
	v_mfma_f32_16x16x32_f16 a[76:79], v[0:3], v[40:43], a[76:79]
	v_mfma_f32_16x16x32_f16 a[72:75], v[4:7], v[40:43], a[72:75]
	v_mfma_f32_16x16x32_f16 a[68:71], v[8:11], v[40:43], a[68:71]
	v_mfma_f32_16x16x32_f16 a[64:67], v[12:15], v[40:43], a[64:67]
	v_mfma_f32_16x16x32_f16 a[44:47], v[0:3], v[44:47], a[44:47]
	v_mfma_f32_16x16x32_f16 a[40:43], v[4:7], v[44:47], a[40:43]
	v_mfma_f32_16x16x32_f16 a[36:39], v[8:11], v[44:47], a[36:39]
	v_mfma_f32_16x16x32_f16 a[16:19], v[12:15], v[44:47], a[16:19]
	ds_read_b128 v[20:23], v136 offset:36928
	ds_read_b128 v[44:47], v137 offset:64
	ds_read_b128 v[58:61], v136 offset:39232
	ds_read_b128 v[62:65], v136 offset:41536
	ds_read_b128 v[74:77], v136 offset:43840
	ds_read_b128 v[78:81], v137 offset:2368
	s_waitcnt vmcnt(8)
	ds_read_b128 v[140:143], v137 offset:4672
	ds_read_b128 v[16:19], v137 offset:6976
	ds_read_b128 v[12:15], v137 offset:9280
	ds_read_b128 v[8:11], v137 offset:11584
	ds_read_b128 v[4:7], v137 offset:13888
	ds_read_b128 v[0:3], v137 offset:16192
	s_waitcnt vmcnt(6)
; #define LD_AF(dst, ks_) _Pragma("unroll") for (int i = 0; i < 8; ++i) dst[i] = *(const h8*)(sA + i * 16 * G_LD + (ks_) * 32)
; #define LD_BF(dst, ks_, nh_) _Pragma("unroll") for (int i = 0; i < 4; ++i) dst[i] = *(const h8*)(sB + ((nh_) * 4 + i) * 16 * G_LD + (ks_) * 32)
; #define MMA_BLK(afx, bfx, nh_) _Pragma("unroll") for (int mi = 0; mi < 8; ++mi) _Pragma("unroll") for (int ni = 0; ni < 4; ++ni) mfma16_acc(acc[mi][(nh_) * 4 + ni], bfx[ni], afx[mi])
; template <class Epi>
; __device__ __forceinline__ void gemm_run(const GemmArgs g, Epi epi, char* smem) {
;     ...
;     for (int kt = 0; kt < nk; ++kt) {
;       const hf* sA = sbase + (kt & 1) * G_STAGE + (wm * 128 + fr) * G_LD + fqs;
;       const hf* sB = sbase + (kt & 1) * G_STAGE + (256 + wn * 128 + fr) * G_LD + fqs;
;       hf* st = sbase + ((kt + 1) & 1) * G_STAGE;
;       h8 afA[8], afB[8], bfA[4], bfB[4];
;     ...
;       LD_AF(afA, 0); LD_BF(bfA, 0, 0);
;       if (kt + 1 < nk) {
; #pragma unroll
;         for (int i = 0; i < 8; ++i) *(u4*)(st + (lr + 32 * i) * G_LD + lcw) = ra[i];
;       }
;       __builtin_amdgcn_sched_barrier(0);
;       LD_BF(bfB, 0, 1);
;       MMA_BLK(afA, bfA, 0);
;       __builtin_amdgcn_sched_barrier(0);
;       if (kt + 1 < nk) {
; #pragma unroll
;         for (int i = 0; i < 8; ++i) *(u4*)(st + (256 + lr + 32 * i) * G_LD + lcw) = rb[i];
;       }
;       LD_AF(afB, 1); LD_BF(bfA, 1, 0);
;       MMA_BLK(afA, bfB, 1);
;       __builtin_amdgcn_sched_barrier(0);
;       if (kt + 2 < nk) {
;         const int ko = (kt + 2) * 64;
; #pragma unroll
;         for (int i = 0; i < 8; ++i) { ra[i] = __builtin_amdgcn_raw_buffer_load_b128(Ars, aoff, i * astep + ko * 2, 0); rb[i] = __builtin_amdgcn_raw_buffer_load_b128(Brs, boff, i * bstep + ko * 2, 0); }
;       }
;       LD_BF(bfB, 1, 1);
;       MMA_BLK(afB, bfA, 0);
;       __builtin_amdgcn_sched_barrier(0);
;       MMA_BLK(afB, bfB, 1);
;       __builtin_amdgcn_sched_barrier(0);
	ds_read_b128 v[144:147], v136 offset:46144
	s_waitcnt vmcnt(5)
	ds_read_b128 v[148:151], v136 offset:48448
	s_waitcnt vmcnt(3)
	ds_read_b128 v[152:155], v136 offset:50752
	ds_read_b128 v[156:159], v136 offset:53056
	s_waitcnt lgkmcnt(14)
	v_mfma_f32_16x16x32_f16 a[204:207], v[20:23], v[44:47], a[204:207]
	s_waitcnt lgkmcnt(13)
	v_mfma_f32_16x16x32_f16 a[200:203], v[58:61], v[44:47], a[200:203]
	s_waitcnt lgkmcnt(12)
	v_mfma_f32_16x16x32_f16 a[196:199], v[62:65], v[44:47], a[196:199]
	s_waitcnt lgkmcnt(11)
	v_mfma_f32_16x16x32_f16 a[188:191], v[74:77], v[44:47], a[188:191]
	s_waitcnt lgkmcnt(10)
	v_mfma_f32_16x16x32_f16 a[192:195], v[20:23], v[78:81], a[192:195]
	v_mfma_f32_16x16x32_f16 a[184:187], v[58:61], v[78:81], a[184:187]
	v_mfma_f32_16x16x32_f16 a[180:183], v[62:65], v[78:81], a[180:183]
	v_mfma_f32_16x16x32_f16 a[176:179], v[74:77], v[78:81], a[176:179]
	s_waitcnt lgkmcnt(9)
	v_mfma_f32_16x16x32_f16 a[156:159], v[20:23], v[140:143], a[156:159]
	v_mfma_f32_16x16x32_f16 a[152:155], v[58:61], v[140:143], a[152:155]
	v_mfma_f32_16x16x32_f16 a[148:151], v[62:65], v[140:143], a[148:151]
	v_mfma_f32_16x16x32_f16 a[144:147], v[74:77], v[140:143], a[144:147]
	s_waitcnt lgkmcnt(8)
	v_mfma_f32_16x16x32_f16 a[124:127], v[20:23], v[16:19], a[124:127]
	v_mfma_f32_16x16x32_f16 a[120:123], v[58:61], v[16:19], a[120:123]
	v_mfma_f32_16x16x32_f16 a[116:119], v[62:65], v[16:19], a[116:119]
	v_mfma_f32_16x16x32_f16 a[112:115], v[74:77], v[16:19], a[112:115]
	s_waitcnt lgkmcnt(7)
	v_mfma_f32_16x16x32_f16 a[92:95], v[20:23], v[12:15], a[92:95]
	v_mfma_f32_16x16x32_f16 a[88:91], v[58:61], v[12:15], a[88:91]
	v_mfma_f32_16x16x32_f16 a[84:87], v[62:65], v[12:15], a[84:87]
	v_mfma_f32_16x16x32_f16 a[80:83], v[74:77], v[12:15], a[80:83]
	v_accvgpr_read_b32 v121, a207
	v_accvgpr_read_b32 v120, a206
	v_accvgpr_read_b32 v119, a203
	v_accvgpr_read_b32 v118, a202
	v_accvgpr_read_b32 v117, a199
	v_accvgpr_read_b32 v116, a198
	v_accvgpr_read_b32 v113, a191
	v_accvgpr_read_b32 v112, a190
	v_accvgpr_read_b32 v105, a195
	v_accvgpr_read_b32 v104, a194
	v_accvgpr_read_b32 v103, a187
	v_accvgpr_read_b32 v102, a186
	v_accvgpr_read_b32 v101, a183
	v_accvgpr_read_b32 v100, a182
	v_accvgpr_read_b32 v97, a179
	v_accvgpr_read_b32 v96, a178
	v_accvgpr_read_b32 v89, a159
	v_accvgpr_read_b32 v88, a158
	v_accvgpr_read_b32 v87, a155
	v_accvgpr_read_b32 v86, a154
	v_accvgpr_read_b32 v85, a151
	v_accvgpr_read_b32 v84, a150
	v_accvgpr_read_b32 v83, a147
	v_accvgpr_read_b32 v82, a146
	v_accvgpr_read_b32 v73, a127
	v_accvgpr_read_b32 v72, a126
	v_accvgpr_read_b32 v71, a123
	v_accvgpr_read_b32 v70, a122
	v_accvgpr_read_b32 v69, a119
	v_accvgpr_read_b32 v68, a118
	v_accvgpr_read_b32 v67, a115
	v_accvgpr_read_b32 v66, a114
	v_accvgpr_read_b32 v57, a95
	v_accvgpr_read_b32 v56, a94
	v_accvgpr_read_b32 v55, a91
	v_accvgpr_read_b32 v54, a90
	v_accvgpr_read_b32 v53, a87
	v_accvgpr_read_b32 v52, a86
	v_accvgpr_read_b32 v51, a83
	v_accvgpr_read_b32 v50, a82
	s_waitcnt lgkmcnt(6)
	v_mfma_f32_16x16x32_f16 a[60:63], v[20:23], v[8:11], a[60:63]
	v_mfma_f32_16x16x32_f16 a[56:59], v[58:61], v[8:11], a[56:59]
	v_mfma_f32_16x16x32_f16 a[52:55], v[62:65], v[8:11], a[52:55]
	v_mfma_f32_16x16x32_f16 a[48:51], v[74:77], v[8:11], a[48:51]
	s_waitcnt lgkmcnt(5)
	v_mfma_f32_16x16x32_f16 a[32:35], v[20:23], v[4:7], a[32:35]
	v_mfma_f32_16x16x32_f16 a[28:31], v[58:61], v[4:7], a[28:31]
	v_mfma_f32_16x16x32_f16 a[24:27], v[62:65], v[4:7], a[24:27]
	v_mfma_f32_16x16x32_f16 a[20:23], v[74:77], v[4:7], a[20:23]
	s_waitcnt lgkmcnt(4)
	v_mfma_f32_16x16x32_f16 a[12:15], v[20:23], v[0:3], a[12:15]
	v_mfma_f32_16x16x32_f16 a[8:11], v[58:61], v[0:3], a[8:11]
	v_mfma_f32_16x16x32_f16 a[4:7], v[62:65], v[0:3], a[4:7]
	v_mfma_f32_16x16x32_f16 a[0:3], v[74:77], v[0:3], a[0:3]
	v_accvgpr_read_b32 v43, a63
	v_accvgpr_read_b32 v42, a62
	v_accvgpr_read_b32 v41, a59
	v_accvgpr_read_b32 v40, a58
	v_accvgpr_read_b32 v39, a55
	v_accvgpr_read_b32 v38, a54
	v_accvgpr_read_b32 v37, a51
	v_accvgpr_read_b32 v36, a50
	v_accvgpr_read_b32 v35, a35
	v_accvgpr_read_b32 v34, a34
	v_accvgpr_read_b32 v33, a31
	v_accvgpr_read_b32 v32, a30
	v_accvgpr_read_b32 v31, a27
	v_accvgpr_read_b32 v30, a26
	v_accvgpr_read_b32 v29, a23
	v_accvgpr_read_b32 v28, a22
	v_accvgpr_read_b32 v27, a15
	v_accvgpr_read_b32 v26, a14
	v_accvgpr_read_b32 v25, a11
	v_accvgpr_read_b32 v24, a10
	v_accvgpr_read_b32 v23, a7
	v_accvgpr_read_b32 v22, a6
	v_accvgpr_read_b32 v21, a3
	v_accvgpr_read_b32 v20, a2
	s_waitcnt lgkmcnt(3)
	v_mfma_f32_16x16x32_f16 a[240:243], v[144:147], v[44:47], a[240:243]
	s_waitcnt lgkmcnt(2)
	v_mfma_f32_16x16x32_f16 a[252:255], v[148:151], v[44:47], a[252:255]
	s_waitcnt lgkmcnt(1)
	v_mfma_f32_16x16x32_f16 a[248:251], v[152:155], v[44:47], a[248:251]
	s_waitcnt lgkmcnt(0)
	v_mfma_f32_16x16x32_f16 a[244:247], v[156:159], v[44:47], a[244:247]
	v_mfma_f32_16x16x32_f16 a[236:239], v[144:147], v[78:81], a[236:239]
	v_mfma_f32_16x16x32_f16 a[232:235], v[148:151], v[78:81], a[232:235]
	v_mfma_f32_16x16x32_f16 a[228:231], v[152:155], v[78:81], a[228:231]
	v_mfma_f32_16x16x32_f16 a[224:227], v[156:159], v[78:81], a[224:227]
	v_mfma_f32_16x16x32_f16 a[220:223], v[144:147], v[140:143], a[220:223]
	v_mfma_f32_16x16x32_f16 a[216:219], v[148:151], v[140:143], a[216:219]
	v_mfma_f32_16x16x32_f16 a[212:215], v[152:155], v[140:143], a[212:215]
	v_mfma_f32_16x16x32_f16 a[208:211], v[156:159], v[140:143], a[208:211]
	v_mfma_f32_16x16x32_f16 a[172:175], v[144:147], v[16:19], a[172:175]
	v_mfma_f32_16x16x32_f16 a[168:171], v[148:151], v[16:19], a[168:171]
	v_mfma_f32_16x16x32_f16 a[164:167], v[152:155], v[16:19], a[164:167]
	v_mfma_f32_16x16x32_f16 a[160:163], v[156:159], v[16:19], a[160:163]
	v_mfma_f32_16x16x32_f16 a[140:143], v[144:147], v[12:15], a[140:143]
	v_mfma_f32_16x16x32_f16 a[136:139], v[148:151], v[12:15], a[136:139]
	v_mfma_f32_16x16x32_f16 a[132:135], v[152:155], v[12:15], a[132:135]
	v_mfma_f32_16x16x32_f16 a[128:131], v[156:159], v[12:15], a[128:131]
	s_waitcnt vmcnt(1)
; #define LD_BF(dst, ks_, nh_) _Pragma("unroll") for (int i = 0; i < 4; ++i) dst[i] = *(const h8*)(sB + ((nh_) * 4 + i) * 16 * G_LD + (ks_) * 32)
; #define MMA_BLK(afx, bfx, nh_) _Pragma("unroll") for (int mi = 0; mi < 8; ++mi) _Pragma("unroll") for (int ni = 0; ni < 4; ++ni) mfma16_acc(acc[mi][(nh_) * 4 + ni], bfx[ni], afx[mi])
; template <class Epi>
; __device__ __forceinline__ void gemm_run(const GemmArgs g, Epi epi, char* smem) {
;     ...
;       LD_BF(bfB, 1, 1);
;       MMA_BLK(afB, bfA, 0);
;       __builtin_amdgcn_sched_barrier(0);
;       MMA_BLK(afB, bfB, 1);
;       __builtin_amdgcn_sched_barrier(0);
	v_accvgpr_read_b32 v161, a243
	v_accvgpr_read_b32 v160, a242
	v_accvgpr_read_b32 v127, a255
	v_accvgpr_read_b32 v126, a254
	v_accvgpr_read_b32 v125, a251
	v_accvgpr_read_b32 v124, a250
	v_accvgpr_read_b32 v123, a247
	v_accvgpr_read_b32 v122, a246
	v_accvgpr_read_b32 v115, a239
	v_accvgpr_read_b32 v114, a238
	v_accvgpr_read_b32 v111, a235
	v_accvgpr_read_b32 v110, a234
	v_accvgpr_read_b32 v109, a231
	v_accvgpr_read_b32 v108, a230
	v_accvgpr_read_b32 v107, a227
	v_accvgpr_read_b32 v106, a226
	v_accvgpr_read_b32 v99, a223
	v_accvgpr_read_b32 v98, a222
	v_accvgpr_read_b32 v95, a219
	v_accvgpr_read_b32 v94, a218
	v_accvgpr_read_b32 v93, a215
	v_accvgpr_read_b32 v92, a214
	v_accvgpr_read_b32 v91, a211
	v_accvgpr_read_b32 v90, a210
	v_accvgpr_read_b32 v81, a175
	v_accvgpr_read_b32 v80, a174
	v_accvgpr_read_b32 v79, a171
	v_accvgpr_read_b32 v78, a170
	v_accvgpr_read_b32 v77, a167
	v_accvgpr_read_b32 v76, a166
	v_accvgpr_read_b32 v75, a163
	v_accvgpr_read_b32 v74, a162
	v_accvgpr_read_b32 v65, a143
	v_accvgpr_read_b32 v64, a142
	v_accvgpr_read_b32 v63, a139
	v_accvgpr_read_b32 v62, a138
	v_accvgpr_read_b32 v61, a135
	v_accvgpr_read_b32 v60, a134
	v_accvgpr_read_b32 v59, a131
	v_accvgpr_read_b32 v58, a130
	v_mfma_f32_16x16x32_f16 a[108:111], v[144:147], v[8:11], a[108:111]
	v_mfma_f32_16x16x32_f16 a[104:107], v[148:151], v[8:11], a[104:107]
	v_mfma_f32_16x16x32_f16 a[100:103], v[152:155], v[8:11], a[100:103]
	v_mfma_f32_16x16x32_f16 a[96:99], v[156:159], v[8:11], a[96:99]
	v_mfma_f32_16x16x32_f16 a[76:79], v[144:147], v[4:7], a[76:79]
	v_mfma_f32_16x16x32_f16 a[72:75], v[148:151], v[4:7], a[72:75]
	v_mfma_f32_16x16x32_f16 a[68:71], v[152:155], v[4:7], a[68:71]
	v_mfma_f32_16x16x32_f16 a[64:67], v[156:159], v[4:7], a[64:67]
	v_mfma_f32_16x16x32_f16 a[44:47], v[144:147], v[0:3], a[44:47]
	v_mfma_f32_16x16x32_f16 a[40:43], v[148:151], v[0:3], a[40:43]
	v_mfma_f32_16x16x32_f16 a[36:39], v[152:155], v[0:3], a[36:39]
	v_mfma_f32_16x16x32_f16 a[16:19], v[156:159], v[0:3], a[16:19]
	s_nop 0
	v_lshl_add_u32 v140, s82, 8, v130
	v_add_u32_e32 v146, 0x8000, v140
	v_min_i32_e32 v3, 0x8000, v146
	v_or_b32_e32 v2, s83, v133
	v_ashrrev_i32_e32 v3, 13, v3
	v_ashrrev_i32_e32 v147, 31, v146
	v_mul_hi_i32_i24_e32 v143, 0xc000, v3
	v_mul_i32_i24_e32 v142, 0xc000, v3
	v_ashrrev_i32_e32 v3, 31, v2
	v_lshlrev_b64 v[146:147], 13, v[146:147]
	v_lshl_add_u64 v[142:143], s[16:17], 0, v[142:143]
	v_lshlrev_b64 v[2:3], 2, v[2:3]
	v_lshl_add_u64 v[146:147], s[28:29], 0, v[146:147]
	v_lshl_add_u64 v[150:151], v[142:143], 0, v[2:3]
	v_lshl_add_u64 v[152:153], v[146:147], 0, v[2:3]
	s_barrier
	global_load_dwordx4 v[4:7], v[150:151], off
	global_load_dwordx4 v[8:11], v[150:151], off offset:64
	global_load_dwordx4 v[12:15], v[150:151], off offset:128
	global_load_dwordx4 v[16:19], v[150:151], off offset:192
	global_load_dwordx4 v[20:23], v[150:151], off offset:256
	global_load_dwordx4 v[24:27], v[150:151], off offset:320
	global_load_dwordx4 v[28:31], v[150:151], off offset:384
	global_load_dwordx4 v[32:35], v[150:151], off offset:448
	global_load_dwordx4 v[36:39], v[152:153], off
	global_load_dwordx4 v[40:43], v[152:153], off offset:64
	global_load_dwordx4 v[44:47], v[152:153], off offset:128
	global_load_dwordx4 v[48:51], v[152:153], off offset:192
	global_load_dwordx4 v[52:55], v[152:153], off offset:256
	global_load_dwordx4 v[56:59], v[152:153], off offset:320
	global_load_dwordx4 v[60:63], v[152:153], off offset:384
	global_load_dwordx4 v[64:67], v[152:153], off offset:448
	v_mov_b32_e32 v106, 0x20000
	v_mov_b32_e32 v107, 0
	v_lshl_add_u64 v[104:105], v[152:153], 0, v[106:107]
	v_mov_b32_e32 v106, 0x40000
	global_load_dwordx4 v[68:71], v[104:105], off
	global_load_dwordx4 v[72:75], v[104:105], off offset:64
	global_load_dwordx4 v[76:79], v[104:105], off offset:128
	global_load_dwordx4 v[80:83], v[104:105], off offset:192
	global_load_dwordx4 v[84:87], v[104:105], off offset:256
	global_load_dwordx4 v[88:91], v[104:105], off offset:320
	global_load_dwordx4 v[92:95], v[104:105], off offset:384
	global_load_dwordx4 v[96:99], v[104:105], off offset:448
	v_accvgpr_read_b32 v100, a204
	v_accvgpr_read_b32 v101, a205
	v_accvgpr_read_b32 v102, a206
	v_accvgpr_read_b32 v103, a207
	s_waitcnt vmcnt(15)
	v_pk_fma_f32 v[36:37], v[100:101], v[4:5], v[36:37]
	v_pk_fma_f32 v[38:39], v[102:103], v[6:7], v[38:39]
	global_store_dwordx4 v[152:153], v[36:39], off
	v_accvgpr_read_b32 v100, a200
	v_accvgpr_read_b32 v101, a201
	v_accvgpr_read_b32 v102, a202
	v_accvgpr_read_b32 v103, a203
	s_waitcnt vmcnt(15)
	v_pk_fma_f32 v[40:41], v[100:101], v[8:9], v[40:41]
	v_pk_fma_f32 v[42:43], v[102:103], v[10:11], v[42:43]
	global_store_dwordx4 v[152:153], v[40:43], off offset:64
	v_accvgpr_read_b32 v100, a196
	v_accvgpr_read_b32 v101, a197
	v_accvgpr_read_b32 v102, a198
	v_accvgpr_read_b32 v103, a199
	s_waitcnt vmcnt(15)
	v_pk_fma_f32 v[44:45], v[100:101], v[12:13], v[44:45]
	v_pk_fma_f32 v[46:47], v[102:103], v[14:15], v[46:47]
	global_store_dwordx4 v[152:153], v[44:47], off offset:128
	v_accvgpr_read_b32 v100, a188
	v_accvgpr_read_b32 v101, a189
	v_accvgpr_read_b32 v102, a190
	v_accvgpr_read_b32 v103, a191
	s_waitcnt vmcnt(15)
	v_pk_fma_f32 v[48:49], v[100:101], v[16:17], v[48:49]
	v_pk_fma_f32 v[50:51], v[102:103], v[18:19], v[50:51]
	global_store_dwordx4 v[152:153], v[48:51], off offset:192
	v_accvgpr_read_b32 v100, a240
	v_accvgpr_read_b32 v101, a241
	v_accvgpr_read_b32 v102, a242
	v_accvgpr_read_b32 v103, a243
	s_waitcnt vmcnt(15)
	v_pk_fma_f32 v[52:53], v[100:101], v[20:21], v[52:53]
	v_pk_fma_f32 v[54:55], v[102:103], v[22:23], v[54:55]
	global_store_dwordx4 v[152:153], v[52:55], off offset:256
	v_accvgpr_read_b32 v100, a252
	v_accvgpr_read_b32 v101, a253
	v_accvgpr_read_b32 v102, a254
	v_accvgpr_read_b32 v103, a255
	s_waitcnt vmcnt(15)
	v_pk_fma_f32 v[56:57], v[100:101], v[24:25], v[56:57]
	v_pk_fma_f32 v[58:59], v[102:103], v[26:27], v[58:59]
	global_store_dwordx4 v[152:153], v[56:59], off offset:320
	v_accvgpr_read_b32 v100, a248
	v_accvgpr_read_b32 v101, a249
	v_accvgpr_read_b32 v102, a250
	v_accvgpr_read_b32 v103, a251
	s_waitcnt vmcnt(15)
	v_pk_fma_f32 v[60:61], v[100:101], v[28:29], v[60:61]
	v_pk_fma_f32 v[62:63], v[102:103], v[30:31], v[62:63]
	global_store_dwordx4 v[152:153], v[60:63], off offset:384
	v_accvgpr_read_b32 v100, a244
	v_accvgpr_read_b32 v101, a245
	v_accvgpr_read_b32 v102, a246
	v_accvgpr_read_b32 v103, a247
	s_waitcnt vmcnt(15)
	v_pk_fma_f32 v[64:65], v[100:101], v[32:33], v[64:65]
	v_pk_fma_f32 v[66:67], v[102:103], v[34:35], v[66:67]
	global_store_dwordx4 v[152:153], v[64:67], off offset:448
	v_lshl_add_u64 v[152:153], v[152:153], 0, v[106:107]
	s_nop 1
	global_load_dwordx4 v[36:39], v[152:153], off
	global_load_dwordx4 v[40:43], v[152:153], off offset:64
	global_load_dwordx4 v[44:47], v[152:153], off offset:128
	global_load_dwordx4 v[48:51], v[152:153], off offset:192
	global_load_dwordx4 v[52:55], v[152:153], off offset:256
	global_load_dwordx4 v[56:59], v[152:153], off offset:320
	global_load_dwordx4 v[60:63], v[152:153], off offset:384
	global_load_dwordx4 v[64:67], v[152:153], off offset:448
	v_accvgpr_read_b32 v100, a192
	v_accvgpr_read_b32 v101, a193
	v_accvgpr_read_b32 v102, a194
	v_accvgpr_read_b32 v103, a195
	s_waitcnt vmcnt(23)
	v_pk_fma_f32 v[68:69], v[100:101], v[4:5], v[68:69]
	v_pk_fma_f32 v[70:71], v[102:103], v[6:7], v[70:71]
	global_store_dwordx4 v[104:105], v[68:71], off
	v_accvgpr_read_b32 v100, a184
	v_accvgpr_read_b32 v101, a185
	v_accvgpr_read_b32 v102, a186
	v_accvgpr_read_b32 v103, a187
	s_waitcnt vmcnt(23)
	v_pk_fma_f32 v[72:73], v[100:101], v[8:9], v[72:73]
	v_pk_fma_f32 v[74:75], v[102:103], v[10:11], v[74:75]
	global_store_dwordx4 v[104:105], v[72:75], off offset:64
	v_accvgpr_read_b32 v100, a180
	v_accvgpr_read_b32 v101, a181
	v_accvgpr_read_b32 v102, a182
	v_accvgpr_read_b32 v103, a183
	s_waitcnt vmcnt(23)
	v_pk_fma_f32 v[76:77], v[100:101], v[12:13], v[76:77]
	v_pk_fma_f32 v[78:79], v[102:103], v[14:15], v[78:79]
	global_store_dwordx4 v[104:105], v[76:79], off offset:128
	v_accvgpr_read_b32 v100, a176
	v_accvgpr_read_b32 v101, a177
	v_accvgpr_read_b32 v102, a178
	v_accvgpr_read_b32 v103, a179
	s_waitcnt vmcnt(23)
	v_pk_fma_f32 v[80:81], v[100:101], v[16:17], v[80:81]
	v_pk_fma_f32 v[82:83], v[102:103], v[18:19], v[82:83]
	global_store_dwordx4 v[104:105], v[80:83], off offset:192
	v_accvgpr_read_b32 v100, a236
	v_accvgpr_read_b32 v101, a237
	v_accvgpr_read_b32 v102, a238
	v_accvgpr_read_b32 v103, a239
	s_waitcnt vmcnt(23)
	v_pk_fma_f32 v[84:85], v[100:101], v[20:21], v[84:85]
	v_pk_fma_f32 v[86:87], v[102:103], v[22:23], v[86:87]
	global_store_dwordx4 v[104:105], v[84:87], off offset:256
	v_accvgpr_read_b32 v100, a232
	v_accvgpr_read_b32 v101, a233
	v_accvgpr_read_b32 v102, a234
	v_accvgpr_read_b32 v103, a235
	s_waitcnt vmcnt(23)
	v_pk_fma_f32 v[88:89], v[100:101], v[24:25], v[88:89]
	v_pk_fma_f32 v[90:91], v[102:103], v[26:27], v[90:91]
	global_store_dwordx4 v[104:105], v[88:91], off offset:320
	v_accvgpr_read_b32 v100, a228
	v_accvgpr_read_b32 v101, a229
	v_accvgpr_read_b32 v102, a230
	v_accvgpr_read_b32 v103, a231
	s_waitcnt vmcnt(23)
	v_pk_fma_f32 v[92:93], v[100:101], v[28:29], v[92:93]
	v_pk_fma_f32 v[94:95], v[102:103], v[30:31], v[94:95]
	global_store_dwordx4 v[104:105], v[92:95], off offset:384
	v_accvgpr_read_b32 v100, a224
	v_accvgpr_read_b32 v101, a225
	v_accvgpr_read_b32 v102, a226
	v_accvgpr_read_b32 v103, a227
	s_waitcnt vmcnt(23)
	v_pk_fma_f32 v[96:97], v[100:101], v[32:33], v[96:97]
	v_pk_fma_f32 v[98:99], v[102:103], v[34:35], v[98:99]
	global_store_dwordx4 v[104:105], v[96:99], off offset:448
	v_lshl_add_u64 v[104:105], v[104:105], 0, v[106:107]
	s_nop 1
	global_load_dwordx4 v[68:71], v[104:105], off
	global_load_dwordx4 v[72:75], v[104:105], off offset:64
	global_load_dwordx4 v[76:79], v[104:105], off offset:128
	global_load_dwordx4 v[80:83], v[104:105], off offset:192
	global_load_dwordx4 v[84:87], v[104:105], off offset:256
	global_load_dwordx4 v[88:91], v[104:105], off offset:320
	global_load_dwordx4 v[92:95], v[104:105], off offset:384
	global_load_dwordx4 v[96:99], v[104:105], off offset:448
	v_accvgpr_read_b32 v100, a156
	v_accvgpr_read_b32 v101, a157
	v_accvgpr_read_b32 v102, a158
	v_accvgpr_read_b32 v103, a159
	s_waitcnt vmcnt(23)
	v_pk_fma_f32 v[36:37], v[100:101], v[4:5], v[36:37]
	v_pk_fma_f32 v[38:39], v[102:103], v[6:7], v[38:39]
	global_store_dwordx4 v[152:153], v[36:39], off
	v_accvgpr_read_b32 v100, a152
	v_accvgpr_read_b32 v101, a153
	v_accvgpr_read_b32 v102, a154
	v_accvgpr_read_b32 v103, a155
	s_waitcnt vmcnt(23)
	v_pk_fma_f32 v[40:41], v[100:101], v[8:9], v[40:41]
	v_pk_fma_f32 v[42:43], v[102:103], v[10:11], v[42:43]
	global_store_dwordx4 v[152:153], v[40:43], off offset:64
	v_accvgpr_read_b32 v100, a148
	v_accvgpr_read_b32 v101, a149
	v_accvgpr_read_b32 v102, a150
	v_accvgpr_read_b32 v103, a151
	s_waitcnt vmcnt(23)
	v_pk_fma_f32 v[44:45], v[100:101], v[12:13], v[44:45]
	v_pk_fma_f32 v[46:47], v[102:103], v[14:15], v[46:47]
	global_store_dwordx4 v[152:153], v[44:47], off offset:128
	v_accvgpr_read_b32 v100, a144
	v_accvgpr_read_b32 v101, a145
	v_accvgpr_read_b32 v102, a146
	v_accvgpr_read_b32 v103, a147
	s_waitcnt vmcnt(23)
	v_pk_fma_f32 v[48:49], v[100:101], v[16:17], v[48:49]
	v_pk_fma_f32 v[50:51], v[102:103], v[18:19], v[50:51]
	global_store_dwordx4 v[152:153], v[48:51], off offset:192
	v_accvgpr_read_b32 v100, a220
	v_accvgpr_read_b32 v101, a221
	v_accvgpr_read_b32 v102, a222
	v_accvgpr_read_b32 v103, a223
	s_waitcnt vmcnt(23)
	v_pk_fma_f32 v[52:53], v[100:101], v[20:21], v[52:53]
	v_pk_fma_f32 v[54:55], v[102:103], v[22:23], v[54:55]
	global_store_dwordx4 v[152:153], v[52:55], off offset:256
	v_accvgpr_read_b32 v100, a216
	v_accvgpr_read_b32 v101, a217
	v_accvgpr_read_b32 v102, a218
	v_accvgpr_read_b32 v103, a219
	s_waitcnt vmcnt(23)
	v_pk_fma_f32 v[56:57], v[100:101], v[24:25], v[56:57]
	v_pk_fma_f32 v[58:59], v[102:103], v[26:27], v[58:59]
	global_store_dwordx4 v[152:153], v[56:59], off offset:320
	v_accvgpr_read_b32 v100, a212
	v_accvgpr_read_b32 v101, a213
	v_accvgpr_read_b32 v102, a214
	v_accvgpr_read_b32 v103, a215
	s_waitcnt vmcnt(23)
	v_pk_fma_f32 v[60:61], v[100:101], v[28:29], v[60:61]
	v_pk_fma_f32 v[62:63], v[102:103], v[30:31], v[62:63]
	global_store_dwordx4 v[152:153], v[60:63], off offset:384
	v_accvgpr_read_b32 v100, a208
	v_accvgpr_read_b32 v101, a209
	v_accvgpr_read_b32 v102, a210
	v_accvgpr_read_b32 v103, a211
	s_waitcnt vmcnt(23)
	v_pk_fma_f32 v[64:65], v[100:101], v[32:33], v[64:65]
	v_pk_fma_f32 v[66:67], v[102:103], v[34:35], v[66:67]
	global_store_dwordx4 v[152:153], v[64:67], off offset:448
	v_lshl_add_u64 v[152:153], v[152:153], 0, v[106:107]
	s_nop 1
	global_load_dwordx4 v[36:39], v[152:153], off
	global_load_dwordx4 v[40:43], v[152:153], off offset:64
	global_load_dwordx4 v[44:47], v[152:153], off offset:128
	global_load_dwordx4 v[48:51], v[152:153], off offset:192
	global_load_dwordx4 v[52:55], v[152:153], off offset:256
	global_load_dwordx4 v[56:59], v[152:153], off offset:320
	global_load_dwordx4 v[60:63], v[152:153], off offset:384
	global_load_dwordx4 v[64:67], v[152:153], off offset:448
	v_accvgpr_read_b32 v100, a124
	v_accvgpr_read_b32 v101, a125
	v_accvgpr_read_b32 v102, a126
	v_accvgpr_read_b32 v103, a127
	s_waitcnt vmcnt(23)
	v_pk_fma_f32 v[68:69], v[100:101], v[4:5], v[68:69]
	v_pk_fma_f32 v[70:71], v[102:103], v[6:7], v[70:71]
	global_store_dwordx4 v[104:105], v[68:71], off
	v_accvgpr_read_b32 v100, a120
	v_accvgpr_read_b32 v101, a121
	v_accvgpr_read_b32 v102, a122
	v_accvgpr_read_b32 v103, a123
	s_waitcnt vmcnt(23)
	v_pk_fma_f32 v[72:73], v[100:101], v[8:9], v[72:73]
	v_pk_fma_f32 v[74:75], v[102:103], v[10:11], v[74:75]
	global_store_dwordx4 v[104:105], v[72:75], off offset:64
	v_accvgpr_read_b32 v100, a116
	v_accvgpr_read_b32 v101, a117
	v_accvgpr_read_b32 v102, a118
	v_accvgpr_read_b32 v103, a119
	s_waitcnt vmcnt(23)
	v_pk_fma_f32 v[76:77], v[100:101], v[12:13], v[76:77]
	v_pk_fma_f32 v[78:79], v[102:103], v[14:15], v[78:79]
	global_store_dwordx4 v[104:105], v[76:79], off offset:128
	v_accvgpr_read_b32 v100, a112
	v_accvgpr_read_b32 v101, a113
	v_accvgpr_read_b32 v102, a114
	v_accvgpr_read_b32 v103, a115
	s_waitcnt vmcnt(23)
	v_pk_fma_f32 v[80:81], v[100:101], v[16:17], v[80:81]
	v_pk_fma_f32 v[82:83], v[102:103], v[18:19], v[82:83]
	global_store_dwordx4 v[104:105], v[80:83], off offset:192
	v_accvgpr_read_b32 v100, a172
	v_accvgpr_read_b32 v101, a173
	v_accvgpr_read_b32 v102, a174
	v_accvgpr_read_b32 v103, a175
	s_waitcnt vmcnt(23)
	v_pk_fma_f32 v[84:85], v[100:101], v[20:21], v[84:85]
	v_pk_fma_f32 v[86:87], v[102:103], v[22:23], v[86:87]
	global_store_dwordx4 v[104:105], v[84:87], off offset:256
	v_accvgpr_read_b32 v100, a168
	v_accvgpr_read_b32 v101, a169
	v_accvgpr_read_b32 v102, a170
	v_accvgpr_read_b32 v103, a171
	s_waitcnt vmcnt(23)
	v_pk_fma_f32 v[88:89], v[100:101], v[24:25], v[88:89]
	v_pk_fma_f32 v[90:91], v[102:103], v[26:27], v[90:91]
	global_store_dwordx4 v[104:105], v[88:91], off offset:320
	v_accvgpr_read_b32 v100, a164
	v_accvgpr_read_b32 v101, a165
	v_accvgpr_read_b32 v102, a166
	v_accvgpr_read_b32 v103, a167
	s_waitcnt vmcnt(23)
	v_pk_fma_f32 v[92:93], v[100:101], v[28:29], v[92:93]
	v_pk_fma_f32 v[94:95], v[102:103], v[30:31], v[94:95]
	global_store_dwordx4 v[104:105], v[92:95], off offset:384
	v_accvgpr_read_b32 v100, a160
	v_accvgpr_read_b32 v101, a161
	v_accvgpr_read_b32 v102, a162
	v_accvgpr_read_b32 v103, a163
	s_waitcnt vmcnt(23)
	v_pk_fma_f32 v[96:97], v[100:101], v[32:33], v[96:97]
	v_pk_fma_f32 v[98:99], v[102:103], v[34:35], v[98:99]
	global_store_dwordx4 v[104:105], v[96:99], off offset:448
	v_lshl_add_u64 v[104:105], v[104:105], 0, v[106:107]
	s_nop 1
	global_load_dwordx4 v[68:71], v[104:105], off
	global_load_dwordx4 v[72:75], v[104:105], off offset:64
	global_load_dwordx4 v[76:79], v[104:105], off offset:128
	global_load_dwordx4 v[80:83], v[104:105], off offset:192
	global_load_dwordx4 v[84:87], v[104:105], off offset:256
	global_load_dwordx4 v[88:91], v[104:105], off offset:320
	global_load_dwordx4 v[92:95], v[104:105], off offset:384
	global_load_dwordx4 v[96:99], v[104:105], off offset:448
	v_accvgpr_read_b32 v100, a92
	v_accvgpr_read_b32 v101, a93
	v_accvgpr_read_b32 v102, a94
	v_accvgpr_read_b32 v103, a95
	s_waitcnt vmcnt(23)
	v_pk_fma_f32 v[36:37], v[100:101], v[4:5], v[36:37]
	v_pk_fma_f32 v[38:39], v[102:103], v[6:7], v[38:39]
	global_store_dwordx4 v[152:153], v[36:39], off
	v_accvgpr_read_b32 v100, a88
	v_accvgpr_read_b32 v101, a89
	v_accvgpr_read_b32 v102, a90
	v_accvgpr_read_b32 v103, a91
	s_waitcnt vmcnt(23)
	v_pk_fma_f32 v[40:41], v[100:101], v[8:9], v[40:41]
	v_pk_fma_f32 v[42:43], v[102:103], v[10:11], v[42:43]
	global_store_dwordx4 v[152:153], v[40:43], off offset:64
	v_accvgpr_read_b32 v100, a84
	v_accvgpr_read_b32 v101, a85
	v_accvgpr_read_b32 v102, a86
	v_accvgpr_read_b32 v103, a87
	s_waitcnt vmcnt(23)
	v_pk_fma_f32 v[44:45], v[100:101], v[12:13], v[44:45]
	v_pk_fma_f32 v[46:47], v[102:103], v[14:15], v[46:47]
	global_store_dwordx4 v[152:153], v[44:47], off offset:128
	v_accvgpr_read_b32 v100, a80
	v_accvgpr_read_b32 v101, a81
	v_accvgpr_read_b32 v102, a82
	v_accvgpr_read_b32 v103, a83
	s_waitcnt vmcnt(23)
	v_pk_fma_f32 v[48:49], v[100:101], v[16:17], v[48:49]
	v_pk_fma_f32 v[50:51], v[102:103], v[18:19], v[50:51]
	global_store_dwordx4 v[152:153], v[48:51], off offset:192
	v_accvgpr_read_b32 v100, a140
	v_accvgpr_read_b32 v101, a141
	v_accvgpr_read_b32 v102, a142
	v_accvgpr_read_b32 v103, a143
	s_waitcnt vmcnt(23)
	v_pk_fma_f32 v[52:53], v[100:101], v[20:21], v[52:53]
	v_pk_fma_f32 v[54:55], v[102:103], v[22:23], v[54:55]
	global_store_dwordx4 v[152:153], v[52:55], off offset:256
	v_accvgpr_read_b32 v100, a136
	v_accvgpr_read_b32 v101, a137
	v_accvgpr_read_b32 v102, a138
	v_accvgpr_read_b32 v103, a139
	s_waitcnt vmcnt(23)
	v_pk_fma_f32 v[56:57], v[100:101], v[24:25], v[56:57]
	v_pk_fma_f32 v[58:59], v[102:103], v[26:27], v[58:59]
	global_store_dwordx4 v[152:153], v[56:59], off offset:320
	v_accvgpr_read_b32 v100, a132
	v_accvgpr_read_b32 v101, a133
	v_accvgpr_read_b32 v102, a134
	v_accvgpr_read_b32 v103, a135
	s_waitcnt vmcnt(23)
	v_pk_fma_f32 v[60:61], v[100:101], v[28:29], v[60:61]
	v_pk_fma_f32 v[62:63], v[102:103], v[30:31], v[62:63]
	global_store_dwordx4 v[152:153], v[60:63], off offset:384
	v_accvgpr_read_b32 v100, a128
	v_accvgpr_read_b32 v101, a129
	v_accvgpr_read_b32 v102, a130
	v_accvgpr_read_b32 v103, a131
	s_waitcnt vmcnt(23)
	v_pk_fma_f32 v[64:65], v[100:101], v[32:33], v[64:65]
	v_pk_fma_f32 v[66:67], v[102:103], v[34:35], v[66:67]
	global_store_dwordx4 v[152:153], v[64:67], off offset:448
	v_lshl_add_u64 v[152:153], v[152:153], 0, v[106:107]
	s_nop 1
	global_load_dwordx4 v[36:39], v[152:153], off
	global_load_dwordx4 v[40:43], v[152:153], off offset:64
	global_load_dwordx4 v[44:47], v[152:153], off offset:128
	global_load_dwordx4 v[48:51], v[152:153], off offset:192
	global_load_dwordx4 v[52:55], v[152:153], off offset:256
	global_load_dwordx4 v[56:59], v[152:153], off offset:320
	global_load_dwordx4 v[60:63], v[152:153], off offset:384
	global_load_dwordx4 v[64:67], v[152:153], off offset:448
	v_accvgpr_read_b32 v100, a60
	v_accvgpr_read_b32 v101, a61
	v_accvgpr_read_b32 v102, a62
	v_accvgpr_read_b32 v103, a63
	s_waitcnt vmcnt(23)
	v_pk_fma_f32 v[68:69], v[100:101], v[4:5], v[68:69]
	v_pk_fma_f32 v[70:71], v[102:103], v[6:7], v[70:71]
	global_store_dwordx4 v[104:105], v[68:71], off
	v_accvgpr_read_b32 v100, a56
	v_accvgpr_read_b32 v101, a57
	v_accvgpr_read_b32 v102, a58
	v_accvgpr_read_b32 v103, a59
	s_waitcnt vmcnt(23)
	v_pk_fma_f32 v[72:73], v[100:101], v[8:9], v[72:73]
	v_pk_fma_f32 v[74:75], v[102:103], v[10:11], v[74:75]
	global_store_dwordx4 v[104:105], v[72:75], off offset:64
	v_accvgpr_read_b32 v100, a52
	v_accvgpr_read_b32 v101, a53
	v_accvgpr_read_b32 v102, a54
	v_accvgpr_read_b32 v103, a55
	s_waitcnt vmcnt(23)
	v_pk_fma_f32 v[76:77], v[100:101], v[12:13], v[76:77]
	v_pk_fma_f32 v[78:79], v[102:103], v[14:15], v[78:79]
	global_store_dwordx4 v[104:105], v[76:79], off offset:128
	v_accvgpr_read_b32 v100, a48
	v_accvgpr_read_b32 v101, a49
	v_accvgpr_read_b32 v102, a50
	v_accvgpr_read_b32 v103, a51
	s_waitcnt vmcnt(23)
	v_pk_fma_f32 v[80:81], v[100:101], v[16:17], v[80:81]
	v_pk_fma_f32 v[82:83], v[102:103], v[18:19], v[82:83]
	global_store_dwordx4 v[104:105], v[80:83], off offset:192
	v_accvgpr_read_b32 v100, a108
	v_accvgpr_read_b32 v101, a109
	v_accvgpr_read_b32 v102, a110
	v_accvgpr_read_b32 v103, a111
	s_waitcnt vmcnt(23)
	v_pk_fma_f32 v[84:85], v[100:101], v[20:21], v[84:85]
	v_pk_fma_f32 v[86:87], v[102:103], v[22:23], v[86:87]
	global_store_dwordx4 v[104:105], v[84:87], off offset:256
	v_accvgpr_read_b32 v100, a104
	v_accvgpr_read_b32 v101, a105
	v_accvgpr_read_b32 v102, a106
	v_accvgpr_read_b32 v103, a107
	s_waitcnt vmcnt(23)
	v_pk_fma_f32 v[88:89], v[100:101], v[24:25], v[88:89]
	v_pk_fma_f32 v[90:91], v[102:103], v[26:27], v[90:91]
	global_store_dwordx4 v[104:105], v[88:91], off offset:320
	v_accvgpr_read_b32 v100, a100
	v_accvgpr_read_b32 v101, a101
	v_accvgpr_read_b32 v102, a102
	v_accvgpr_read_b32 v103, a103
	s_waitcnt vmcnt(23)
	v_pk_fma_f32 v[92:93], v[100:101], v[28:29], v[92:93]
	v_pk_fma_f32 v[94:95], v[102:103], v[30:31], v[94:95]
	global_store_dwordx4 v[104:105], v[92:95], off offset:384
	v_accvgpr_read_b32 v100, a96
	v_accvgpr_read_b32 v101, a97
	v_accvgpr_read_b32 v102, a98
	v_accvgpr_read_b32 v103, a99
	s_waitcnt vmcnt(23)
	v_pk_fma_f32 v[96:97], v[100:101], v[32:33], v[96:97]
	v_pk_fma_f32 v[98:99], v[102:103], v[34:35], v[98:99]
	global_store_dwordx4 v[104:105], v[96:99], off offset:448
	v_lshl_add_u64 v[104:105], v[104:105], 0, v[106:107]
	s_nop 1
	global_load_dwordx4 v[68:71], v[104:105], off
	global_load_dwordx4 v[72:75], v[104:105], off offset:64
	global_load_dwordx4 v[76:79], v[104:105], off offset:128
	global_load_dwordx4 v[80:83], v[104:105], off offset:192
	global_load_dwordx4 v[84:87], v[104:105], off offset:256
	global_load_dwordx4 v[88:91], v[104:105], off offset:320
	global_load_dwordx4 v[92:95], v[104:105], off offset:384
	global_load_dwordx4 v[96:99], v[104:105], off offset:448
	v_accvgpr_read_b32 v100, a32
	v_accvgpr_read_b32 v101, a33
	v_accvgpr_read_b32 v102, a34
	v_accvgpr_read_b32 v103, a35
	s_waitcnt vmcnt(23)
; template <class Epi>
; __device__ __forceinline__ void gemm_run(const GemmArgs g, Epi epi, char* smem) {
;     ...
;   for (int tile = blockIdx.x; tile < total; tile += gridDim.x) {
	v_pk_fma_f32 v[36:37], v[100:101], v[4:5], v[36:37]
	v_pk_fma_f32 v[38:39], v[102:103], v[6:7], v[38:39]
	global_store_dwordx4 v[152:153], v[36:39], off
	v_accvgpr_read_b32 v100, a28
	v_accvgpr_read_b32 v101, a29
	v_accvgpr_read_b32 v102, a30
	v_accvgpr_read_b32 v103, a31
	s_waitcnt vmcnt(23)
	v_pk_fma_f32 v[40:41], v[100:101], v[8:9], v[40:41]
	v_pk_fma_f32 v[42:43], v[102:103], v[10:11], v[42:43]
	global_store_dwordx4 v[152:153], v[40:43], off offset:64
	v_accvgpr_read_b32 v100, a24
	v_accvgpr_read_b32 v101, a25
	v_accvgpr_read_b32 v102, a26
	v_accvgpr_read_b32 v103, a27
	s_waitcnt vmcnt(23)
	v_pk_fma_f32 v[44:45], v[100:101], v[12:13], v[44:45]
	v_pk_fma_f32 v[46:47], v[102:103], v[14:15], v[46:47]
	global_store_dwordx4 v[152:153], v[44:47], off offset:128
	v_accvgpr_read_b32 v100, a20
	v_accvgpr_read_b32 v101, a21
	v_accvgpr_read_b32 v102, a22
	v_accvgpr_read_b32 v103, a23
	s_waitcnt vmcnt(23)
	v_pk_fma_f32 v[48:49], v[100:101], v[16:17], v[48:49]
	v_pk_fma_f32 v[50:51], v[102:103], v[18:19], v[50:51]
	global_store_dwordx4 v[152:153], v[48:51], off offset:192
	v_accvgpr_read_b32 v100, a76
	v_accvgpr_read_b32 v101, a77
	v_accvgpr_read_b32 v102, a78
	v_accvgpr_read_b32 v103, a79
	s_waitcnt vmcnt(23)
	v_pk_fma_f32 v[52:53], v[100:101], v[20:21], v[52:53]
	v_pk_fma_f32 v[54:55], v[102:103], v[22:23], v[54:55]
	global_store_dwordx4 v[152:153], v[52:55], off offset:256
	v_accvgpr_read_b32 v100, a72
	v_accvgpr_read_b32 v101, a73
	v_accvgpr_read_b32 v102, a74
	v_accvgpr_read_b32 v103, a75
	s_waitcnt vmcnt(23)
	v_pk_fma_f32 v[56:57], v[100:101], v[24:25], v[56:57]
	v_pk_fma_f32 v[58:59], v[102:103], v[26:27], v[58:59]
	global_store_dwordx4 v[152:153], v[56:59], off offset:320
	v_accvgpr_read_b32 v100, a68
	v_accvgpr_read_b32 v101, a69
	v_accvgpr_read_b32 v102, a70
	v_accvgpr_read_b32 v103, a71
	s_waitcnt vmcnt(23)
	v_pk_fma_f32 v[60:61], v[100:101], v[28:29], v[60:61]
	v_pk_fma_f32 v[62:63], v[102:103], v[30:31], v[62:63]
	global_store_dwordx4 v[152:153], v[60:63], off offset:384
	v_accvgpr_read_b32 v100, a64
	v_accvgpr_read_b32 v101, a65
	v_accvgpr_read_b32 v102, a66
	v_accvgpr_read_b32 v103, a67
	s_waitcnt vmcnt(23)
	v_pk_fma_f32 v[64:65], v[100:101], v[32:33], v[64:65]
	v_pk_fma_f32 v[66:67], v[102:103], v[34:35], v[66:67]
	global_store_dwordx4 v[152:153], v[64:67], off offset:448
	v_accvgpr_read_b32 v100, a12
	v_accvgpr_read_b32 v101, a13
	v_accvgpr_read_b32 v102, a14
	v_accvgpr_read_b32 v103, a15
	s_waitcnt vmcnt(15)
	v_pk_fma_f32 v[68:69], v[100:101], v[4:5], v[68:69]
	v_pk_fma_f32 v[70:71], v[102:103], v[6:7], v[70:71]
	global_store_dwordx4 v[104:105], v[68:71], off
	v_accvgpr_read_b32 v100, a8
	v_accvgpr_read_b32 v101, a9
	v_accvgpr_read_b32 v102, a10
	v_accvgpr_read_b32 v103, a11
	s_waitcnt vmcnt(15)
	v_pk_fma_f32 v[72:73], v[100:101], v[8:9], v[72:73]
	v_pk_fma_f32 v[74:75], v[102:103], v[10:11], v[74:75]
	global_store_dwordx4 v[104:105], v[72:75], off offset:64
	v_accvgpr_read_b32 v100, a4
	v_accvgpr_read_b32 v101, a5
	v_accvgpr_read_b32 v102, a6
	v_accvgpr_read_b32 v103, a7
	s_waitcnt vmcnt(15)
	v_pk_fma_f32 v[76:77], v[100:101], v[12:13], v[76:77]
	v_pk_fma_f32 v[78:79], v[102:103], v[14:15], v[78:79]
	global_store_dwordx4 v[104:105], v[76:79], off offset:128
	v_accvgpr_read_b32 v100, a0
	v_accvgpr_read_b32 v101, a1
	v_accvgpr_read_b32 v102, a2
	v_accvgpr_read_b32 v103, a3
	s_waitcnt vmcnt(15)
	v_pk_fma_f32 v[80:81], v[100:101], v[16:17], v[80:81]
	v_pk_fma_f32 v[82:83], v[102:103], v[18:19], v[82:83]
	global_store_dwordx4 v[104:105], v[80:83], off offset:192
	v_accvgpr_read_b32 v100, a44
	v_accvgpr_read_b32 v101, a45
	v_accvgpr_read_b32 v102, a46
	v_accvgpr_read_b32 v103, a47
	s_waitcnt vmcnt(15)
	v_pk_fma_f32 v[84:85], v[100:101], v[20:21], v[84:85]
	v_pk_fma_f32 v[86:87], v[102:103], v[22:23], v[86:87]
	global_store_dwordx4 v[104:105], v[84:87], off offset:256
	v_accvgpr_read_b32 v100, a40
	v_accvgpr_read_b32 v101, a41
	v_accvgpr_read_b32 v102, a42
	v_accvgpr_read_b32 v103, a43
	s_waitcnt vmcnt(15)
	v_pk_fma_f32 v[88:89], v[100:101], v[24:25], v[88:89]
	v_pk_fma_f32 v[90:91], v[102:103], v[26:27], v[90:91]
	global_store_dwordx4 v[104:105], v[88:91], off offset:320
	v_accvgpr_read_b32 v100, a36
	v_accvgpr_read_b32 v101, a37
	v_accvgpr_read_b32 v102, a38
	v_accvgpr_read_b32 v103, a39
	s_waitcnt vmcnt(15)
	v_pk_fma_f32 v[92:93], v[100:101], v[28:29], v[92:93]
	v_pk_fma_f32 v[94:95], v[102:103], v[30:31], v[94:95]
	global_store_dwordx4 v[104:105], v[92:95], off offset:384
	v_accvgpr_read_b32 v100, a16
	v_accvgpr_read_b32 v101, a17
	v_accvgpr_read_b32 v102, a18
	v_accvgpr_read_b32 v103, a19
	s_waitcnt vmcnt(15)
	v_pk_fma_f32 v[96:97], v[100:101], v[32:33], v[96:97]
	v_pk_fma_f32 v[98:99], v[102:103], v[34:35], v[98:99]
	global_store_dwordx4 v[104:105], v[96:99], off offset:448
	s_add_i32 s77, s77, s2
	s_cmpk_lt_i32 s77, 0x200
	s_cbranch_scc0 .LBB0_1119

; DI f4 mfma16(h8 a, h8 b, f4 c) { return __builtin_amdgcn_mfma_f32_16x16x32_f16(a, b, c, 0, 0, 0); }
; template <int DQK, bool BIAS>
; __device__ __forceinline__ void attn_pass(const hf* __restrict__ Q, int ldq, const hf* __restrict__ Kp, int ldk, const hf* __restrict__ VT,
;                                           int s0, int L, int q0, float scale_l2, const float* sBias, f4 (&oacc)[8][4], char* smem) {
;     ...
;   for (int kt = 0; kt < nkt; ++kt) {
;     const hf* sK = sbase + (kt & 1) * A_STG; const hf* sVT = sK + 64 * 104;
;     f4 sacc[4][4];
; #pragma unroll
;     for (int mk = 0; mk < 4; ++mk) {
;       h8 kf[NKS];
; #pragma unroll
;       for (int ks = 0; ks < NKS; ++ks) kf[ks] = *(const h8*)(sK + (mk * 16 + fr) * KS + ks * 32 + (fq ^ (((fr >> 2) ^ (fr >> 3)) & 1)) * 8);
; #pragma unroll
;       for (int nq = 0; nq < 4; ++nq) {
;         f4 a = {0.f, 0.f, 0.f, 0.f};
; #pragma unroll
;         for (int ks = 0; ks < NKS; ++ks) a = mfma16(kf[ks], qf[nq][ks], a);
;         sacc[mk][nq] = a;
;       }
;     }
;     if (kt + 1 < nkt) storeKV((kt + 1) & 1);
;     if (kt + 2 < nkt) loadKV(kt + 2);
.LBB0_1948:
	s_bitcmp1_b32 s16, 0
	s_cselect_b32 s17, 0x7c00, 0
	s_add_i32 s95, s17, 16
	v_add_u32_e32 v40, s95, v239
	v_lshl_add_u32 v36, v238, 1, v40
	ds_read_b128 v[32:35], v36
	ds_read_b128 v[36:39], v36 offset:64
	v_add_u32_e32 v44, v40, v240
	ds_read_b128 v[40:43], v44 offset:6912
	s_waitcnt lgkmcnt(2)
	v_mfma_f32_16x16x32_f16 v[188:191], v[32:35], v[0:3], 0
	s_waitcnt lgkmcnt(1)
	v_mfma_f32_16x16x32_f16 v[188:191], v[36:39], v[4:7], v[188:191]
	v_mfma_f32_16x16x32_f16 v[156:159], v[32:35], v[16:19], 0
	v_mfma_f32_16x16x32_f16 v[172:175], v[32:35], v[8:11], 0
	v_mfma_f32_16x16x32_f16 v[156:159], v[36:39], v[20:23], v[156:159]
	v_mfma_f32_16x16x32_f16 v[124:127], v[32:35], v[24:27], 0
	ds_read_b128 v[32:35], v44 offset:2304
	v_mfma_f32_16x16x32_f16 v[172:175], v[36:39], v[12:15], v[172:175]
	v_mfma_f32_16x16x32_f16 v[124:127], v[36:39], v[28:31], v[124:127]
	ds_read_b128 v[36:39], v44 offset:2368
	s_waitcnt lgkmcnt(1)
	v_mfma_f32_16x16x32_f16 v[184:187], v[32:35], v[0:3], 0
	s_waitcnt lgkmcnt(0)
	v_mfma_f32_16x16x32_f16 v[184:187], v[36:39], v[4:7], v[184:187]
	v_mfma_f32_16x16x32_f16 v[168:171], v[32:35], v[8:11], 0
	v_mfma_f32_16x16x32_f16 v[168:171], v[36:39], v[12:15], v[168:171]
	s_add_i32 s94, s16, 1
	v_mfma_f32_16x16x32_f16 v[152:155], v[32:35], v[16:19], 0
	v_mfma_f32_16x16x32_f16 v[152:155], v[36:39], v[20:23], v[152:155]
	v_mfma_f32_16x16x32_f16 v[120:123], v[32:35], v[24:27], 0
	ds_read_b128 v[32:35], v44 offset:4608
	v_mfma_f32_16x16x32_f16 v[120:123], v[36:39], v[28:31], v[120:123]
	ds_read_b128 v[36:39], v44 offset:4672
	s_waitcnt lgkmcnt(1)
	v_mfma_f32_16x16x32_f16 v[180:183], v[32:35], v[0:3], 0
	s_waitcnt lgkmcnt(0)
	v_mfma_f32_16x16x32_f16 v[180:183], v[36:39], v[4:7], v[180:183]
	v_mfma_f32_16x16x32_f16 v[164:167], v[32:35], v[8:11], 0
	v_mfma_f32_16x16x32_f16 v[164:167], v[36:39], v[12:15], v[164:167]
	v_mfma_f32_16x16x32_f16 v[148:151], v[32:35], v[16:19], 0
	v_mfma_f32_16x16x32_f16 v[148:151], v[36:39], v[20:23], v[148:151]
	v_mfma_f32_16x16x32_f16 v[116:119], v[32:35], v[24:27], 0
	ds_read_b128 v[32:35], v44 offset:6976
	v_mfma_f32_16x16x32_f16 v[176:179], v[40:43], v[0:3], 0
	s_waitcnt lgkmcnt(0)
	v_mfma_f32_16x16x32_f16 v[176:179], v[32:35], v[4:7], v[176:179]
	v_mfma_f32_16x16x32_f16 v[160:163], v[40:43], v[8:11], 0
	v_mfma_f32_16x16x32_f16 v[160:163], v[32:35], v[12:15], v[160:163]
	v_mfma_f32_16x16x32_f16 v[144:147], v[40:43], v[16:19], 0
	v_mfma_f32_16x16x32_f16 v[144:147], v[32:35], v[20:23], v[144:147]
	v_mfma_f32_16x16x32_f16 v[112:115], v[40:43], v[24:27], 0
	v_mfma_f32_16x16x32_f16 v[116:119], v[36:39], v[28:31], v[116:119]
	v_mfma_f32_16x16x32_f16 v[112:115], v[32:35], v[28:31], v[112:115]
	s_cmp_ge_u32 s94, s73
	s_cbranch_scc1 .LBB0_1950
	s_bitcmp1_b32 s94, 0
	s_cselect_b32 s17, 0x7c00, 0
	s_add_i32 s17, s17, 16
	v_add3_u32 v32, s17, v211, v244
	s_waitcnt vmcnt(1)
	ds_write_b128 v32, a[200:203]
	s_waitcnt vmcnt(0)
	ds_write_b128 v32, a[204:207] offset:64
	v_add3_u32 v32, s17, v232, v210
	ds_write_b128 v32, a[192:195] offset:13312
	v_add3_u32 v32, s17, v234, v210
	ds_write_b128 v32, a[196:199] offset:13312
	v_add3_u32 v32, s17, v235, v210
	ds_write_b128 v32, a[208:211] offset:13312
	v_add3_u32 v32, s17, v236, v210
	ds_write_b128 v32, a[212:215] offset:13312

; template <int DQK, bool BIAS>
; __device__ __forceinline__ void attn_pass(const hf* __restrict__ Q, int ldq, const hf* __restrict__ Kp, int ldk, const hf* __restrict__ VT,
;                                           int s0, int L, int q0, float scale_l2, const float* sBias, f4 (&oacc)[8][4], char* smem) {
;     ...
;     const int key0 = kt * 64;
;     bool uni = true; float add = 0.f;
;     if (BIAS) {
;       const int dmin = key0 - (q0 + 255), dmax = key0 + 63 - q0;
;       uni = (dmax <= -91) || (dmin >= 91);
;       add = dmax <= -91 ? sBias[0] : sBias[256];
;     }
; #pragma unroll
;     for (int nq = 0; nq < 4; ++nq) {
;       if (BIAS) {
;         if (uni) {
; #pragma unroll
;           for (int mk = 0; mk < 4; ++mk)
; #pragma unroll
;             for (int j = 0; j < 4; ++j) sacc[mk][nq][j] = sacc[mk][nq][j] * scale_l2 + add;
;         } else {
; #pragma unroll
;           for (int mk = 0; mk < 4; ++mk)
; #pragma unroll
;             for (int j = 0; j < 4; ++j) {
;               int rel = (key0 + mk * 16 + fq * 4 + j) - (q0 + wv * 64 + nq * 16 + fr);
;               rel = min(max(rel, -128), 128);
;               sacc[mk][nq][j] = sacc[mk][nq][j] * scale_l2 + sBias[rel + 128];
;             }
.LBB0_1952:
	s_add_i32 s16, s93, s20
	s_add_i32 s17, s16, 0xffffff80
	s_addk_i32 s16, 0xfe26
	s_cmp_gt_u32 s16, 0xfffffe0c
	s_cselect_b64 s[26:27], -1, 0
	s_cmpk_lt_i32 s17, 0xff67
	s_mov_b32 s17, 0xfc00
	s_cselect_b32 s17, 0xf800, s17
	s_add_i32 s17, s17, 16
	v_mov_b32_e32 v32, s17
	ds_read_b32 v196, v32
	v_add_u32_e32 v252, s20, v241
	s_cmp_lt_u32 s16, 0xfffffe0d
	s_mov_b64 s[16:17], -1
	v_add_u32_e32 v251, 0xffffff80, v252
	v_add_u32_e32 v250, 0xffffff81, v252
	v_add_u32_e32 v249, 0xffffff82, v252
	v_add_u32_e32 v248, 0xffffff83, v252
	v_add_u32_e32 v229, 0xffffff90, v252
	v_add_u32_e32 v228, 0xffffff91, v252
	v_add_u32_e32 v227, 0xffffff92, v252
	v_add_u32_e32 v230, 0xffffff93, v252
	v_add_u32_e32 v222, 0xffffffa0, v252
	v_add_u32_e32 v195, 0xffffffa1, v252
	v_add_u32_e32 v194, 0xffffffa2, v252
	v_add_u32_e32 v225, 0xffffffa3, v252
	s_cbranch_scc1 .LBB0_1954
	v_med3_i32 v32, v251, s2, v223
	v_med3_i32 v33, v250, s2, v223
	v_med3_i32 v34, v249, s2, v223
	v_med3_i32 v35, v248, s2, v223
	v_med3_i32 v36, v229, s2, v223
	v_med3_i32 v37, v228, s2, v223
	v_med3_i32 v38, v227, s2, v223
	v_med3_i32 v39, v230, s2, v223
	v_med3_i32 v40, v222, s2, v223
	v_med3_i32 v41, v195, s2, v223
	v_med3_i32 v42, v194, s2, v223
	v_med3_i32 v43, v225, s2, v223
	v_add_u32_e32 v44, 0xffffffb0, v252
	v_add_u32_e32 v45, 0xffffffb1, v252
	v_add_u32_e32 v46, 0xffffffb2, v252
	v_add_u32_e32 v47, 0xffffffb3, v252
	v_lshl_add_u32 v32, v32, 2, 16
	v_lshl_add_u32 v33, v33, 2, 16
	v_lshl_add_u32 v34, v34, 2, 16
	v_lshl_add_u32 v35, v35, 2, 16
	v_lshl_add_u32 v36, v36, 2, 16
	v_lshl_add_u32 v37, v37, 2, 16
	v_lshl_add_u32 v38, v38, 2, 16
	v_lshl_add_u32 v39, v39, 2, 16
	v_lshl_add_u32 v40, v40, 2, 16
	v_lshl_add_u32 v41, v41, 2, 16
	v_lshl_add_u32 v42, v42, 2, 16
	v_lshl_add_u32 v43, v43, 2, 16
	v_med3_i32 v44, v44, s2, v223
	v_med3_i32 v45, v45, s2, v223
	v_med3_i32 v46, v46, s2, v223
	v_med3_i32 v47, v47, s2, v223
	ds_read_b32 v32, v32 offset:64000
	ds_read_b32 v33, v33 offset:64000
	ds_read_b32 v34, v34 offset:64000
	ds_read_b32 v35, v35 offset:64000
	ds_read_b32 v36, v36 offset:64000
	ds_read_b32 v37, v37 offset:64000
	ds_read_b32 v38, v38 offset:64000
	ds_read_b32 v39, v39 offset:64000
	v_lshl_add_u32 v44, v44, 2, 16
	v_lshl_add_u32 v45, v45, 2, 16
	v_lshl_add_u32 v46, v46, 2, 16
	v_lshl_add_u32 v47, v47, 2, 16
	ds_read_b32 v40, v40 offset:64000
	ds_read_b32 v41, v41 offset:64000
	ds_read_b32 v42, v42 offset:64000
	ds_read_b32 v43, v43 offset:64000
	ds_read_b32 v202, v44 offset:64000
	ds_read_b32 v203, v45 offset:64000
	ds_read_b32 v204, v46 offset:64000
	ds_read_b32 v205, v47 offset:64000
	s_waitcnt lgkmcnt(12)
	v_pk_fma_f32 v[34:35], v[190:191], s[22:23], v[34:35] op_sel_hi:[1,0,1]
	v_pk_fma_f32 v[32:33], v[188:189], s[22:23], v[32:33] op_sel_hi:[1,0,1]
	s_waitcnt lgkmcnt(8)
	v_pk_fma_f32 v[46:47], v[186:187], s[22:23], v[38:39] op_sel_hi:[1,0,1]
	v_pk_fma_f32 v[44:45], v[184:185], s[22:23], v[36:37] op_sel_hi:[1,0,1]
	s_waitcnt lgkmcnt(4)
	v_pk_fma_f32 v[42:43], v[182:183], s[22:23], v[42:43] op_sel_hi:[1,0,1]
	v_pk_fma_f32 v[40:41], v[180:181], s[22:23], v[40:41] op_sel_hi:[1,0,1]
	s_waitcnt lgkmcnt(0)
	v_pk_fma_f32 v[38:39], v[178:179], s[22:23], v[204:205] op_sel_hi:[1,0,1]
	v_pk_fma_f32 v[36:37], v[176:177], s[22:23], v[202:203] op_sel_hi:[1,0,1]
	s_mov_b64 s[16:17], 0

; DI float max3_(float a, float b, float c) { float r; asm("v_max3_f32 %0, %1, %2, %3" : "=v"(r) : "v"(a), "v"(b), "v"(c)); return r; }
; template <int DQK, bool BIAS>
; __device__ __forceinline__ void attn_pass(const hf* __restrict__ Q, int ldq, const hf* __restrict__ Kp, int ldk, const hf* __restrict__ VT,
;                                           int s0, int L, int q0, float scale_l2, const float* sBias, f4 (&oacc)[8][4], char* smem) {
;     ...
; #pragma unroll
;           for (int mk = 0; mk < 4; ++mk)
; #pragma unroll
;             for (int j = 0; j < 4; ++j) {
;               int rel = (key0 + mk * 16 + fq * 4 + j) - (q0 + wv * 64 + nq * 16 + fr);
;               rel = min(max(rel, -128), 128);
;               sacc[mk][nq][j] = sacc[mk][nq][j] * scale_l2 + sBias[rel + 128];
;             }
;         }
;       }
;       float mx = -1e30f;
; #pragma unroll
;       for (int mk = 0; mk < 4; ++mk) { mx = max3_(mx, sacc[mk][nq][0], sacc[mk][nq][1]); mx = max3_(mx, sacc[mk][nq][2], sacc[mk][nq][3]); }
;       mx = max3_(mx, shx(mx, 16), mx); mx = max3_(mx, shx(mx, 32), mx);
;       if (!BIAS) mx *= scale_l2;
;       const bool upd = mx > mrun[nq] + 8.f;
;       const float mnew = upd ? mx : mrun[nq];
;       if (__builtin_amdgcn_ballot_w64(upd) != 0) {
;         const float alpha = __builtin_amdgcn_exp2f(mrun[nq] - mnew);
;         lrun[nq] *= alpha;
; #pragma unroll
;         for (int md = 0; md < 8; ++md) { oacc[md][nq][0] *= alpha; oacc[md][nq][1] *= alpha; oacc[md][nq][2] *= alpha; oacc[md][nq][3] *= alpha; }
;       }
;       mrun[nq] = mnew;
.LBB0_1956:
	v_max3_f32 v176, v199, v32, v33
	s_nop 0
	v_max3_f32 v176, v176, v34, v35
	s_nop 0
	v_max3_f32 v176, v176, v44, v45
	s_nop 0
	v_max3_f32 v176, v176, v46, v47
	s_nop 0
	v_max3_f32 v176, v176, v40, v41
	s_nop 0
	v_max3_f32 v176, v176, v42, v43
	s_nop 0
	v_max3_f32 v176, v176, v36, v37
	s_nop 0
	v_max3_f32 v176, v176, v38, v39
	v_mov_b32_e32 v177, v176
	s_nop 1
	v_permlane16_swap_b32_e32 v177, v176
	v_max_f32_e32 v176, v176, v177
	v_mov_b32_e32 v177, v176
	s_nop 1
	v_permlane32_swap_b32_e32 v177, v176
	v_max_f32_e32 v176, v176, v177
	v_add_f32_e32 v177, 0x41000000, v198
	v_cmp_gt_f32_e32 vcc, v176, v177
	s_nop 1
	v_cndmask_b32_e32 v176, v198, v176, vcc
	s_cbranch_vccz .LBB0_1958
	v_accvgpr_read_b32 v55, a95
	v_accvgpr_read_b32 v51, a107
	v_accvgpr_read_b32 v56, a76
	v_accvgpr_read_b32 v60, a64
	v_accvgpr_read_b32 v64, a44
	v_accvgpr_read_b32 v72, a24
	v_accvgpr_read_b32 v68, a8
	v_accvgpr_read_b32 v76, a0
	v_accvgpr_read_b32 v50, a106
	v_accvgpr_read_b32 v49, a105
	v_accvgpr_read_b32 v48, a104
	v_accvgpr_read_b32 v54, a94
	v_accvgpr_read_b32 v53, a93
	v_accvgpr_read_b32 v52, a92
	v_accvgpr_read_b32 v57, a77
	v_accvgpr_read_b32 v58, a78
	v_accvgpr_read_b32 v59, a79
	v_accvgpr_read_b32 v61, a65
	v_accvgpr_read_b32 v62, a66
	v_accvgpr_read_b32 v63, a67
	v_accvgpr_read_b32 v65, a45
	v_accvgpr_read_b32 v66, a46
	v_accvgpr_read_b32 v67, a47
	v_accvgpr_read_b32 v73, a25
	v_accvgpr_read_b32 v74, a26
	v_accvgpr_read_b32 v75, a27
	v_accvgpr_read_b32 v69, a9
	v_accvgpr_read_b32 v70, a10
	v_accvgpr_read_b32 v71, a11
	v_accvgpr_read_b32 v77, a1
	v_accvgpr_read_b32 v78, a2
	v_accvgpr_read_b32 v79, a3
	v_sub_f32_e32 v177, v198, v176
	v_exp_f32_e32 v178, v177
	s_nop 0
	v_pk_mul_f32 v[76:77], v[76:77], v[178:179] op_sel_hi:[1,0]
	v_pk_mul_f32 v[68:69], v[68:69], v[178:179] op_sel_hi:[1,0]
	v_pk_mul_f32 v[72:73], v[72:73], v[178:179] op_sel_hi:[1,0]
	v_pk_mul_f32 v[64:65], v[64:65], v[178:179] op_sel_hi:[1,0]
	v_pk_mul_f32 v[60:61], v[60:61], v[178:179] op_sel_hi:[1,0]
	v_pk_mul_f32 v[56:57], v[56:57], v[178:179] op_sel_hi:[1,0]
	v_pk_mul_f32 v[54:55], v[54:55], v[178:179] op_sel_hi:[1,0]
	v_pk_mul_f32 v[50:51], v[50:51], v[178:179] op_sel_hi:[1,0]
	v_pk_mul_f32 v[78:79], v[78:79], v[178:179] op_sel_hi:[1,0]
	v_pk_mul_f32 v[70:71], v[70:71], v[178:179] op_sel_hi:[1,0]
	v_pk_mul_f32 v[74:75], v[74:75], v[178:179] op_sel_hi:[1,0]
	v_pk_mul_f32 v[66:67], v[66:67], v[178:179] op_sel_hi:[1,0]
	v_pk_mul_f32 v[62:63], v[62:63], v[178:179] op_sel_hi:[1,0]
	v_pk_mul_f32 v[58:59], v[58:59], v[178:179] op_sel_hi:[1,0]
	v_pk_mul_f32 v[52:53], v[52:53], v[178:179] op_sel_hi:[1,0]
	v_pk_mul_f32 v[48:49], v[48:49], v[178:179] op_sel_hi:[1,0]
	v_accvgpr_write_b32 a95, v55
	v_accvgpr_write_b32 a107, v51
	v_accvgpr_write_b32 a76, v56
	v_accvgpr_write_b32 a64, v60
	v_accvgpr_write_b32 a44, v64
	v_accvgpr_write_b32 a24, v72
	v_accvgpr_write_b32 a8, v68
	v_accvgpr_write_b32 a0, v76
	v_mul_f32_e32 v245, v245, v178
	v_accvgpr_write_b32 a106, v50
	v_accvgpr_write_b32 a105, v49
	v_accvgpr_write_b32 a104, v48
	v_accvgpr_write_b32 a94, v54
	v_accvgpr_write_b32 a93, v53
	v_accvgpr_write_b32 a92, v52
	v_accvgpr_write_b32 a77, v57
	v_accvgpr_write_b32 a78, v58
	v_accvgpr_write_b32 a79, v59
	v_accvgpr_write_b32 a65, v61
	v_accvgpr_write_b32 a66, v62
	v_accvgpr_write_b32 a67, v63
	v_accvgpr_write_b32 a45, v65
	v_accvgpr_write_b32 a46, v66
	v_accvgpr_write_b32 a47, v67
	v_accvgpr_write_b32 a25, v73
	v_accvgpr_write_b32 a26, v74
	v_accvgpr_write_b32 a27, v75
	v_accvgpr_write_b32 a9, v69
	v_accvgpr_write_b32 a10, v70
	v_accvgpr_write_b32 a11, v71
	v_accvgpr_write_b32 a1, v77
	v_accvgpr_write_b32 a2, v78
	v_accvgpr_write_b32 a3, v79
.LBB0_1958:
	v_cndmask_b32_e64 v80, 0, 1, s[26:27]
	s_mov_b64 s[70:71], -1
	v_cmp_ne_u32_e64 s[16:17], 1, v80
	s_andn2_b64 vcc, exec, s[26:27]
	v_add_u32_e32 v180, 0xffffff70, v252
	v_add_u32_e32 v179, 0xffffff71, v252
	v_add_u32_e32 v178, 0xffffff72, v252
	v_add_u32_e32 v177, 0xffffff73, v252
	s_cbranch_vccnz .LBB0_1960
	v_med3_i32 v80, v180, s2, v223
	v_med3_i32 v81, v179, s2, v223
	v_med3_i32 v82, v178, s2, v223
	v_med3_i32 v83, v177, s2, v223
	v_med3_i32 v84, v251, s2, v223
	v_med3_i32 v85, v250, s2, v223
	v_med3_i32 v86, v249, s2, v223
	v_med3_i32 v87, v248, s2, v223
	v_med3_i32 v88, v229, s2, v223
	v_med3_i32 v89, v228, s2, v223
	v_med3_i32 v90, v227, s2, v223
	v_med3_i32 v91, v230, s2, v223
	v_lshl_add_u32 v80, v80, 2, 16
	v_lshl_add_u32 v81, v81, 2, 16
	v_lshl_add_u32 v82, v82, 2, 16
	v_lshl_add_u32 v83, v83, 2, 16
	v_lshl_add_u32 v84, v84, 2, 16
	v_lshl_add_u32 v85, v85, 2, 16
	v_lshl_add_u32 v86, v86, 2, 16
	v_lshl_add_u32 v87, v87, 2, 16
	v_lshl_add_u32 v88, v88, 2, 16
	v_lshl_add_u32 v89, v89, 2, 16
	v_lshl_add_u32 v90, v90, 2, 16
	v_lshl_add_u32 v91, v91, 2, 16
	v_med3_i32 v92, v222, s2, v223
	v_med3_i32 v93, v195, s2, v223
	v_med3_i32 v94, v194, s2, v223
	v_med3_i32 v95, v225, s2, v223
	ds_read_b32 v80, v80 offset:64000
	ds_read_b32 v81, v81 offset:64000
	ds_read_b32 v82, v82 offset:64000
	ds_read_b32 v83, v83 offset:64000
	ds_read_b32 v84, v84 offset:64000
	ds_read_b32 v85, v85 offset:64000
	ds_read_b32 v86, v86 offset:64000
	ds_read_b32 v87, v87 offset:64000
	v_lshl_add_u32 v92, v92, 2, 16
	v_lshl_add_u32 v93, v93, 2, 16
	v_lshl_add_u32 v94, v94, 2, 16
	v_lshl_add_u32 v95, v95, 2, 16
	ds_read_b32 v88, v88 offset:64000
	ds_read_b32 v89, v89 offset:64000
	ds_read_b32 v90, v90 offset:64000
	ds_read_b32 v91, v91 offset:64000
	ds_read_b32 v182, v92 offset:64000
	ds_read_b32 v183, v93 offset:64000
	ds_read_b32 v184, v94 offset:64000
	ds_read_b32 v185, v95 offset:64000
	s_waitcnt lgkmcnt(12)
	v_pk_fma_f32 v[82:83], v[174:175], s[22:23], v[82:83] op_sel_hi:[1,0,1]
	v_pk_fma_f32 v[80:81], v[172:173], s[22:23], v[80:81] op_sel_hi:[1,0,1]
	s_waitcnt lgkmcnt(8)
	v_pk_fma_f32 v[94:95], v[170:171], s[22:23], v[86:87] op_sel_hi:[1,0,1]
	v_pk_fma_f32 v[92:93], v[168:169], s[22:23], v[84:85] op_sel_hi:[1,0,1]
	s_waitcnt lgkmcnt(4)
	v_pk_fma_f32 v[86:87], v[166:167], s[22:23], v[90:91] op_sel_hi:[1,0,1]
	v_pk_fma_f32 v[84:85], v[164:165], s[22:23], v[88:89] op_sel_hi:[1,0,1]
	s_waitcnt lgkmcnt(0)
	v_pk_fma_f32 v[90:91], v[162:163], s[22:23], v[184:185] op_sel_hi:[1,0,1]
	v_pk_fma_f32 v[88:89], v[160:161], s[22:23], v[182:183] op_sel_hi:[1,0,1]
	s_mov_b64 s[70:71], 0

; DI float max3_(float a, float b, float c) { float r; asm("v_max3_f32 %0, %1, %2, %3" : "=v"(r) : "v"(a), "v"(b), "v"(c)); return r; }
; template <int DQK, bool BIAS>
; __device__ __forceinline__ void attn_pass(const hf* __restrict__ Q, int ldq, const hf* __restrict__ Kp, int ldk, const hf* __restrict__ VT,
;                                           int s0, int L, int q0, float scale_l2, const float* sBias, f4 (&oacc)[8][4], char* smem) {
;     ...
; #pragma unroll
;           for (int mk = 0; mk < 4; ++mk)
; #pragma unroll
;             for (int j = 0; j < 4; ++j) {
;               int rel = (key0 + mk * 16 + fq * 4 + j) - (q0 + wv * 64 + nq * 16 + fr);
;               rel = min(max(rel, -128), 128);
;               sacc[mk][nq][j] = sacc[mk][nq][j] * scale_l2 + sBias[rel + 128];
;             }
;         }
;       }
;       float mx = -1e30f;
; #pragma unroll
;       for (int mk = 0; mk < 4; ++mk) { mx = max3_(mx, sacc[mk][nq][0], sacc[mk][nq][1]); mx = max3_(mx, sacc[mk][nq][2], sacc[mk][nq][3]); }
;       mx = max3_(mx, shx(mx, 16), mx); mx = max3_(mx, shx(mx, 32), mx);
;       if (!BIAS) mx *= scale_l2;
;       const bool upd = mx > mrun[nq] + 8.f;
;       const float mnew = upd ? mx : mrun[nq];
;       if (__builtin_amdgcn_ballot_w64(upd) != 0) {
;         const float alpha = __builtin_amdgcn_exp2f(mrun[nq] - mnew);
;         lrun[nq] *= alpha;
; #pragma unroll
;         for (int md = 0; md < 8; ++md) { oacc[md][nq][0] *= alpha; oacc[md][nq][1] *= alpha; oacc[md][nq][2] *= alpha; oacc[md][nq][3] *= alpha; }
;       }
;       mrun[nq] = mnew;
.LBB0_1962:
	v_max3_f32 v160, v199, v80, v81
	s_nop 0
	v_max3_f32 v160, v160, v82, v83
	s_nop 0
	v_max3_f32 v160, v160, v92, v93
	s_nop 0
	v_max3_f32 v160, v160, v94, v95
	s_nop 0
	v_max3_f32 v160, v160, v84, v85
	s_nop 0
	v_max3_f32 v160, v160, v86, v87
	s_nop 0
	v_max3_f32 v160, v160, v88, v89
	s_nop 0
	v_max3_f32 v160, v160, v90, v91
	v_mov_b32_e32 v161, v160
	s_nop 1
	v_permlane16_swap_b32_e32 v161, v160
	v_max_f32_e32 v160, v160, v161
	v_mov_b32_e32 v161, v160
	s_nop 1
	v_permlane32_swap_b32_e32 v161, v160
	v_max_f32_e32 v160, v160, v161
	v_add_f32_e32 v161, 0x41000000, v253
	v_cmp_gt_f32_e32 vcc, v160, v161
	s_nop 1
	v_cndmask_b32_e32 v160, v253, v160, vcc
	s_cbranch_vccz .LBB0_1964
	v_accvgpr_read_b32 v52, a100
	v_accvgpr_read_b32 v48, a116
	v_accvgpr_read_b32 v56, a84
	v_accvgpr_read_b32 v60, a68
	v_accvgpr_read_b32 v64, a52
	v_accvgpr_read_b32 v72, a36
	v_accvgpr_read_b32 v68, a16
	v_accvgpr_read_b32 v76, a4
	v_accvgpr_read_b32 v49, a117
	v_accvgpr_read_b32 v50, a118
	v_accvgpr_read_b32 v51, a119
	v_accvgpr_read_b32 v53, a101
	v_accvgpr_read_b32 v54, a102
	v_accvgpr_read_b32 v55, a103
	v_accvgpr_read_b32 v57, a85
	v_accvgpr_read_b32 v58, a86
	v_accvgpr_read_b32 v59, a87
	v_accvgpr_read_b32 v61, a69
	v_accvgpr_read_b32 v62, a70
	v_accvgpr_read_b32 v63, a71
	v_accvgpr_read_b32 v65, a53
	v_accvgpr_read_b32 v66, a54
	v_accvgpr_read_b32 v67, a55
	v_accvgpr_read_b32 v73, a37
	v_accvgpr_read_b32 v74, a38
	v_accvgpr_read_b32 v75, a39
	v_accvgpr_read_b32 v69, a17
	v_accvgpr_read_b32 v70, a18
	v_accvgpr_read_b32 v71, a19
	v_accvgpr_read_b32 v77, a5
	v_accvgpr_read_b32 v78, a6
	v_accvgpr_read_b32 v79, a7
	v_sub_f32_e32 v161, v253, v160
	v_exp_f32_e32 v162, v161
	s_nop 0
	v_pk_mul_f32 v[76:77], v[76:77], v[162:163] op_sel_hi:[1,0]
	v_pk_mul_f32 v[68:69], v[68:69], v[162:163] op_sel_hi:[1,0]
	v_pk_mul_f32 v[72:73], v[72:73], v[162:163] op_sel_hi:[1,0]
	v_pk_mul_f32 v[64:65], v[64:65], v[162:163] op_sel_hi:[1,0]
	v_pk_mul_f32 v[60:61], v[60:61], v[162:163] op_sel_hi:[1,0]
	v_pk_mul_f32 v[56:57], v[56:57], v[162:163] op_sel_hi:[1,0]
	v_pk_mul_f32 v[52:53], v[52:53], v[162:163] op_sel_hi:[1,0]
	v_pk_mul_f32 v[48:49], v[48:49], v[162:163] op_sel_hi:[1,0]
	v_pk_mul_f32 v[78:79], v[78:79], v[162:163] op_sel_hi:[1,0]
	v_pk_mul_f32 v[70:71], v[70:71], v[162:163] op_sel_hi:[1,0]
	v_pk_mul_f32 v[74:75], v[74:75], v[162:163] op_sel_hi:[1,0]
	v_pk_mul_f32 v[66:67], v[66:67], v[162:163] op_sel_hi:[1,0]
	v_pk_mul_f32 v[62:63], v[62:63], v[162:163] op_sel_hi:[1,0]
	v_pk_mul_f32 v[58:59], v[58:59], v[162:163] op_sel_hi:[1,0]
	v_pk_mul_f32 v[54:55], v[54:55], v[162:163] op_sel_hi:[1,0]
	v_pk_mul_f32 v[50:51], v[50:51], v[162:163] op_sel_hi:[1,0]
	v_accvgpr_write_b32 a100, v52
	v_accvgpr_write_b32 a116, v48
	v_accvgpr_write_b32 a84, v56
	v_accvgpr_write_b32 a68, v60
	v_accvgpr_write_b32 a52, v64
	v_accvgpr_write_b32 a36, v72
	v_accvgpr_write_b32 a16, v68
	v_accvgpr_write_b32 a4, v76
	v_mul_f32_e32 v243, v243, v162
	v_accvgpr_write_b32 a117, v49
	v_accvgpr_write_b32 a118, v50
	v_accvgpr_write_b32 a119, v51
	v_accvgpr_write_b32 a101, v53
	v_accvgpr_write_b32 a102, v54
	v_accvgpr_write_b32 a103, v55
	v_accvgpr_write_b32 a85, v57
	v_accvgpr_write_b32 a86, v58
	v_accvgpr_write_b32 a87, v59
	v_accvgpr_write_b32 a69, v61
	v_accvgpr_write_b32 a70, v62
	v_accvgpr_write_b32 a71, v63
	v_accvgpr_write_b32 a53, v65
	v_accvgpr_write_b32 a54, v66
	v_accvgpr_write_b32 a55, v67
	v_accvgpr_write_b32 a37, v73
	v_accvgpr_write_b32 a38, v74
	v_accvgpr_write_b32 a39, v75
	v_accvgpr_write_b32 a17, v69
	v_accvgpr_write_b32 a18, v70
	v_accvgpr_write_b32 a19, v71
	v_accvgpr_write_b32 a5, v77
	v_accvgpr_write_b32 a6, v78
	v_accvgpr_write_b32 a7, v79
.LBB0_1964:
	s_and_b64 vcc, exec, s[16:17]
	s_mov_b64 s[26:27], -1
	s_cbranch_vccnz .LBB0_1966
	v_add_u32_e32 v128, 0xffffff60, v252
	v_add_u32_e32 v129, 0xffffff61, v252
	v_add_u32_e32 v130, 0xffffff62, v252
	v_add_u32_e32 v131, 0xffffff63, v252
	v_med3_i32 v128, v128, s2, v223
	v_med3_i32 v129, v129, s2, v223
	v_med3_i32 v130, v130, s2, v223
	v_med3_i32 v131, v131, s2, v223
	v_med3_i32 v132, v180, s2, v223
	v_med3_i32 v133, v179, s2, v223
	v_med3_i32 v134, v178, s2, v223
	v_med3_i32 v135, v177, s2, v223
	v_med3_i32 v136, v251, s2, v223
	v_med3_i32 v137, v250, s2, v223
	v_med3_i32 v138, v249, s2, v223
	v_med3_i32 v139, v248, s2, v223
	v_lshl_add_u32 v128, v128, 2, 16
	v_lshl_add_u32 v129, v129, 2, 16
	v_lshl_add_u32 v130, v130, 2, 16
	v_lshl_add_u32 v131, v131, 2, 16
	v_lshl_add_u32 v132, v132, 2, 16
	v_lshl_add_u32 v133, v133, 2, 16
	v_lshl_add_u32 v134, v134, 2, 16
	v_lshl_add_u32 v135, v135, 2, 16
	v_lshl_add_u32 v136, v136, 2, 16
	v_lshl_add_u32 v137, v137, 2, 16
	v_lshl_add_u32 v138, v138, 2, 16
	v_lshl_add_u32 v139, v139, 2, 16
	v_med3_i32 v140, v229, s2, v223
	v_med3_i32 v141, v228, s2, v223
	v_med3_i32 v142, v227, s2, v223
	v_med3_i32 v143, v230, s2, v223
	ds_read_b32 v128, v128 offset:64000
	ds_read_b32 v129, v129 offset:64000
	ds_read_b32 v130, v130 offset:64000
	ds_read_b32 v131, v131 offset:64000
	ds_read_b32 v132, v132 offset:64000
	ds_read_b32 v133, v133 offset:64000
	ds_read_b32 v134, v134 offset:64000
	ds_read_b32 v135, v135 offset:64000
	v_lshl_add_u32 v140, v140, 2, 16
	v_lshl_add_u32 v141, v141, 2, 16
	v_lshl_add_u32 v142, v142, 2, 16
	v_lshl_add_u32 v143, v143, 2, 16
	ds_read_b32 v136, v136 offset:64000
	ds_read_b32 v137, v137 offset:64000
	ds_read_b32 v138, v138 offset:64000
	ds_read_b32 v139, v139 offset:64000
	ds_read_b32 v162, v140 offset:64000
	ds_read_b32 v163, v141 offset:64000
	ds_read_b32 v164, v142 offset:64000
	ds_read_b32 v165, v143 offset:64000
	s_waitcnt lgkmcnt(12)
	v_pk_fma_f32 v[130:131], v[158:159], s[22:23], v[130:131] op_sel_hi:[1,0,1]
	v_pk_fma_f32 v[128:129], v[156:157], s[22:23], v[128:129] op_sel_hi:[1,0,1]
	s_waitcnt lgkmcnt(8)
	v_pk_fma_f32 v[142:143], v[154:155], s[22:23], v[134:135] op_sel_hi:[1,0,1]
	v_pk_fma_f32 v[140:141], v[152:153], s[22:23], v[132:133] op_sel_hi:[1,0,1]
	s_waitcnt lgkmcnt(4)
	v_pk_fma_f32 v[138:139], v[150:151], s[22:23], v[138:139] op_sel_hi:[1,0,1]
	v_pk_fma_f32 v[136:137], v[148:149], s[22:23], v[136:137] op_sel_hi:[1,0,1]
	s_waitcnt lgkmcnt(0)
	v_pk_fma_f32 v[134:135], v[146:147], s[22:23], v[164:165] op_sel_hi:[1,0,1]
	v_pk_fma_f32 v[132:133], v[144:145], s[22:23], v[162:163] op_sel_hi:[1,0,1]
	s_mov_b64 s[26:27], 0

; DI float max3_(float a, float b, float c) { float r; asm("v_max3_f32 %0, %1, %2, %3" : "=v"(r) : "v"(a), "v"(b), "v"(c)); return r; }
; template <int DQK, bool BIAS>
; __device__ __forceinline__ void attn_pass(const hf* __restrict__ Q, int ldq, const hf* __restrict__ Kp, int ldk, const hf* __restrict__ VT,
;                                           int s0, int L, int q0, float scale_l2, const float* sBias, f4 (&oacc)[8][4], char* smem) {
;     ...
; #pragma unroll
;           for (int mk = 0; mk < 4; ++mk)
; #pragma unroll
;             for (int j = 0; j < 4; ++j) {
;               int rel = (key0 + mk * 16 + fq * 4 + j) - (q0 + wv * 64 + nq * 16 + fr);
;               rel = min(max(rel, -128), 128);
;               sacc[mk][nq][j] = sacc[mk][nq][j] * scale_l2 + sBias[rel + 128];
;             }
;         }
;       }
;       float mx = -1e30f;
; #pragma unroll
;       for (int mk = 0; mk < 4; ++mk) { mx = max3_(mx, sacc[mk][nq][0], sacc[mk][nq][1]); mx = max3_(mx, sacc[mk][nq][2], sacc[mk][nq][3]); }
;       mx = max3_(mx, shx(mx, 16), mx); mx = max3_(mx, shx(mx, 32), mx);
;       if (!BIAS) mx *= scale_l2;
;       const bool upd = mx > mrun[nq] + 8.f;
;       const float mnew = upd ? mx : mrun[nq];
;       if (__builtin_amdgcn_ballot_w64(upd) != 0) {
;         const float alpha = __builtin_amdgcn_exp2f(mrun[nq] - mnew);
;         lrun[nq] *= alpha;
; #pragma unroll
;         for (int md = 0; md < 8; ++md) { oacc[md][nq][0] *= alpha; oacc[md][nq][1] *= alpha; oacc[md][nq][2] *= alpha; oacc[md][nq][3] *= alpha; }
;       }
;       mrun[nq] = mnew;
.LBB0_1968:
	v_max3_f32 v144, v199, v128, v129
	s_nop 0
	v_max3_f32 v144, v144, v130, v131
	s_nop 0
	v_max3_f32 v144, v144, v140, v141
	s_nop 0
	v_max3_f32 v144, v144, v142, v143
	s_nop 0
	v_max3_f32 v144, v144, v136, v137
	s_nop 0
	v_max3_f32 v144, v144, v138, v139
	s_nop 0
	v_max3_f32 v144, v144, v132, v133
	s_nop 0
	v_max3_f32 v144, v144, v134, v135
	v_mov_b32_e32 v145, v144
	s_nop 1
	v_permlane16_swap_b32_e32 v145, v144
	v_max_f32_e32 v144, v144, v145
	v_mov_b32_e32 v145, v144
	s_nop 1
	v_permlane32_swap_b32_e32 v145, v144
	v_max_f32_e32 v144, v144, v145
	v_add_f32_e32 v145, 0x41000000, v247
	v_cmp_gt_f32_e32 vcc, v144, v145
	s_nop 1
	v_cndmask_b32_e32 v144, v247, v144, vcc
	s_cbranch_vccz .LBB0_1970
	v_accvgpr_read_b32 v55, a111
	v_accvgpr_read_b32 v51, a123
	v_accvgpr_read_b32 v56, a88
	v_accvgpr_read_b32 v60, a72
	v_accvgpr_read_b32 v64, a56
	v_accvgpr_read_b32 v72, a40
	v_accvgpr_read_b32 v68, a28
	v_accvgpr_read_b32 v76, a12
	v_accvgpr_read_b32 v50, a122
	v_accvgpr_read_b32 v49, a121
	v_accvgpr_read_b32 v48, a120
	v_accvgpr_read_b32 v54, a110
	v_accvgpr_read_b32 v53, a109
	v_accvgpr_read_b32 v52, a108
	v_accvgpr_read_b32 v57, a89
	v_accvgpr_read_b32 v58, a90
	v_accvgpr_read_b32 v59, a91
	v_accvgpr_read_b32 v61, a73
	v_accvgpr_read_b32 v62, a74
	v_accvgpr_read_b32 v63, a75
	v_accvgpr_read_b32 v65, a57
	v_accvgpr_read_b32 v66, a58
	v_accvgpr_read_b32 v67, a59
	v_accvgpr_read_b32 v73, a41
	v_accvgpr_read_b32 v74, a42
	v_accvgpr_read_b32 v75, a43
	v_accvgpr_read_b32 v69, a29
	v_accvgpr_read_b32 v70, a30
	v_accvgpr_read_b32 v71, a31
	v_accvgpr_read_b32 v77, a13
	v_accvgpr_read_b32 v78, a14
	v_accvgpr_read_b32 v79, a15
	v_sub_f32_e32 v145, v247, v144
	v_exp_f32_e32 v146, v145
	s_nop 0
	v_pk_mul_f32 v[76:77], v[76:77], v[146:147] op_sel_hi:[1,0]
	v_pk_mul_f32 v[68:69], v[68:69], v[146:147] op_sel_hi:[1,0]
	v_pk_mul_f32 v[72:73], v[72:73], v[146:147] op_sel_hi:[1,0]
	v_pk_mul_f32 v[64:65], v[64:65], v[146:147] op_sel_hi:[1,0]
	v_pk_mul_f32 v[60:61], v[60:61], v[146:147] op_sel_hi:[1,0]
	v_pk_mul_f32 v[56:57], v[56:57], v[146:147] op_sel_hi:[1,0]
	v_pk_mul_f32 v[54:55], v[54:55], v[146:147] op_sel_hi:[1,0]
	v_pk_mul_f32 v[50:51], v[50:51], v[146:147] op_sel_hi:[1,0]
	v_pk_mul_f32 v[78:79], v[78:79], v[146:147] op_sel_hi:[1,0]
	v_pk_mul_f32 v[70:71], v[70:71], v[146:147] op_sel_hi:[1,0]
	v_pk_mul_f32 v[74:75], v[74:75], v[146:147] op_sel_hi:[1,0]
	v_pk_mul_f32 v[66:67], v[66:67], v[146:147] op_sel_hi:[1,0]
	v_pk_mul_f32 v[62:63], v[62:63], v[146:147] op_sel_hi:[1,0]
	v_pk_mul_f32 v[58:59], v[58:59], v[146:147] op_sel_hi:[1,0]
	v_pk_mul_f32 v[52:53], v[52:53], v[146:147] op_sel_hi:[1,0]
	v_pk_mul_f32 v[48:49], v[48:49], v[146:147] op_sel_hi:[1,0]
	v_accvgpr_write_b32 a111, v55
	v_accvgpr_write_b32 a123, v51
	v_accvgpr_write_b32 a88, v56
	v_accvgpr_write_b32 a72, v60
	v_accvgpr_write_b32 a56, v64
	v_accvgpr_write_b32 a40, v72
	v_accvgpr_write_b32 a28, v68
	v_accvgpr_write_b32 a12, v76
	v_mul_f32_e32 v242, v242, v146
	v_accvgpr_write_b32 a122, v50
	v_accvgpr_write_b32 a121, v49
	v_accvgpr_write_b32 a120, v48
	v_accvgpr_write_b32 a110, v54
	v_accvgpr_write_b32 a109, v53
	v_accvgpr_write_b32 a108, v52
	v_accvgpr_write_b32 a89, v57
	v_accvgpr_write_b32 a90, v58
	v_accvgpr_write_b32 a91, v59
	v_accvgpr_write_b32 a73, v61
	v_accvgpr_write_b32 a74, v62
	v_accvgpr_write_b32 a75, v63
	v_accvgpr_write_b32 a57, v65
	v_accvgpr_write_b32 a58, v66
	v_accvgpr_write_b32 a59, v67
	v_accvgpr_write_b32 a41, v73
	v_accvgpr_write_b32 a42, v74
	v_accvgpr_write_b32 a43, v75
	v_accvgpr_write_b32 a29, v69
	v_accvgpr_write_b32 a30, v70
	v_accvgpr_write_b32 a31, v71
	v_accvgpr_write_b32 a13, v77
	v_accvgpr_write_b32 a14, v78
	v_accvgpr_write_b32 a15, v79
.LBB0_1970:
	s_and_b64 vcc, exec, s[16:17]
	s_mov_b64 s[16:17], -1
	s_cbranch_vccnz .LBB0_1972
	v_add_u32_e32 v96, 0xffffff50, v252
	s_movk_i32 s16, 0xff7f
	v_mov_b32_e32 v98, 0x7f
	v_med3_i32 v98, v96, s16, v98
	s_movk_i32 s16, 0xff7e
	v_mov_b32_e32 v99, 0x7e
	v_med3_i32 v99, v96, s16, v99
	s_movk_i32 s16, 0xff7d
	v_mov_b32_e32 v100, 0x7d
	v_med3_i32 v100, v96, s16, v100
	s_movk_i32 s16, 0xff70
	v_mov_b32_e32 v101, 0x70
	v_med3_i32 v101, v96, s16, v101
	s_movk_i32 s16, 0xff6f
	v_mov_b32_e32 v102, 0x6f
	v_med3_i32 v102, v96, s16, v102
	s_movk_i32 s16, 0xff6e
	v_mov_b32_e32 v103, 0x6e
	v_mov_b32_e32 v104, 0x6d
	v_med3_i32 v108, v251, s2, v223
	v_med3_i32 v97, v96, s2, v223
	v_med3_i32 v103, v96, s16, v103
	v_med3_i32 v96, v96, s82, v104
	v_lshl_add_u32 v145, v108, 2, 16
	v_med3_i32 v108, v250, s2, v223
	v_lshl_add_u32 v97, v97, 2, 16
	v_lshl_add_u32 v98, v98, 2, 16
	v_lshl_add_u32 v99, v99, 2, 16
	v_lshl_add_u32 v100, v100, 2, 16
	v_lshl_add_u32 v101, v101, 2, 16
	v_lshl_add_u32 v102, v102, 2, 16
	v_lshl_add_u32 v103, v103, 2, 16
	v_lshl_add_u32 v104, v96, 2, 16
	v_lshl_add_u32 v147, v108, 2, 16
	v_med3_i32 v108, v249, s2, v223
	ds_read_b32 v96, v97 offset:64000
	ds_read_b32 v97, v98 offset:64004
	ds_read_b32 v98, v99 offset:64008
	ds_read_b32 v99, v100 offset:64012
	ds_read_b32 v100, v101 offset:64064
	ds_read_b32 v101, v102 offset:64068
	ds_read_b32 v102, v103 offset:64072
	ds_read_b32 v103, v104 offset:64076
	v_med3_i32 v104, v180, s2, v223
	v_lshl_add_u32 v148, v108, 2, 16
	v_med3_i32 v108, v248, s2, v223
	v_lshl_add_u32 v104, v104, 2, 16
	v_med3_i32 v105, v179, s2, v223
	v_med3_i32 v106, v178, s2, v223
	v_med3_i32 v107, v177, s2, v223
	v_lshl_add_u32 v149, v108, 2, 16
	v_lshl_add_u32 v105, v105, 2, 16
	v_lshl_add_u32 v106, v106, 2, 16
	v_lshl_add_u32 v107, v107, 2, 16
	ds_read_b32 v108, v104 offset:64000
	ds_read_b32 v109, v105 offset:64000
	ds_read_b32 v110, v106 offset:64000
	ds_read_b32 v111, v107 offset:64000
	ds_read_b32 v146, v145 offset:64000
	ds_read_b32 v147, v147 offset:64000
	ds_read_b32 v148, v148 offset:64000
	ds_read_b32 v149, v149 offset:64000
	s_waitcnt lgkmcnt(12)
	v_pk_fma_f32 v[98:99], v[126:127], s[22:23], v[98:99] op_sel_hi:[1,0,1]
	v_pk_fma_f32 v[96:97], v[124:125], s[22:23], v[96:97] op_sel_hi:[1,0,1]
	s_waitcnt lgkmcnt(8)
	v_pk_fma_f32 v[106:107], v[122:123], s[22:23], v[102:103] op_sel_hi:[1,0,1]
	v_pk_fma_f32 v[104:105], v[120:121], s[22:23], v[100:101] op_sel_hi:[1,0,1]
	s_waitcnt lgkmcnt(4)
	v_pk_fma_f32 v[102:103], v[118:119], s[22:23], v[110:111] op_sel_hi:[1,0,1]
	v_pk_fma_f32 v[100:101], v[116:117], s[22:23], v[108:109] op_sel_hi:[1,0,1]
	s_waitcnt lgkmcnt(0)
	v_pk_fma_f32 v[110:111], v[114:115], s[22:23], v[148:149] op_sel_hi:[1,0,1]
	v_pk_fma_f32 v[108:109], v[112:113], s[22:23], v[146:147] op_sel_hi:[1,0,1]
	s_mov_b64 s[16:17], 0

; DI float max3_(float a, float b, float c) { float r; asm("v_max3_f32 %0, %1, %2, %3" : "=v"(r) : "v"(a), "v"(b), "v"(c)); return r; }
; template <int DQK, bool BIAS>
; __device__ __forceinline__ void attn_pass(const hf* __restrict__ Q, int ldq, const hf* __restrict__ Kp, int ldk, const hf* __restrict__ VT,
;                                           int s0, int L, int q0, float scale_l2, const float* sBias, f4 (&oacc)[8][4], char* smem) {
;     ...
;       float mx = -1e30f;
; #pragma unroll
;       for (int mk = 0; mk < 4; ++mk) { mx = max3_(mx, sacc[mk][nq][0], sacc[mk][nq][1]); mx = max3_(mx, sacc[mk][nq][2], sacc[mk][nq][3]); }
;       mx = max3_(mx, shx(mx, 16), mx); mx = max3_(mx, shx(mx, 32), mx);
;       if (!BIAS) mx *= scale_l2;
;       const bool upd = mx > mrun[nq] + 8.f;
;       const float mnew = upd ? mx : mrun[nq];
;       if (__builtin_amdgcn_ballot_w64(upd) != 0) {
;         const float alpha = __builtin_amdgcn_exp2f(mrun[nq] - mnew);
;         lrun[nq] *= alpha;
; #pragma unroll
;         for (int md = 0; md < 8; ++md) { oacc[md][nq][0] *= alpha; oacc[md][nq][1] *= alpha; oacc[md][nq][2] *= alpha; oacc[md][nq][3] *= alpha; }
;       }
;       mrun[nq] = mnew;
.LBB0_1974:
	v_max3_f32 v112, v199, v96, v97
	s_nop 0
	v_max3_f32 v112, v112, v98, v99
	s_nop 0
	v_max3_f32 v112, v112, v104, v105
	s_nop 0
	v_max3_f32 v112, v112, v106, v107
	s_nop 0
	v_max3_f32 v112, v112, v100, v101
	s_nop 0
	v_max3_f32 v112, v112, v102, v103
	s_nop 0
	v_max3_f32 v112, v112, v108, v109
	s_nop 0
	v_max3_f32 v112, v112, v110, v111
	v_mov_b32_e32 v113, v112
	s_nop 1
	v_permlane16_swap_b32_e32 v113, v112
	v_max_f32_e32 v112, v112, v113
	v_mov_b32_e32 v113, v112
	s_nop 1
	v_permlane32_swap_b32_e32 v113, v112
	v_max_f32_e32 v112, v112, v113
	v_add_f32_e32 v113, 0x41000000, v246
	v_cmp_gt_f32_e32 vcc, v112, v113
	s_nop 1
	v_cndmask_b32_e32 v112, v246, v112, vcc
	s_cbranch_vccz .LBB0_1976
	v_accvgpr_read_b32 v55, a115
	v_accvgpr_read_b32 v51, a127
	v_accvgpr_read_b32 v59, a99
	v_accvgpr_read_b32 v63, a83
	v_accvgpr_read_b32 v64, a60
	v_accvgpr_read_b32 v72, a48
	v_accvgpr_read_b32 v68, a32
	v_accvgpr_read_b32 v76, a20
	v_accvgpr_read_b32 v50, a126
	v_accvgpr_read_b32 v49, a125
	v_accvgpr_read_b32 v48, a124
	v_accvgpr_read_b32 v54, a114
	v_accvgpr_read_b32 v53, a113
	v_accvgpr_read_b32 v52, a112
	v_accvgpr_read_b32 v58, a98
	v_accvgpr_read_b32 v57, a97
	v_accvgpr_read_b32 v56, a96
	v_accvgpr_read_b32 v62, a82
	v_accvgpr_read_b32 v61, a81
	v_accvgpr_read_b32 v60, a80
	v_accvgpr_read_b32 v65, a61
	v_accvgpr_read_b32 v66, a62
	v_accvgpr_read_b32 v67, a63
	v_accvgpr_read_b32 v73, a49
	v_accvgpr_read_b32 v74, a50
	v_accvgpr_read_b32 v75, a51
	v_accvgpr_read_b32 v69, a33
	v_accvgpr_read_b32 v70, a34
	v_accvgpr_read_b32 v71, a35
	v_accvgpr_read_b32 v77, a21
	v_accvgpr_read_b32 v78, a22
	v_accvgpr_read_b32 v79, a23
	v_sub_f32_e32 v113, v246, v112
	v_exp_f32_e32 v114, v113
	s_nop 0
	v_pk_mul_f32 v[76:77], v[76:77], v[114:115] op_sel_hi:[1,0]
	v_pk_mul_f32 v[68:69], v[68:69], v[114:115] op_sel_hi:[1,0]
	v_pk_mul_f32 v[72:73], v[72:73], v[114:115] op_sel_hi:[1,0]
	v_pk_mul_f32 v[64:65], v[64:65], v[114:115] op_sel_hi:[1,0]
	v_pk_mul_f32 v[62:63], v[62:63], v[114:115] op_sel_hi:[1,0]
	v_pk_mul_f32 v[58:59], v[58:59], v[114:115] op_sel_hi:[1,0]
	v_pk_mul_f32 v[54:55], v[54:55], v[114:115] op_sel_hi:[1,0]
	v_pk_mul_f32 v[50:51], v[50:51], v[114:115] op_sel_hi:[1,0]
	v_pk_mul_f32 v[78:79], v[78:79], v[114:115] op_sel_hi:[1,0]
	v_pk_mul_f32 v[70:71], v[70:71], v[114:115] op_sel_hi:[1,0]
	v_pk_mul_f32 v[74:75], v[74:75], v[114:115] op_sel_hi:[1,0]
	v_pk_mul_f32 v[66:67], v[66:67], v[114:115] op_sel_hi:[1,0]
	v_pk_mul_f32 v[60:61], v[60:61], v[114:115] op_sel_hi:[1,0]
	v_pk_mul_f32 v[56:57], v[56:57], v[114:115] op_sel_hi:[1,0]
	v_pk_mul_f32 v[52:53], v[52:53], v[114:115] op_sel_hi:[1,0]
	v_pk_mul_f32 v[48:49], v[48:49], v[114:115] op_sel_hi:[1,0]
	v_accvgpr_write_b32 a115, v55
	v_accvgpr_write_b32 a127, v51
	v_accvgpr_write_b32 a99, v59
	v_accvgpr_write_b32 a83, v63
	v_accvgpr_write_b32 a60, v64
	v_accvgpr_write_b32 a48, v72
	v_accvgpr_write_b32 a32, v68
	v_accvgpr_write_b32 a20, v76
	v_mul_f32_e32 v233, v233, v114
	v_accvgpr_write_b32 a126, v50
	v_accvgpr_write_b32 a125, v49
	v_accvgpr_write_b32 a124, v48
	v_accvgpr_write_b32 a114, v54
	v_accvgpr_write_b32 a113, v53
	v_accvgpr_write_b32 a112, v52
	v_accvgpr_write_b32 a98, v58
	v_accvgpr_write_b32 a97, v57
	v_accvgpr_write_b32 a96, v56
	v_accvgpr_write_b32 a82, v62
	v_accvgpr_write_b32 a81, v61
	v_accvgpr_write_b32 a80, v60
	v_accvgpr_write_b32 a61, v65
	v_accvgpr_write_b32 a62, v66
	v_accvgpr_write_b32 a63, v67
	v_accvgpr_write_b32 a49, v73
	v_accvgpr_write_b32 a50, v74
	v_accvgpr_write_b32 a51, v75
	v_accvgpr_write_b32 a33, v69
	v_accvgpr_write_b32 a34, v70
	v_accvgpr_write_b32 a35, v71
	v_accvgpr_write_b32 a21, v77
	v_accvgpr_write_b32 a22, v78
	v_accvgpr_write_b32 a23, v79

; DI f4 mfma16(h8 a, h8 b, f4 c) { return __builtin_amdgcn_mfma_f32_16x16x32_f16(a, b, c, 0, 0, 0); }
; template <int DQK, bool BIAS>
; __device__ __forceinline__ void attn_pass(const hf* __restrict__ Q, int ldq, const hf* __restrict__ Kp, int ldk, const hf* __restrict__ VT,
;                                           int s0, int L, int q0, float scale_l2, const float* sBias, f4 (&oacc)[8][4], char* smem) {
;     ...
; #pragma unroll
;     for (int mk = 0; mk < 4; ++mk) {
;       h8 kf[NKS];
; #pragma unroll
;       for (int ks = 0; ks < NKS; ++ks) kf[ks] = *(const h8*)(sK + (mk * 16 + fr) * KS + ks * 32 + (fq ^ (((fr >> 2) ^ (fr >> 3)) & 1)) * 8);
; #pragma unroll
;       for (int nq = 0; nq < 4; ++nq) {
;         f4 a = {0.f, 0.f, 0.f, 0.f};
; #pragma unroll
;         for (int ks = 0; ks < NKS; ++ks) a = mfma16(kf[ks], qf[nq][ks], a);
;         sacc[mk][nq] = a;
;       }
;     }
;     if (kt + 1 < nkt) storeKV((kt + 1) & 1);
.LBB0_1994:
	s_bitcmp1_b32 s19, 0
	s_cselect_b32 s14, 0x7c00, 0
	s_add_i32 s15, s14, 16
	v_add3_u32 v64, s15, v208, v233
	ds_read_b128 v[48:51], v64
	ds_read_b128 v[52:55], v64 offset:64
	ds_read_b128 v[56:59], v64 offset:128
	ds_read_b128 v[60:63], v64 offset:3328
	s_waitcnt lgkmcnt(3)
	v_mfma_f32_16x16x32_f16 a[128:131], v[48:51], v[0:3], 0
	s_waitcnt lgkmcnt(2)
	v_mfma_f32_16x16x32_f16 a[128:131], v[52:55], v[4:7], a[128:131]
	s_waitcnt lgkmcnt(1)
	v_mfma_f32_16x16x32_f16 a[168:171], v[56:59], v[8:11], a[128:131]
	v_mfma_f32_16x16x32_f16 a[128:131], v[48:51], v[24:27], 0
	v_mfma_f32_16x16x32_f16 a[128:131], v[52:55], v[28:31], a[128:131]
	v_mfma_f32_16x16x32_f16 a[132:135], v[48:51], v[12:15], 0
	v_mfma_f32_16x16x32_f16 a[144:147], v[56:59], v[32:35], a[128:131]
	v_mfma_f32_16x16x32_f16 a[128:131], v[48:51], v[36:39], 0
	ds_read_b128 v[48:51], v64 offset:3392
	v_mfma_f32_16x16x32_f16 a[132:135], v[52:55], v[16:19], a[132:135]
	v_mfma_f32_16x16x32_f16 a[128:131], v[52:55], v[40:43], a[128:131]
	ds_read_b128 v[52:55], v64 offset:3456
	v_mfma_f32_16x16x32_f16 a[160:163], v[56:59], v[20:23], a[132:135]
	s_add_i32 s14, s19, 1
	s_waitcnt lgkmcnt(2)
	v_mfma_f32_16x16x32_f16 a[132:135], v[60:63], v[0:3], 0
	s_waitcnt lgkmcnt(1)
	v_mfma_f32_16x16x32_f16 a[132:135], v[48:51], v[4:7], a[132:135]
	s_waitcnt lgkmcnt(0)
	v_mfma_f32_16x16x32_f16 a[176:179], v[52:55], v[8:11], a[132:135]
	v_mfma_f32_16x16x32_f16 a[132:135], v[60:63], v[12:15], 0
	v_mfma_f32_16x16x32_f16 a[132:135], v[48:51], v[16:19], a[132:135]
	v_mfma_f32_16x16x32_f16 a[164:167], v[52:55], v[20:23], a[132:135]
	v_mfma_f32_16x16x32_f16 a[132:135], v[60:63], v[24:27], 0
	v_mfma_f32_16x16x32_f16 a[132:135], v[48:51], v[28:31], a[132:135]
	v_mfma_f32_16x16x32_f16 a[148:151], v[52:55], v[32:35], a[132:135]
	v_mfma_f32_16x16x32_f16 a[132:135], v[60:63], v[36:39], 0
	v_mfma_f32_16x16x32_f16 a[132:135], v[48:51], v[40:43], a[132:135]
	ds_read_b128 v[48:51], v64 offset:6656
	v_mfma_f32_16x16x32_f16 a[132:135], v[52:55], v[44:47], a[132:135]
	ds_read_b128 v[52:55], v64 offset:6720
	s_waitcnt lgkmcnt(1)
	v_mfma_f32_16x16x32_f16 a[136:139], v[48:51], v[0:3], 0
	v_mfma_f32_16x16x32_f16 a[128:131], v[56:59], v[44:47], a[128:131]
	ds_read_b128 v[56:59], v64 offset:6784
	ds_read_b128 v[60:63], v64 offset:9984
	s_waitcnt lgkmcnt(2)
	v_mfma_f32_16x16x32_f16 a[136:139], v[52:55], v[4:7], a[136:139]
	s_waitcnt lgkmcnt(1)
	v_mfma_f32_16x16x32_f16 a[184:187], v[56:59], v[8:11], a[136:139]
	v_mfma_f32_16x16x32_f16 a[136:139], v[48:51], v[12:15], 0
	v_mfma_f32_16x16x32_f16 a[136:139], v[52:55], v[16:19], a[136:139]
	v_mfma_f32_16x16x32_f16 a[172:175], v[56:59], v[20:23], a[136:139]
	v_mfma_f32_16x16x32_f16 a[136:139], v[48:51], v[24:27], 0
	v_mfma_f32_16x16x32_f16 a[136:139], v[52:55], v[28:31], a[136:139]
	v_mfma_f32_16x16x32_f16 a[152:155], v[56:59], v[32:35], a[136:139]
	v_mfma_f32_16x16x32_f16 a[136:139], v[48:51], v[36:39], 0
	ds_read_b128 v[48:51], v64 offset:10048
	v_mfma_f32_16x16x32_f16 a[136:139], v[52:55], v[40:43], a[136:139]
	ds_read_b128 v[52:55], v64 offset:10112
	s_waitcnt lgkmcnt(2)
	v_mfma_f32_16x16x32_f16 a[140:143], v[60:63], v[0:3], 0
	s_waitcnt lgkmcnt(1)
	v_mfma_f32_16x16x32_f16 a[140:143], v[48:51], v[4:7], a[140:143]
	s_waitcnt lgkmcnt(0)
	v_mfma_f32_16x16x32_f16 a[188:191], v[52:55], v[8:11], a[140:143]
	v_mfma_f32_16x16x32_f16 a[140:143], v[60:63], v[12:15], 0
	v_mfma_f32_16x16x32_f16 a[140:143], v[48:51], v[16:19], a[140:143]
	v_mfma_f32_16x16x32_f16 a[180:183], v[52:55], v[20:23], a[140:143]
	v_mfma_f32_16x16x32_f16 a[140:143], v[60:63], v[24:27], 0
	v_mfma_f32_16x16x32_f16 a[140:143], v[48:51], v[28:31], a[140:143]
	v_mfma_f32_16x16x32_f16 a[156:159], v[52:55], v[32:35], a[140:143]
	v_mfma_f32_16x16x32_f16 a[140:143], v[60:63], v[36:39], 0
	s_cmp_ge_u32 s14, s18
	v_mfma_f32_16x16x32_f16 a[140:143], v[48:51], v[40:43], a[140:143]
	v_mfma_f32_16x16x32_f16 a[136:139], v[56:59], v[44:47], a[136:139]
	v_mfma_f32_16x16x32_f16 a[140:143], v[52:55], v[44:47], a[140:143]
	s_cbranch_scc1 .LBB0_1996
	s_bitcmp1_b32 s14, 0
	s_cselect_b32 s27, 0x7c00, 0
	s_add_i32 s27, s27, 16
	v_add3_u32 v48, s27, v213, v238
	s_waitcnt vmcnt(6)
	ds_write_b128 v48, v[246:249]
	s_waitcnt vmcnt(1)
	ds_write_b128 v48, a[196:199] offset:64
	s_waitcnt vmcnt(0)
	ds_write_b128 v48, a[204:207] offset:128
	v_add3_u32 v48, s27, v229, v212
	ds_write_b128 v48, v[250:253] offset:13312
	v_add3_u32 v48, s27, v230, v212
	ds_write_b128 v48, a[192:195] offset:13312
	v_add3_u32 v48, s27, v231, v212
	ds_write_b128 v48, a[200:203] offset:13312
	v_add3_u32 v48, s27, v232, v212
	ds_write_b128 v48, a[208:211] offset:13312

; DI float max3_(float a, float b, float c) { float r; asm("v_max3_f32 %0, %1, %2, %3" : "=v"(r) : "v"(a), "v"(b), "v"(c)); return r; }
; template <int DQK, bool BIAS>
; __device__ __forceinline__ void attn_pass(const hf* __restrict__ Q, int ldq, const hf* __restrict__ Kp, int ldk, const hf* __restrict__ VT,
;                                           int s0, int L, int q0, float scale_l2, const float* sBias, f4 (&oacc)[8][4], char* smem) {
;     ...
;       float mx = -1e30f;
; #pragma unroll
;       for (int mk = 0; mk < 4; ++mk) { mx = max3_(mx, sacc[mk][nq][0], sacc[mk][nq][1]); mx = max3_(mx, sacc[mk][nq][2], sacc[mk][nq][3]); }
;       mx = max3_(mx, shx(mx, 16), mx); mx = max3_(mx, shx(mx, 32), mx);
;       if (!BIAS) mx *= scale_l2;
;       const bool upd = mx > mrun[nq] + 8.f;
;       const float mnew = upd ? mx : mrun[nq];
;       if (__builtin_amdgcn_ballot_w64(upd) != 0) {
;         const float alpha = __builtin_amdgcn_exp2f(mrun[nq] - mnew);
;         lrun[nq] *= alpha;
; #pragma unroll
;         for (int md = 0; md < 8; ++md) { oacc[md][nq][0] *= alpha; oacc[md][nq][1] *= alpha; oacc[md][nq][2] *= alpha; oacc[md][nq][3] *= alpha; }
;       }
;       mrun[nq] = mnew;
.LBB0_1998:
	v_accvgpr_read_b32 v68, a168
	v_accvgpr_read_b32 v69, a169
	v_max3_f32 v48, v226, v68, v69
	v_accvgpr_read_b32 v70, a170
	v_accvgpr_read_b32 v71, a171
	v_accvgpr_read_b32 v64, a176
	v_max3_f32 v48, v48, v70, v71
	v_accvgpr_read_b32 v65, a177
	v_max3_f32 v48, v48, v64, v65
	v_accvgpr_read_b32 v66, a178
	v_accvgpr_read_b32 v67, a179
	v_accvgpr_read_b32 v60, a184
	v_max3_f32 v48, v48, v66, v67
	v_accvgpr_read_b32 v61, a185
	v_max3_f32 v48, v48, v60, v61
	v_accvgpr_read_b32 v62, a186
	v_accvgpr_read_b32 v63, a187
	v_accvgpr_read_b32 v56, a188
	v_max3_f32 v48, v48, v62, v63
	v_accvgpr_read_b32 v57, a189
	v_max3_f32 v48, v48, v56, v57
	v_accvgpr_read_b32 v58, a190
	v_accvgpr_read_b32 v59, a191
	v_max3_f32 v48, v48, v58, v59
	v_mov_b32_e32 v50, v224
	v_mov_b32_e32 v49, v48
	v_mov_b32_e32 v210, v48
	s_nop 1
	v_permlane16_swap_b32_e32 v49, v210
	v_max_f32_e32 v210, v49, v210
	v_mov_b32_e32 v211, v210
	v_mov_b32_e32 v49, v210
	s_nop 1
	v_permlane32_swap_b32_e32 v211, v49
	v_max_f32_e32 v210, v211, v49
	v_accvgpr_read_b32 v80, a160
	v_add_f32_e32 v211, 0x41000000, v225
	v_mul_f32_e32 v210, 0x3e16c740, v210
	v_accvgpr_read_b32 v72, a164
	v_accvgpr_read_b32 v52, a172
	v_accvgpr_read_b32 v48, a180
	v_cmp_gt_f32_e32 vcc, v210, v211
	v_accvgpr_read_b32 v81, a161
	v_accvgpr_read_b32 v82, a162
	v_accvgpr_read_b32 v83, a163
	v_accvgpr_read_b32 v73, a165
	v_accvgpr_read_b32 v74, a166
	v_accvgpr_read_b32 v75, a167
	v_accvgpr_read_b32 v53, a173
	v_accvgpr_read_b32 v54, a174
	v_accvgpr_read_b32 v55, a175
	v_accvgpr_read_b32 v49, a181
	v_accvgpr_read_b32 v50, a182
	v_accvgpr_read_b32 v51, a183
	v_cndmask_b32_e32 v241, v225, v210, vcc
	s_cbranch_vccz .LBB0_2000
	v_accvgpr_read_b32 v164, a92
	v_accvgpr_read_b32 v160, a108
	v_accvgpr_read_b32 v168, a76
	v_accvgpr_read_b32 v172, a64
	v_accvgpr_read_b32 v192, a40
	v_accvgpr_read_b32 v196, a28
	v_accvgpr_read_b32 v200, a8
	v_accvgpr_read_b32 v204, a0
	v_accvgpr_read_b32 v161, a109
	v_accvgpr_read_b32 v162, a110
	v_accvgpr_read_b32 v163, a111
	v_accvgpr_read_b32 v165, a93
	v_accvgpr_read_b32 v166, a94
	v_accvgpr_read_b32 v167, a95
	v_accvgpr_read_b32 v169, a77
	v_accvgpr_read_b32 v170, a78
	v_accvgpr_read_b32 v171, a79
	v_accvgpr_read_b32 v173, a65
	v_accvgpr_read_b32 v174, a66
	v_accvgpr_read_b32 v175, a67
	v_accvgpr_read_b32 v193, a41
	v_accvgpr_read_b32 v194, a42
	v_accvgpr_read_b32 v195, a43
	v_accvgpr_read_b32 v197, a29
	v_accvgpr_read_b32 v198, a30
	v_accvgpr_read_b32 v199, a31
	v_accvgpr_read_b32 v201, a9
	v_accvgpr_read_b32 v202, a10
	v_accvgpr_read_b32 v203, a11
	v_accvgpr_read_b32 v205, a1
	v_accvgpr_read_b32 v206, a2
	v_accvgpr_read_b32 v207, a3
	v_sub_f32_e32 v210, v225, v241
	v_exp_f32_e32 v210, v210
	s_nop 0
	v_pk_mul_f32 v[204:205], v[204:205], v[210:211] op_sel_hi:[1,0]
	v_pk_mul_f32 v[200:201], v[200:201], v[210:211] op_sel_hi:[1,0]
	v_pk_mul_f32 v[196:197], v[196:197], v[210:211] op_sel_hi:[1,0]
	v_pk_mul_f32 v[192:193], v[192:193], v[210:211] op_sel_hi:[1,0]
	v_pk_mul_f32 v[172:173], v[172:173], v[210:211] op_sel_hi:[1,0]
	v_pk_mul_f32 v[168:169], v[168:169], v[210:211] op_sel_hi:[1,0]
	v_pk_mul_f32 v[164:165], v[164:165], v[210:211] op_sel_hi:[1,0]
	v_pk_mul_f32 v[160:161], v[160:161], v[210:211] op_sel_hi:[1,0]
	v_pk_mul_f32 v[206:207], v[206:207], v[210:211] op_sel_hi:[1,0]
	v_pk_mul_f32 v[202:203], v[202:203], v[210:211] op_sel_hi:[1,0]
	v_pk_mul_f32 v[198:199], v[198:199], v[210:211] op_sel_hi:[1,0]
	v_pk_mul_f32 v[194:195], v[194:195], v[210:211] op_sel_hi:[1,0]
	v_pk_mul_f32 v[174:175], v[174:175], v[210:211] op_sel_hi:[1,0]
	v_pk_mul_f32 v[170:171], v[170:171], v[210:211] op_sel_hi:[1,0]
	v_pk_mul_f32 v[166:167], v[166:167], v[210:211] op_sel_hi:[1,0]
	v_pk_mul_f32 v[162:163], v[162:163], v[210:211] op_sel_hi:[1,0]
	v_accvgpr_write_b32 a92, v164
	v_accvgpr_write_b32 a108, v160
	v_accvgpr_write_b32 a76, v168
	v_accvgpr_write_b32 a64, v172
	v_accvgpr_write_b32 a40, v192
	v_accvgpr_write_b32 a28, v196
	v_accvgpr_write_b32 a8, v200
	v_accvgpr_write_b32 a0, v204
	v_mul_f32_e32 v240, v240, v210
	v_accvgpr_write_b32 a109, v161
	v_accvgpr_write_b32 a110, v162
	v_accvgpr_write_b32 a111, v163
	v_accvgpr_write_b32 a93, v165
	v_accvgpr_write_b32 a94, v166
	v_accvgpr_write_b32 a95, v167
	v_accvgpr_write_b32 a77, v169
	v_accvgpr_write_b32 a78, v170
	v_accvgpr_write_b32 a79, v171
	v_accvgpr_write_b32 a65, v173
	v_accvgpr_write_b32 a66, v174
	v_accvgpr_write_b32 a67, v175
	v_accvgpr_write_b32 a41, v193
	v_accvgpr_write_b32 a42, v194
	v_accvgpr_write_b32 a43, v195
	v_accvgpr_write_b32 a29, v197
	v_accvgpr_write_b32 a30, v198
	v_accvgpr_write_b32 a31, v199
	v_accvgpr_write_b32 a9, v201
	v_accvgpr_write_b32 a10, v202
	v_accvgpr_write_b32 a11, v203
	v_accvgpr_write_b32 a1, v205
	v_accvgpr_write_b32 a2, v206
	v_accvgpr_write_b32 a3, v207
; DI float max3_(float a, float b, float c) { float r; asm("v_max3_f32 %0, %1, %2, %3" : "=v"(r) : "v"(a), "v"(b), "v"(c)); return r; }
; template <int DQK, bool BIAS>
; __device__ __forceinline__ void attn_pass(const hf* __restrict__ Q, int ldq, const hf* __restrict__ Kp, int ldk, const hf* __restrict__ VT,
;                                           int s0, int L, int q0, float scale_l2, const float* sBias, f4 (&oacc)[8][4], char* smem) {
;     ...
;       float mx = -1e30f;
; #pragma unroll
;       for (int mk = 0; mk < 4; ++mk) { mx = max3_(mx, sacc[mk][nq][0], sacc[mk][nq][1]); mx = max3_(mx, sacc[mk][nq][2], sacc[mk][nq][3]); }
;       mx = max3_(mx, shx(mx, 16), mx); mx = max3_(mx, shx(mx, 32), mx);
;       if (!BIAS) mx *= scale_l2;
;       const bool upd = mx > mrun[nq] + 8.f;
;       const float mnew = upd ? mx : mrun[nq];
;       if (__builtin_amdgcn_ballot_w64(upd) != 0) {
;         const float alpha = __builtin_amdgcn_exp2f(mrun[nq] - mnew);
;         lrun[nq] *= alpha;
; #pragma unroll
;         for (int md = 0; md < 8; ++md) { oacc[md][nq][0] *= alpha; oacc[md][nq][1] *= alpha; oacc[md][nq][2] *= alpha; oacc[md][nq][3] *= alpha; }
;       }
;       mrun[nq] = mnew;
.LBB0_2000:
	v_max3_f32 v160, v226, v80, v81
	v_mov_b32_e32 v162, v224
	v_max3_f32 v160, v160, v82, v83
	v_accvgpr_read_b32 v175, a147
	v_max3_f32 v160, v160, v72, v73
	v_lshlrev_b32_e32 v162, 2, v162
	v_max3_f32 v160, v160, v74, v75
	v_bitop3_b32 v162, v162, s23, v227 bitop3:0x6c
	v_max3_f32 v160, v160, v52, v53
	v_accvgpr_read_b32 v171, a151
	v_max3_f32 v160, v160, v54, v55
	v_accvgpr_read_b32 v167, a155
	v_max3_f32 v160, v160, v48, v49
	v_accvgpr_read_b32 v174, a146
	v_max3_f32 v160, v160, v50, v51
	v_mov_b32_e32 v161, v160
	v_mov_b32_e32 v192, v160
	s_nop 1
	v_permlane16_swap_b32_e32 v161, v192
	v_max_f32_e32 v192, v161, v192
	v_mov_b32_e32 v193, v192
	v_mov_b32_e32 v161, v192
	s_nop 1
	v_permlane32_swap_b32_e32 v193, v161
	v_max_f32_e32 v192, v193, v161
	v_add_f32_e32 v193, 0x41000000, v244
	v_mul_f32_e32 v192, 0x3e16c740, v192
	v_accvgpr_read_b32 v163, a159
	v_cmp_gt_f32_e32 vcc, v192, v193
	v_accvgpr_read_b32 v173, a145
	v_accvgpr_read_b32 v172, a144
	v_accvgpr_read_b32 v170, a150
	v_accvgpr_read_b32 v169, a149
	v_accvgpr_read_b32 v168, a148
	v_accvgpr_read_b32 v166, a154
	v_accvgpr_read_b32 v165, a153
	v_accvgpr_read_b32 v164, a152
	v_accvgpr_read_b32 v162, a158
	v_accvgpr_read_b32 v161, a157
	v_accvgpr_read_b32 v160, a156
	v_cndmask_b32_e32 v192, v244, v192, vcc
	s_cbranch_vccz .LBB0_2002
	v_accvgpr_read_b32 v87, a103
	v_accvgpr_read_b32 v79, a119
	v_accvgpr_read_b32 v104, a84
	v_accvgpr_read_b32 v124, a68
	v_accvgpr_read_b32 v176, a48
	v_accvgpr_read_b32 v180, a32
	v_accvgpr_read_b32 v184, a16
	v_accvgpr_read_b32 v188, a4
	v_accvgpr_read_b32 v78, a118
	v_accvgpr_read_b32 v77, a117
	v_accvgpr_read_b32 v76, a116
	v_accvgpr_read_b32 v86, a102
	v_accvgpr_read_b32 v85, a101
	v_accvgpr_read_b32 v84, a100
	v_accvgpr_read_b32 v105, a85
	v_accvgpr_read_b32 v106, a86
	v_accvgpr_read_b32 v107, a87
	v_accvgpr_read_b32 v125, a69
	v_accvgpr_read_b32 v126, a70
	v_accvgpr_read_b32 v127, a71
	v_accvgpr_read_b32 v177, a49
	v_accvgpr_read_b32 v178, a50
	v_accvgpr_read_b32 v179, a51
	v_accvgpr_read_b32 v181, a33
	v_accvgpr_read_b32 v182, a34
	v_accvgpr_read_b32 v183, a35
	v_accvgpr_read_b32 v185, a17
	v_accvgpr_read_b32 v186, a18
	v_accvgpr_read_b32 v187, a19
	v_accvgpr_read_b32 v189, a5
	v_accvgpr_read_b32 v190, a6
	v_accvgpr_read_b32 v191, a7
	v_sub_f32_e32 v193, v244, v192
	v_exp_f32_e32 v194, v193
	s_nop 0
	v_pk_mul_f32 v[188:189], v[188:189], v[194:195] op_sel_hi:[1,0]
	v_pk_mul_f32 v[184:185], v[184:185], v[194:195] op_sel_hi:[1,0]
	v_pk_mul_f32 v[180:181], v[180:181], v[194:195] op_sel_hi:[1,0]
	v_pk_mul_f32 v[176:177], v[176:177], v[194:195] op_sel_hi:[1,0]
	v_pk_mul_f32 v[124:125], v[124:125], v[194:195] op_sel_hi:[1,0]
	v_pk_mul_f32 v[104:105], v[104:105], v[194:195] op_sel_hi:[1,0]
	v_pk_mul_f32 v[86:87], v[86:87], v[194:195] op_sel_hi:[1,0]
	v_pk_mul_f32 v[78:79], v[78:79], v[194:195] op_sel_hi:[1,0]
	v_pk_mul_f32 v[190:191], v[190:191], v[194:195] op_sel_hi:[1,0]
	v_pk_mul_f32 v[186:187], v[186:187], v[194:195] op_sel_hi:[1,0]
	v_pk_mul_f32 v[182:183], v[182:183], v[194:195] op_sel_hi:[1,0]
	v_pk_mul_f32 v[178:179], v[178:179], v[194:195] op_sel_hi:[1,0]
	v_pk_mul_f32 v[126:127], v[126:127], v[194:195] op_sel_hi:[1,0]
	v_pk_mul_f32 v[106:107], v[106:107], v[194:195] op_sel_hi:[1,0]
	v_pk_mul_f32 v[84:85], v[84:85], v[194:195] op_sel_hi:[1,0]
	v_pk_mul_f32 v[76:77], v[76:77], v[194:195] op_sel_hi:[1,0]
	v_accvgpr_write_b32 a103, v87
	v_accvgpr_write_b32 a119, v79
	v_accvgpr_write_b32 a84, v104
	v_accvgpr_write_b32 a68, v124
	v_accvgpr_write_b32 a48, v176
	v_accvgpr_write_b32 a32, v180
	v_accvgpr_write_b32 a16, v184
	v_accvgpr_write_b32 a4, v188
	v_mul_f32_e32 v237, v237, v194
	v_accvgpr_write_b32 a118, v78
	v_accvgpr_write_b32 a117, v77
	v_accvgpr_write_b32 a116, v76
	v_accvgpr_write_b32 a102, v86
	v_accvgpr_write_b32 a101, v85
	v_accvgpr_write_b32 a100, v84
	v_accvgpr_write_b32 a85, v105
	v_accvgpr_write_b32 a86, v106
	v_accvgpr_write_b32 a87, v107
	v_accvgpr_write_b32 a69, v125
	v_accvgpr_write_b32 a70, v126
	v_accvgpr_write_b32 a71, v127
	v_accvgpr_write_b32 a49, v177
	v_accvgpr_write_b32 a50, v178
	v_accvgpr_write_b32 a51, v179
	v_accvgpr_write_b32 a33, v181
	v_accvgpr_write_b32 a34, v182
	v_accvgpr_write_b32 a35, v183
	v_accvgpr_write_b32 a17, v185
	v_accvgpr_write_b32 a18, v186
	v_accvgpr_write_b32 a19, v187
	v_accvgpr_write_b32 a5, v189
	v_accvgpr_write_b32 a6, v190
	v_accvgpr_write_b32 a7, v191
; DI float max3_(float a, float b, float c) { float r; asm("v_max3_f32 %0, %1, %2, %3" : "=v"(r) : "v"(a), "v"(b), "v"(c)); return r; }
; template <int DQK, bool BIAS>
; __device__ __forceinline__ void attn_pass(const hf* __restrict__ Q, int ldq, const hf* __restrict__ Kp, int ldk, const hf* __restrict__ VT,
;                                           int s0, int L, int q0, float scale_l2, const float* sBias, f4 (&oacc)[8][4], char* smem) {
;     ...
;       float mx = -1e30f;
; #pragma unroll
;       for (int mk = 0; mk < 4; ++mk) { mx = max3_(mx, sacc[mk][nq][0], sacc[mk][nq][1]); mx = max3_(mx, sacc[mk][nq][2], sacc[mk][nq][3]); }
;       mx = max3_(mx, shx(mx, 16), mx); mx = max3_(mx, shx(mx, 32), mx);
;       if (!BIAS) mx *= scale_l2;
;       const bool upd = mx > mrun[nq] + 8.f;
;       const float mnew = upd ? mx : mrun[nq];
;       if (__builtin_amdgcn_ballot_w64(upd) != 0) {
;         const float alpha = __builtin_amdgcn_exp2f(mrun[nq] - mnew);
;         lrun[nq] *= alpha;
; #pragma unroll
;         for (int md = 0; md < 8; ++md) { oacc[md][nq][0] *= alpha; oacc[md][nq][1] *= alpha; oacc[md][nq][2] *= alpha; oacc[md][nq][3] *= alpha; }
;       }
;       mrun[nq] = mnew;
.LBB0_2002:
	v_max3_f32 v76, v226, v172, v173
	v_mov_b32_e32 v78, v224
	v_max3_f32 v76, v76, v174, v175
	v_accvgpr_read_b32 v124, a128
	v_max3_f32 v76, v76, v168, v169
	v_lshlrev_b32_e32 v78, 2, v78
	v_max3_f32 v76, v76, v170, v171
	v_bitop3_b32 v78, v78, s23, v227 bitop3:0x6c
	v_max3_f32 v76, v76, v164, v165
	v_accvgpr_read_b32 v104, a132
	v_max3_f32 v76, v76, v166, v167
	v_accvgpr_read_b32 v84, a136
	v_max3_f32 v76, v76, v160, v161
	v_accvgpr_read_b32 v125, a129
	v_max3_f32 v76, v76, v162, v163
	v_mov_b32_e32 v77, v76
	v_mov_b32_e32 v176, v76
	s_nop 1
	v_permlane16_swap_b32_e32 v77, v176
	v_max_f32_e32 v176, v77, v176
	v_mov_b32_e32 v177, v176
	v_mov_b32_e32 v77, v176
	s_nop 1
	v_permlane32_swap_b32_e32 v177, v77
	v_max_f32_e32 v176, v177, v77
	v_add_f32_e32 v177, 0x41000000, v243
	v_mul_f32_e32 v176, 0x3e16c740, v176
	v_accvgpr_read_b32 v76, a140
	v_cmp_gt_f32_e32 vcc, v176, v177
	v_accvgpr_read_b32 v126, a130
	v_accvgpr_read_b32 v127, a131
	v_accvgpr_read_b32 v105, a133
	v_accvgpr_read_b32 v106, a134
	v_accvgpr_read_b32 v107, a135
	v_accvgpr_read_b32 v85, a137
	v_accvgpr_read_b32 v86, a138
	v_accvgpr_read_b32 v87, a139
	v_accvgpr_read_b32 v77, a141
	v_accvgpr_read_b32 v78, a142
	v_accvgpr_read_b32 v79, a143
	v_cndmask_b32_e32 v176, v243, v176, vcc
	s_cbranch_vccz .LBB0_2004
	v_accvgpr_read_b32 v132, a104
	v_accvgpr_read_b32 v128, a120
	v_accvgpr_read_b32 v136, a88
	v_accvgpr_read_b32 v140, a72
	v_accvgpr_read_b32 v144, a56
	v_accvgpr_read_b32 v148, a44
	v_accvgpr_read_b32 v152, a24
	v_accvgpr_read_b32 v156, a12
	v_accvgpr_read_b32 v129, a121
	v_accvgpr_read_b32 v130, a122
	v_accvgpr_read_b32 v131, a123
	v_accvgpr_read_b32 v133, a105
	v_accvgpr_read_b32 v134, a106
	v_accvgpr_read_b32 v135, a107
	v_accvgpr_read_b32 v137, a89
	v_accvgpr_read_b32 v138, a90
	v_accvgpr_read_b32 v139, a91
	v_accvgpr_read_b32 v141, a73
	v_accvgpr_read_b32 v142, a74
	v_accvgpr_read_b32 v143, a75
	v_accvgpr_read_b32 v145, a57
	v_accvgpr_read_b32 v146, a58
	v_accvgpr_read_b32 v147, a59
	v_accvgpr_read_b32 v149, a45
	v_accvgpr_read_b32 v150, a46
	v_accvgpr_read_b32 v151, a47
	v_accvgpr_read_b32 v153, a25
	v_accvgpr_read_b32 v154, a26
	v_accvgpr_read_b32 v155, a27
	v_accvgpr_read_b32 v157, a13
	v_accvgpr_read_b32 v158, a14
	v_accvgpr_read_b32 v159, a15
	v_sub_f32_e32 v177, v243, v176
	v_exp_f32_e32 v178, v177
	s_nop 0
	v_pk_mul_f32 v[156:157], v[156:157], v[178:179] op_sel_hi:[1,0]
	v_pk_mul_f32 v[152:153], v[152:153], v[178:179] op_sel_hi:[1,0]
	v_pk_mul_f32 v[148:149], v[148:149], v[178:179] op_sel_hi:[1,0]
	v_pk_mul_f32 v[144:145], v[144:145], v[178:179] op_sel_hi:[1,0]
	v_pk_mul_f32 v[140:141], v[140:141], v[178:179] op_sel_hi:[1,0]
	v_pk_mul_f32 v[136:137], v[136:137], v[178:179] op_sel_hi:[1,0]
	v_pk_mul_f32 v[132:133], v[132:133], v[178:179] op_sel_hi:[1,0]
	v_pk_mul_f32 v[128:129], v[128:129], v[178:179] op_sel_hi:[1,0]
	v_pk_mul_f32 v[158:159], v[158:159], v[178:179] op_sel_hi:[1,0]
	v_pk_mul_f32 v[154:155], v[154:155], v[178:179] op_sel_hi:[1,0]
	v_pk_mul_f32 v[150:151], v[150:151], v[178:179] op_sel_hi:[1,0]
	v_pk_mul_f32 v[146:147], v[146:147], v[178:179] op_sel_hi:[1,0]
	v_pk_mul_f32 v[142:143], v[142:143], v[178:179] op_sel_hi:[1,0]
	v_pk_mul_f32 v[138:139], v[138:139], v[178:179] op_sel_hi:[1,0]
	v_pk_mul_f32 v[134:135], v[134:135], v[178:179] op_sel_hi:[1,0]
	v_pk_mul_f32 v[130:131], v[130:131], v[178:179] op_sel_hi:[1,0]
	v_accvgpr_write_b32 a104, v132
	v_accvgpr_write_b32 a120, v128
	v_accvgpr_write_b32 a88, v136
	v_accvgpr_write_b32 a72, v140
	v_accvgpr_write_b32 a56, v144
	v_accvgpr_write_b32 a44, v148
	v_accvgpr_write_b32 a24, v152
	v_accvgpr_write_b32 a12, v156
	v_mul_f32_e32 v236, v236, v178
	v_accvgpr_write_b32 a121, v129
	v_accvgpr_write_b32 a122, v130
	v_accvgpr_write_b32 a123, v131
	v_accvgpr_write_b32 a105, v133
	v_accvgpr_write_b32 a106, v134
	v_accvgpr_write_b32 a107, v135
	v_accvgpr_write_b32 a89, v137
	v_accvgpr_write_b32 a90, v138
	v_accvgpr_write_b32 a91, v139
	v_accvgpr_write_b32 a73, v141
	v_accvgpr_write_b32 a74, v142
	v_accvgpr_write_b32 a75, v143
	v_accvgpr_write_b32 a57, v145
	v_accvgpr_write_b32 a58, v146
	v_accvgpr_write_b32 a59, v147
	v_accvgpr_write_b32 a45, v149
	v_accvgpr_write_b32 a46, v150
	v_accvgpr_write_b32 a47, v151
	v_accvgpr_write_b32 a25, v153
	v_accvgpr_write_b32 a26, v154
	v_accvgpr_write_b32 a27, v155
	v_accvgpr_write_b32 a13, v157
	v_accvgpr_write_b32 a14, v158
	v_accvgpr_write_b32 a15, v159
; DI float max3_(float a, float b, float c) { float r; asm("v_max3_f32 %0, %1, %2, %3" : "=v"(r) : "v"(a), "v"(b), "v"(c)); return r; }
; template <int DQK, bool BIAS>
; __device__ __forceinline__ void attn_pass(const hf* __restrict__ Q, int ldq, const hf* __restrict__ Kp, int ldk, const hf* __restrict__ VT,
;                                           int s0, int L, int q0, float scale_l2, const float* sBias, f4 (&oacc)[8][4], char* smem) {
;     ...
;       float mx = -1e30f;
; #pragma unroll
;       for (int mk = 0; mk < 4; ++mk) { mx = max3_(mx, sacc[mk][nq][0], sacc[mk][nq][1]); mx = max3_(mx, sacc[mk][nq][2], sacc[mk][nq][3]); }
;       mx = max3_(mx, shx(mx, 16), mx); mx = max3_(mx, shx(mx, 32), mx);
;       if (!BIAS) mx *= scale_l2;
;       const bool upd = mx > mrun[nq] + 8.f;
;       const float mnew = upd ? mx : mrun[nq];
;       if (__builtin_amdgcn_ballot_w64(upd) != 0) {
;         const float alpha = __builtin_amdgcn_exp2f(mrun[nq] - mnew);
;         lrun[nq] *= alpha;
; #pragma unroll
;         for (int md = 0; md < 8; ++md) { oacc[md][nq][0] *= alpha; oacc[md][nq][1] *= alpha; oacc[md][nq][2] *= alpha; oacc[md][nq][3] *= alpha; }
;       }
;       mrun[nq] = mnew;
.LBB0_2004:
	v_max3_f32 v128, v226, v124, v125
	v_mov_b32_e32 v130, v224
	v_max3_f32 v128, v128, v126, v127
	s_nop 0
	v_max3_f32 v128, v128, v104, v105
	v_lshlrev_b32_e32 v130, 2, v130
	v_max3_f32 v128, v128, v106, v107
	v_bitop3_b32 v130, v130, s23, v227 bitop3:0x6c
	v_max3_f32 v128, v128, v84, v85
	s_nop 0
	v_max3_f32 v128, v128, v86, v87
	s_nop 0
	v_max3_f32 v128, v128, v76, v77
	s_nop 0
	v_max3_f32 v128, v128, v78, v79
	v_mov_b32_e32 v129, v128
	s_nop 1
	v_permlane16_swap_b32_e32 v129, v128
	v_max_f32_e32 v128, v128, v129
	v_mov_b32_e32 v129, v128
	s_nop 1
	v_permlane32_swap_b32_e32 v129, v128
	v_max_f32_e32 v128, v128, v129
	v_add_f32_e32 v130, 0x41000000, v242
	v_mul_f32_e32 v128, 0x3e16c740, v128
	v_cmp_gt_f32_e32 vcc, v128, v130
	s_nop 1
	v_cndmask_b32_e32 v128, v242, v128, vcc
	s_cbranch_vccz .LBB0_2006
	v_accvgpr_read_b32 v95, a115
	v_accvgpr_read_b32 v91, a127
	v_accvgpr_read_b32 v96, a96
	v_accvgpr_read_b32 v100, a80
	v_accvgpr_read_b32 v108, a60
	v_accvgpr_read_b32 v112, a52
	v_accvgpr_read_b32 v116, a36
	v_accvgpr_read_b32 v120, a20
	v_accvgpr_read_b32 v90, a126
	v_accvgpr_read_b32 v89, a125
	v_accvgpr_read_b32 v88, a124
	v_accvgpr_read_b32 v94, a114
	v_accvgpr_read_b32 v93, a113
	v_accvgpr_read_b32 v92, a112
	v_accvgpr_read_b32 v97, a97
	v_accvgpr_read_b32 v98, a98
	v_accvgpr_read_b32 v99, a99
	v_accvgpr_read_b32 v101, a81
	v_accvgpr_read_b32 v102, a82
	v_accvgpr_read_b32 v103, a83
	v_accvgpr_read_b32 v109, a61
	v_accvgpr_read_b32 v110, a62
	v_accvgpr_read_b32 v111, a63
	v_accvgpr_read_b32 v113, a53
	v_accvgpr_read_b32 v114, a54
	v_accvgpr_read_b32 v115, a55
	v_accvgpr_read_b32 v117, a37
	v_accvgpr_read_b32 v118, a38
	v_accvgpr_read_b32 v119, a39
	v_accvgpr_read_b32 v121, a21
	v_accvgpr_read_b32 v122, a22
	v_accvgpr_read_b32 v123, a23
	v_sub_f32_e32 v129, v242, v128
	v_exp_f32_e32 v130, v129
	s_nop 0
	v_pk_mul_f32 v[120:121], v[120:121], v[130:131] op_sel_hi:[1,0]
	v_pk_mul_f32 v[116:117], v[116:117], v[130:131] op_sel_hi:[1,0]
	v_pk_mul_f32 v[112:113], v[112:113], v[130:131] op_sel_hi:[1,0]
	v_pk_mul_f32 v[108:109], v[108:109], v[130:131] op_sel_hi:[1,0]
	v_pk_mul_f32 v[100:101], v[100:101], v[130:131] op_sel_hi:[1,0]
	v_pk_mul_f32 v[96:97], v[96:97], v[130:131] op_sel_hi:[1,0]
	v_pk_mul_f32 v[94:95], v[94:95], v[130:131] op_sel_hi:[1,0]
	v_pk_mul_f32 v[90:91], v[90:91], v[130:131] op_sel_hi:[1,0]
	v_pk_mul_f32 v[122:123], v[122:123], v[130:131] op_sel_hi:[1,0]
	v_pk_mul_f32 v[118:119], v[118:119], v[130:131] op_sel_hi:[1,0]
	v_pk_mul_f32 v[114:115], v[114:115], v[130:131] op_sel_hi:[1,0]
	v_pk_mul_f32 v[110:111], v[110:111], v[130:131] op_sel_hi:[1,0]
	v_pk_mul_f32 v[102:103], v[102:103], v[130:131] op_sel_hi:[1,0]
	v_pk_mul_f32 v[98:99], v[98:99], v[130:131] op_sel_hi:[1,0]
	v_pk_mul_f32 v[92:93], v[92:93], v[130:131] op_sel_hi:[1,0]
	v_pk_mul_f32 v[88:89], v[88:89], v[130:131] op_sel_hi:[1,0]
	v_accvgpr_write_b32 a115, v95
	v_accvgpr_write_b32 a127, v91
	v_accvgpr_write_b32 a96, v96
	v_accvgpr_write_b32 a80, v100
	v_accvgpr_write_b32 a60, v108
	v_accvgpr_write_b32 a52, v112
	v_accvgpr_write_b32 a36, v116
	v_accvgpr_write_b32 a20, v120
	v_mul_f32_e32 v235, v235, v130
	v_accvgpr_write_b32 a126, v90
	v_accvgpr_write_b32 a125, v89
	v_accvgpr_write_b32 a124, v88
	v_accvgpr_write_b32 a114, v94
	v_accvgpr_write_b32 a113, v93
	v_accvgpr_write_b32 a112, v92
	v_accvgpr_write_b32 a97, v97
	v_accvgpr_write_b32 a98, v98
	v_accvgpr_write_b32 a99, v99
	v_accvgpr_write_b32 a81, v101
	v_accvgpr_write_b32 a82, v102
	v_accvgpr_write_b32 a83, v103
	v_accvgpr_write_b32 a61, v109
	v_accvgpr_write_b32 a62, v110
	v_accvgpr_write_b32 a63, v111
	v_accvgpr_write_b32 a53, v113
	v_accvgpr_write_b32 a54, v114
	v_accvgpr_write_b32 a55, v115
	v_accvgpr_write_b32 a37, v117
	v_accvgpr_write_b32 a38, v118
	v_accvgpr_write_b32 a39, v119
	v_accvgpr_write_b32 a21, v121
	v_accvgpr_write_b32 a22, v122
	v_accvgpr_write_b32 a23, v123

; #define LD_AF(dst, ks_) _Pragma("unroll") for (int i = 0; i < 8; ++i) dst[i] = *(const h8*)(sA + i * 16 * G_LD + (ks_) * 32)
; #define LD_BF(dst, ks_, nh_) _Pragma("unroll") for (int i = 0; i < 4; ++i) dst[i] = *(const h8*)(sB + ((nh_) * 4 + i) * 16 * G_LD + (ks_) * 32)
; #define MMA_BLK(afx, bfx, nh_) _Pragma("unroll") for (int mi = 0; mi < 8; ++mi) _Pragma("unroll") for (int ni = 0; ni < 4; ++ni) mfma16_acc(acc[mi][(nh_) * 4 + ni], bfx[ni], afx[mi])
; template <class Epi>
; __device__ __forceinline__ void gemm_run(const GemmArgs g, Epi epi, char* smem) {
;     ...
;       const hf* sA = sbase + (kt & 1) * G_STAGE + (wm * 128 + fr) * G_LD + fqs;
;       const hf* sB = sbase + (kt & 1) * G_STAGE + (256 + wn * 128 + fr) * G_LD + fqs;
;       hf* st = sbase + ((kt + 1) & 1) * G_STAGE;
;       h8 afA[8], afB[8], bfA[4], bfB[4];
;     ...
;       LD_AF(afA, 0); LD_BF(bfA, 0, 0);
;       if (kt + 1 < nk) {
; #pragma unroll
;         for (int i = 0; i < 8; ++i) *(u4*)(st + (lr + 32 * i) * G_LD + lcw) = ra[i];
;       }
;       __builtin_amdgcn_sched_barrier(0);
;       LD_BF(bfB, 0, 1);
;       MMA_BLK(afA, bfA, 0);
;       __builtin_amdgcn_sched_barrier(0);
;       if (kt + 1 < nk) {
; #pragma unroll
;         for (int i = 0; i < 8; ++i) *(u4*)(st + (256 + lr + 32 * i) * G_LD + lcw) = rb[i];
;       }
;       LD_AF(afB, 1); LD_BF(bfA, 1, 0);
;       MMA_BLK(afA, bfB, 1);
;       __builtin_amdgcn_sched_barrier(0);
;       if (kt + 2 < nk) {
;         const int ko = (kt + 2) * 64;
; #pragma unroll
;         for (int i = 0; i < 8; ++i) { ra[i] = __builtin_amdgcn_raw_buffer_load_b128(Ars, aoff, i * astep + ko * 2, 0); rb[i] = __builtin_amdgcn_raw_buffer_load_b128(Brs, boff, i * bstep + ko * 2, 0); }
;       }
;       LD_BF(bfB, 1, 1);
;       MMA_BLK(afB, bfA, 0);
;       __builtin_amdgcn_sched_barrier(0);
;       MMA_BLK(afB, bfB, 1);
;       __builtin_amdgcn_sched_barrier(0);
.LBB0_2020:
	ds_read_b128 v[0:3], v136 offset:36864
	ds_read_b128 v[4:7], v136 offset:39168
	ds_read_b128 v[8:11], v136 offset:41472
	ds_read_b128 v[12:15], v136 offset:43776
	ds_read_b128 v[16:19], v137
	ds_read_b128 v[20:23], v137 offset:2304
	ds_read_b128 v[24:27], v137 offset:4608
	ds_read_b128 v[28:31], v137 offset:6912
	ds_read_b128 v[32:35], v137 offset:9216
	ds_read_b128 v[36:39], v137 offset:11520
	ds_read_b128 v[40:43], v137 offset:13824
	ds_read_b128 v[44:47], v137 offset:16128
	ds_read_b128 v[48:51], v136 offset:46080
	ds_read_b128 v[52:55], v136 offset:48384
	ds_read_b128 v[56:59], v136 offset:50688
	ds_read_b128 v[60:63], v136 offset:52992
	s_waitcnt lgkmcnt(11)
	v_mfma_f32_16x16x32_f16 a[208:211], v[0:3], v[16:19], a[208:211]
	v_mfma_f32_16x16x32_f16 a[200:203], v[4:7], v[16:19], a[200:203]
	v_mfma_f32_16x16x32_f16 a[196:199], v[8:11], v[16:19], a[196:199]
	v_mfma_f32_16x16x32_f16 a[192:195], v[12:15], v[16:19], a[192:195]
	s_waitcnt lgkmcnt(10)
	v_mfma_f32_16x16x32_f16 a[188:191], v[0:3], v[20:23], a[188:191]
	v_mfma_f32_16x16x32_f16 a[184:187], v[4:7], v[20:23], a[184:187]
	v_mfma_f32_16x16x32_f16 a[180:183], v[8:11], v[20:23], a[180:183]
	v_mfma_f32_16x16x32_f16 a[176:179], v[12:15], v[20:23], a[176:179]
	s_waitcnt lgkmcnt(9)
	v_mfma_f32_16x16x32_f16 a[156:159], v[0:3], v[24:27], a[156:159]
	v_mfma_f32_16x16x32_f16 a[152:155], v[4:7], v[24:27], a[152:155]
	v_mfma_f32_16x16x32_f16 a[148:151], v[8:11], v[24:27], a[148:151]
	v_mfma_f32_16x16x32_f16 a[144:147], v[12:15], v[24:27], a[144:147]
	s_waitcnt lgkmcnt(8)
	v_mfma_f32_16x16x32_f16 a[124:127], v[0:3], v[28:31], a[124:127]
	v_mfma_f32_16x16x32_f16 a[120:123], v[4:7], v[28:31], a[120:123]
	v_mfma_f32_16x16x32_f16 a[116:119], v[8:11], v[28:31], a[116:119]
	v_mfma_f32_16x16x32_f16 a[112:115], v[12:15], v[28:31], a[112:115]
	s_waitcnt lgkmcnt(7)
	v_mfma_f32_16x16x32_f16 a[92:95], v[0:3], v[32:35], a[92:95]
	v_mfma_f32_16x16x32_f16 a[88:91], v[4:7], v[32:35], a[88:91]
	v_mfma_f32_16x16x32_f16 a[84:87], v[8:11], v[32:35], a[84:87]
	v_mfma_f32_16x16x32_f16 a[80:83], v[12:15], v[32:35], a[80:83]
	s_waitcnt lgkmcnt(6)
	v_mfma_f32_16x16x32_f16 a[60:63], v[0:3], v[36:39], a[60:63]
	v_mfma_f32_16x16x32_f16 a[56:59], v[4:7], v[36:39], a[56:59]
	v_mfma_f32_16x16x32_f16 a[52:55], v[8:11], v[36:39], a[52:55]
	v_mfma_f32_16x16x32_f16 a[48:51], v[12:15], v[36:39], a[48:51]
	s_waitcnt lgkmcnt(5)
	v_mfma_f32_16x16x32_f16 a[28:31], v[0:3], v[40:43], a[28:31]
	v_mfma_f32_16x16x32_f16 a[24:27], v[4:7], v[40:43], a[24:27]
	v_mfma_f32_16x16x32_f16 a[20:23], v[8:11], v[40:43], a[20:23]
	v_mfma_f32_16x16x32_f16 a[16:19], v[12:15], v[40:43], a[16:19]
	s_waitcnt lgkmcnt(4)
	v_mfma_f32_16x16x32_f16 a[12:15], v[0:3], v[44:47], a[12:15]
	v_mfma_f32_16x16x32_f16 a[8:11], v[4:7], v[44:47], a[8:11]
	v_mfma_f32_16x16x32_f16 a[4:7], v[8:11], v[44:47], a[4:7]
	v_mfma_f32_16x16x32_f16 a[0:3], v[12:15], v[44:47], a[0:3]
	s_waitcnt lgkmcnt(3)
	v_mfma_f32_16x16x32_f16 a[172:175], v[48:51], v[28:31], a[172:175]
	s_waitcnt lgkmcnt(2)
	v_mfma_f32_16x16x32_f16 a[168:171], v[52:55], v[28:31], a[168:171]
	s_waitcnt lgkmcnt(1)
	v_mfma_f32_16x16x32_f16 a[164:167], v[56:59], v[28:31], a[164:167]
	s_waitcnt lgkmcnt(0)
	v_mfma_f32_16x16x32_f16 a[160:163], v[60:63], v[28:31], a[160:163]
	v_mfma_f32_16x16x32_f16 a[140:143], v[48:51], v[32:35], a[140:143]
	v_mfma_f32_16x16x32_f16 a[136:139], v[52:55], v[32:35], a[136:139]
	v_mfma_f32_16x16x32_f16 a[132:135], v[56:59], v[32:35], a[132:135]
	v_mfma_f32_16x16x32_f16 a[128:131], v[60:63], v[32:35], a[128:131]
	ds_read_b128 v[12:15], v136 offset:36928
	ds_read_b128 v[28:31], v136 offset:39232
	ds_read_b128 v[32:35], v136 offset:41536
	ds_read_b128 v[64:67], v136 offset:43840
	ds_read_b128 v[76:79], v137 offset:64
	ds_read_b128 v[80:83], v137 offset:2368
	s_waitcnt vmcnt(8)
	ds_read_b128 v[140:143], v137 offset:4672
	s_waitcnt vmcnt(6)
	ds_read_b128 v[144:147], v137 offset:6976
	s_waitcnt vmcnt(3)
	ds_read_b128 v[148:151], v137 offset:9280
	ds_read_b128 v[8:11], v137 offset:11584
	ds_read_b128 v[4:7], v137 offset:13888
	ds_read_b128 v[0:3], v137 offset:16192
	v_mfma_f32_16x16x32_f16 a[240:243], v[48:51], v[16:19], a[240:243]
	v_mfma_f32_16x16x32_f16 a[252:255], v[52:55], v[16:19], a[252:255]
	v_mfma_f32_16x16x32_f16 a[248:251], v[56:59], v[16:19], a[248:251]
	v_mfma_f32_16x16x32_f16 a[244:247], v[60:63], v[16:19], a[244:247]
	v_mfma_f32_16x16x32_f16 a[236:239], v[48:51], v[20:23], a[236:239]
	v_mfma_f32_16x16x32_f16 a[232:235], v[52:55], v[20:23], a[232:235]
	v_mfma_f32_16x16x32_f16 a[228:231], v[56:59], v[20:23], a[228:231]
	v_mfma_f32_16x16x32_f16 a[224:227], v[60:63], v[20:23], a[224:227]
	v_mfma_f32_16x16x32_f16 a[220:223], v[48:51], v[24:27], a[220:223]
	v_mfma_f32_16x16x32_f16 a[216:219], v[52:55], v[24:27], a[216:219]
	v_mfma_f32_16x16x32_f16 a[212:215], v[56:59], v[24:27], a[212:215]
	v_mfma_f32_16x16x32_f16 a[204:207], v[60:63], v[24:27], a[204:207]
	v_mfma_f32_16x16x32_f16 a[108:111], v[48:51], v[36:39], a[108:111]
	v_mfma_f32_16x16x32_f16 a[104:107], v[52:55], v[36:39], a[104:107]
	v_mfma_f32_16x16x32_f16 a[100:103], v[56:59], v[36:39], a[100:103]
	v_mfma_f32_16x16x32_f16 a[96:99], v[60:63], v[36:39], a[96:99]
	v_mfma_f32_16x16x32_f16 a[76:79], v[48:51], v[40:43], a[76:79]
	v_mfma_f32_16x16x32_f16 a[72:75], v[52:55], v[40:43], a[72:75]
	v_mfma_f32_16x16x32_f16 a[68:71], v[56:59], v[40:43], a[68:71]
	v_mfma_f32_16x16x32_f16 a[64:67], v[60:63], v[40:43], a[64:67]
	v_mfma_f32_16x16x32_f16 a[44:47], v[48:51], v[44:47], a[44:47]
	v_mfma_f32_16x16x32_f16 a[40:43], v[52:55], v[44:47], a[40:43]
	v_mfma_f32_16x16x32_f16 a[36:39], v[56:59], v[44:47], a[36:39]
	v_mfma_f32_16x16x32_f16 a[32:35], v[60:63], v[44:47], a[32:35]
	ds_read_b128 v[152:155], v136 offset:46144
	s_waitcnt vmcnt(2)
; #define LD_AF(dst, ks_) _Pragma("unroll") for (int i = 0; i < 8; ++i) dst[i] = *(const h8*)(sA + i * 16 * G_LD + (ks_) * 32)
; #define LD_BF(dst, ks_, nh_) _Pragma("unroll") for (int i = 0; i < 4; ++i) dst[i] = *(const h8*)(sB + ((nh_) * 4 + i) * 16 * G_LD + (ks_) * 32)
; #define MMA_BLK(afx, bfx, nh_) _Pragma("unroll") for (int mi = 0; mi < 8; ++mi) _Pragma("unroll") for (int ni = 0; ni < 4; ++ni) mfma16_acc(acc[mi][(nh_) * 4 + ni], bfx[ni], afx[mi])
; template <class Epi>
; __device__ __forceinline__ void gemm_run(const GemmArgs g, Epi epi, char* smem) {
;     ...
;       LD_AF(afB, 1); LD_BF(bfA, 1, 0);
;       MMA_BLK(afA, bfB, 1);
;       __builtin_amdgcn_sched_barrier(0);
;       if (kt + 2 < nk) {
;         const int ko = (kt + 2) * 64;
; #pragma unroll
;         for (int i = 0; i < 8; ++i) { ra[i] = __builtin_amdgcn_raw_buffer_load_b128(Ars, aoff, i * astep + ko * 2, 0); rb[i] = __builtin_amdgcn_raw_buffer_load_b128(Brs, boff, i * bstep + ko * 2, 0); }
;       }
;       LD_BF(bfB, 1, 1);
;       MMA_BLK(afB, bfA, 0);
;       __builtin_amdgcn_sched_barrier(0);
;       MMA_BLK(afB, bfB, 1);
;       __builtin_amdgcn_sched_barrier(0);
	ds_read_b128 v[156:159], v136 offset:48448
	ds_read_b128 v[160:163], v136 offset:50752
	s_waitcnt vmcnt(1)
	ds_read_b128 v[164:167], v136 offset:53056
	s_waitcnt lgkmcnt(11)
	v_mfma_f32_16x16x32_f16 a[208:211], v[12:15], v[76:79], a[208:211]
	v_mfma_f32_16x16x32_f16 a[200:203], v[28:31], v[76:79], a[200:203]
	v_mfma_f32_16x16x32_f16 a[196:199], v[32:35], v[76:79], a[196:199]
	v_mfma_f32_16x16x32_f16 a[192:195], v[64:67], v[76:79], a[192:195]
	s_waitcnt lgkmcnt(10)
	v_mfma_f32_16x16x32_f16 a[188:191], v[12:15], v[80:83], a[188:191]
	v_mfma_f32_16x16x32_f16 a[184:187], v[28:31], v[80:83], a[184:187]
	v_mfma_f32_16x16x32_f16 a[180:183], v[32:35], v[80:83], a[180:183]
	v_mfma_f32_16x16x32_f16 a[176:179], v[64:67], v[80:83], a[176:179]
	s_waitcnt lgkmcnt(9)
	v_mfma_f32_16x16x32_f16 a[156:159], v[12:15], v[140:143], a[156:159]
	v_mfma_f32_16x16x32_f16 a[152:155], v[28:31], v[140:143], a[152:155]
	v_mfma_f32_16x16x32_f16 a[148:151], v[32:35], v[140:143], a[148:151]
	v_mfma_f32_16x16x32_f16 a[144:147], v[64:67], v[140:143], a[144:147]
	s_waitcnt lgkmcnt(8)
	v_mfma_f32_16x16x32_f16 a[124:127], v[12:15], v[144:147], a[124:127]
	v_mfma_f32_16x16x32_f16 a[120:123], v[28:31], v[144:147], a[120:123]
	v_mfma_f32_16x16x32_f16 a[116:119], v[32:35], v[144:147], a[116:119]
	v_mfma_f32_16x16x32_f16 a[112:115], v[64:67], v[144:147], a[112:115]
	s_waitcnt lgkmcnt(7)
	v_mfma_f32_16x16x32_f16 a[92:95], v[12:15], v[148:151], a[92:95]
	v_mfma_f32_16x16x32_f16 a[88:91], v[28:31], v[148:151], a[88:91]
	v_mfma_f32_16x16x32_f16 a[84:87], v[32:35], v[148:151], a[84:87]
	v_mfma_f32_16x16x32_f16 a[80:83], v[64:67], v[148:151], a[80:83]
	v_accvgpr_read_b32 v123, a211
	v_accvgpr_read_b32 v122, a210
	v_accvgpr_read_b32 v121, a203
	v_accvgpr_read_b32 v120, a202
	v_accvgpr_read_b32 v119, a199
	v_accvgpr_read_b32 v118, a198
	v_accvgpr_read_b32 v117, a195
	v_accvgpr_read_b32 v116, a194
	v_accvgpr_read_b32 v107, a191
	v_accvgpr_read_b32 v106, a190
	v_accvgpr_read_b32 v105, a187
	v_accvgpr_read_b32 v104, a186
	v_accvgpr_read_b32 v103, a183
	v_accvgpr_read_b32 v102, a182
	v_accvgpr_read_b32 v101, a179
	v_accvgpr_read_b32 v100, a178
	v_accvgpr_read_b32 v91, a159
	v_accvgpr_read_b32 v90, a158
	v_accvgpr_read_b32 v89, a155
	v_accvgpr_read_b32 v88, a154
	v_accvgpr_read_b32 v87, a151
	v_accvgpr_read_b32 v86, a150
	v_accvgpr_read_b32 v85, a147
	v_accvgpr_read_b32 v84, a146
	v_accvgpr_read_b32 v75, a127
	v_accvgpr_read_b32 v74, a126
	v_accvgpr_read_b32 v73, a123
	v_accvgpr_read_b32 v72, a122
	v_accvgpr_read_b32 v71, a119
	v_accvgpr_read_b32 v70, a118
	v_accvgpr_read_b32 v69, a115
	v_accvgpr_read_b32 v68, a114
	v_accvgpr_read_b32 v59, a95
	v_accvgpr_read_b32 v58, a94
	v_accvgpr_read_b32 v57, a91
	v_accvgpr_read_b32 v56, a90
	v_accvgpr_read_b32 v55, a87
	v_accvgpr_read_b32 v54, a86
	v_accvgpr_read_b32 v53, a83
	v_accvgpr_read_b32 v52, a82
	s_waitcnt lgkmcnt(6)
	v_mfma_f32_16x16x32_f16 a[60:63], v[12:15], v[8:11], a[60:63]
	v_mfma_f32_16x16x32_f16 a[56:59], v[28:31], v[8:11], a[56:59]
	v_mfma_f32_16x16x32_f16 a[52:55], v[32:35], v[8:11], a[52:55]
	v_mfma_f32_16x16x32_f16 a[48:51], v[64:67], v[8:11], a[48:51]
	s_waitcnt lgkmcnt(5)
	v_mfma_f32_16x16x32_f16 a[28:31], v[12:15], v[4:7], a[28:31]
	v_mfma_f32_16x16x32_f16 a[24:27], v[28:31], v[4:7], a[24:27]
	v_mfma_f32_16x16x32_f16 a[20:23], v[32:35], v[4:7], a[20:23]
	v_mfma_f32_16x16x32_f16 a[16:19], v[64:67], v[4:7], a[16:19]
	s_waitcnt lgkmcnt(4)
	v_mfma_f32_16x16x32_f16 a[12:15], v[12:15], v[0:3], a[12:15]
	v_mfma_f32_16x16x32_f16 a[8:11], v[28:31], v[0:3], a[8:11]
	v_mfma_f32_16x16x32_f16 a[4:7], v[32:35], v[0:3], a[4:7]
	v_mfma_f32_16x16x32_f16 a[0:3], v[64:67], v[0:3], a[0:3]
	v_accvgpr_read_b32 v43, a63
	v_accvgpr_read_b32 v42, a62
	v_accvgpr_read_b32 v41, a59
	v_accvgpr_read_b32 v40, a58
	v_accvgpr_read_b32 v39, a55
	v_accvgpr_read_b32 v38, a54
	v_accvgpr_read_b32 v37, a51
	v_accvgpr_read_b32 v36, a50
	v_accvgpr_read_b32 v27, a31
	v_accvgpr_read_b32 v26, a30
	v_accvgpr_read_b32 v25, a27
	v_accvgpr_read_b32 v24, a26
	v_accvgpr_read_b32 v23, a23
	v_accvgpr_read_b32 v22, a22
	v_accvgpr_read_b32 v21, a19
	v_accvgpr_read_b32 v20, a18
	v_accvgpr_read_b32 v19, a15
	v_accvgpr_read_b32 v18, a14
	v_accvgpr_read_b32 v17, a11
	v_accvgpr_read_b32 v16, a10
	v_accvgpr_read_b32 v15, a7
	v_accvgpr_read_b32 v14, a6
	v_accvgpr_read_b32 v13, a3
	v_accvgpr_read_b32 v12, a2
	s_waitcnt lgkmcnt(3)
	v_mfma_f32_16x16x32_f16 a[240:243], v[152:155], v[76:79], a[240:243]
	s_waitcnt lgkmcnt(2)
	v_mfma_f32_16x16x32_f16 a[252:255], v[156:159], v[76:79], a[252:255]
	s_waitcnt lgkmcnt(1)
	v_mfma_f32_16x16x32_f16 a[248:251], v[160:163], v[76:79], a[248:251]
	s_waitcnt lgkmcnt(0)
	v_mfma_f32_16x16x32_f16 a[244:247], v[164:167], v[76:79], a[244:247]
	v_mfma_f32_16x16x32_f16 a[236:239], v[152:155], v[80:83], a[236:239]
	v_mfma_f32_16x16x32_f16 a[232:235], v[156:159], v[80:83], a[232:235]
	v_mfma_f32_16x16x32_f16 a[228:231], v[160:163], v[80:83], a[228:231]
	v_mfma_f32_16x16x32_f16 a[224:227], v[164:167], v[80:83], a[224:227]
	v_mfma_f32_16x16x32_f16 a[220:223], v[152:155], v[140:143], a[220:223]
	v_mfma_f32_16x16x32_f16 a[216:219], v[156:159], v[140:143], a[216:219]
	v_mfma_f32_16x16x32_f16 a[212:215], v[160:163], v[140:143], a[212:215]
	v_mfma_f32_16x16x32_f16 a[204:207], v[164:167], v[140:143], a[204:207]
	v_mfma_f32_16x16x32_f16 a[172:175], v[152:155], v[144:147], a[172:175]
	v_mfma_f32_16x16x32_f16 a[168:171], v[156:159], v[144:147], a[168:171]
	v_mfma_f32_16x16x32_f16 a[164:167], v[160:163], v[144:147], a[164:167]
	v_mfma_f32_16x16x32_f16 a[160:163], v[164:167], v[144:147], a[160:163]
	v_mfma_f32_16x16x32_f16 a[140:143], v[152:155], v[148:151], a[140:143]
	v_mfma_f32_16x16x32_f16 a[136:139], v[156:159], v[148:151], a[136:139]
	v_mfma_f32_16x16x32_f16 a[132:135], v[160:163], v[148:151], a[132:135]
	v_mfma_f32_16x16x32_f16 a[128:131], v[164:167], v[148:151], a[128:131]
	s_waitcnt vmcnt(0)
; #define MMA_BLK(afx, bfx, nh_) _Pragma("unroll") for (int mi = 0; mi < 8; ++mi) _Pragma("unroll") for (int ni = 0; ni < 4; ++ni) mfma16_acc(acc[mi][(nh_) * 4 + ni], bfx[ni], afx[mi])
; template <class Epi>
; __device__ __forceinline__ void gemm_run(const GemmArgs g, Epi epi, char* smem) {
;     ...
;       MMA_BLK(afB, bfB, 1);
;       __builtin_amdgcn_sched_barrier(0);
;     ...
;       __syncthreads();
	v_accvgpr_read_b32 v169, a243
	v_accvgpr_read_b32 v168, a242
	v_accvgpr_read_b32 v171, a255
	v_accvgpr_read_b32 v170, a254
	v_accvgpr_read_b32 v127, a251
	v_accvgpr_read_b32 v126, a250
	v_accvgpr_read_b32 v125, a247
	v_accvgpr_read_b32 v124, a246
	v_accvgpr_read_b32 v115, a239
	v_accvgpr_read_b32 v114, a238
	v_accvgpr_read_b32 v113, a235
	v_accvgpr_read_b32 v112, a234
	v_accvgpr_read_b32 v111, a231
	v_accvgpr_read_b32 v110, a230
	v_accvgpr_read_b32 v109, a227
	v_accvgpr_read_b32 v108, a226
	v_accvgpr_read_b32 v99, a223
	v_accvgpr_read_b32 v98, a222
	v_accvgpr_read_b32 v97, a219
	v_accvgpr_read_b32 v96, a218
	v_accvgpr_read_b32 v95, a215
	v_accvgpr_read_b32 v94, a214
	v_accvgpr_read_b32 v93, a207
	v_accvgpr_read_b32 v92, a206
	v_accvgpr_read_b32 v83, a175
	v_accvgpr_read_b32 v82, a174
	v_accvgpr_read_b32 v81, a171
	v_accvgpr_read_b32 v80, a170
	v_accvgpr_read_b32 v79, a167
	v_accvgpr_read_b32 v78, a166
	v_accvgpr_read_b32 v77, a163
	v_accvgpr_read_b32 v76, a162
	v_accvgpr_read_b32 v67, a143
	v_accvgpr_read_b32 v66, a142
	v_accvgpr_read_b32 v65, a139
	v_accvgpr_read_b32 v64, a138
	v_accvgpr_read_b32 v63, a135
	v_accvgpr_read_b32 v62, a134
	v_accvgpr_read_b32 v61, a131
	v_accvgpr_read_b32 v60, a130
	v_mfma_f32_16x16x32_f16 a[108:111], v[152:155], v[8:11], a[108:111]
	v_mfma_f32_16x16x32_f16 a[104:107], v[156:159], v[8:11], a[104:107]
	v_mfma_f32_16x16x32_f16 a[100:103], v[160:163], v[8:11], a[100:103]
	v_mfma_f32_16x16x32_f16 a[96:99], v[164:167], v[8:11], a[96:99]
	v_mfma_f32_16x16x32_f16 a[76:79], v[152:155], v[4:7], a[76:79]
	v_mfma_f32_16x16x32_f16 a[72:75], v[156:159], v[4:7], a[72:75]
	v_mfma_f32_16x16x32_f16 a[68:71], v[160:163], v[4:7], a[68:71]
	v_mfma_f32_16x16x32_f16 a[64:67], v[164:167], v[4:7], a[64:67]
	v_mfma_f32_16x16x32_f16 a[44:47], v[152:155], v[0:3], a[44:47]
	v_mfma_f32_16x16x32_f16 a[40:43], v[156:159], v[0:3], a[40:43]
	v_mfma_f32_16x16x32_f16 a[36:39], v[160:163], v[0:3], a[36:39]
	v_mfma_f32_16x16x32_f16 a[32:35], v[164:167], v[0:3], a[32:35]
	s_nop 0
	v_add_u32_e32 v30, s20, v130
	v_min_i32_e32 v3, 0x8000, v30
	v_or_b32_e32 v2, s22, v133
	v_ashrrev_i32_e32 v3, 13, v3
	v_mul_hi_i32_i24_e32 v141, 0xc000, v3
	v_mul_i32_i24_e32 v140, 0xc000, v3
	v_ashrrev_i32_e32 v3, 31, v2
	v_lshl_add_u64 v[140:141], s[16:17], 0, v[140:141]
	v_lshlrev_b64 v[2:3], 2, v[2:3]
	v_ashrrev_i32_e32 v31, 31, v30
	v_lshl_add_u64 v[148:149], v[140:141], 0, v[2:3]
	v_lshlrev_b64 v[140:141], 13, v[30:31]
	v_lshl_add_u64 v[140:141], s[28:29], 0, v[140:141]
	v_lshl_add_u64 v[150:151], v[140:141], 0, v[2:3]
	s_barrier
	global_load_dwordx4 v[4:7], v[148:149], off
	global_load_dwordx4 v[8:11], v[148:149], off offset:64
	global_load_dwordx4 v[12:15], v[148:149], off offset:128
	global_load_dwordx4 v[16:19], v[148:149], off offset:192
	global_load_dwordx4 v[20:23], v[148:149], off offset:256
	global_load_dwordx4 v[24:27], v[148:149], off offset:320
	global_load_dwordx4 v[32:35], v[148:149], off offset:384
	global_load_dwordx4 v[36:39], v[148:149], off offset:448
	global_load_dwordx4 v[40:43], v[150:151], off
	global_load_dwordx4 v[44:47], v[150:151], off offset:64
	global_load_dwordx4 v[48:51], v[150:151], off offset:128
	global_load_dwordx4 v[52:55], v[150:151], off offset:192
	global_load_dwordx4 v[56:59], v[150:151], off offset:256
	global_load_dwordx4 v[60:63], v[150:151], off offset:320
	global_load_dwordx4 v[64:67], v[150:151], off offset:384
	global_load_dwordx4 v[68:71], v[150:151], off offset:448
	v_mov_b32_e32 v110, 0x20000
	v_mov_b32_e32 v111, 0
	v_lshl_add_u64 v[108:109], v[150:151], 0, v[110:111]
	v_mov_b32_e32 v110, 0x40000
	global_load_dwordx4 v[72:75], v[108:109], off
	global_load_dwordx4 v[76:79], v[108:109], off offset:64
	global_load_dwordx4 v[80:83], v[108:109], off offset:128
	global_load_dwordx4 v[84:87], v[108:109], off offset:192
	global_load_dwordx4 v[88:91], v[108:109], off offset:256
	global_load_dwordx4 v[92:95], v[108:109], off offset:320
	global_load_dwordx4 v[96:99], v[108:109], off offset:384
	global_load_dwordx4 v[100:103], v[108:109], off offset:448
	v_accvgpr_read_b32 v104, a208
	v_accvgpr_read_b32 v105, a209
	v_accvgpr_read_b32 v106, a210
	v_accvgpr_read_b32 v107, a211
	s_waitcnt vmcnt(15)
	v_pk_fma_f32 v[40:41], v[104:105], v[4:5], v[40:41]
	v_pk_fma_f32 v[42:43], v[106:107], v[6:7], v[42:43]
	global_store_dwordx4 v[150:151], v[40:43], off
	v_accvgpr_read_b32 v104, a200
	v_accvgpr_read_b32 v105, a201
	v_accvgpr_read_b32 v106, a202
	v_accvgpr_read_b32 v107, a203
	s_waitcnt vmcnt(15)
	v_pk_fma_f32 v[44:45], v[104:105], v[8:9], v[44:45]
	v_pk_fma_f32 v[46:47], v[106:107], v[10:11], v[46:47]
	global_store_dwordx4 v[150:151], v[44:47], off offset:64
	v_accvgpr_read_b32 v104, a196
	v_accvgpr_read_b32 v105, a197
	v_accvgpr_read_b32 v106, a198
	v_accvgpr_read_b32 v107, a199
	s_waitcnt vmcnt(15)
	v_pk_fma_f32 v[48:49], v[104:105], v[12:13], v[48:49]
	v_pk_fma_f32 v[50:51], v[106:107], v[14:15], v[50:51]
	global_store_dwordx4 v[150:151], v[48:51], off offset:128
	v_accvgpr_read_b32 v104, a192
	v_accvgpr_read_b32 v105, a193
	v_accvgpr_read_b32 v106, a194
	v_accvgpr_read_b32 v107, a195
	s_waitcnt vmcnt(15)
	v_pk_fma_f32 v[52:53], v[104:105], v[16:17], v[52:53]
	v_pk_fma_f32 v[54:55], v[106:107], v[18:19], v[54:55]
	global_store_dwordx4 v[150:151], v[52:55], off offset:192
	v_accvgpr_read_b32 v104, a240
	v_accvgpr_read_b32 v105, a241
	v_accvgpr_read_b32 v106, a242
	v_accvgpr_read_b32 v107, a243
	s_waitcnt vmcnt(15)
	v_pk_fma_f32 v[56:57], v[104:105], v[20:21], v[56:57]
	v_pk_fma_f32 v[58:59], v[106:107], v[22:23], v[58:59]
	global_store_dwordx4 v[150:151], v[56:59], off offset:256
	v_accvgpr_read_b32 v104, a252
	v_accvgpr_read_b32 v105, a253
	v_accvgpr_read_b32 v106, a254
	v_accvgpr_read_b32 v107, a255
	s_waitcnt vmcnt(15)
	v_pk_fma_f32 v[60:61], v[104:105], v[24:25], v[60:61]
	v_pk_fma_f32 v[62:63], v[106:107], v[26:27], v[62:63]
	global_store_dwordx4 v[150:151], v[60:63], off offset:320
	v_accvgpr_read_b32 v104, a248
	v_accvgpr_read_b32 v105, a249
	v_accvgpr_read_b32 v106, a250
	v_accvgpr_read_b32 v107, a251
	s_waitcnt vmcnt(15)
	v_pk_fma_f32 v[64:65], v[104:105], v[32:33], v[64:65]
	v_pk_fma_f32 v[66:67], v[106:107], v[34:35], v[66:67]
	global_store_dwordx4 v[150:151], v[64:67], off offset:384
	v_accvgpr_read_b32 v104, a244
	v_accvgpr_read_b32 v105, a245
	v_accvgpr_read_b32 v106, a246
	v_accvgpr_read_b32 v107, a247
	s_waitcnt vmcnt(15)
	v_pk_fma_f32 v[68:69], v[104:105], v[36:37], v[68:69]
	v_pk_fma_f32 v[70:71], v[106:107], v[38:39], v[70:71]
	global_store_dwordx4 v[150:151], v[68:71], off offset:448
	v_lshl_add_u64 v[150:151], v[150:151], 0, v[110:111]
	s_nop 1
	global_load_dwordx4 v[40:43], v[150:151], off
	global_load_dwordx4 v[44:47], v[150:151], off offset:64
	global_load_dwordx4 v[48:51], v[150:151], off offset:128
	global_load_dwordx4 v[52:55], v[150:151], off offset:192
	global_load_dwordx4 v[56:59], v[150:151], off offset:256
	global_load_dwordx4 v[60:63], v[150:151], off offset:320
	global_load_dwordx4 v[64:67], v[150:151], off offset:384
	global_load_dwordx4 v[68:71], v[150:151], off offset:448
	v_accvgpr_read_b32 v104, a188
	v_accvgpr_read_b32 v105, a189
	v_accvgpr_read_b32 v106, a190
	v_accvgpr_read_b32 v107, a191
	s_waitcnt vmcnt(23)
	v_pk_fma_f32 v[72:73], v[104:105], v[4:5], v[72:73]
	v_pk_fma_f32 v[74:75], v[106:107], v[6:7], v[74:75]
	global_store_dwordx4 v[108:109], v[72:75], off
	v_accvgpr_read_b32 v104, a184
	v_accvgpr_read_b32 v105, a185
	v_accvgpr_read_b32 v106, a186
	v_accvgpr_read_b32 v107, a187
	s_waitcnt vmcnt(23)
	v_pk_fma_f32 v[76:77], v[104:105], v[8:9], v[76:77]
	v_pk_fma_f32 v[78:79], v[106:107], v[10:11], v[78:79]
	global_store_dwordx4 v[108:109], v[76:79], off offset:64
	v_accvgpr_read_b32 v104, a180
	v_accvgpr_read_b32 v105, a181
	v_accvgpr_read_b32 v106, a182
	v_accvgpr_read_b32 v107, a183
	s_waitcnt vmcnt(23)
	v_pk_fma_f32 v[80:81], v[104:105], v[12:13], v[80:81]
	v_pk_fma_f32 v[82:83], v[106:107], v[14:15], v[82:83]
	global_store_dwordx4 v[108:109], v[80:83], off offset:128
	v_accvgpr_read_b32 v104, a176
	v_accvgpr_read_b32 v105, a177
	v_accvgpr_read_b32 v106, a178
	v_accvgpr_read_b32 v107, a179
	s_waitcnt vmcnt(23)
	v_pk_fma_f32 v[84:85], v[104:105], v[16:17], v[84:85]
	v_pk_fma_f32 v[86:87], v[106:107], v[18:19], v[86:87]
	global_store_dwordx4 v[108:109], v[84:87], off offset:192
	v_accvgpr_read_b32 v104, a236
	v_accvgpr_read_b32 v105, a237
	v_accvgpr_read_b32 v106, a238
	v_accvgpr_read_b32 v107, a239
	s_waitcnt vmcnt(23)
	v_pk_fma_f32 v[88:89], v[104:105], v[20:21], v[88:89]
	v_pk_fma_f32 v[90:91], v[106:107], v[22:23], v[90:91]
	global_store_dwordx4 v[108:109], v[88:91], off offset:256
	v_accvgpr_read_b32 v104, a232
	v_accvgpr_read_b32 v105, a233
	v_accvgpr_read_b32 v106, a234
	v_accvgpr_read_b32 v107, a235
	s_waitcnt vmcnt(23)
	v_pk_fma_f32 v[92:93], v[104:105], v[24:25], v[92:93]
	v_pk_fma_f32 v[94:95], v[106:107], v[26:27], v[94:95]
	global_store_dwordx4 v[108:109], v[92:95], off offset:320
	v_accvgpr_read_b32 v104, a228
	v_accvgpr_read_b32 v105, a229
	v_accvgpr_read_b32 v106, a230
	v_accvgpr_read_b32 v107, a231
	s_waitcnt vmcnt(23)
	v_pk_fma_f32 v[96:97], v[104:105], v[32:33], v[96:97]
	v_pk_fma_f32 v[98:99], v[106:107], v[34:35], v[98:99]
	global_store_dwordx4 v[108:109], v[96:99], off offset:384
	v_accvgpr_read_b32 v104, a224
	v_accvgpr_read_b32 v105, a225
	v_accvgpr_read_b32 v106, a226
	v_accvgpr_read_b32 v107, a227
	s_waitcnt vmcnt(23)
	v_pk_fma_f32 v[100:101], v[104:105], v[36:37], v[100:101]
	v_pk_fma_f32 v[102:103], v[106:107], v[38:39], v[102:103]
	global_store_dwordx4 v[108:109], v[100:103], off offset:448
	v_lshl_add_u64 v[108:109], v[108:109], 0, v[110:111]
	s_nop 1
	global_load_dwordx4 v[72:75], v[108:109], off
	global_load_dwordx4 v[76:79], v[108:109], off offset:64
	global_load_dwordx4 v[80:83], v[108:109], off offset:128
	global_load_dwordx4 v[84:87], v[108:109], off offset:192
	global_load_dwordx4 v[88:91], v[108:109], off offset:256
	global_load_dwordx4 v[92:95], v[108:109], off offset:320
	global_load_dwordx4 v[96:99], v[108:109], off offset:384
	global_load_dwordx4 v[100:103], v[108:109], off offset:448
	v_accvgpr_read_b32 v104, a156
	v_accvgpr_read_b32 v105, a157
	v_accvgpr_read_b32 v106, a158
	v_accvgpr_read_b32 v107, a159
	s_waitcnt vmcnt(23)
	v_pk_fma_f32 v[40:41], v[104:105], v[4:5], v[40:41]
	v_pk_fma_f32 v[42:43], v[106:107], v[6:7], v[42:43]
	global_store_dwordx4 v[150:151], v[40:43], off
	v_accvgpr_read_b32 v104, a152
	v_accvgpr_read_b32 v105, a153
	v_accvgpr_read_b32 v106, a154
	v_accvgpr_read_b32 v107, a155
	s_waitcnt vmcnt(23)
	v_pk_fma_f32 v[44:45], v[104:105], v[8:9], v[44:45]
	v_pk_fma_f32 v[46:47], v[106:107], v[10:11], v[46:47]
	global_store_dwordx4 v[150:151], v[44:47], off offset:64
	v_accvgpr_read_b32 v104, a148
	v_accvgpr_read_b32 v105, a149
	v_accvgpr_read_b32 v106, a150
	v_accvgpr_read_b32 v107, a151
	s_waitcnt vmcnt(23)
	v_pk_fma_f32 v[48:49], v[104:105], v[12:13], v[48:49]
	v_pk_fma_f32 v[50:51], v[106:107], v[14:15], v[50:51]
	global_store_dwordx4 v[150:151], v[48:51], off offset:128
	v_accvgpr_read_b32 v104, a144
	v_accvgpr_read_b32 v105, a145
	v_accvgpr_read_b32 v106, a146
	v_accvgpr_read_b32 v107, a147
	s_waitcnt vmcnt(23)
	v_pk_fma_f32 v[52:53], v[104:105], v[16:17], v[52:53]
	v_pk_fma_f32 v[54:55], v[106:107], v[18:19], v[54:55]
	global_store_dwordx4 v[150:151], v[52:55], off offset:192
	v_accvgpr_read_b32 v104, a220
	v_accvgpr_read_b32 v105, a221
	v_accvgpr_read_b32 v106, a222
	v_accvgpr_read_b32 v107, a223
	s_waitcnt vmcnt(23)
	v_pk_fma_f32 v[56:57], v[104:105], v[20:21], v[56:57]
	v_pk_fma_f32 v[58:59], v[106:107], v[22:23], v[58:59]
	global_store_dwordx4 v[150:151], v[56:59], off offset:256
	v_accvgpr_read_b32 v104, a216
	v_accvgpr_read_b32 v105, a217
	v_accvgpr_read_b32 v106, a218
	v_accvgpr_read_b32 v107, a219
	s_waitcnt vmcnt(23)
	v_pk_fma_f32 v[60:61], v[104:105], v[24:25], v[60:61]
	v_pk_fma_f32 v[62:63], v[106:107], v[26:27], v[62:63]
	global_store_dwordx4 v[150:151], v[60:63], off offset:320
	v_accvgpr_read_b32 v104, a212
	v_accvgpr_read_b32 v105, a213
	v_accvgpr_read_b32 v106, a214
	v_accvgpr_read_b32 v107, a215
	s_waitcnt vmcnt(23)
	v_pk_fma_f32 v[64:65], v[104:105], v[32:33], v[64:65]
	v_pk_fma_f32 v[66:67], v[106:107], v[34:35], v[66:67]
	global_store_dwordx4 v[150:151], v[64:67], off offset:384
	v_accvgpr_read_b32 v104, a204
	v_accvgpr_read_b32 v105, a205
	v_accvgpr_read_b32 v106, a206
	v_accvgpr_read_b32 v107, a207
	s_waitcnt vmcnt(23)
	v_pk_fma_f32 v[68:69], v[104:105], v[36:37], v[68:69]
	v_pk_fma_f32 v[70:71], v[106:107], v[38:39], v[70:71]
	global_store_dwordx4 v[150:151], v[68:71], off offset:448
	v_lshl_add_u64 v[150:151], v[150:151], 0, v[110:111]
	s_nop 1
	global_load_dwordx4 v[40:43], v[150:151], off
	global_load_dwordx4 v[44:47], v[150:151], off offset:64
	global_load_dwordx4 v[48:51], v[150:151], off offset:128
	global_load_dwordx4 v[52:55], v[150:151], off offset:192
	global_load_dwordx4 v[56:59], v[150:151], off offset:256
	global_load_dwordx4 v[60:63], v[150:151], off offset:320
	global_load_dwordx4 v[64:67], v[150:151], off offset:384
	global_load_dwordx4 v[68:71], v[150:151], off offset:448
	v_accvgpr_read_b32 v104, a124
	v_accvgpr_read_b32 v105, a125
	v_accvgpr_read_b32 v106, a126
	v_accvgpr_read_b32 v107, a127
	s_waitcnt vmcnt(23)
	v_pk_fma_f32 v[72:73], v[104:105], v[4:5], v[72:73]
	v_pk_fma_f32 v[74:75], v[106:107], v[6:7], v[74:75]
	global_store_dwordx4 v[108:109], v[72:75], off
	v_accvgpr_read_b32 v104, a120
	v_accvgpr_read_b32 v105, a121
	v_accvgpr_read_b32 v106, a122
	v_accvgpr_read_b32 v107, a123
	s_waitcnt vmcnt(23)
	v_pk_fma_f32 v[76:77], v[104:105], v[8:9], v[76:77]
	v_pk_fma_f32 v[78:79], v[106:107], v[10:11], v[78:79]
	global_store_dwordx4 v[108:109], v[76:79], off offset:64
	v_accvgpr_read_b32 v104, a116
	v_accvgpr_read_b32 v105, a117
	v_accvgpr_read_b32 v106, a118
	v_accvgpr_read_b32 v107, a119
	s_waitcnt vmcnt(23)
	v_pk_fma_f32 v[80:81], v[104:105], v[12:13], v[80:81]
	v_pk_fma_f32 v[82:83], v[106:107], v[14:15], v[82:83]
	global_store_dwordx4 v[108:109], v[80:83], off offset:128
	v_accvgpr_read_b32 v104, a112
	v_accvgpr_read_b32 v105, a113
	v_accvgpr_read_b32 v106, a114
	v_accvgpr_read_b32 v107, a115
	s_waitcnt vmcnt(23)
	v_pk_fma_f32 v[84:85], v[104:105], v[16:17], v[84:85]
	v_pk_fma_f32 v[86:87], v[106:107], v[18:19], v[86:87]
	global_store_dwordx4 v[108:109], v[84:87], off offset:192
	v_accvgpr_read_b32 v104, a172
	v_accvgpr_read_b32 v105, a173
	v_accvgpr_read_b32 v106, a174
	v_accvgpr_read_b32 v107, a175
	s_waitcnt vmcnt(23)
	v_pk_fma_f32 v[88:89], v[104:105], v[20:21], v[88:89]
	v_pk_fma_f32 v[90:91], v[106:107], v[22:23], v[90:91]
	global_store_dwordx4 v[108:109], v[88:91], off offset:256
	v_accvgpr_read_b32 v104, a168
	v_accvgpr_read_b32 v105, a169
	v_accvgpr_read_b32 v106, a170
	v_accvgpr_read_b32 v107, a171
	s_waitcnt vmcnt(23)
	v_pk_fma_f32 v[92:93], v[104:105], v[24:25], v[92:93]
	v_pk_fma_f32 v[94:95], v[106:107], v[26:27], v[94:95]
	global_store_dwordx4 v[108:109], v[92:95], off offset:320
	v_accvgpr_read_b32 v104, a164
	v_accvgpr_read_b32 v105, a165
	v_accvgpr_read_b32 v106, a166
	v_accvgpr_read_b32 v107, a167
	s_waitcnt vmcnt(23)
	v_pk_fma_f32 v[96:97], v[104:105], v[32:33], v[96:97]
	v_pk_fma_f32 v[98:99], v[106:107], v[34:35], v[98:99]
	global_store_dwordx4 v[108:109], v[96:99], off offset:384
	v_accvgpr_read_b32 v104, a160
	v_accvgpr_read_b32 v105, a161
	v_accvgpr_read_b32 v106, a162
	v_accvgpr_read_b32 v107, a163
	s_waitcnt vmcnt(23)
	v_pk_fma_f32 v[100:101], v[104:105], v[36:37], v[100:101]
	v_pk_fma_f32 v[102:103], v[106:107], v[38:39], v[102:103]
	global_store_dwordx4 v[108:109], v[100:103], off offset:448
	v_lshl_add_u64 v[108:109], v[108:109], 0, v[110:111]
	s_nop 1
	global_load_dwordx4 v[72:75], v[108:109], off
	global_load_dwordx4 v[76:79], v[108:109], off offset:64
	global_load_dwordx4 v[80:83], v[108:109], off offset:128
	global_load_dwordx4 v[84:87], v[108:109], off offset:192
	global_load_dwordx4 v[88:91], v[108:109], off offset:256
	global_load_dwordx4 v[92:95], v[108:109], off offset:320
	global_load_dwordx4 v[96:99], v[108:109], off offset:384
	global_load_dwordx4 v[100:103], v[108:109], off offset:448
	v_accvgpr_read_b32 v104, a92
	v_accvgpr_read_b32 v105, a93
	v_accvgpr_read_b32 v106, a94
	v_accvgpr_read_b32 v107, a95
	s_waitcnt vmcnt(23)
	v_pk_fma_f32 v[40:41], v[104:105], v[4:5], v[40:41]
	v_pk_fma_f32 v[42:43], v[106:107], v[6:7], v[42:43]
	global_store_dwordx4 v[150:151], v[40:43], off
	v_accvgpr_read_b32 v104, a88
	v_accvgpr_read_b32 v105, a89
	v_accvgpr_read_b32 v106, a90
	v_accvgpr_read_b32 v107, a91
	s_waitcnt vmcnt(23)
	v_pk_fma_f32 v[44:45], v[104:105], v[8:9], v[44:45]
	v_pk_fma_f32 v[46:47], v[106:107], v[10:11], v[46:47]
	global_store_dwordx4 v[150:151], v[44:47], off offset:64
	v_accvgpr_read_b32 v104, a84
	v_accvgpr_read_b32 v105, a85
	v_accvgpr_read_b32 v106, a86
	v_accvgpr_read_b32 v107, a87
	s_waitcnt vmcnt(23)
	v_pk_fma_f32 v[48:49], v[104:105], v[12:13], v[48:49]
	v_pk_fma_f32 v[50:51], v[106:107], v[14:15], v[50:51]
	global_store_dwordx4 v[150:151], v[48:51], off offset:128
	v_accvgpr_read_b32 v104, a80
	v_accvgpr_read_b32 v105, a81
	v_accvgpr_read_b32 v106, a82
	v_accvgpr_read_b32 v107, a83
	s_waitcnt vmcnt(23)
	v_pk_fma_f32 v[52:53], v[104:105], v[16:17], v[52:53]
	v_pk_fma_f32 v[54:55], v[106:107], v[18:19], v[54:55]
	global_store_dwordx4 v[150:151], v[52:55], off offset:192
	v_accvgpr_read_b32 v104, a140
	v_accvgpr_read_b32 v105, a141
	v_accvgpr_read_b32 v106, a142
	v_accvgpr_read_b32 v107, a143
	s_waitcnt vmcnt(23)
	v_pk_fma_f32 v[56:57], v[104:105], v[20:21], v[56:57]
	v_pk_fma_f32 v[58:59], v[106:107], v[22:23], v[58:59]
	global_store_dwordx4 v[150:151], v[56:59], off offset:256
	v_accvgpr_read_b32 v104, a136
	v_accvgpr_read_b32 v105, a137
	v_accvgpr_read_b32 v106, a138
	v_accvgpr_read_b32 v107, a139
	s_waitcnt vmcnt(23)
	v_pk_fma_f32 v[60:61], v[104:105], v[24:25], v[60:61]
	v_pk_fma_f32 v[62:63], v[106:107], v[26:27], v[62:63]
	global_store_dwordx4 v[150:151], v[60:63], off offset:320
	v_accvgpr_read_b32 v104, a132
	v_accvgpr_read_b32 v105, a133
	v_accvgpr_read_b32 v106, a134
	v_accvgpr_read_b32 v107, a135
	s_waitcnt vmcnt(23)
	v_pk_fma_f32 v[64:65], v[104:105], v[32:33], v[64:65]
	v_pk_fma_f32 v[66:67], v[106:107], v[34:35], v[66:67]
	global_store_dwordx4 v[150:151], v[64:67], off offset:384
	v_accvgpr_read_b32 v104, a128
	v_accvgpr_read_b32 v105, a129
	v_accvgpr_read_b32 v106, a130
	v_accvgpr_read_b32 v107, a131
	s_waitcnt vmcnt(23)
	v_pk_fma_f32 v[68:69], v[104:105], v[36:37], v[68:69]
	v_pk_fma_f32 v[70:71], v[106:107], v[38:39], v[70:71]
	global_store_dwordx4 v[150:151], v[68:71], off offset:448
	v_lshl_add_u64 v[150:151], v[150:151], 0, v[110:111]
	s_nop 1
	global_load_dwordx4 v[40:43], v[150:151], off
	global_load_dwordx4 v[44:47], v[150:151], off offset:64
	global_load_dwordx4 v[48:51], v[150:151], off offset:128
	global_load_dwordx4 v[52:55], v[150:151], off offset:192
	global_load_dwordx4 v[56:59], v[150:151], off offset:256
	global_load_dwordx4 v[60:63], v[150:151], off offset:320
	global_load_dwordx4 v[64:67], v[150:151], off offset:384
	global_load_dwordx4 v[68:71], v[150:151], off offset:448
	v_accvgpr_read_b32 v104, a60
	v_accvgpr_read_b32 v105, a61
	v_accvgpr_read_b32 v106, a62
	v_accvgpr_read_b32 v107, a63
	s_waitcnt vmcnt(23)
	v_pk_fma_f32 v[72:73], v[104:105], v[4:5], v[72:73]
	v_pk_fma_f32 v[74:75], v[106:107], v[6:7], v[74:75]
	global_store_dwordx4 v[108:109], v[72:75], off
	v_accvgpr_read_b32 v104, a56
	v_accvgpr_read_b32 v105, a57
	v_accvgpr_read_b32 v106, a58
	v_accvgpr_read_b32 v107, a59
	s_waitcnt vmcnt(23)
	v_pk_fma_f32 v[76:77], v[104:105], v[8:9], v[76:77]
	v_pk_fma_f32 v[78:79], v[106:107], v[10:11], v[78:79]
	global_store_dwordx4 v[108:109], v[76:79], off offset:64
	v_accvgpr_read_b32 v104, a52
	v_accvgpr_read_b32 v105, a53
	v_accvgpr_read_b32 v106, a54
	v_accvgpr_read_b32 v107, a55
	s_waitcnt vmcnt(23)
	v_pk_fma_f32 v[80:81], v[104:105], v[12:13], v[80:81]
	v_pk_fma_f32 v[82:83], v[106:107], v[14:15], v[82:83]
	global_store_dwordx4 v[108:109], v[80:83], off offset:128
	v_accvgpr_read_b32 v104, a48
	v_accvgpr_read_b32 v105, a49
	v_accvgpr_read_b32 v106, a50
	v_accvgpr_read_b32 v107, a51
	s_waitcnt vmcnt(23)
	v_pk_fma_f32 v[84:85], v[104:105], v[16:17], v[84:85]
	v_pk_fma_f32 v[86:87], v[106:107], v[18:19], v[86:87]
	global_store_dwordx4 v[108:109], v[84:87], off offset:192
	v_accvgpr_read_b32 v104, a108
	v_accvgpr_read_b32 v105, a109
	v_accvgpr_read_b32 v106, a110
	v_accvgpr_read_b32 v107, a111
	s_waitcnt vmcnt(23)
	v_pk_fma_f32 v[88:89], v[104:105], v[20:21], v[88:89]
	v_pk_fma_f32 v[90:91], v[106:107], v[22:23], v[90:91]
	global_store_dwordx4 v[108:109], v[88:91], off offset:256
	v_accvgpr_read_b32 v104, a104
	v_accvgpr_read_b32 v105, a105
	v_accvgpr_read_b32 v106, a106
	v_accvgpr_read_b32 v107, a107
	s_waitcnt vmcnt(23)
	v_pk_fma_f32 v[92:93], v[104:105], v[24:25], v[92:93]
	v_pk_fma_f32 v[94:95], v[106:107], v[26:27], v[94:95]
	global_store_dwordx4 v[108:109], v[92:95], off offset:320
	v_accvgpr_read_b32 v104, a100
	v_accvgpr_read_b32 v105, a101
	v_accvgpr_read_b32 v106, a102
	v_accvgpr_read_b32 v107, a103
	s_waitcnt vmcnt(23)
	v_pk_fma_f32 v[96:97], v[104:105], v[32:33], v[96:97]
	v_pk_fma_f32 v[98:99], v[106:107], v[34:35], v[98:99]
	global_store_dwordx4 v[108:109], v[96:99], off offset:384
	v_accvgpr_read_b32 v104, a96
	v_accvgpr_read_b32 v105, a97
	v_accvgpr_read_b32 v106, a98
	v_accvgpr_read_b32 v107, a99
	s_waitcnt vmcnt(23)
	v_pk_fma_f32 v[100:101], v[104:105], v[36:37], v[100:101]
	v_pk_fma_f32 v[102:103], v[106:107], v[38:39], v[102:103]
	global_store_dwordx4 v[108:109], v[100:103], off offset:448
	v_lshl_add_u64 v[108:109], v[108:109], 0, v[110:111]
	s_nop 1
	global_load_dwordx4 v[72:75], v[108:109], off
	global_load_dwordx4 v[76:79], v[108:109], off offset:64
	global_load_dwordx4 v[80:83], v[108:109], off offset:128
	global_load_dwordx4 v[84:87], v[108:109], off offset:192
	global_load_dwordx4 v[88:91], v[108:109], off offset:256
	global_load_dwordx4 v[92:95], v[108:109], off offset:320
	global_load_dwordx4 v[96:99], v[108:109], off offset:384
	global_load_dwordx4 v[100:103], v[108:109], off offset:448
	v_accvgpr_read_b32 v104, a28
	v_accvgpr_read_b32 v105, a29
	v_accvgpr_read_b32 v106, a30
	v_accvgpr_read_b32 v107, a31
	s_waitcnt vmcnt(23)
	v_pk_fma_f32 v[40:41], v[104:105], v[4:5], v[40:41]
	v_pk_fma_f32 v[42:43], v[106:107], v[6:7], v[42:43]
	global_store_dwordx4 v[150:151], v[40:43], off
	v_accvgpr_read_b32 v104, a24
	v_accvgpr_read_b32 v105, a25
	v_accvgpr_read_b32 v106, a26
	v_accvgpr_read_b32 v107, a27
	s_waitcnt vmcnt(23)
	v_pk_fma_f32 v[44:45], v[104:105], v[8:9], v[44:45]
	v_pk_fma_f32 v[46:47], v[106:107], v[10:11], v[46:47]
	global_store_dwordx4 v[150:151], v[44:47], off offset:64
	v_accvgpr_read_b32 v104, a20
	v_accvgpr_read_b32 v105, a21
	v_accvgpr_read_b32 v106, a22
	v_accvgpr_read_b32 v107, a23
	s_waitcnt vmcnt(23)
	v_pk_fma_f32 v[48:49], v[104:105], v[12:13], v[48:49]
	v_pk_fma_f32 v[50:51], v[106:107], v[14:15], v[50:51]
	global_store_dwordx4 v[150:151], v[48:51], off offset:128
	v_accvgpr_read_b32 v104, a16
	v_accvgpr_read_b32 v105, a17
	v_accvgpr_read_b32 v106, a18
	v_accvgpr_read_b32 v107, a19
	s_waitcnt vmcnt(23)
	v_pk_fma_f32 v[52:53], v[104:105], v[16:17], v[52:53]
	v_pk_fma_f32 v[54:55], v[106:107], v[18:19], v[54:55]
	global_store_dwordx4 v[150:151], v[52:55], off offset:192
	v_accvgpr_read_b32 v104, a76
	v_accvgpr_read_b32 v105, a77
	v_accvgpr_read_b32 v106, a78
	v_accvgpr_read_b32 v107, a79
	s_waitcnt vmcnt(23)
	v_pk_fma_f32 v[56:57], v[104:105], v[20:21], v[56:57]
	v_pk_fma_f32 v[58:59], v[106:107], v[22:23], v[58:59]
	global_store_dwordx4 v[150:151], v[56:59], off offset:256
	v_accvgpr_read_b32 v104, a72
	v_accvgpr_read_b32 v105, a73
	v_accvgpr_read_b32 v106, a74
	v_accvgpr_read_b32 v107, a75
	s_waitcnt vmcnt(23)
	v_pk_fma_f32 v[60:61], v[104:105], v[24:25], v[60:61]
	v_pk_fma_f32 v[62:63], v[106:107], v[26:27], v[62:63]
	global_store_dwordx4 v[150:151], v[60:63], off offset:320
	v_accvgpr_read_b32 v104, a68
	v_accvgpr_read_b32 v105, a69
	v_accvgpr_read_b32 v106, a70
	v_accvgpr_read_b32 v107, a71
	s_waitcnt vmcnt(23)
	v_pk_fma_f32 v[64:65], v[104:105], v[32:33], v[64:65]
	v_pk_fma_f32 v[66:67], v[106:107], v[34:35], v[66:67]
	global_store_dwordx4 v[150:151], v[64:67], off offset:384
	v_accvgpr_read_b32 v104, a64
	v_accvgpr_read_b32 v105, a65
	v_accvgpr_read_b32 v106, a66
	v_accvgpr_read_b32 v107, a67
	s_waitcnt vmcnt(23)
	v_pk_fma_f32 v[68:69], v[104:105], v[36:37], v[68:69]
	v_pk_fma_f32 v[70:71], v[106:107], v[38:39], v[70:71]
	global_store_dwordx4 v[150:151], v[68:71], off offset:448
	v_accvgpr_read_b32 v104, a12
	v_accvgpr_read_b32 v105, a13
	v_accvgpr_read_b32 v106, a14
	v_accvgpr_read_b32 v107, a15
	s_waitcnt vmcnt(15)
	v_pk_fma_f32 v[72:73], v[104:105], v[4:5], v[72:73]
	v_pk_fma_f32 v[74:75], v[106:107], v[6:7], v[74:75]
	global_store_dwordx4 v[108:109], v[72:75], off
	v_accvgpr_read_b32 v104, a8
	v_accvgpr_read_b32 v105, a9
	v_accvgpr_read_b32 v106, a10
	v_accvgpr_read_b32 v107, a11
	s_waitcnt vmcnt(15)
	v_pk_fma_f32 v[76:77], v[104:105], v[8:9], v[76:77]
	v_pk_fma_f32 v[78:79], v[106:107], v[10:11], v[78:79]
	global_store_dwordx4 v[108:109], v[76:79], off offset:64
	v_accvgpr_read_b32 v104, a4
	v_accvgpr_read_b32 v105, a5
	v_accvgpr_read_b32 v106, a6
	v_accvgpr_read_b32 v107, a7
	s_waitcnt vmcnt(15)
	v_pk_fma_f32 v[80:81], v[104:105], v[12:13], v[80:81]
	v_pk_fma_f32 v[82:83], v[106:107], v[14:15], v[82:83]
	global_store_dwordx4 v[108:109], v[80:83], off offset:128
	v_accvgpr_read_b32 v104, a0
	v_accvgpr_read_b32 v105, a1
	v_accvgpr_read_b32 v106, a2
	v_accvgpr_read_b32 v107, a3
	s_waitcnt vmcnt(15)
	v_pk_fma_f32 v[84:85], v[104:105], v[16:17], v[84:85]
	v_pk_fma_f32 v[86:87], v[106:107], v[18:19], v[86:87]
	global_store_dwordx4 v[108:109], v[84:87], off offset:192
	v_accvgpr_read_b32 v104, a44
	v_accvgpr_read_b32 v105, a45
	v_accvgpr_read_b32 v106, a46
	v_accvgpr_read_b32 v107, a47
	s_waitcnt vmcnt(15)
	v_pk_fma_f32 v[88:89], v[104:105], v[20:21], v[88:89]
	v_pk_fma_f32 v[90:91], v[106:107], v[22:23], v[90:91]
	global_store_dwordx4 v[108:109], v[88:91], off offset:256
	v_accvgpr_read_b32 v104, a40
	v_accvgpr_read_b32 v105, a41
	v_accvgpr_read_b32 v106, a42
	v_accvgpr_read_b32 v107, a43
	s_waitcnt vmcnt(15)
	v_pk_fma_f32 v[92:93], v[104:105], v[24:25], v[92:93]
	v_pk_fma_f32 v[94:95], v[106:107], v[26:27], v[94:95]
	global_store_dwordx4 v[108:109], v[92:95], off offset:320
	v_accvgpr_read_b32 v104, a36
	v_accvgpr_read_b32 v105, a37
	v_accvgpr_read_b32 v106, a38
	v_accvgpr_read_b32 v107, a39
	s_waitcnt vmcnt(15)
	v_pk_fma_f32 v[96:97], v[104:105], v[32:33], v[96:97]
	v_pk_fma_f32 v[98:99], v[106:107], v[34:35], v[98:99]
	global_store_dwordx4 v[108:109], v[96:99], off offset:384
	v_accvgpr_read_b32 v104, a32
	v_accvgpr_read_b32 v105, a33
	v_accvgpr_read_b32 v106, a34
	v_accvgpr_read_b32 v107, a35
	s_waitcnt vmcnt(15)
	v_pk_fma_f32 v[100:101], v[104:105], v[36:37], v[100:101]
	v_pk_fma_f32 v[102:103], v[106:107], v[38:39], v[102:103]
	global_store_dwordx4 v[108:109], v[100:103], off offset:448
	v_readlane_b32 s8, v255, 22
	s_add_i32 s55, s55, s8
	s_cmpk_gt_i32 s55, 0x5ff
	s_cbranch_scc1 .LBB0_2025

; #define LD_AF(dst, ks_) _Pragma("unroll") for (int i = 0; i < 8; ++i) dst[i] = *(const h8*)(sA + i * 16 * G_LD + (ks_) * 32)
; #define LD_BF(dst, ks_, nh_) _Pragma("unroll") for (int i = 0; i < 4; ++i) dst[i] = *(const h8*)(sB + ((nh_) * 4 + i) * 16 * G_LD + (ks_) * 32)
; #define MMA_BLK(afx, bfx, nh_) _Pragma("unroll") for (int mi = 0; mi < 8; ++mi) _Pragma("unroll") for (int ni = 0; ni < 4; ++ni) mfma16_acc(acc[mi][(nh_) * 4 + ni], bfx[ni], afx[mi])
; template <class Epi>
; __device__ __forceinline__ void gemm_run(const GemmArgs g, Epi epi, char* smem) {
;     ...
;       const hf* sA = sbase + (kt & 1) * G_STAGE + (wm * 128 + fr) * G_LD + fqs;
;       const hf* sB = sbase + (kt & 1) * G_STAGE + (256 + wn * 128 + fr) * G_LD + fqs;
;       hf* st = sbase + ((kt + 1) & 1) * G_STAGE;
;       h8 afA[8], afB[8], bfA[4], bfB[4];
;     ...
;       LD_AF(afA, 0); LD_BF(bfA, 0, 0);
;       if (kt + 1 < nk) {
; #pragma unroll
;         for (int i = 0; i < 8; ++i) *(u4*)(st + (lr + 32 * i) * G_LD + lcw) = ra[i];
;       }
;       __builtin_amdgcn_sched_barrier(0);
;       LD_BF(bfB, 0, 1);
;       MMA_BLK(afA, bfA, 0);
;       __builtin_amdgcn_sched_barrier(0);
;       if (kt + 1 < nk) {
; #pragma unroll
;         for (int i = 0; i < 8; ++i) *(u4*)(st + (256 + lr + 32 * i) * G_LD + lcw) = rb[i];
;       }
;       LD_AF(afB, 1); LD_BF(bfA, 1, 0);
;       MMA_BLK(afA, bfB, 1);
;       __builtin_amdgcn_sched_barrier(0);
;       if (kt + 2 < nk) {
;         const int ko = (kt + 2) * 64;
; #pragma unroll
;         for (int i = 0; i < 8; ++i) { ra[i] = __builtin_amdgcn_raw_buffer_load_b128(Ars, aoff, i * astep + ko * 2, 0); rb[i] = __builtin_amdgcn_raw_buffer_load_b128(Brs, boff, i * bstep + ko * 2, 0); }
;       }
;       LD_BF(bfB, 1, 1);
;       MMA_BLK(afB, bfA, 0);
;       __builtin_amdgcn_sched_barrier(0);
;       MMA_BLK(afB, bfB, 1);
;       __builtin_amdgcn_sched_barrier(0);
.LBB0_2100:
	ds_read_b128 v[0:3], v136 offset:36864
	ds_read_b128 v[4:7], v136 offset:39168
	ds_read_b128 v[8:11], v136 offset:41472
	ds_read_b128 v[12:15], v136 offset:43776
	ds_read_b128 v[16:19], v137
	ds_read_b128 v[20:23], v137 offset:2304
	ds_read_b128 v[24:27], v137 offset:4608
	ds_read_b128 v[28:31], v137 offset:6912
	ds_read_b128 v[32:35], v137 offset:9216
	ds_read_b128 v[36:39], v137 offset:11520
	ds_read_b128 v[40:43], v137 offset:13824
	ds_read_b128 v[44:47], v137 offset:16128
	ds_read_b128 v[48:51], v136 offset:46080
	ds_read_b128 v[52:55], v136 offset:48384
	ds_read_b128 v[56:59], v136 offset:50688
	ds_read_b128 v[60:63], v136 offset:52992
	s_waitcnt lgkmcnt(11)
	v_mfma_f32_16x16x32_f16 a[208:211], v[0:3], v[16:19], a[208:211]
	v_mfma_f32_16x16x32_f16 a[200:203], v[4:7], v[16:19], a[200:203]
	v_mfma_f32_16x16x32_f16 a[196:199], v[8:11], v[16:19], a[196:199]
	v_mfma_f32_16x16x32_f16 a[192:195], v[12:15], v[16:19], a[192:195]
	s_waitcnt lgkmcnt(10)
	v_mfma_f32_16x16x32_f16 a[188:191], v[0:3], v[20:23], a[188:191]
	v_mfma_f32_16x16x32_f16 a[184:187], v[4:7], v[20:23], a[184:187]
	v_mfma_f32_16x16x32_f16 a[180:183], v[8:11], v[20:23], a[180:183]
	v_mfma_f32_16x16x32_f16 a[176:179], v[12:15], v[20:23], a[176:179]
	s_waitcnt lgkmcnt(9)
	v_mfma_f32_16x16x32_f16 a[156:159], v[0:3], v[24:27], a[156:159]
	v_mfma_f32_16x16x32_f16 a[152:155], v[4:7], v[24:27], a[152:155]
	v_mfma_f32_16x16x32_f16 a[148:151], v[8:11], v[24:27], a[148:151]
	v_mfma_f32_16x16x32_f16 a[144:147], v[12:15], v[24:27], a[144:147]
	s_waitcnt lgkmcnt(8)
	v_mfma_f32_16x16x32_f16 a[124:127], v[0:3], v[28:31], a[124:127]
	v_mfma_f32_16x16x32_f16 a[120:123], v[4:7], v[28:31], a[120:123]
	v_mfma_f32_16x16x32_f16 a[116:119], v[8:11], v[28:31], a[116:119]
	v_mfma_f32_16x16x32_f16 a[112:115], v[12:15], v[28:31], a[112:115]
	s_waitcnt lgkmcnt(7)
	v_mfma_f32_16x16x32_f16 a[92:95], v[0:3], v[32:35], a[92:95]
	v_mfma_f32_16x16x32_f16 a[88:91], v[4:7], v[32:35], a[88:91]
	v_mfma_f32_16x16x32_f16 a[84:87], v[8:11], v[32:35], a[84:87]
	v_mfma_f32_16x16x32_f16 a[80:83], v[12:15], v[32:35], a[80:83]
	s_waitcnt lgkmcnt(6)
	v_mfma_f32_16x16x32_f16 a[60:63], v[0:3], v[36:39], a[60:63]
	v_mfma_f32_16x16x32_f16 a[56:59], v[4:7], v[36:39], a[56:59]
	v_mfma_f32_16x16x32_f16 a[52:55], v[8:11], v[36:39], a[52:55]
	v_mfma_f32_16x16x32_f16 a[48:51], v[12:15], v[36:39], a[48:51]
	s_waitcnt lgkmcnt(5)
	v_mfma_f32_16x16x32_f16 a[28:31], v[0:3], v[40:43], a[28:31]
	v_mfma_f32_16x16x32_f16 a[24:27], v[4:7], v[40:43], a[24:27]
	v_mfma_f32_16x16x32_f16 a[20:23], v[8:11], v[40:43], a[20:23]
	v_mfma_f32_16x16x32_f16 a[16:19], v[12:15], v[40:43], a[16:19]
	s_waitcnt lgkmcnt(4)
	v_mfma_f32_16x16x32_f16 a[12:15], v[0:3], v[44:47], a[12:15]
	v_mfma_f32_16x16x32_f16 a[8:11], v[4:7], v[44:47], a[8:11]
	v_mfma_f32_16x16x32_f16 a[4:7], v[8:11], v[44:47], a[4:7]
	v_mfma_f32_16x16x32_f16 a[0:3], v[12:15], v[44:47], a[0:3]
	s_waitcnt lgkmcnt(3)
	v_mfma_f32_16x16x32_f16 a[172:175], v[48:51], v[28:31], a[172:175]
	s_waitcnt lgkmcnt(2)
	v_mfma_f32_16x16x32_f16 a[168:171], v[52:55], v[28:31], a[168:171]
	s_waitcnt lgkmcnt(1)
	v_mfma_f32_16x16x32_f16 a[164:167], v[56:59], v[28:31], a[164:167]
	s_waitcnt lgkmcnt(0)
	v_mfma_f32_16x16x32_f16 a[160:163], v[60:63], v[28:31], a[160:163]
	v_mfma_f32_16x16x32_f16 a[140:143], v[48:51], v[32:35], a[140:143]
	v_mfma_f32_16x16x32_f16 a[136:139], v[52:55], v[32:35], a[136:139]
	v_mfma_f32_16x16x32_f16 a[132:135], v[56:59], v[32:35], a[132:135]
	v_mfma_f32_16x16x32_f16 a[128:131], v[60:63], v[32:35], a[128:131]
	ds_read_b128 v[12:15], v136 offset:36928
	ds_read_b128 v[28:31], v136 offset:39232
	ds_read_b128 v[32:35], v136 offset:41536
	ds_read_b128 v[64:67], v136 offset:43840
	ds_read_b128 v[76:79], v137 offset:64
	ds_read_b128 v[80:83], v137 offset:2368
	s_waitcnt vmcnt(8)
	ds_read_b128 v[140:143], v137 offset:4672
	s_waitcnt vmcnt(6)
	ds_read_b128 v[144:147], v137 offset:6976
	s_waitcnt vmcnt(3)
	ds_read_b128 v[148:151], v137 offset:9280
	ds_read_b128 v[8:11], v137 offset:11584
	ds_read_b128 v[4:7], v137 offset:13888
	ds_read_b128 v[0:3], v137 offset:16192
	v_mfma_f32_16x16x32_f16 a[240:243], v[48:51], v[16:19], a[240:243]
	v_mfma_f32_16x16x32_f16 a[252:255], v[52:55], v[16:19], a[252:255]
	v_mfma_f32_16x16x32_f16 a[248:251], v[56:59], v[16:19], a[248:251]
	v_mfma_f32_16x16x32_f16 a[244:247], v[60:63], v[16:19], a[244:247]
	v_mfma_f32_16x16x32_f16 a[236:239], v[48:51], v[20:23], a[236:239]
	v_mfma_f32_16x16x32_f16 a[232:235], v[52:55], v[20:23], a[232:235]
	v_mfma_f32_16x16x32_f16 a[228:231], v[56:59], v[20:23], a[228:231]
	v_mfma_f32_16x16x32_f16 a[224:227], v[60:63], v[20:23], a[224:227]
	v_mfma_f32_16x16x32_f16 a[220:223], v[48:51], v[24:27], a[220:223]
	v_mfma_f32_16x16x32_f16 a[216:219], v[52:55], v[24:27], a[216:219]
	v_mfma_f32_16x16x32_f16 a[212:215], v[56:59], v[24:27], a[212:215]
	v_mfma_f32_16x16x32_f16 a[204:207], v[60:63], v[24:27], a[204:207]
	v_mfma_f32_16x16x32_f16 a[108:111], v[48:51], v[36:39], a[108:111]
	v_mfma_f32_16x16x32_f16 a[104:107], v[52:55], v[36:39], a[104:107]
	v_mfma_f32_16x16x32_f16 a[100:103], v[56:59], v[36:39], a[100:103]
	v_mfma_f32_16x16x32_f16 a[96:99], v[60:63], v[36:39], a[96:99]
	v_mfma_f32_16x16x32_f16 a[76:79], v[48:51], v[40:43], a[76:79]
	v_mfma_f32_16x16x32_f16 a[72:75], v[52:55], v[40:43], a[72:75]
	v_mfma_f32_16x16x32_f16 a[68:71], v[56:59], v[40:43], a[68:71]
	v_mfma_f32_16x16x32_f16 a[64:67], v[60:63], v[40:43], a[64:67]
	v_mfma_f32_16x16x32_f16 a[44:47], v[48:51], v[44:47], a[44:47]
	v_mfma_f32_16x16x32_f16 a[40:43], v[52:55], v[44:47], a[40:43]
	v_mfma_f32_16x16x32_f16 a[36:39], v[56:59], v[44:47], a[36:39]
	v_mfma_f32_16x16x32_f16 a[32:35], v[60:63], v[44:47], a[32:35]
	ds_read_b128 v[152:155], v136 offset:46144
	s_waitcnt vmcnt(2)
; #define LD_AF(dst, ks_) _Pragma("unroll") for (int i = 0; i < 8; ++i) dst[i] = *(const h8*)(sA + i * 16 * G_LD + (ks_) * 32)
; #define LD_BF(dst, ks_, nh_) _Pragma("unroll") for (int i = 0; i < 4; ++i) dst[i] = *(const h8*)(sB + ((nh_) * 4 + i) * 16 * G_LD + (ks_) * 32)
; #define MMA_BLK(afx, bfx, nh_) _Pragma("unroll") for (int mi = 0; mi < 8; ++mi) _Pragma("unroll") for (int ni = 0; ni < 4; ++ni) mfma16_acc(acc[mi][(nh_) * 4 + ni], bfx[ni], afx[mi])
; template <class Epi>
; __device__ __forceinline__ void gemm_run(const GemmArgs g, Epi epi, char* smem) {
;     ...
;       LD_AF(afB, 1); LD_BF(bfA, 1, 0);
;       MMA_BLK(afA, bfB, 1);
;       __builtin_amdgcn_sched_barrier(0);
;       if (kt + 2 < nk) {
;         const int ko = (kt + 2) * 64;
; #pragma unroll
;         for (int i = 0; i < 8; ++i) { ra[i] = __builtin_amdgcn_raw_buffer_load_b128(Ars, aoff, i * astep + ko * 2, 0); rb[i] = __builtin_amdgcn_raw_buffer_load_b128(Brs, boff, i * bstep + ko * 2, 0); }
;       }
;       LD_BF(bfB, 1, 1);
;       MMA_BLK(afB, bfA, 0);
;       __builtin_amdgcn_sched_barrier(0);
;       MMA_BLK(afB, bfB, 1);
;       __builtin_amdgcn_sched_barrier(0);
	ds_read_b128 v[156:159], v136 offset:48448
	ds_read_b128 v[160:163], v136 offset:50752
	s_waitcnt vmcnt(1)
	ds_read_b128 v[164:167], v136 offset:53056
	s_waitcnt lgkmcnt(11)
	v_mfma_f32_16x16x32_f16 a[208:211], v[12:15], v[76:79], a[208:211]
	v_mfma_f32_16x16x32_f16 a[200:203], v[28:31], v[76:79], a[200:203]
	v_mfma_f32_16x16x32_f16 a[196:199], v[32:35], v[76:79], a[196:199]
	v_mfma_f32_16x16x32_f16 a[192:195], v[64:67], v[76:79], a[192:195]
	s_waitcnt lgkmcnt(10)
	v_mfma_f32_16x16x32_f16 a[188:191], v[12:15], v[80:83], a[188:191]
	v_mfma_f32_16x16x32_f16 a[184:187], v[28:31], v[80:83], a[184:187]
	v_mfma_f32_16x16x32_f16 a[180:183], v[32:35], v[80:83], a[180:183]
	v_mfma_f32_16x16x32_f16 a[176:179], v[64:67], v[80:83], a[176:179]
	s_waitcnt lgkmcnt(9)
	v_mfma_f32_16x16x32_f16 a[156:159], v[12:15], v[140:143], a[156:159]
	v_mfma_f32_16x16x32_f16 a[152:155], v[28:31], v[140:143], a[152:155]
	v_mfma_f32_16x16x32_f16 a[148:151], v[32:35], v[140:143], a[148:151]
	v_mfma_f32_16x16x32_f16 a[144:147], v[64:67], v[140:143], a[144:147]
	s_waitcnt lgkmcnt(8)
	v_mfma_f32_16x16x32_f16 a[124:127], v[12:15], v[144:147], a[124:127]
	v_mfma_f32_16x16x32_f16 a[120:123], v[28:31], v[144:147], a[120:123]
	v_mfma_f32_16x16x32_f16 a[116:119], v[32:35], v[144:147], a[116:119]
	v_mfma_f32_16x16x32_f16 a[112:115], v[64:67], v[144:147], a[112:115]
	s_waitcnt lgkmcnt(7)
	v_mfma_f32_16x16x32_f16 a[92:95], v[12:15], v[148:151], a[92:95]
	v_mfma_f32_16x16x32_f16 a[88:91], v[28:31], v[148:151], a[88:91]
	v_mfma_f32_16x16x32_f16 a[84:87], v[32:35], v[148:151], a[84:87]
	v_mfma_f32_16x16x32_f16 a[80:83], v[64:67], v[148:151], a[80:83]
	v_accvgpr_read_b32 v123, a211
	v_accvgpr_read_b32 v122, a210
	v_accvgpr_read_b32 v121, a203
	v_accvgpr_read_b32 v120, a202
	v_accvgpr_read_b32 v119, a199
	v_accvgpr_read_b32 v118, a198
	v_accvgpr_read_b32 v117, a195
	v_accvgpr_read_b32 v116, a194
	v_accvgpr_read_b32 v107, a191
	v_accvgpr_read_b32 v106, a190
	v_accvgpr_read_b32 v105, a187
	v_accvgpr_read_b32 v104, a186
	v_accvgpr_read_b32 v103, a183
	v_accvgpr_read_b32 v102, a182
	v_accvgpr_read_b32 v101, a179
	v_accvgpr_read_b32 v100, a178
	v_accvgpr_read_b32 v91, a159
	v_accvgpr_read_b32 v90, a158
	v_accvgpr_read_b32 v89, a155
	v_accvgpr_read_b32 v88, a154
	v_accvgpr_read_b32 v87, a151
	v_accvgpr_read_b32 v86, a150
	v_accvgpr_read_b32 v85, a147
	v_accvgpr_read_b32 v84, a146
	v_accvgpr_read_b32 v75, a127
	v_accvgpr_read_b32 v74, a126
	v_accvgpr_read_b32 v73, a123
	v_accvgpr_read_b32 v72, a122
	v_accvgpr_read_b32 v71, a119
	v_accvgpr_read_b32 v70, a118
	v_accvgpr_read_b32 v69, a115
	v_accvgpr_read_b32 v68, a114
	v_accvgpr_read_b32 v59, a95
	v_accvgpr_read_b32 v58, a94
	v_accvgpr_read_b32 v57, a91
	v_accvgpr_read_b32 v56, a90
	v_accvgpr_read_b32 v55, a87
	v_accvgpr_read_b32 v54, a86
	v_accvgpr_read_b32 v53, a83
	v_accvgpr_read_b32 v52, a82
	s_waitcnt lgkmcnt(6)
	v_mfma_f32_16x16x32_f16 a[60:63], v[12:15], v[8:11], a[60:63]
	v_mfma_f32_16x16x32_f16 a[56:59], v[28:31], v[8:11], a[56:59]
	v_mfma_f32_16x16x32_f16 a[52:55], v[32:35], v[8:11], a[52:55]
	v_mfma_f32_16x16x32_f16 a[48:51], v[64:67], v[8:11], a[48:51]
	s_waitcnt lgkmcnt(5)
	v_mfma_f32_16x16x32_f16 a[28:31], v[12:15], v[4:7], a[28:31]
	v_mfma_f32_16x16x32_f16 a[24:27], v[28:31], v[4:7], a[24:27]
	v_mfma_f32_16x16x32_f16 a[20:23], v[32:35], v[4:7], a[20:23]
	v_mfma_f32_16x16x32_f16 a[16:19], v[64:67], v[4:7], a[16:19]
	s_waitcnt lgkmcnt(4)
	v_mfma_f32_16x16x32_f16 a[12:15], v[12:15], v[0:3], a[12:15]
	v_mfma_f32_16x16x32_f16 a[8:11], v[28:31], v[0:3], a[8:11]
	v_mfma_f32_16x16x32_f16 a[4:7], v[32:35], v[0:3], a[4:7]
	v_mfma_f32_16x16x32_f16 a[0:3], v[64:67], v[0:3], a[0:3]
	v_accvgpr_read_b32 v43, a63
	v_accvgpr_read_b32 v42, a62
	v_accvgpr_read_b32 v41, a59
	v_accvgpr_read_b32 v40, a58
	v_accvgpr_read_b32 v39, a55
	v_accvgpr_read_b32 v38, a54
	v_accvgpr_read_b32 v37, a51
	v_accvgpr_read_b32 v36, a50
	v_accvgpr_read_b32 v27, a31
	v_accvgpr_read_b32 v26, a30
	v_accvgpr_read_b32 v25, a27
	v_accvgpr_read_b32 v24, a26
	v_accvgpr_read_b32 v23, a23
	v_accvgpr_read_b32 v22, a22
	v_accvgpr_read_b32 v21, a19
	v_accvgpr_read_b32 v20, a18
	v_accvgpr_read_b32 v19, a15
	v_accvgpr_read_b32 v18, a14
	v_accvgpr_read_b32 v17, a11
	v_accvgpr_read_b32 v16, a10
	v_accvgpr_read_b32 v15, a7
	v_accvgpr_read_b32 v14, a6
	v_accvgpr_read_b32 v13, a3
	v_accvgpr_read_b32 v12, a2
	s_waitcnt lgkmcnt(3)
	v_mfma_f32_16x16x32_f16 a[240:243], v[152:155], v[76:79], a[240:243]
	s_waitcnt lgkmcnt(2)
	v_mfma_f32_16x16x32_f16 a[252:255], v[156:159], v[76:79], a[252:255]
	s_waitcnt lgkmcnt(1)
	v_mfma_f32_16x16x32_f16 a[248:251], v[160:163], v[76:79], a[248:251]
	s_waitcnt lgkmcnt(0)
	v_mfma_f32_16x16x32_f16 a[244:247], v[164:167], v[76:79], a[244:247]
	v_mfma_f32_16x16x32_f16 a[236:239], v[152:155], v[80:83], a[236:239]
	v_mfma_f32_16x16x32_f16 a[232:235], v[156:159], v[80:83], a[232:235]
	v_mfma_f32_16x16x32_f16 a[228:231], v[160:163], v[80:83], a[228:231]
	v_mfma_f32_16x16x32_f16 a[224:227], v[164:167], v[80:83], a[224:227]
	v_mfma_f32_16x16x32_f16 a[220:223], v[152:155], v[140:143], a[220:223]
	v_mfma_f32_16x16x32_f16 a[216:219], v[156:159], v[140:143], a[216:219]
	v_mfma_f32_16x16x32_f16 a[212:215], v[160:163], v[140:143], a[212:215]
	v_mfma_f32_16x16x32_f16 a[204:207], v[164:167], v[140:143], a[204:207]
	v_mfma_f32_16x16x32_f16 a[172:175], v[152:155], v[144:147], a[172:175]
	v_mfma_f32_16x16x32_f16 a[168:171], v[156:159], v[144:147], a[168:171]
	v_mfma_f32_16x16x32_f16 a[164:167], v[160:163], v[144:147], a[164:167]
	v_mfma_f32_16x16x32_f16 a[160:163], v[164:167], v[144:147], a[160:163]
	v_mfma_f32_16x16x32_f16 a[140:143], v[152:155], v[148:151], a[140:143]
	v_mfma_f32_16x16x32_f16 a[136:139], v[156:159], v[148:151], a[136:139]
	v_mfma_f32_16x16x32_f16 a[132:135], v[160:163], v[148:151], a[132:135]
	v_mfma_f32_16x16x32_f16 a[128:131], v[164:167], v[148:151], a[128:131]
	s_waitcnt vmcnt(0)
; #define MMA_BLK(afx, bfx, nh_) _Pragma("unroll") for (int mi = 0; mi < 8; ++mi) _Pragma("unroll") for (int ni = 0; ni < 4; ++ni) mfma16_acc(acc[mi][(nh_) * 4 + ni], bfx[ni], afx[mi])
; template <class Epi>
; __device__ __forceinline__ void gemm_run(const GemmArgs g, Epi epi, char* smem) {
;     ...
;       MMA_BLK(afB, bfA, 0);
;       __builtin_amdgcn_sched_barrier(0);
;       MMA_BLK(afB, bfB, 1);
	v_accvgpr_read_b32 v169, a243
	v_accvgpr_read_b32 v168, a242
	v_accvgpr_read_b32 v171, a255
	v_accvgpr_read_b32 v170, a254
	v_accvgpr_read_b32 v127, a251
	v_accvgpr_read_b32 v126, a250
	v_accvgpr_read_b32 v125, a247
	v_accvgpr_read_b32 v124, a246
	v_accvgpr_read_b32 v115, a239
	v_accvgpr_read_b32 v114, a238
	v_accvgpr_read_b32 v113, a235
	v_accvgpr_read_b32 v112, a234
	v_accvgpr_read_b32 v111, a231
	v_accvgpr_read_b32 v110, a230
	v_accvgpr_read_b32 v109, a227
	v_accvgpr_read_b32 v108, a226
	v_accvgpr_read_b32 v99, a223
	v_accvgpr_read_b32 v98, a222
	v_accvgpr_read_b32 v97, a219
	v_accvgpr_read_b32 v96, a218
	v_accvgpr_read_b32 v95, a215
	v_accvgpr_read_b32 v94, a214
	v_accvgpr_read_b32 v93, a207
	v_accvgpr_read_b32 v92, a206
	v_accvgpr_read_b32 v83, a175
	v_accvgpr_read_b32 v82, a174
	v_accvgpr_read_b32 v81, a171
	v_accvgpr_read_b32 v80, a170
	v_accvgpr_read_b32 v79, a167
	v_accvgpr_read_b32 v78, a166
	v_accvgpr_read_b32 v77, a163
	v_accvgpr_read_b32 v76, a162
	v_accvgpr_read_b32 v67, a143
	v_accvgpr_read_b32 v66, a142
	v_accvgpr_read_b32 v65, a139
	v_accvgpr_read_b32 v64, a138
	v_accvgpr_read_b32 v63, a135
	v_accvgpr_read_b32 v62, a134
	v_accvgpr_read_b32 v61, a131
	v_accvgpr_read_b32 v60, a130
	v_mfma_f32_16x16x32_f16 a[108:111], v[152:155], v[8:11], a[108:111]
	v_mfma_f32_16x16x32_f16 a[104:107], v[156:159], v[8:11], a[104:107]
	v_mfma_f32_16x16x32_f16 a[100:103], v[160:163], v[8:11], a[100:103]
	v_mfma_f32_16x16x32_f16 a[96:99], v[164:167], v[8:11], a[96:99]
	v_mfma_f32_16x16x32_f16 a[76:79], v[152:155], v[4:7], a[76:79]
	v_mfma_f32_16x16x32_f16 a[72:75], v[156:159], v[4:7], a[72:75]
	v_mfma_f32_16x16x32_f16 a[68:71], v[160:163], v[4:7], a[68:71]
	v_mfma_f32_16x16x32_f16 a[64:67], v[164:167], v[4:7], a[64:67]
	v_mfma_f32_16x16x32_f16 a[44:47], v[152:155], v[0:3], a[44:47]
	v_mfma_f32_16x16x32_f16 a[40:43], v[156:159], v[0:3], a[40:43]
	v_mfma_f32_16x16x32_f16 a[36:39], v[160:163], v[0:3], a[36:39]
	v_mfma_f32_16x16x32_f16 a[32:35], v[164:167], v[0:3], a[32:35]
	s_nop 0
	v_lshl_add_u32 v30, s52, 8, v130
	v_min_i32_e32 v3, 0x8000, v30
	v_or_b32_e32 v2, s53, v133
	v_ashrrev_i32_e32 v3, 13, v3
	v_mul_hi_i32_i24_e32 v141, 0xc000, v3
	v_mul_i32_i24_e32 v140, 0xc000, v3
	v_ashrrev_i32_e32 v3, 31, v2
	v_lshl_add_u64 v[140:141], s[16:17], 0, v[140:141]
	v_lshlrev_b64 v[2:3], 2, v[2:3]
	v_ashrrev_i32_e32 v31, 31, v30
	v_lshl_add_u64 v[148:149], v[140:141], 0, v[2:3]
	v_lshlrev_b64 v[140:141], 13, v[30:31]
	v_lshl_add_u64 v[140:141], s[28:29], 0, v[140:141]
	v_lshl_add_u64 v[150:151], v[140:141], 0, v[2:3]
	s_barrier
	global_load_dwordx4 v[4:7], v[148:149], off
	global_load_dwordx4 v[8:11], v[148:149], off offset:64
	global_load_dwordx4 v[12:15], v[148:149], off offset:128
	global_load_dwordx4 v[16:19], v[148:149], off offset:192
	global_load_dwordx4 v[20:23], v[148:149], off offset:256
	global_load_dwordx4 v[24:27], v[148:149], off offset:320
	global_load_dwordx4 v[32:35], v[148:149], off offset:384
	global_load_dwordx4 v[36:39], v[148:149], off offset:448
	global_load_dwordx4 v[40:43], v[150:151], off
	global_load_dwordx4 v[44:47], v[150:151], off offset:64
	global_load_dwordx4 v[48:51], v[150:151], off offset:128
	global_load_dwordx4 v[52:55], v[150:151], off offset:192
	global_load_dwordx4 v[56:59], v[150:151], off offset:256
	global_load_dwordx4 v[60:63], v[150:151], off offset:320
	global_load_dwordx4 v[64:67], v[150:151], off offset:384
	global_load_dwordx4 v[68:71], v[150:151], off offset:448
	v_mov_b32_e32 v110, 0x20000
	v_mov_b32_e32 v111, 0
	v_lshl_add_u64 v[108:109], v[150:151], 0, v[110:111]
	v_mov_b32_e32 v110, 0x40000
	global_load_dwordx4 v[72:75], v[108:109], off
	global_load_dwordx4 v[76:79], v[108:109], off offset:64
	global_load_dwordx4 v[80:83], v[108:109], off offset:128
	global_load_dwordx4 v[84:87], v[108:109], off offset:192
	global_load_dwordx4 v[88:91], v[108:109], off offset:256
	global_load_dwordx4 v[92:95], v[108:109], off offset:320
	global_load_dwordx4 v[96:99], v[108:109], off offset:384
	global_load_dwordx4 v[100:103], v[108:109], off offset:448
	v_accvgpr_read_b32 v104, a208
	v_accvgpr_read_b32 v105, a209
	v_accvgpr_read_b32 v106, a210
	v_accvgpr_read_b32 v107, a211
	s_waitcnt vmcnt(15)
	v_pk_fma_f32 v[40:41], v[104:105], v[4:5], v[40:41]
	v_pk_fma_f32 v[42:43], v[106:107], v[6:7], v[42:43]
	global_store_dwordx4 v[150:151], v[40:43], off
	v_accvgpr_read_b32 v104, a200
	v_accvgpr_read_b32 v105, a201
	v_accvgpr_read_b32 v106, a202
	v_accvgpr_read_b32 v107, a203
	s_waitcnt vmcnt(15)
	v_pk_fma_f32 v[44:45], v[104:105], v[8:9], v[44:45]
	v_pk_fma_f32 v[46:47], v[106:107], v[10:11], v[46:47]
	global_store_dwordx4 v[150:151], v[44:47], off offset:64
	v_accvgpr_read_b32 v104, a196
	v_accvgpr_read_b32 v105, a197
	v_accvgpr_read_b32 v106, a198
	v_accvgpr_read_b32 v107, a199
	s_waitcnt vmcnt(15)
	v_pk_fma_f32 v[48:49], v[104:105], v[12:13], v[48:49]
	v_pk_fma_f32 v[50:51], v[106:107], v[14:15], v[50:51]
	global_store_dwordx4 v[150:151], v[48:51], off offset:128
	v_accvgpr_read_b32 v104, a192
	v_accvgpr_read_b32 v105, a193
	v_accvgpr_read_b32 v106, a194
	v_accvgpr_read_b32 v107, a195
	s_waitcnt vmcnt(15)
	v_pk_fma_f32 v[52:53], v[104:105], v[16:17], v[52:53]
	v_pk_fma_f32 v[54:55], v[106:107], v[18:19], v[54:55]
	global_store_dwordx4 v[150:151], v[52:55], off offset:192
	v_accvgpr_read_b32 v104, a240
	v_accvgpr_read_b32 v105, a241
	v_accvgpr_read_b32 v106, a242
	v_accvgpr_read_b32 v107, a243
	s_waitcnt vmcnt(15)
	v_pk_fma_f32 v[56:57], v[104:105], v[20:21], v[56:57]
	v_pk_fma_f32 v[58:59], v[106:107], v[22:23], v[58:59]
	global_store_dwordx4 v[150:151], v[56:59], off offset:256
	v_accvgpr_read_b32 v104, a252
	v_accvgpr_read_b32 v105, a253
	v_accvgpr_read_b32 v106, a254
	v_accvgpr_read_b32 v107, a255
	s_waitcnt vmcnt(15)
	v_pk_fma_f32 v[60:61], v[104:105], v[24:25], v[60:61]
	v_pk_fma_f32 v[62:63], v[106:107], v[26:27], v[62:63]
	global_store_dwordx4 v[150:151], v[60:63], off offset:320
	v_accvgpr_read_b32 v104, a248
	v_accvgpr_read_b32 v105, a249
	v_accvgpr_read_b32 v106, a250
	v_accvgpr_read_b32 v107, a251
	s_waitcnt vmcnt(15)
	v_pk_fma_f32 v[64:65], v[104:105], v[32:33], v[64:65]
	v_pk_fma_f32 v[66:67], v[106:107], v[34:35], v[66:67]
	global_store_dwordx4 v[150:151], v[64:67], off offset:384
	v_accvgpr_read_b32 v104, a244
	v_accvgpr_read_b32 v105, a245
	v_accvgpr_read_b32 v106, a246
	v_accvgpr_read_b32 v107, a247
	s_waitcnt vmcnt(15)
	v_pk_fma_f32 v[68:69], v[104:105], v[36:37], v[68:69]
	v_pk_fma_f32 v[70:71], v[106:107], v[38:39], v[70:71]
	global_store_dwordx4 v[150:151], v[68:71], off offset:448
	v_lshl_add_u64 v[150:151], v[150:151], 0, v[110:111]
	s_nop 1
	global_load_dwordx4 v[40:43], v[150:151], off
	global_load_dwordx4 v[44:47], v[150:151], off offset:64
	global_load_dwordx4 v[48:51], v[150:151], off offset:128
	global_load_dwordx4 v[52:55], v[150:151], off offset:192
	global_load_dwordx4 v[56:59], v[150:151], off offset:256
	global_load_dwordx4 v[60:63], v[150:151], off offset:320
	global_load_dwordx4 v[64:67], v[150:151], off offset:384
	global_load_dwordx4 v[68:71], v[150:151], off offset:448
	v_accvgpr_read_b32 v104, a188
	v_accvgpr_read_b32 v105, a189
	v_accvgpr_read_b32 v106, a190
	v_accvgpr_read_b32 v107, a191
	s_waitcnt vmcnt(23)
	v_pk_fma_f32 v[72:73], v[104:105], v[4:5], v[72:73]
	v_pk_fma_f32 v[74:75], v[106:107], v[6:7], v[74:75]
	global_store_dwordx4 v[108:109], v[72:75], off
	v_accvgpr_read_b32 v104, a184
	v_accvgpr_read_b32 v105, a185
	v_accvgpr_read_b32 v106, a186
	v_accvgpr_read_b32 v107, a187
	s_waitcnt vmcnt(23)
	v_pk_fma_f32 v[76:77], v[104:105], v[8:9], v[76:77]
	v_pk_fma_f32 v[78:79], v[106:107], v[10:11], v[78:79]
	global_store_dwordx4 v[108:109], v[76:79], off offset:64
	v_accvgpr_read_b32 v104, a180
	v_accvgpr_read_b32 v105, a181
	v_accvgpr_read_b32 v106, a182
	v_accvgpr_read_b32 v107, a183
	s_waitcnt vmcnt(23)
	v_pk_fma_f32 v[80:81], v[104:105], v[12:13], v[80:81]
	v_pk_fma_f32 v[82:83], v[106:107], v[14:15], v[82:83]
	global_store_dwordx4 v[108:109], v[80:83], off offset:128
	v_accvgpr_read_b32 v104, a176
	v_accvgpr_read_b32 v105, a177
	v_accvgpr_read_b32 v106, a178
	v_accvgpr_read_b32 v107, a179
	s_waitcnt vmcnt(23)
	v_pk_fma_f32 v[84:85], v[104:105], v[16:17], v[84:85]
	v_pk_fma_f32 v[86:87], v[106:107], v[18:19], v[86:87]
	global_store_dwordx4 v[108:109], v[84:87], off offset:192
	v_accvgpr_read_b32 v104, a236
	v_accvgpr_read_b32 v105, a237
	v_accvgpr_read_b32 v106, a238
	v_accvgpr_read_b32 v107, a239
	s_waitcnt vmcnt(23)
	v_pk_fma_f32 v[88:89], v[104:105], v[20:21], v[88:89]
	v_pk_fma_f32 v[90:91], v[106:107], v[22:23], v[90:91]
	global_store_dwordx4 v[108:109], v[88:91], off offset:256
	v_accvgpr_read_b32 v104, a232
	v_accvgpr_read_b32 v105, a233
	v_accvgpr_read_b32 v106, a234
	v_accvgpr_read_b32 v107, a235
	s_waitcnt vmcnt(23)
	v_pk_fma_f32 v[92:93], v[104:105], v[24:25], v[92:93]
	v_pk_fma_f32 v[94:95], v[106:107], v[26:27], v[94:95]
	global_store_dwordx4 v[108:109], v[92:95], off offset:320
	v_accvgpr_read_b32 v104, a228
	v_accvgpr_read_b32 v105, a229
	v_accvgpr_read_b32 v106, a230
	v_accvgpr_read_b32 v107, a231
	s_waitcnt vmcnt(23)
	v_pk_fma_f32 v[96:97], v[104:105], v[32:33], v[96:97]
	v_pk_fma_f32 v[98:99], v[106:107], v[34:35], v[98:99]
	global_store_dwordx4 v[108:109], v[96:99], off offset:384
	v_accvgpr_read_b32 v104, a224
	v_accvgpr_read_b32 v105, a225
	v_accvgpr_read_b32 v106, a226
	v_accvgpr_read_b32 v107, a227
	s_waitcnt vmcnt(23)
	v_pk_fma_f32 v[100:101], v[104:105], v[36:37], v[100:101]
	v_pk_fma_f32 v[102:103], v[106:107], v[38:39], v[102:103]
	global_store_dwordx4 v[108:109], v[100:103], off offset:448
	v_lshl_add_u64 v[108:109], v[108:109], 0, v[110:111]
	s_nop 1
	global_load_dwordx4 v[72:75], v[108:109], off
	global_load_dwordx4 v[76:79], v[108:109], off offset:64
	global_load_dwordx4 v[80:83], v[108:109], off offset:128
	global_load_dwordx4 v[84:87], v[108:109], off offset:192
	global_load_dwordx4 v[88:91], v[108:109], off offset:256
	global_load_dwordx4 v[92:95], v[108:109], off offset:320
	global_load_dwordx4 v[96:99], v[108:109], off offset:384
	global_load_dwordx4 v[100:103], v[108:109], off offset:448
	v_accvgpr_read_b32 v104, a156
	v_accvgpr_read_b32 v105, a157
	v_accvgpr_read_b32 v106, a158
	v_accvgpr_read_b32 v107, a159
	s_waitcnt vmcnt(23)
	v_pk_fma_f32 v[40:41], v[104:105], v[4:5], v[40:41]
	v_pk_fma_f32 v[42:43], v[106:107], v[6:7], v[42:43]
	global_store_dwordx4 v[150:151], v[40:43], off
	v_accvgpr_read_b32 v104, a152
	v_accvgpr_read_b32 v105, a153
	v_accvgpr_read_b32 v106, a154
	v_accvgpr_read_b32 v107, a155
	s_waitcnt vmcnt(23)
	v_pk_fma_f32 v[44:45], v[104:105], v[8:9], v[44:45]
	v_pk_fma_f32 v[46:47], v[106:107], v[10:11], v[46:47]
	global_store_dwordx4 v[150:151], v[44:47], off offset:64
	v_accvgpr_read_b32 v104, a148
	v_accvgpr_read_b32 v105, a149
	v_accvgpr_read_b32 v106, a150
	v_accvgpr_read_b32 v107, a151
	s_waitcnt vmcnt(23)
	v_pk_fma_f32 v[48:49], v[104:105], v[12:13], v[48:49]
	v_pk_fma_f32 v[50:51], v[106:107], v[14:15], v[50:51]
	global_store_dwordx4 v[150:151], v[48:51], off offset:128
	v_accvgpr_read_b32 v104, a144
	v_accvgpr_read_b32 v105, a145
	v_accvgpr_read_b32 v106, a146
	v_accvgpr_read_b32 v107, a147
	s_waitcnt vmcnt(23)
	v_pk_fma_f32 v[52:53], v[104:105], v[16:17], v[52:53]
	v_pk_fma_f32 v[54:55], v[106:107], v[18:19], v[54:55]
	global_store_dwordx4 v[150:151], v[52:55], off offset:192
	v_accvgpr_read_b32 v104, a220
	v_accvgpr_read_b32 v105, a221
	v_accvgpr_read_b32 v106, a222
	v_accvgpr_read_b32 v107, a223
	s_waitcnt vmcnt(23)
	v_pk_fma_f32 v[56:57], v[104:105], v[20:21], v[56:57]
	v_pk_fma_f32 v[58:59], v[106:107], v[22:23], v[58:59]
	global_store_dwordx4 v[150:151], v[56:59], off offset:256
	v_accvgpr_read_b32 v104, a216
	v_accvgpr_read_b32 v105, a217
	v_accvgpr_read_b32 v106, a218
	v_accvgpr_read_b32 v107, a219
	s_waitcnt vmcnt(23)
	v_pk_fma_f32 v[60:61], v[104:105], v[24:25], v[60:61]
	v_pk_fma_f32 v[62:63], v[106:107], v[26:27], v[62:63]
	global_store_dwordx4 v[150:151], v[60:63], off offset:320
	v_accvgpr_read_b32 v104, a212
	v_accvgpr_read_b32 v105, a213
	v_accvgpr_read_b32 v106, a214
	v_accvgpr_read_b32 v107, a215
	s_waitcnt vmcnt(23)
	v_pk_fma_f32 v[64:65], v[104:105], v[32:33], v[64:65]
	v_pk_fma_f32 v[66:67], v[106:107], v[34:35], v[66:67]
	global_store_dwordx4 v[150:151], v[64:67], off offset:384
	v_accvgpr_read_b32 v104, a204
	v_accvgpr_read_b32 v105, a205
	v_accvgpr_read_b32 v106, a206
	v_accvgpr_read_b32 v107, a207
	s_waitcnt vmcnt(23)
	v_pk_fma_f32 v[68:69], v[104:105], v[36:37], v[68:69]
	v_pk_fma_f32 v[70:71], v[106:107], v[38:39], v[70:71]
	global_store_dwordx4 v[150:151], v[68:71], off offset:448
	v_lshl_add_u64 v[150:151], v[150:151], 0, v[110:111]
	s_nop 1
	global_load_dwordx4 v[40:43], v[150:151], off
	global_load_dwordx4 v[44:47], v[150:151], off offset:64
	global_load_dwordx4 v[48:51], v[150:151], off offset:128
	global_load_dwordx4 v[52:55], v[150:151], off offset:192
	global_load_dwordx4 v[56:59], v[150:151], off offset:256
	global_load_dwordx4 v[60:63], v[150:151], off offset:320
	global_load_dwordx4 v[64:67], v[150:151], off offset:384
	global_load_dwordx4 v[68:71], v[150:151], off offset:448
	v_accvgpr_read_b32 v104, a124
	v_accvgpr_read_b32 v105, a125
	v_accvgpr_read_b32 v106, a126
	v_accvgpr_read_b32 v107, a127
	s_waitcnt vmcnt(23)
	v_pk_fma_f32 v[72:73], v[104:105], v[4:5], v[72:73]
	v_pk_fma_f32 v[74:75], v[106:107], v[6:7], v[74:75]
	global_store_dwordx4 v[108:109], v[72:75], off
	v_accvgpr_read_b32 v104, a120
	v_accvgpr_read_b32 v105, a121
	v_accvgpr_read_b32 v106, a122
	v_accvgpr_read_b32 v107, a123
	s_waitcnt vmcnt(23)
	v_pk_fma_f32 v[76:77], v[104:105], v[8:9], v[76:77]
	v_pk_fma_f32 v[78:79], v[106:107], v[10:11], v[78:79]
	global_store_dwordx4 v[108:109], v[76:79], off offset:64
	v_accvgpr_read_b32 v104, a116
	v_accvgpr_read_b32 v105, a117
	v_accvgpr_read_b32 v106, a118
	v_accvgpr_read_b32 v107, a119
	s_waitcnt vmcnt(23)
	v_pk_fma_f32 v[80:81], v[104:105], v[12:13], v[80:81]
	v_pk_fma_f32 v[82:83], v[106:107], v[14:15], v[82:83]
	global_store_dwordx4 v[108:109], v[80:83], off offset:128
	v_accvgpr_read_b32 v104, a112
	v_accvgpr_read_b32 v105, a113
	v_accvgpr_read_b32 v106, a114
	v_accvgpr_read_b32 v107, a115
	s_waitcnt vmcnt(23)
	v_pk_fma_f32 v[84:85], v[104:105], v[16:17], v[84:85]
	v_pk_fma_f32 v[86:87], v[106:107], v[18:19], v[86:87]
	global_store_dwordx4 v[108:109], v[84:87], off offset:192
	v_accvgpr_read_b32 v104, a172
	v_accvgpr_read_b32 v105, a173
	v_accvgpr_read_b32 v106, a174
	v_accvgpr_read_b32 v107, a175
	s_waitcnt vmcnt(23)
	v_pk_fma_f32 v[88:89], v[104:105], v[20:21], v[88:89]
	v_pk_fma_f32 v[90:91], v[106:107], v[22:23], v[90:91]
	global_store_dwordx4 v[108:109], v[88:91], off offset:256
	v_accvgpr_read_b32 v104, a168
	v_accvgpr_read_b32 v105, a169
	v_accvgpr_read_b32 v106, a170
	v_accvgpr_read_b32 v107, a171
	s_waitcnt vmcnt(23)
	v_pk_fma_f32 v[92:93], v[104:105], v[24:25], v[92:93]
	v_pk_fma_f32 v[94:95], v[106:107], v[26:27], v[94:95]
	global_store_dwordx4 v[108:109], v[92:95], off offset:320
	v_accvgpr_read_b32 v104, a164
	v_accvgpr_read_b32 v105, a165
	v_accvgpr_read_b32 v106, a166
	v_accvgpr_read_b32 v107, a167
	s_waitcnt vmcnt(23)
	v_pk_fma_f32 v[96:97], v[104:105], v[32:33], v[96:97]
	v_pk_fma_f32 v[98:99], v[106:107], v[34:35], v[98:99]
	global_store_dwordx4 v[108:109], v[96:99], off offset:384
	v_accvgpr_read_b32 v104, a160
	v_accvgpr_read_b32 v105, a161
	v_accvgpr_read_b32 v106, a162
	v_accvgpr_read_b32 v107, a163
	s_waitcnt vmcnt(23)
	v_pk_fma_f32 v[100:101], v[104:105], v[36:37], v[100:101]
	v_pk_fma_f32 v[102:103], v[106:107], v[38:39], v[102:103]
	global_store_dwordx4 v[108:109], v[100:103], off offset:448
	v_lshl_add_u64 v[108:109], v[108:109], 0, v[110:111]
	s_nop 1
	global_load_dwordx4 v[72:75], v[108:109], off
	global_load_dwordx4 v[76:79], v[108:109], off offset:64
	global_load_dwordx4 v[80:83], v[108:109], off offset:128
	global_load_dwordx4 v[84:87], v[108:109], off offset:192
	global_load_dwordx4 v[88:91], v[108:109], off offset:256
	global_load_dwordx4 v[92:95], v[108:109], off offset:320
	global_load_dwordx4 v[96:99], v[108:109], off offset:384
	global_load_dwordx4 v[100:103], v[108:109], off offset:448
	v_accvgpr_read_b32 v104, a92
	v_accvgpr_read_b32 v105, a93
	v_accvgpr_read_b32 v106, a94
	v_accvgpr_read_b32 v107, a95
	s_waitcnt vmcnt(23)
	v_pk_fma_f32 v[40:41], v[104:105], v[4:5], v[40:41]
	v_pk_fma_f32 v[42:43], v[106:107], v[6:7], v[42:43]
	global_store_dwordx4 v[150:151], v[40:43], off
	v_accvgpr_read_b32 v104, a88
	v_accvgpr_read_b32 v105, a89
	v_accvgpr_read_b32 v106, a90
	v_accvgpr_read_b32 v107, a91
	s_waitcnt vmcnt(23)
	v_pk_fma_f32 v[44:45], v[104:105], v[8:9], v[44:45]
	v_pk_fma_f32 v[46:47], v[106:107], v[10:11], v[46:47]
	global_store_dwordx4 v[150:151], v[44:47], off offset:64
	v_accvgpr_read_b32 v104, a84
	v_accvgpr_read_b32 v105, a85
	v_accvgpr_read_b32 v106, a86
	v_accvgpr_read_b32 v107, a87
	s_waitcnt vmcnt(23)
	v_pk_fma_f32 v[48:49], v[104:105], v[12:13], v[48:49]
	v_pk_fma_f32 v[50:51], v[106:107], v[14:15], v[50:51]
	global_store_dwordx4 v[150:151], v[48:51], off offset:128
	v_accvgpr_read_b32 v104, a80
	v_accvgpr_read_b32 v105, a81
	v_accvgpr_read_b32 v106, a82
	v_accvgpr_read_b32 v107, a83
	s_waitcnt vmcnt(23)
	v_pk_fma_f32 v[52:53], v[104:105], v[16:17], v[52:53]
	v_pk_fma_f32 v[54:55], v[106:107], v[18:19], v[54:55]
	global_store_dwordx4 v[150:151], v[52:55], off offset:192
	v_accvgpr_read_b32 v104, a140
	v_accvgpr_read_b32 v105, a141
	v_accvgpr_read_b32 v106, a142
	v_accvgpr_read_b32 v107, a143
	s_waitcnt vmcnt(23)
	v_pk_fma_f32 v[56:57], v[104:105], v[20:21], v[56:57]
	v_pk_fma_f32 v[58:59], v[106:107], v[22:23], v[58:59]
	global_store_dwordx4 v[150:151], v[56:59], off offset:256
	v_accvgpr_read_b32 v104, a136
	v_accvgpr_read_b32 v105, a137
	v_accvgpr_read_b32 v106, a138
	v_accvgpr_read_b32 v107, a139
	s_waitcnt vmcnt(23)
	v_pk_fma_f32 v[60:61], v[104:105], v[24:25], v[60:61]
	v_pk_fma_f32 v[62:63], v[106:107], v[26:27], v[62:63]
	global_store_dwordx4 v[150:151], v[60:63], off offset:320
	v_accvgpr_read_b32 v104, a132
	v_accvgpr_read_b32 v105, a133
	v_accvgpr_read_b32 v106, a134
	v_accvgpr_read_b32 v107, a135
	s_waitcnt vmcnt(23)
	v_pk_fma_f32 v[64:65], v[104:105], v[32:33], v[64:65]
	v_pk_fma_f32 v[66:67], v[106:107], v[34:35], v[66:67]
	global_store_dwordx4 v[150:151], v[64:67], off offset:384
	v_accvgpr_read_b32 v104, a128
	v_accvgpr_read_b32 v105, a129
	v_accvgpr_read_b32 v106, a130
	v_accvgpr_read_b32 v107, a131
	s_waitcnt vmcnt(23)
	v_pk_fma_f32 v[68:69], v[104:105], v[36:37], v[68:69]
	v_pk_fma_f32 v[70:71], v[106:107], v[38:39], v[70:71]
	global_store_dwordx4 v[150:151], v[68:71], off offset:448
	v_lshl_add_u64 v[150:151], v[150:151], 0, v[110:111]
	s_nop 1
	global_load_dwordx4 v[40:43], v[150:151], off
	global_load_dwordx4 v[44:47], v[150:151], off offset:64
	global_load_dwordx4 v[48:51], v[150:151], off offset:128
	global_load_dwordx4 v[52:55], v[150:151], off offset:192
	global_load_dwordx4 v[56:59], v[150:151], off offset:256
	global_load_dwordx4 v[60:63], v[150:151], off offset:320
	global_load_dwordx4 v[64:67], v[150:151], off offset:384
	global_load_dwordx4 v[68:71], v[150:151], off offset:448
	v_accvgpr_read_b32 v104, a60
	v_accvgpr_read_b32 v105, a61
	v_accvgpr_read_b32 v106, a62
	v_accvgpr_read_b32 v107, a63
	s_waitcnt vmcnt(23)
	v_pk_fma_f32 v[72:73], v[104:105], v[4:5], v[72:73]
	v_pk_fma_f32 v[74:75], v[106:107], v[6:7], v[74:75]
	global_store_dwordx4 v[108:109], v[72:75], off
	v_accvgpr_read_b32 v104, a56
	v_accvgpr_read_b32 v105, a57
	v_accvgpr_read_b32 v106, a58
	v_accvgpr_read_b32 v107, a59
	s_waitcnt vmcnt(23)
	v_pk_fma_f32 v[76:77], v[104:105], v[8:9], v[76:77]
	v_pk_fma_f32 v[78:79], v[106:107], v[10:11], v[78:79]
	global_store_dwordx4 v[108:109], v[76:79], off offset:64
	v_accvgpr_read_b32 v104, a52
	v_accvgpr_read_b32 v105, a53
	v_accvgpr_read_b32 v106, a54
	v_accvgpr_read_b32 v107, a55
	s_waitcnt vmcnt(23)
	v_pk_fma_f32 v[80:81], v[104:105], v[12:13], v[80:81]
	v_pk_fma_f32 v[82:83], v[106:107], v[14:15], v[82:83]
	global_store_dwordx4 v[108:109], v[80:83], off offset:128
	v_accvgpr_read_b32 v104, a48
	v_accvgpr_read_b32 v105, a49
	v_accvgpr_read_b32 v106, a50
	v_accvgpr_read_b32 v107, a51
	s_waitcnt vmcnt(23)
	v_pk_fma_f32 v[84:85], v[104:105], v[16:17], v[84:85]
	v_pk_fma_f32 v[86:87], v[106:107], v[18:19], v[86:87]
	global_store_dwordx4 v[108:109], v[84:87], off offset:192
	v_accvgpr_read_b32 v104, a108
	v_accvgpr_read_b32 v105, a109
	v_accvgpr_read_b32 v106, a110
	v_accvgpr_read_b32 v107, a111
	s_waitcnt vmcnt(23)
	v_pk_fma_f32 v[88:89], v[104:105], v[20:21], v[88:89]
	v_pk_fma_f32 v[90:91], v[106:107], v[22:23], v[90:91]
	global_store_dwordx4 v[108:109], v[88:91], off offset:256
	v_accvgpr_read_b32 v104, a104
	v_accvgpr_read_b32 v105, a105
	v_accvgpr_read_b32 v106, a106
	v_accvgpr_read_b32 v107, a107
	s_waitcnt vmcnt(23)
	v_pk_fma_f32 v[92:93], v[104:105], v[24:25], v[92:93]
	v_pk_fma_f32 v[94:95], v[106:107], v[26:27], v[94:95]
	global_store_dwordx4 v[108:109], v[92:95], off offset:320
	v_accvgpr_read_b32 v104, a100
	v_accvgpr_read_b32 v105, a101
	v_accvgpr_read_b32 v106, a102
	v_accvgpr_read_b32 v107, a103
	s_waitcnt vmcnt(23)
	v_pk_fma_f32 v[96:97], v[104:105], v[32:33], v[96:97]
	v_pk_fma_f32 v[98:99], v[106:107], v[34:35], v[98:99]
	global_store_dwordx4 v[108:109], v[96:99], off offset:384
	v_accvgpr_read_b32 v104, a96
	v_accvgpr_read_b32 v105, a97
	v_accvgpr_read_b32 v106, a98
	v_accvgpr_read_b32 v107, a99
	s_waitcnt vmcnt(23)
	v_pk_fma_f32 v[100:101], v[104:105], v[36:37], v[100:101]
	v_pk_fma_f32 v[102:103], v[106:107], v[38:39], v[102:103]
	global_store_dwordx4 v[108:109], v[100:103], off offset:448
	v_lshl_add_u64 v[108:109], v[108:109], 0, v[110:111]
	s_nop 1
	global_load_dwordx4 v[72:75], v[108:109], off
	global_load_dwordx4 v[76:79], v[108:109], off offset:64
	global_load_dwordx4 v[80:83], v[108:109], off offset:128
	global_load_dwordx4 v[84:87], v[108:109], off offset:192
	global_load_dwordx4 v[88:91], v[108:109], off offset:256
	global_load_dwordx4 v[92:95], v[108:109], off offset:320
	global_load_dwordx4 v[96:99], v[108:109], off offset:384
	global_load_dwordx4 v[100:103], v[108:109], off offset:448
	v_accvgpr_read_b32 v104, a28
	v_accvgpr_read_b32 v105, a29
	v_accvgpr_read_b32 v106, a30
	v_accvgpr_read_b32 v107, a31
	s_waitcnt vmcnt(23)
	v_pk_fma_f32 v[40:41], v[104:105], v[4:5], v[40:41]
	v_pk_fma_f32 v[42:43], v[106:107], v[6:7], v[42:43]
	global_store_dwordx4 v[150:151], v[40:43], off
	v_accvgpr_read_b32 v104, a24
	v_accvgpr_read_b32 v105, a25
	v_accvgpr_read_b32 v106, a26
	v_accvgpr_read_b32 v107, a27
	s_waitcnt vmcnt(23)
	v_pk_fma_f32 v[44:45], v[104:105], v[8:9], v[44:45]
	v_pk_fma_f32 v[46:47], v[106:107], v[10:11], v[46:47]
	global_store_dwordx4 v[150:151], v[44:47], off offset:64
	v_accvgpr_read_b32 v104, a20
	v_accvgpr_read_b32 v105, a21
	v_accvgpr_read_b32 v106, a22
	v_accvgpr_read_b32 v107, a23
	s_waitcnt vmcnt(23)
	v_pk_fma_f32 v[48:49], v[104:105], v[12:13], v[48:49]
	v_pk_fma_f32 v[50:51], v[106:107], v[14:15], v[50:51]
	global_store_dwordx4 v[150:151], v[48:51], off offset:128
	v_accvgpr_read_b32 v104, a16
	v_accvgpr_read_b32 v105, a17
	v_accvgpr_read_b32 v106, a18
	v_accvgpr_read_b32 v107, a19
	s_waitcnt vmcnt(23)
	v_pk_fma_f32 v[52:53], v[104:105], v[16:17], v[52:53]
	v_pk_fma_f32 v[54:55], v[106:107], v[18:19], v[54:55]
	global_store_dwordx4 v[150:151], v[52:55], off offset:192
	v_accvgpr_read_b32 v104, a76
	v_accvgpr_read_b32 v105, a77
	v_accvgpr_read_b32 v106, a78
	v_accvgpr_read_b32 v107, a79
	s_waitcnt vmcnt(23)
	v_pk_fma_f32 v[56:57], v[104:105], v[20:21], v[56:57]
	v_pk_fma_f32 v[58:59], v[106:107], v[22:23], v[58:59]
	global_store_dwordx4 v[150:151], v[56:59], off offset:256
	v_accvgpr_read_b32 v104, a72
	v_accvgpr_read_b32 v105, a73
	v_accvgpr_read_b32 v106, a74
	v_accvgpr_read_b32 v107, a75
	s_waitcnt vmcnt(23)
	v_pk_fma_f32 v[60:61], v[104:105], v[24:25], v[60:61]
	v_pk_fma_f32 v[62:63], v[106:107], v[26:27], v[62:63]
	global_store_dwordx4 v[150:151], v[60:63], off offset:320
	v_accvgpr_read_b32 v104, a68
	v_accvgpr_read_b32 v105, a69
	v_accvgpr_read_b32 v106, a70
	v_accvgpr_read_b32 v107, a71
	s_waitcnt vmcnt(23)
	v_pk_fma_f32 v[64:65], v[104:105], v[32:33], v[64:65]
	v_pk_fma_f32 v[66:67], v[106:107], v[34:35], v[66:67]
	global_store_dwordx4 v[150:151], v[64:67], off offset:384
	v_accvgpr_read_b32 v104, a64
	v_accvgpr_read_b32 v105, a65
	v_accvgpr_read_b32 v106, a66
	v_accvgpr_read_b32 v107, a67
	s_waitcnt vmcnt(23)
	v_pk_fma_f32 v[68:69], v[104:105], v[36:37], v[68:69]
	v_pk_fma_f32 v[70:71], v[106:107], v[38:39], v[70:71]
	global_store_dwordx4 v[150:151], v[68:71], off offset:448
	v_accvgpr_read_b32 v104, a12
	v_accvgpr_read_b32 v105, a13
	v_accvgpr_read_b32 v106, a14
	v_accvgpr_read_b32 v107, a15
	s_waitcnt vmcnt(15)
	v_pk_fma_f32 v[72:73], v[104:105], v[4:5], v[72:73]
	v_pk_fma_f32 v[74:75], v[106:107], v[6:7], v[74:75]
	global_store_dwordx4 v[108:109], v[72:75], off
	v_accvgpr_read_b32 v104, a8
	v_accvgpr_read_b32 v105, a9
	v_accvgpr_read_b32 v106, a10
	v_accvgpr_read_b32 v107, a11
	s_waitcnt vmcnt(15)
	v_pk_fma_f32 v[76:77], v[104:105], v[8:9], v[76:77]
	v_pk_fma_f32 v[78:79], v[106:107], v[10:11], v[78:79]
	global_store_dwordx4 v[108:109], v[76:79], off offset:64
	v_accvgpr_read_b32 v104, a4
	v_accvgpr_read_b32 v105, a5
	v_accvgpr_read_b32 v106, a6
	v_accvgpr_read_b32 v107, a7
	s_waitcnt vmcnt(15)
	v_pk_fma_f32 v[80:81], v[104:105], v[12:13], v[80:81]
	v_pk_fma_f32 v[82:83], v[106:107], v[14:15], v[82:83]
	global_store_dwordx4 v[108:109], v[80:83], off offset:128
	v_accvgpr_read_b32 v104, a0
	v_accvgpr_read_b32 v105, a1
	v_accvgpr_read_b32 v106, a2
	v_accvgpr_read_b32 v107, a3
	s_waitcnt vmcnt(15)
	v_pk_fma_f32 v[84:85], v[104:105], v[16:17], v[84:85]
	v_pk_fma_f32 v[86:87], v[106:107], v[18:19], v[86:87]
	global_store_dwordx4 v[108:109], v[84:87], off offset:192
	v_accvgpr_read_b32 v104, a44
	v_accvgpr_read_b32 v105, a45
	v_accvgpr_read_b32 v106, a46
	v_accvgpr_read_b32 v107, a47
	s_waitcnt vmcnt(15)
	v_pk_fma_f32 v[88:89], v[104:105], v[20:21], v[88:89]
	v_pk_fma_f32 v[90:91], v[106:107], v[22:23], v[90:91]
	global_store_dwordx4 v[108:109], v[88:91], off offset:256
	v_accvgpr_read_b32 v104, a40
	v_accvgpr_read_b32 v105, a41
	v_accvgpr_read_b32 v106, a42
	v_accvgpr_read_b32 v107, a43
	s_waitcnt vmcnt(15)
	v_pk_fma_f32 v[92:93], v[104:105], v[24:25], v[92:93]
	v_pk_fma_f32 v[94:95], v[106:107], v[26:27], v[94:95]
	global_store_dwordx4 v[108:109], v[92:95], off offset:320
	v_accvgpr_read_b32 v104, a36
	v_accvgpr_read_b32 v105, a37
	v_accvgpr_read_b32 v106, a38
	v_accvgpr_read_b32 v107, a39
	s_waitcnt vmcnt(15)
	v_pk_fma_f32 v[96:97], v[104:105], v[32:33], v[96:97]
	v_pk_fma_f32 v[98:99], v[106:107], v[34:35], v[98:99]
	global_store_dwordx4 v[108:109], v[96:99], off offset:384
	v_accvgpr_read_b32 v104, a32
	v_accvgpr_read_b32 v105, a33
	v_accvgpr_read_b32 v106, a34
	v_accvgpr_read_b32 v107, a35
	s_waitcnt vmcnt(15)
	v_pk_fma_f32 v[100:101], v[104:105], v[36:37], v[100:101]
	v_pk_fma_f32 v[102:103], v[106:107], v[38:39], v[102:103]
	global_store_dwordx4 v[108:109], v[100:103], off offset:448
	s_add_i32 s49, s49, s2
	s_cmpk_gt_i32 s49, 0x1ff
	s_cbranch_scc1 .LBB0_2105

; #define LD_AF(dst, ks_) _Pragma("unroll") for (int i = 0; i < 8; ++i) dst[i] = *(const h8*)(sA + i * 16 * G_LD + (ks_) * 32)
; #define LD_BF(dst, ks_, nh_) _Pragma("unroll") for (int i = 0; i < 4; ++i) dst[i] = *(const h8*)(sB + ((nh_) * 4 + i) * 16 * G_LD + (ks_) * 32)
; #define MMA_BLK(afx, bfx, nh_) _Pragma("unroll") for (int mi = 0; mi < 8; ++mi) _Pragma("unroll") for (int ni = 0; ni < 4; ++ni) mfma16_acc(acc[mi][(nh_) * 4 + ni], bfx[ni], afx[mi])
; template <class Epi>
; __device__ __forceinline__ void gemm_run(const GemmArgs g, Epi epi, char* smem) {
;     ...
;       const hf* sA = sbase + (kt & 1) * G_STAGE + (wm * 128 + fr) * G_LD + fqs;
;       const hf* sB = sbase + (kt & 1) * G_STAGE + (256 + wn * 128 + fr) * G_LD + fqs;
;       hf* st = sbase + ((kt + 1) & 1) * G_STAGE;
;       h8 afA[8], afB[8], bfA[4], bfB[4];
;     ...
;       LD_AF(afA, 0); LD_BF(bfA, 0, 0);
;       if (kt + 1 < nk) {
; #pragma unroll
;         for (int i = 0; i < 8; ++i) *(u4*)(st + (lr + 32 * i) * G_LD + lcw) = ra[i];
;       }
;       __builtin_amdgcn_sched_barrier(0);
;       LD_BF(bfB, 0, 1);
;       MMA_BLK(afA, bfA, 0);
;       __builtin_amdgcn_sched_barrier(0);
;       if (kt + 1 < nk) {
; #pragma unroll
;         for (int i = 0; i < 8; ++i) *(u4*)(st + (256 + lr + 32 * i) * G_LD + lcw) = rb[i];
;       }
;       LD_AF(afB, 1); LD_BF(bfA, 1, 0);
;       MMA_BLK(afA, bfB, 1);
;       __builtin_amdgcn_sched_barrier(0);
;       if (kt + 2 < nk) {
;         const int ko = (kt + 2) * 64;
; #pragma unroll
;         for (int i = 0; i < 8; ++i) { ra[i] = __builtin_amdgcn_raw_buffer_load_b128(Ars, aoff, i * astep + ko * 2, 0); rb[i] = __builtin_amdgcn_raw_buffer_load_b128(Brs, boff, i * bstep + ko * 2, 0); }
;       }
;       LD_BF(bfB, 1, 1);
;       MMA_BLK(afB, bfA, 0);
;       __builtin_amdgcn_sched_barrier(0);
;       MMA_BLK(afB, bfB, 1);
.LBB0_2157:
	ds_read_b128 v[0:3], v134 offset:36864
	ds_read_b128 v[4:7], v134 offset:39168
	ds_read_b128 v[8:11], v134 offset:41472
	ds_read_b128 v[12:15], v134 offset:43776
	ds_read_b128 v[16:19], v135
	ds_read_b128 v[20:23], v135 offset:2304
	ds_read_b128 v[24:27], v135 offset:4608
	ds_read_b128 v[28:31], v135 offset:6912
	ds_read_b128 v[32:35], v135 offset:9216
	ds_read_b128 v[36:39], v135 offset:11520
	ds_read_b128 v[40:43], v135 offset:13824
	ds_read_b128 v[44:47], v135 offset:16128
	ds_read_b128 v[48:51], v134 offset:46080
	ds_read_b128 v[52:55], v134 offset:48384
	ds_read_b128 v[56:59], v134 offset:50688
	ds_read_b128 v[60:63], v134 offset:52992
	s_waitcnt lgkmcnt(11)
	v_mfma_f32_16x16x32_f16 a[208:211], v[0:3], v[16:19], a[208:211]
	v_mfma_f32_16x16x32_f16 a[200:203], v[4:7], v[16:19], a[200:203]
	v_mfma_f32_16x16x32_f16 a[196:199], v[8:11], v[16:19], a[196:199]
	v_mfma_f32_16x16x32_f16 a[192:195], v[12:15], v[16:19], a[192:195]
	s_waitcnt lgkmcnt(10)
	v_mfma_f32_16x16x32_f16 a[188:191], v[0:3], v[20:23], a[188:191]
	v_mfma_f32_16x16x32_f16 a[184:187], v[4:7], v[20:23], a[184:187]
	v_mfma_f32_16x16x32_f16 a[180:183], v[8:11], v[20:23], a[180:183]
	v_mfma_f32_16x16x32_f16 a[176:179], v[12:15], v[20:23], a[176:179]
	s_waitcnt lgkmcnt(9)
	v_mfma_f32_16x16x32_f16 a[156:159], v[0:3], v[24:27], a[156:159]
	v_mfma_f32_16x16x32_f16 a[152:155], v[4:7], v[24:27], a[152:155]
	v_mfma_f32_16x16x32_f16 a[148:151], v[8:11], v[24:27], a[148:151]
	v_mfma_f32_16x16x32_f16 a[144:147], v[12:15], v[24:27], a[144:147]
	s_waitcnt lgkmcnt(8)
	v_mfma_f32_16x16x32_f16 a[124:127], v[0:3], v[28:31], a[124:127]
	v_mfma_f32_16x16x32_f16 a[120:123], v[4:7], v[28:31], a[120:123]
	v_mfma_f32_16x16x32_f16 a[116:119], v[8:11], v[28:31], a[116:119]
	v_mfma_f32_16x16x32_f16 a[112:115], v[12:15], v[28:31], a[112:115]
	s_waitcnt lgkmcnt(7)
	v_mfma_f32_16x16x32_f16 a[92:95], v[0:3], v[32:35], a[92:95]
	v_mfma_f32_16x16x32_f16 a[88:91], v[4:7], v[32:35], a[88:91]
	v_mfma_f32_16x16x32_f16 a[84:87], v[8:11], v[32:35], a[84:87]
	v_mfma_f32_16x16x32_f16 a[80:83], v[12:15], v[32:35], a[80:83]
	s_waitcnt lgkmcnt(6)
	v_mfma_f32_16x16x32_f16 a[60:63], v[0:3], v[36:39], a[60:63]
	v_mfma_f32_16x16x32_f16 a[56:59], v[4:7], v[36:39], a[56:59]
	v_mfma_f32_16x16x32_f16 a[52:55], v[8:11], v[36:39], a[52:55]
	v_mfma_f32_16x16x32_f16 a[48:51], v[12:15], v[36:39], a[48:51]
	s_waitcnt lgkmcnt(5)
	v_mfma_f32_16x16x32_f16 a[28:31], v[0:3], v[40:43], a[28:31]
	v_mfma_f32_16x16x32_f16 a[24:27], v[4:7], v[40:43], a[24:27]
	v_mfma_f32_16x16x32_f16 a[20:23], v[8:11], v[40:43], a[20:23]
	v_mfma_f32_16x16x32_f16 a[16:19], v[12:15], v[40:43], a[16:19]
	s_waitcnt lgkmcnt(4)
	v_mfma_f32_16x16x32_f16 a[12:15], v[0:3], v[44:47], a[12:15]
	v_mfma_f32_16x16x32_f16 a[8:11], v[4:7], v[44:47], a[8:11]
	v_mfma_f32_16x16x32_f16 a[4:7], v[8:11], v[44:47], a[4:7]
	v_mfma_f32_16x16x32_f16 a[0:3], v[12:15], v[44:47], a[0:3]
	s_waitcnt lgkmcnt(3)
	v_mfma_f32_16x16x32_f16 a[172:175], v[48:51], v[28:31], a[172:175]
	s_waitcnt lgkmcnt(2)
	v_mfma_f32_16x16x32_f16 a[168:171], v[52:55], v[28:31], a[168:171]
	s_waitcnt lgkmcnt(1)
	v_mfma_f32_16x16x32_f16 a[164:167], v[56:59], v[28:31], a[164:167]
	s_waitcnt lgkmcnt(0)
	v_mfma_f32_16x16x32_f16 a[160:163], v[60:63], v[28:31], a[160:163]
	ds_read_b128 v[12:15], v134 offset:36928
	ds_read_b128 v[28:31], v134 offset:39232
	ds_read_b128 v[74:77], v134 offset:41536
	ds_read_b128 v[78:81], v134 offset:43840
	ds_read_b128 v[90:93], v135 offset:64
	s_waitcnt vmcnt(15)
	ds_read_b128 v[94:97], v135 offset:2368
	s_waitcnt vmcnt(8)
	ds_read_b128 v[138:141], v135 offset:4672
	s_waitcnt vmcnt(6)
	ds_read_b128 v[142:145], v135 offset:6976
	s_waitcnt vmcnt(3)
	ds_read_b128 v[146:149], v135 offset:9280
	ds_read_b128 v[8:11], v135 offset:11584
	ds_read_b128 v[4:7], v135 offset:13888
	ds_read_b128 v[0:3], v135 offset:16192
	v_mfma_f32_16x16x32_f16 a[240:243], v[48:51], v[16:19], a[240:243]
	v_mfma_f32_16x16x32_f16 a[252:255], v[52:55], v[16:19], a[252:255]
	v_mfma_f32_16x16x32_f16 a[248:251], v[56:59], v[16:19], a[248:251]
	v_mfma_f32_16x16x32_f16 a[244:247], v[60:63], v[16:19], a[244:247]
	v_mfma_f32_16x16x32_f16 a[236:239], v[48:51], v[20:23], a[236:239]
	v_mfma_f32_16x16x32_f16 a[232:235], v[52:55], v[20:23], a[232:235]
	v_mfma_f32_16x16x32_f16 a[228:231], v[56:59], v[20:23], a[228:231]
	v_mfma_f32_16x16x32_f16 a[224:227], v[60:63], v[20:23], a[224:227]
	v_mfma_f32_16x16x32_f16 a[220:223], v[48:51], v[24:27], a[220:223]
	v_mfma_f32_16x16x32_f16 a[216:219], v[52:55], v[24:27], a[216:219]
	v_mfma_f32_16x16x32_f16 a[212:215], v[56:59], v[24:27], a[212:215]
	v_mfma_f32_16x16x32_f16 a[204:207], v[60:63], v[24:27], a[204:207]
	v_mfma_f32_16x16x32_f16 a[140:143], v[48:51], v[32:35], a[140:143]
	v_mfma_f32_16x16x32_f16 a[136:139], v[52:55], v[32:35], a[136:139]
	v_mfma_f32_16x16x32_f16 a[132:135], v[56:59], v[32:35], a[132:135]
	v_mfma_f32_16x16x32_f16 a[128:131], v[60:63], v[32:35], a[128:131]
	v_mfma_f32_16x16x32_f16 a[108:111], v[48:51], v[36:39], a[108:111]
	v_mfma_f32_16x16x32_f16 a[104:107], v[52:55], v[36:39], a[104:107]
	v_mfma_f32_16x16x32_f16 a[100:103], v[56:59], v[36:39], a[100:103]
	v_mfma_f32_16x16x32_f16 a[96:99], v[60:63], v[36:39], a[96:99]
	v_mfma_f32_16x16x32_f16 a[76:79], v[48:51], v[40:43], a[76:79]
	v_mfma_f32_16x16x32_f16 a[72:75], v[52:55], v[40:43], a[72:75]
	v_mfma_f32_16x16x32_f16 a[68:71], v[56:59], v[40:43], a[68:71]
	v_mfma_f32_16x16x32_f16 a[64:67], v[60:63], v[40:43], a[64:67]
	v_mfma_f32_16x16x32_f16 a[44:47], v[48:51], v[44:47], a[44:47]
	v_mfma_f32_16x16x32_f16 a[40:43], v[52:55], v[44:47], a[40:43]
	v_mfma_f32_16x16x32_f16 a[36:39], v[56:59], v[44:47], a[36:39]
	v_mfma_f32_16x16x32_f16 a[32:35], v[60:63], v[44:47], a[32:35]
	ds_read_b128 v[150:153], v134 offset:46144
	s_waitcnt vmcnt(2)
; #define LD_AF(dst, ks_) _Pragma("unroll") for (int i = 0; i < 8; ++i) dst[i] = *(const h8*)(sA + i * 16 * G_LD + (ks_) * 32)
; #define LD_BF(dst, ks_, nh_) _Pragma("unroll") for (int i = 0; i < 4; ++i) dst[i] = *(const h8*)(sB + ((nh_) * 4 + i) * 16 * G_LD + (ks_) * 32)
; #define MMA_BLK(afx, bfx, nh_) _Pragma("unroll") for (int mi = 0; mi < 8; ++mi) _Pragma("unroll") for (int ni = 0; ni < 4; ++ni) mfma16_acc(acc[mi][(nh_) * 4 + ni], bfx[ni], afx[mi])
; template <class Epi>
; __device__ __forceinline__ void gemm_run(const GemmArgs g, Epi epi, char* smem) {
;     ...
;       LD_AF(afB, 1); LD_BF(bfA, 1, 0);
;       MMA_BLK(afA, bfB, 1);
;       __builtin_amdgcn_sched_barrier(0);
;       if (kt + 2 < nk) {
;         const int ko = (kt + 2) * 64;
; #pragma unroll
;         for (int i = 0; i < 8; ++i) { ra[i] = __builtin_amdgcn_raw_buffer_load_b128(Ars, aoff, i * astep + ko * 2, 0); rb[i] = __builtin_amdgcn_raw_buffer_load_b128(Brs, boff, i * bstep + ko * 2, 0); }
;       }
;       LD_BF(bfB, 1, 1);
;       MMA_BLK(afB, bfA, 0);
;       __builtin_amdgcn_sched_barrier(0);
;       MMA_BLK(afB, bfB, 1);
	ds_read_b128 v[154:157], v134 offset:48448
	ds_read_b128 v[158:161], v134 offset:50752
	s_waitcnt vmcnt(1)
	ds_read_b128 v[162:165], v134 offset:53056
	s_waitcnt lgkmcnt(11)
	v_mfma_f32_16x16x32_f16 a[208:211], v[12:15], v[90:93], a[208:211]
	v_mfma_f32_16x16x32_f16 a[200:203], v[28:31], v[90:93], a[200:203]
	v_mfma_f32_16x16x32_f16 a[196:199], v[74:77], v[90:93], a[196:199]
	v_mfma_f32_16x16x32_f16 a[192:195], v[78:81], v[90:93], a[192:195]
	s_waitcnt lgkmcnt(10)
	v_mfma_f32_16x16x32_f16 a[188:191], v[12:15], v[94:97], a[188:191]
	v_mfma_f32_16x16x32_f16 a[184:187], v[28:31], v[94:97], a[184:187]
	v_mfma_f32_16x16x32_f16 a[180:183], v[74:77], v[94:97], a[180:183]
	v_mfma_f32_16x16x32_f16 a[176:179], v[78:81], v[94:97], a[176:179]
	s_waitcnt lgkmcnt(9)
	v_mfma_f32_16x16x32_f16 a[156:159], v[12:15], v[138:141], a[156:159]
	v_mfma_f32_16x16x32_f16 a[152:155], v[28:31], v[138:141], a[152:155]
	v_mfma_f32_16x16x32_f16 a[148:151], v[74:77], v[138:141], a[148:151]
	v_mfma_f32_16x16x32_f16 a[144:147], v[78:81], v[138:141], a[144:147]
	s_waitcnt lgkmcnt(8)
	v_mfma_f32_16x16x32_f16 a[124:127], v[12:15], v[142:145], a[124:127]
	v_mfma_f32_16x16x32_f16 a[120:123], v[28:31], v[142:145], a[120:123]
	v_mfma_f32_16x16x32_f16 a[116:119], v[74:77], v[142:145], a[116:119]
	v_mfma_f32_16x16x32_f16 a[112:115], v[78:81], v[142:145], a[112:115]
	s_waitcnt lgkmcnt(7)
	v_mfma_f32_16x16x32_f16 a[92:95], v[12:15], v[146:149], a[92:95]
	v_mfma_f32_16x16x32_f16 a[88:91], v[28:31], v[146:149], a[88:91]
	v_mfma_f32_16x16x32_f16 a[84:87], v[74:77], v[146:149], a[84:87]
	v_mfma_f32_16x16x32_f16 a[80:83], v[78:81], v[146:149], a[80:83]
	v_accvgpr_read_b32 v121, a211
	v_accvgpr_read_b32 v120, a210
	v_accvgpr_read_b32 v119, a203
	v_accvgpr_read_b32 v118, a202
	v_accvgpr_read_b32 v117, a199
	v_accvgpr_read_b32 v116, a198
	v_accvgpr_read_b32 v115, a195
	v_accvgpr_read_b32 v114, a194
	v_accvgpr_read_b32 v105, a191
	v_accvgpr_read_b32 v104, a190
	v_accvgpr_read_b32 v103, a187
	v_accvgpr_read_b32 v102, a186
	v_accvgpr_read_b32 v101, a183
	v_accvgpr_read_b32 v100, a182
	v_accvgpr_read_b32 v99, a179
	v_accvgpr_read_b32 v98, a178
	v_accvgpr_read_b32 v89, a159
	v_accvgpr_read_b32 v88, a158
	v_accvgpr_read_b32 v87, a155
	v_accvgpr_read_b32 v86, a154
	v_accvgpr_read_b32 v85, a151
	v_accvgpr_read_b32 v84, a150
	v_accvgpr_read_b32 v83, a147
	v_accvgpr_read_b32 v82, a146
	v_accvgpr_read_b32 v73, a127
	v_accvgpr_read_b32 v72, a126
	v_accvgpr_read_b32 v71, a123
	v_accvgpr_read_b32 v70, a122
	v_accvgpr_read_b32 v69, a119
	v_accvgpr_read_b32 v68, a118
	v_accvgpr_read_b32 v67, a115
	v_accvgpr_read_b32 v66, a114
	v_accvgpr_read_b32 v57, a95
	v_accvgpr_read_b32 v56, a94
	v_accvgpr_read_b32 v55, a91
	v_accvgpr_read_b32 v54, a90
	v_accvgpr_read_b32 v53, a87
	v_accvgpr_read_b32 v52, a86
	v_accvgpr_read_b32 v51, a83
	v_accvgpr_read_b32 v50, a82
	s_waitcnt lgkmcnt(6)
	v_mfma_f32_16x16x32_f16 a[60:63], v[12:15], v[8:11], a[60:63]
	v_mfma_f32_16x16x32_f16 a[56:59], v[28:31], v[8:11], a[56:59]
	v_mfma_f32_16x16x32_f16 a[52:55], v[74:77], v[8:11], a[52:55]
	v_mfma_f32_16x16x32_f16 a[48:51], v[78:81], v[8:11], a[48:51]
	s_waitcnt lgkmcnt(5)
	v_mfma_f32_16x16x32_f16 a[28:31], v[12:15], v[4:7], a[28:31]
	v_mfma_f32_16x16x32_f16 a[24:27], v[28:31], v[4:7], a[24:27]
	v_mfma_f32_16x16x32_f16 a[20:23], v[74:77], v[4:7], a[20:23]
	v_mfma_f32_16x16x32_f16 a[16:19], v[78:81], v[4:7], a[16:19]
	s_waitcnt lgkmcnt(4)
	v_mfma_f32_16x16x32_f16 a[12:15], v[12:15], v[0:3], a[12:15]
	v_mfma_f32_16x16x32_f16 a[8:11], v[28:31], v[0:3], a[8:11]
	v_mfma_f32_16x16x32_f16 a[4:7], v[74:77], v[0:3], a[4:7]
	v_mfma_f32_16x16x32_f16 a[0:3], v[78:81], v[0:3], a[0:3]
	v_accvgpr_read_b32 v41, a63
	v_accvgpr_read_b32 v40, a62
	v_accvgpr_read_b32 v39, a59
	v_accvgpr_read_b32 v38, a58
	v_accvgpr_read_b32 v37, a55
	v_accvgpr_read_b32 v36, a54
	v_accvgpr_read_b32 v35, a51
	v_accvgpr_read_b32 v34, a50
	v_accvgpr_read_b32 v27, a31
	v_accvgpr_read_b32 v26, a30
	v_accvgpr_read_b32 v25, a27
	v_accvgpr_read_b32 v24, a26
	v_accvgpr_read_b32 v23, a23
	v_accvgpr_read_b32 v22, a22
	v_accvgpr_read_b32 v21, a19
	v_accvgpr_read_b32 v20, a18
	v_accvgpr_read_b32 v19, a15
	v_accvgpr_read_b32 v18, a14
	v_accvgpr_read_b32 v17, a11
	v_accvgpr_read_b32 v16, a10
	v_accvgpr_read_b32 v15, a7
	v_accvgpr_read_b32 v14, a6
	v_accvgpr_read_b32 v13, a3
	v_accvgpr_read_b32 v12, a2
	s_waitcnt lgkmcnt(3)
	v_mfma_f32_16x16x32_f16 a[240:243], v[150:153], v[90:93], a[240:243]
	s_waitcnt lgkmcnt(2)
	v_mfma_f32_16x16x32_f16 a[252:255], v[154:157], v[90:93], a[252:255]
	s_waitcnt lgkmcnt(1)
	v_mfma_f32_16x16x32_f16 a[248:251], v[158:161], v[90:93], a[248:251]
	s_waitcnt lgkmcnt(0)
	v_mfma_f32_16x16x32_f16 a[244:247], v[162:165], v[90:93], a[244:247]
	v_mfma_f32_16x16x32_f16 a[236:239], v[150:153], v[94:97], a[236:239]
	v_mfma_f32_16x16x32_f16 a[232:235], v[154:157], v[94:97], a[232:235]
	v_mfma_f32_16x16x32_f16 a[228:231], v[158:161], v[94:97], a[228:231]
	v_mfma_f32_16x16x32_f16 a[224:227], v[162:165], v[94:97], a[224:227]
	v_mfma_f32_16x16x32_f16 a[220:223], v[150:153], v[138:141], a[220:223]
	v_mfma_f32_16x16x32_f16 a[216:219], v[154:157], v[138:141], a[216:219]
	v_mfma_f32_16x16x32_f16 a[212:215], v[158:161], v[138:141], a[212:215]
	v_mfma_f32_16x16x32_f16 a[204:207], v[162:165], v[138:141], a[204:207]
	v_mfma_f32_16x16x32_f16 a[172:175], v[150:153], v[142:145], a[172:175]
	v_mfma_f32_16x16x32_f16 a[168:171], v[154:157], v[142:145], a[168:171]
	v_mfma_f32_16x16x32_f16 a[164:167], v[158:161], v[142:145], a[164:167]
	v_mfma_f32_16x16x32_f16 a[160:163], v[162:165], v[142:145], a[160:163]
	v_mfma_f32_16x16x32_f16 a[140:143], v[150:153], v[146:149], a[140:143]
	v_mfma_f32_16x16x32_f16 a[136:139], v[154:157], v[146:149], a[136:139]
	v_mfma_f32_16x16x32_f16 a[132:135], v[158:161], v[146:149], a[132:135]
	v_mfma_f32_16x16x32_f16 a[128:131], v[162:165], v[146:149], a[128:131]
	s_waitcnt vmcnt(0)
; #define MMA_BLK(afx, bfx, nh_) _Pragma("unroll") for (int mi = 0; mi < 8; ++mi) _Pragma("unroll") for (int ni = 0; ni < 4; ++ni) mfma16_acc(acc[mi][(nh_) * 4 + ni], bfx[ni], afx[mi])
; template <class Epi>
; __device__ __forceinline__ void gemm_run(const GemmArgs g, Epi epi, char* smem) {
;     ...
;       MMA_BLK(afB, bfA, 0);
;       __builtin_amdgcn_sched_barrier(0);
;       MMA_BLK(afB, bfB, 1);
	v_accvgpr_read_b32 v167, a243
	v_accvgpr_read_b32 v166, a242
	v_accvgpr_read_b32 v169, a255
	v_accvgpr_read_b32 v168, a254
	v_accvgpr_read_b32 v125, a251
	v_accvgpr_read_b32 v124, a250
	v_accvgpr_read_b32 v123, a247
	v_accvgpr_read_b32 v122, a246
	v_accvgpr_read_b32 v113, a239
	v_accvgpr_read_b32 v112, a238
	v_accvgpr_read_b32 v111, a235
	v_accvgpr_read_b32 v110, a234
	v_accvgpr_read_b32 v109, a231
	v_accvgpr_read_b32 v108, a230
	v_accvgpr_read_b32 v107, a227
	v_accvgpr_read_b32 v106, a226
	v_accvgpr_read_b32 v97, a223
	v_accvgpr_read_b32 v96, a222
	v_accvgpr_read_b32 v95, a219
	v_accvgpr_read_b32 v94, a218
	v_accvgpr_read_b32 v93, a215
	v_accvgpr_read_b32 v92, a214
	v_accvgpr_read_b32 v91, a207
	v_accvgpr_read_b32 v90, a206
	v_accvgpr_read_b32 v81, a175
	v_accvgpr_read_b32 v80, a174
	v_accvgpr_read_b32 v79, a171
	v_accvgpr_read_b32 v78, a170
	v_accvgpr_read_b32 v77, a167
	v_accvgpr_read_b32 v76, a166
	v_accvgpr_read_b32 v75, a163
	v_accvgpr_read_b32 v74, a162
	v_accvgpr_read_b32 v65, a143
	v_accvgpr_read_b32 v64, a142
	v_accvgpr_read_b32 v63, a139
	v_accvgpr_read_b32 v62, a138
	v_accvgpr_read_b32 v61, a135
	v_accvgpr_read_b32 v60, a134
	v_accvgpr_read_b32 v59, a131
	v_accvgpr_read_b32 v58, a130
	v_mfma_f32_16x16x32_f16 a[108:111], v[150:153], v[8:11], a[108:111]
	v_mfma_f32_16x16x32_f16 a[104:107], v[154:157], v[8:11], a[104:107]
	v_mfma_f32_16x16x32_f16 a[100:103], v[158:161], v[8:11], a[100:103]
	v_mfma_f32_16x16x32_f16 a[96:99], v[162:165], v[8:11], a[96:99]
	v_mfma_f32_16x16x32_f16 a[76:79], v[150:153], v[4:7], a[76:79]
	v_mfma_f32_16x16x32_f16 a[72:75], v[154:157], v[4:7], a[72:75]
	v_mfma_f32_16x16x32_f16 a[68:71], v[158:161], v[4:7], a[68:71]
	v_mfma_f32_16x16x32_f16 a[64:67], v[162:165], v[4:7], a[64:67]
	v_mfma_f32_16x16x32_f16 a[44:47], v[150:153], v[0:3], a[44:47]
	v_mfma_f32_16x16x32_f16 a[40:43], v[154:157], v[0:3], a[40:43]
	v_mfma_f32_16x16x32_f16 a[36:39], v[158:161], v[0:3], a[36:39]
	v_mfma_f32_16x16x32_f16 a[32:35], v[162:165], v[0:3], a[32:35]
	s_nop 0
	v_lshl_add_u32 v138, s52, 8, v128
	v_add_u32_e32 v140, 0x4000, v138
	v_min_i32_e32 v3, 0x8000, v140
	v_or_b32_e32 v2, s53, v131
	v_ashrrev_i32_e32 v3, 13, v3
	v_ashrrev_i32_e32 v141, 31, v140
	v_mul_hi_i32_i24_e32 v143, 0xc000, v3
	v_mul_i32_i24_e32 v142, 0xc000, v3
	v_ashrrev_i32_e32 v3, 31, v2
	v_lshlrev_b64 v[140:141], 13, v[140:141]
	v_lshlrev_b64 v[2:3], 2, v[2:3]
	v_lshl_add_u64 v[140:141], s[28:29], 0, v[140:141]
	v_lshl_add_u64 v[142:143], s[16:17], 0, v[142:143]
	v_lshl_add_u64 v[150:151], v[140:141], 0, v[2:3]
	s_barrier
	v_lshl_add_u64 v[148:149], v[142:143], 0, v[2:3]
	global_load_dwordx4 v[4:7], v[148:149], off
	global_load_dwordx4 v[8:11], v[148:149], off offset:64
	global_load_dwordx4 v[12:15], v[148:149], off offset:128
	global_load_dwordx4 v[16:19], v[148:149], off offset:192
	global_load_dwordx4 v[20:23], v[148:149], off offset:256
	global_load_dwordx4 v[24:27], v[148:149], off offset:320
	global_load_dwordx4 v[28:31], v[148:149], off offset:384
	global_load_dwordx4 v[32:35], v[148:149], off offset:448
	global_load_dwordx4 v[36:39], v[150:151], off
	global_load_dwordx4 v[40:43], v[150:151], off offset:64
	global_load_dwordx4 v[44:47], v[150:151], off offset:128
	global_load_dwordx4 v[48:51], v[150:151], off offset:192
	global_load_dwordx4 v[52:55], v[150:151], off offset:256
	global_load_dwordx4 v[56:59], v[150:151], off offset:320
	global_load_dwordx4 v[60:63], v[150:151], off offset:384
	global_load_dwordx4 v[64:67], v[150:151], off offset:448
	v_mov_b32_e32 v106, 0x20000
	v_mov_b32_e32 v107, 0
	v_lshl_add_u64 v[104:105], v[150:151], 0, v[106:107]
	v_mov_b32_e32 v106, 0x40000
	global_load_dwordx4 v[68:71], v[104:105], off
	global_load_dwordx4 v[72:75], v[104:105], off offset:64
	global_load_dwordx4 v[76:79], v[104:105], off offset:128
	global_load_dwordx4 v[80:83], v[104:105], off offset:192
	global_load_dwordx4 v[84:87], v[104:105], off offset:256
	global_load_dwordx4 v[88:91], v[104:105], off offset:320
	global_load_dwordx4 v[92:95], v[104:105], off offset:384
	global_load_dwordx4 v[96:99], v[104:105], off offset:448
	v_accvgpr_read_b32 v100, a208
	v_accvgpr_read_b32 v101, a209
	v_accvgpr_read_b32 v102, a210
	v_accvgpr_read_b32 v103, a211
	s_waitcnt vmcnt(15)
	v_pk_fma_f32 v[36:37], v[100:101], v[4:5], v[36:37]
	v_pk_fma_f32 v[38:39], v[102:103], v[6:7], v[38:39]
	global_store_dwordx4 v[150:151], v[36:39], off
	v_accvgpr_read_b32 v100, a200
	v_accvgpr_read_b32 v101, a201
	v_accvgpr_read_b32 v102, a202
	v_accvgpr_read_b32 v103, a203
	s_waitcnt vmcnt(15)
	v_pk_fma_f32 v[40:41], v[100:101], v[8:9], v[40:41]
	v_pk_fma_f32 v[42:43], v[102:103], v[10:11], v[42:43]
	global_store_dwordx4 v[150:151], v[40:43], off offset:64
	v_accvgpr_read_b32 v100, a196
	v_accvgpr_read_b32 v101, a197
	v_accvgpr_read_b32 v102, a198
	v_accvgpr_read_b32 v103, a199
	s_waitcnt vmcnt(15)
	v_pk_fma_f32 v[44:45], v[100:101], v[12:13], v[44:45]
	v_pk_fma_f32 v[46:47], v[102:103], v[14:15], v[46:47]
	global_store_dwordx4 v[150:151], v[44:47], off offset:128
	v_accvgpr_read_b32 v100, a192
	v_accvgpr_read_b32 v101, a193
	v_accvgpr_read_b32 v102, a194
	v_accvgpr_read_b32 v103, a195
	s_waitcnt vmcnt(15)
	v_pk_fma_f32 v[48:49], v[100:101], v[16:17], v[48:49]
	v_pk_fma_f32 v[50:51], v[102:103], v[18:19], v[50:51]
	global_store_dwordx4 v[150:151], v[48:51], off offset:192
	v_accvgpr_read_b32 v100, a240
	v_accvgpr_read_b32 v101, a241
	v_accvgpr_read_b32 v102, a242
	v_accvgpr_read_b32 v103, a243
	s_waitcnt vmcnt(15)
	v_pk_fma_f32 v[52:53], v[100:101], v[20:21], v[52:53]
	v_pk_fma_f32 v[54:55], v[102:103], v[22:23], v[54:55]
	global_store_dwordx4 v[150:151], v[52:55], off offset:256
	v_accvgpr_read_b32 v100, a252
	v_accvgpr_read_b32 v101, a253
	v_accvgpr_read_b32 v102, a254
	v_accvgpr_read_b32 v103, a255
	s_waitcnt vmcnt(15)
	v_pk_fma_f32 v[56:57], v[100:101], v[24:25], v[56:57]
	v_pk_fma_f32 v[58:59], v[102:103], v[26:27], v[58:59]
	global_store_dwordx4 v[150:151], v[56:59], off offset:320
	v_accvgpr_read_b32 v100, a248
	v_accvgpr_read_b32 v101, a249
	v_accvgpr_read_b32 v102, a250
	v_accvgpr_read_b32 v103, a251
	s_waitcnt vmcnt(15)
	v_pk_fma_f32 v[60:61], v[100:101], v[28:29], v[60:61]
	v_pk_fma_f32 v[62:63], v[102:103], v[30:31], v[62:63]
	global_store_dwordx4 v[150:151], v[60:63], off offset:384
	v_accvgpr_read_b32 v100, a244
	v_accvgpr_read_b32 v101, a245
	v_accvgpr_read_b32 v102, a246
	v_accvgpr_read_b32 v103, a247
	s_waitcnt vmcnt(15)
	v_pk_fma_f32 v[64:65], v[100:101], v[32:33], v[64:65]
	v_pk_fma_f32 v[66:67], v[102:103], v[34:35], v[66:67]
	global_store_dwordx4 v[150:151], v[64:67], off offset:448
	v_lshl_add_u64 v[150:151], v[150:151], 0, v[106:107]
	s_nop 1
	global_load_dwordx4 v[36:39], v[150:151], off
	global_load_dwordx4 v[40:43], v[150:151], off offset:64
	global_load_dwordx4 v[44:47], v[150:151], off offset:128
	global_load_dwordx4 v[48:51], v[150:151], off offset:192
	global_load_dwordx4 v[52:55], v[150:151], off offset:256
	global_load_dwordx4 v[56:59], v[150:151], off offset:320
	global_load_dwordx4 v[60:63], v[150:151], off offset:384
	global_load_dwordx4 v[64:67], v[150:151], off offset:448
	v_accvgpr_read_b32 v100, a188
	v_accvgpr_read_b32 v101, a189
	v_accvgpr_read_b32 v102, a190
	v_accvgpr_read_b32 v103, a191
	s_waitcnt vmcnt(23)
	v_pk_fma_f32 v[68:69], v[100:101], v[4:5], v[68:69]
	v_pk_fma_f32 v[70:71], v[102:103], v[6:7], v[70:71]
	global_store_dwordx4 v[104:105], v[68:71], off
	v_accvgpr_read_b32 v100, a184
	v_accvgpr_read_b32 v101, a185
	v_accvgpr_read_b32 v102, a186
	v_accvgpr_read_b32 v103, a187
	s_waitcnt vmcnt(23)
	v_pk_fma_f32 v[72:73], v[100:101], v[8:9], v[72:73]
	v_pk_fma_f32 v[74:75], v[102:103], v[10:11], v[74:75]
	global_store_dwordx4 v[104:105], v[72:75], off offset:64
	v_accvgpr_read_b32 v100, a180
	v_accvgpr_read_b32 v101, a181
	v_accvgpr_read_b32 v102, a182
	v_accvgpr_read_b32 v103, a183
	s_waitcnt vmcnt(23)
	v_pk_fma_f32 v[76:77], v[100:101], v[12:13], v[76:77]
	v_pk_fma_f32 v[78:79], v[102:103], v[14:15], v[78:79]
	global_store_dwordx4 v[104:105], v[76:79], off offset:128
	v_accvgpr_read_b32 v100, a176
	v_accvgpr_read_b32 v101, a177
	v_accvgpr_read_b32 v102, a178
	v_accvgpr_read_b32 v103, a179
	s_waitcnt vmcnt(23)
	v_pk_fma_f32 v[80:81], v[100:101], v[16:17], v[80:81]
	v_pk_fma_f32 v[82:83], v[102:103], v[18:19], v[82:83]
	global_store_dwordx4 v[104:105], v[80:83], off offset:192
	v_accvgpr_read_b32 v100, a236
	v_accvgpr_read_b32 v101, a237
	v_accvgpr_read_b32 v102, a238
	v_accvgpr_read_b32 v103, a239
	s_waitcnt vmcnt(23)
	v_pk_fma_f32 v[84:85], v[100:101], v[20:21], v[84:85]
	v_pk_fma_f32 v[86:87], v[102:103], v[22:23], v[86:87]
	global_store_dwordx4 v[104:105], v[84:87], off offset:256
	v_accvgpr_read_b32 v100, a232
	v_accvgpr_read_b32 v101, a233
	v_accvgpr_read_b32 v102, a234
	v_accvgpr_read_b32 v103, a235
	s_waitcnt vmcnt(23)
	v_pk_fma_f32 v[88:89], v[100:101], v[24:25], v[88:89]
	v_pk_fma_f32 v[90:91], v[102:103], v[26:27], v[90:91]
	global_store_dwordx4 v[104:105], v[88:91], off offset:320
	v_accvgpr_read_b32 v100, a228
	v_accvgpr_read_b32 v101, a229
	v_accvgpr_read_b32 v102, a230
	v_accvgpr_read_b32 v103, a231
	s_waitcnt vmcnt(23)
	v_pk_fma_f32 v[92:93], v[100:101], v[28:29], v[92:93]
	v_pk_fma_f32 v[94:95], v[102:103], v[30:31], v[94:95]
	global_store_dwordx4 v[104:105], v[92:95], off offset:384
	v_accvgpr_read_b32 v100, a224
	v_accvgpr_read_b32 v101, a225
	v_accvgpr_read_b32 v102, a226
	v_accvgpr_read_b32 v103, a227
	s_waitcnt vmcnt(23)
	v_pk_fma_f32 v[96:97], v[100:101], v[32:33], v[96:97]
	v_pk_fma_f32 v[98:99], v[102:103], v[34:35], v[98:99]
	global_store_dwordx4 v[104:105], v[96:99], off offset:448
	v_lshl_add_u64 v[104:105], v[104:105], 0, v[106:107]
	s_nop 1
	global_load_dwordx4 v[68:71], v[104:105], off
	global_load_dwordx4 v[72:75], v[104:105], off offset:64
	global_load_dwordx4 v[76:79], v[104:105], off offset:128
	global_load_dwordx4 v[80:83], v[104:105], off offset:192
	global_load_dwordx4 v[84:87], v[104:105], off offset:256
	global_load_dwordx4 v[88:91], v[104:105], off offset:320
	global_load_dwordx4 v[92:95], v[104:105], off offset:384
	global_load_dwordx4 v[96:99], v[104:105], off offset:448
	v_accvgpr_read_b32 v100, a156
	v_accvgpr_read_b32 v101, a157
	v_accvgpr_read_b32 v102, a158
	v_accvgpr_read_b32 v103, a159
	s_waitcnt vmcnt(23)
	v_pk_fma_f32 v[36:37], v[100:101], v[4:5], v[36:37]
	v_pk_fma_f32 v[38:39], v[102:103], v[6:7], v[38:39]
	global_store_dwordx4 v[150:151], v[36:39], off
	v_accvgpr_read_b32 v100, a152
	v_accvgpr_read_b32 v101, a153
	v_accvgpr_read_b32 v102, a154
	v_accvgpr_read_b32 v103, a155
	s_waitcnt vmcnt(23)
	v_pk_fma_f32 v[40:41], v[100:101], v[8:9], v[40:41]
	v_pk_fma_f32 v[42:43], v[102:103], v[10:11], v[42:43]
	global_store_dwordx4 v[150:151], v[40:43], off offset:64
	v_accvgpr_read_b32 v100, a148
	v_accvgpr_read_b32 v101, a149
	v_accvgpr_read_b32 v102, a150
	v_accvgpr_read_b32 v103, a151
	s_waitcnt vmcnt(23)
	v_pk_fma_f32 v[44:45], v[100:101], v[12:13], v[44:45]
	v_pk_fma_f32 v[46:47], v[102:103], v[14:15], v[46:47]
	global_store_dwordx4 v[150:151], v[44:47], off offset:128
	v_accvgpr_read_b32 v100, a144
	v_accvgpr_read_b32 v101, a145
	v_accvgpr_read_b32 v102, a146
	v_accvgpr_read_b32 v103, a147
	s_waitcnt vmcnt(23)
	v_pk_fma_f32 v[48:49], v[100:101], v[16:17], v[48:49]
	v_pk_fma_f32 v[50:51], v[102:103], v[18:19], v[50:51]
	global_store_dwordx4 v[150:151], v[48:51], off offset:192
	v_accvgpr_read_b32 v100, a220
	v_accvgpr_read_b32 v101, a221
	v_accvgpr_read_b32 v102, a222
	v_accvgpr_read_b32 v103, a223
	s_waitcnt vmcnt(23)
	v_pk_fma_f32 v[52:53], v[100:101], v[20:21], v[52:53]
	v_pk_fma_f32 v[54:55], v[102:103], v[22:23], v[54:55]
	global_store_dwordx4 v[150:151], v[52:55], off offset:256
	v_accvgpr_read_b32 v100, a216
	v_accvgpr_read_b32 v101, a217
	v_accvgpr_read_b32 v102, a218
	v_accvgpr_read_b32 v103, a219
	s_waitcnt vmcnt(23)
	v_pk_fma_f32 v[56:57], v[100:101], v[24:25], v[56:57]
	v_pk_fma_f32 v[58:59], v[102:103], v[26:27], v[58:59]
	global_store_dwordx4 v[150:151], v[56:59], off offset:320
	v_accvgpr_read_b32 v100, a212
	v_accvgpr_read_b32 v101, a213
	v_accvgpr_read_b32 v102, a214
	v_accvgpr_read_b32 v103, a215
	s_waitcnt vmcnt(23)
	v_pk_fma_f32 v[60:61], v[100:101], v[28:29], v[60:61]
	v_pk_fma_f32 v[62:63], v[102:103], v[30:31], v[62:63]
	global_store_dwordx4 v[150:151], v[60:63], off offset:384
	v_accvgpr_read_b32 v100, a204
	v_accvgpr_read_b32 v101, a205
	v_accvgpr_read_b32 v102, a206
	v_accvgpr_read_b32 v103, a207
	s_waitcnt vmcnt(23)
	v_pk_fma_f32 v[64:65], v[100:101], v[32:33], v[64:65]
	v_pk_fma_f32 v[66:67], v[102:103], v[34:35], v[66:67]
	global_store_dwordx4 v[150:151], v[64:67], off offset:448
	v_lshl_add_u64 v[150:151], v[150:151], 0, v[106:107]
	s_nop 1
	global_load_dwordx4 v[36:39], v[150:151], off
	global_load_dwordx4 v[40:43], v[150:151], off offset:64
	global_load_dwordx4 v[44:47], v[150:151], off offset:128
	global_load_dwordx4 v[48:51], v[150:151], off offset:192
	global_load_dwordx4 v[52:55], v[150:151], off offset:256
	global_load_dwordx4 v[56:59], v[150:151], off offset:320
	global_load_dwordx4 v[60:63], v[150:151], off offset:384
	global_load_dwordx4 v[64:67], v[150:151], off offset:448
	v_accvgpr_read_b32 v100, a124
	v_accvgpr_read_b32 v101, a125
	v_accvgpr_read_b32 v102, a126
	v_accvgpr_read_b32 v103, a127
	s_waitcnt vmcnt(23)
	v_pk_fma_f32 v[68:69], v[100:101], v[4:5], v[68:69]
	v_pk_fma_f32 v[70:71], v[102:103], v[6:7], v[70:71]
	global_store_dwordx4 v[104:105], v[68:71], off
	v_accvgpr_read_b32 v100, a120
	v_accvgpr_read_b32 v101, a121
	v_accvgpr_read_b32 v102, a122
	v_accvgpr_read_b32 v103, a123
	s_waitcnt vmcnt(23)
	v_pk_fma_f32 v[72:73], v[100:101], v[8:9], v[72:73]
	v_pk_fma_f32 v[74:75], v[102:103], v[10:11], v[74:75]
	global_store_dwordx4 v[104:105], v[72:75], off offset:64
	v_accvgpr_read_b32 v100, a116
	v_accvgpr_read_b32 v101, a117
	v_accvgpr_read_b32 v102, a118
	v_accvgpr_read_b32 v103, a119
	s_waitcnt vmcnt(23)
	v_pk_fma_f32 v[76:77], v[100:101], v[12:13], v[76:77]
	v_pk_fma_f32 v[78:79], v[102:103], v[14:15], v[78:79]
	global_store_dwordx4 v[104:105], v[76:79], off offset:128
	v_accvgpr_read_b32 v100, a112
	v_accvgpr_read_b32 v101, a113
	v_accvgpr_read_b32 v102, a114
	v_accvgpr_read_b32 v103, a115
	s_waitcnt vmcnt(23)
	v_pk_fma_f32 v[80:81], v[100:101], v[16:17], v[80:81]
	v_pk_fma_f32 v[82:83], v[102:103], v[18:19], v[82:83]
	global_store_dwordx4 v[104:105], v[80:83], off offset:192
	v_accvgpr_read_b32 v100, a172
	v_accvgpr_read_b32 v101, a173
	v_accvgpr_read_b32 v102, a174
	v_accvgpr_read_b32 v103, a175
	s_waitcnt vmcnt(23)
	v_pk_fma_f32 v[84:85], v[100:101], v[20:21], v[84:85]
	v_pk_fma_f32 v[86:87], v[102:103], v[22:23], v[86:87]
	global_store_dwordx4 v[104:105], v[84:87], off offset:256
	v_accvgpr_read_b32 v100, a168
	v_accvgpr_read_b32 v101, a169
	v_accvgpr_read_b32 v102, a170
	v_accvgpr_read_b32 v103, a171
	s_waitcnt vmcnt(23)
	v_pk_fma_f32 v[88:89], v[100:101], v[24:25], v[88:89]
	v_pk_fma_f32 v[90:91], v[102:103], v[26:27], v[90:91]
	global_store_dwordx4 v[104:105], v[88:91], off offset:320
	v_accvgpr_read_b32 v100, a164
	v_accvgpr_read_b32 v101, a165
	v_accvgpr_read_b32 v102, a166
	v_accvgpr_read_b32 v103, a167
	s_waitcnt vmcnt(23)
	v_pk_fma_f32 v[92:93], v[100:101], v[28:29], v[92:93]
	v_pk_fma_f32 v[94:95], v[102:103], v[30:31], v[94:95]
	global_store_dwordx4 v[104:105], v[92:95], off offset:384
	v_accvgpr_read_b32 v100, a160
	v_accvgpr_read_b32 v101, a161
	v_accvgpr_read_b32 v102, a162
	v_accvgpr_read_b32 v103, a163
	s_waitcnt vmcnt(23)
	v_pk_fma_f32 v[96:97], v[100:101], v[32:33], v[96:97]
	v_pk_fma_f32 v[98:99], v[102:103], v[34:35], v[98:99]
	global_store_dwordx4 v[104:105], v[96:99], off offset:448
	v_lshl_add_u64 v[104:105], v[104:105], 0, v[106:107]
	s_nop 1
	global_load_dwordx4 v[68:71], v[104:105], off
	global_load_dwordx4 v[72:75], v[104:105], off offset:64
	global_load_dwordx4 v[76:79], v[104:105], off offset:128
	global_load_dwordx4 v[80:83], v[104:105], off offset:192
	global_load_dwordx4 v[84:87], v[104:105], off offset:256
	global_load_dwordx4 v[88:91], v[104:105], off offset:320
	global_load_dwordx4 v[92:95], v[104:105], off offset:384
	global_load_dwordx4 v[96:99], v[104:105], off offset:448
	v_accvgpr_read_b32 v100, a92
	v_accvgpr_read_b32 v101, a93
	v_accvgpr_read_b32 v102, a94
	v_accvgpr_read_b32 v103, a95
	s_waitcnt vmcnt(23)
	v_pk_fma_f32 v[36:37], v[100:101], v[4:5], v[36:37]
	v_pk_fma_f32 v[38:39], v[102:103], v[6:7], v[38:39]
	global_store_dwordx4 v[150:151], v[36:39], off
	v_accvgpr_read_b32 v100, a88
	v_accvgpr_read_b32 v101, a89
	v_accvgpr_read_b32 v102, a90
	v_accvgpr_read_b32 v103, a91
	s_waitcnt vmcnt(23)
	v_pk_fma_f32 v[40:41], v[100:101], v[8:9], v[40:41]
	v_pk_fma_f32 v[42:43], v[102:103], v[10:11], v[42:43]
	global_store_dwordx4 v[150:151], v[40:43], off offset:64
	v_accvgpr_read_b32 v100, a84
	v_accvgpr_read_b32 v101, a85
	v_accvgpr_read_b32 v102, a86
	v_accvgpr_read_b32 v103, a87
	s_waitcnt vmcnt(23)
	v_pk_fma_f32 v[44:45], v[100:101], v[12:13], v[44:45]
	v_pk_fma_f32 v[46:47], v[102:103], v[14:15], v[46:47]
	global_store_dwordx4 v[150:151], v[44:47], off offset:128
	v_accvgpr_read_b32 v100, a80
	v_accvgpr_read_b32 v101, a81
	v_accvgpr_read_b32 v102, a82
	v_accvgpr_read_b32 v103, a83
	s_waitcnt vmcnt(23)
	v_pk_fma_f32 v[48:49], v[100:101], v[16:17], v[48:49]
	v_pk_fma_f32 v[50:51], v[102:103], v[18:19], v[50:51]
	global_store_dwordx4 v[150:151], v[48:51], off offset:192
	v_accvgpr_read_b32 v100, a140
	v_accvgpr_read_b32 v101, a141
	v_accvgpr_read_b32 v102, a142
	v_accvgpr_read_b32 v103, a143
	s_waitcnt vmcnt(23)
	v_pk_fma_f32 v[52:53], v[100:101], v[20:21], v[52:53]
	v_pk_fma_f32 v[54:55], v[102:103], v[22:23], v[54:55]
	global_store_dwordx4 v[150:151], v[52:55], off offset:256
	v_accvgpr_read_b32 v100, a136
	v_accvgpr_read_b32 v101, a137
	v_accvgpr_read_b32 v102, a138
	v_accvgpr_read_b32 v103, a139
	s_waitcnt vmcnt(23)
	v_pk_fma_f32 v[56:57], v[100:101], v[24:25], v[56:57]
	v_pk_fma_f32 v[58:59], v[102:103], v[26:27], v[58:59]
	global_store_dwordx4 v[150:151], v[56:59], off offset:320
	v_accvgpr_read_b32 v100, a132
	v_accvgpr_read_b32 v101, a133
	v_accvgpr_read_b32 v102, a134
	v_accvgpr_read_b32 v103, a135
	s_waitcnt vmcnt(23)
	v_pk_fma_f32 v[60:61], v[100:101], v[28:29], v[60:61]
	v_pk_fma_f32 v[62:63], v[102:103], v[30:31], v[62:63]
	global_store_dwordx4 v[150:151], v[60:63], off offset:384
	v_accvgpr_read_b32 v100, a128
	v_accvgpr_read_b32 v101, a129
	v_accvgpr_read_b32 v102, a130
	v_accvgpr_read_b32 v103, a131
	s_waitcnt vmcnt(23)
	v_pk_fma_f32 v[64:65], v[100:101], v[32:33], v[64:65]
	v_pk_fma_f32 v[66:67], v[102:103], v[34:35], v[66:67]
	global_store_dwordx4 v[150:151], v[64:67], off offset:448
	v_lshl_add_u64 v[150:151], v[150:151], 0, v[106:107]
	s_nop 1
	global_load_dwordx4 v[36:39], v[150:151], off
	global_load_dwordx4 v[40:43], v[150:151], off offset:64
	global_load_dwordx4 v[44:47], v[150:151], off offset:128
	global_load_dwordx4 v[48:51], v[150:151], off offset:192
	global_load_dwordx4 v[52:55], v[150:151], off offset:256
	global_load_dwordx4 v[56:59], v[150:151], off offset:320
	global_load_dwordx4 v[60:63], v[150:151], off offset:384
	global_load_dwordx4 v[64:67], v[150:151], off offset:448
	v_accvgpr_read_b32 v100, a60
	v_accvgpr_read_b32 v101, a61
	v_accvgpr_read_b32 v102, a62
	v_accvgpr_read_b32 v103, a63
	s_waitcnt vmcnt(23)
	v_pk_fma_f32 v[68:69], v[100:101], v[4:5], v[68:69]
	v_pk_fma_f32 v[70:71], v[102:103], v[6:7], v[70:71]
	global_store_dwordx4 v[104:105], v[68:71], off
	v_accvgpr_read_b32 v100, a56
	v_accvgpr_read_b32 v101, a57
	v_accvgpr_read_b32 v102, a58
	v_accvgpr_read_b32 v103, a59
	s_waitcnt vmcnt(23)
	v_pk_fma_f32 v[72:73], v[100:101], v[8:9], v[72:73]
	v_pk_fma_f32 v[74:75], v[102:103], v[10:11], v[74:75]
	global_store_dwordx4 v[104:105], v[72:75], off offset:64
	v_accvgpr_read_b32 v100, a52
	v_accvgpr_read_b32 v101, a53
	v_accvgpr_read_b32 v102, a54
	v_accvgpr_read_b32 v103, a55
	s_waitcnt vmcnt(23)
	v_pk_fma_f32 v[76:77], v[100:101], v[12:13], v[76:77]
	v_pk_fma_f32 v[78:79], v[102:103], v[14:15], v[78:79]
	global_store_dwordx4 v[104:105], v[76:79], off offset:128
	v_accvgpr_read_b32 v100, a48
	v_accvgpr_read_b32 v101, a49
	v_accvgpr_read_b32 v102, a50
	v_accvgpr_read_b32 v103, a51
	s_waitcnt vmcnt(23)
	v_pk_fma_f32 v[80:81], v[100:101], v[16:17], v[80:81]
	v_pk_fma_f32 v[82:83], v[102:103], v[18:19], v[82:83]
	global_store_dwordx4 v[104:105], v[80:83], off offset:192
	v_accvgpr_read_b32 v100, a108
	v_accvgpr_read_b32 v101, a109
	v_accvgpr_read_b32 v102, a110
	v_accvgpr_read_b32 v103, a111
	s_waitcnt vmcnt(23)
	v_pk_fma_f32 v[84:85], v[100:101], v[20:21], v[84:85]
	v_pk_fma_f32 v[86:87], v[102:103], v[22:23], v[86:87]
	global_store_dwordx4 v[104:105], v[84:87], off offset:256
	v_accvgpr_read_b32 v100, a104
	v_accvgpr_read_b32 v101, a105
	v_accvgpr_read_b32 v102, a106
	v_accvgpr_read_b32 v103, a107
	s_waitcnt vmcnt(23)
	v_pk_fma_f32 v[88:89], v[100:101], v[24:25], v[88:89]
	v_pk_fma_f32 v[90:91], v[102:103], v[26:27], v[90:91]
	global_store_dwordx4 v[104:105], v[88:91], off offset:320
	v_accvgpr_read_b32 v100, a100
	v_accvgpr_read_b32 v101, a101
	v_accvgpr_read_b32 v102, a102
	v_accvgpr_read_b32 v103, a103
	s_waitcnt vmcnt(23)
	v_pk_fma_f32 v[92:93], v[100:101], v[28:29], v[92:93]
	v_pk_fma_f32 v[94:95], v[102:103], v[30:31], v[94:95]
	global_store_dwordx4 v[104:105], v[92:95], off offset:384
	v_accvgpr_read_b32 v100, a96
	v_accvgpr_read_b32 v101, a97
	v_accvgpr_read_b32 v102, a98
	v_accvgpr_read_b32 v103, a99
	s_waitcnt vmcnt(23)
	v_pk_fma_f32 v[96:97], v[100:101], v[32:33], v[96:97]
	v_pk_fma_f32 v[98:99], v[102:103], v[34:35], v[98:99]
	global_store_dwordx4 v[104:105], v[96:99], off offset:448
	v_lshl_add_u64 v[104:105], v[104:105], 0, v[106:107]
	s_nop 1
	global_load_dwordx4 v[68:71], v[104:105], off
	global_load_dwordx4 v[72:75], v[104:105], off offset:64
	global_load_dwordx4 v[76:79], v[104:105], off offset:128
	global_load_dwordx4 v[80:83], v[104:105], off offset:192
	global_load_dwordx4 v[84:87], v[104:105], off offset:256
	global_load_dwordx4 v[88:91], v[104:105], off offset:320
	global_load_dwordx4 v[92:95], v[104:105], off offset:384
	global_load_dwordx4 v[96:99], v[104:105], off offset:448
	v_accvgpr_read_b32 v100, a28
	v_accvgpr_read_b32 v101, a29
	v_accvgpr_read_b32 v102, a30
	v_accvgpr_read_b32 v103, a31
	s_waitcnt vmcnt(23)
	v_pk_fma_f32 v[36:37], v[100:101], v[4:5], v[36:37]
	v_pk_fma_f32 v[38:39], v[102:103], v[6:7], v[38:39]
	global_store_dwordx4 v[150:151], v[36:39], off
	v_accvgpr_read_b32 v100, a24
	v_accvgpr_read_b32 v101, a25
	v_accvgpr_read_b32 v102, a26
	v_accvgpr_read_b32 v103, a27
	s_waitcnt vmcnt(23)
	v_pk_fma_f32 v[40:41], v[100:101], v[8:9], v[40:41]
	v_pk_fma_f32 v[42:43], v[102:103], v[10:11], v[42:43]
	global_store_dwordx4 v[150:151], v[40:43], off offset:64
	v_accvgpr_read_b32 v100, a20
	v_accvgpr_read_b32 v101, a21
	v_accvgpr_read_b32 v102, a22
	v_accvgpr_read_b32 v103, a23
	s_waitcnt vmcnt(23)
	v_pk_fma_f32 v[44:45], v[100:101], v[12:13], v[44:45]
	v_pk_fma_f32 v[46:47], v[102:103], v[14:15], v[46:47]
	global_store_dwordx4 v[150:151], v[44:47], off offset:128
	v_accvgpr_read_b32 v100, a16
	v_accvgpr_read_b32 v101, a17
	v_accvgpr_read_b32 v102, a18
	v_accvgpr_read_b32 v103, a19
	s_waitcnt vmcnt(23)
	v_pk_fma_f32 v[48:49], v[100:101], v[16:17], v[48:49]
	v_pk_fma_f32 v[50:51], v[102:103], v[18:19], v[50:51]
	global_store_dwordx4 v[150:151], v[48:51], off offset:192
	v_accvgpr_read_b32 v100, a76
	v_accvgpr_read_b32 v101, a77
	v_accvgpr_read_b32 v102, a78
	v_accvgpr_read_b32 v103, a79
	s_waitcnt vmcnt(23)
	v_pk_fma_f32 v[52:53], v[100:101], v[20:21], v[52:53]
	v_pk_fma_f32 v[54:55], v[102:103], v[22:23], v[54:55]
	global_store_dwordx4 v[150:151], v[52:55], off offset:256
	v_accvgpr_read_b32 v100, a72
	v_accvgpr_read_b32 v101, a73
	v_accvgpr_read_b32 v102, a74
	v_accvgpr_read_b32 v103, a75
	s_waitcnt vmcnt(23)
	v_pk_fma_f32 v[56:57], v[100:101], v[24:25], v[56:57]
	v_pk_fma_f32 v[58:59], v[102:103], v[26:27], v[58:59]
	global_store_dwordx4 v[150:151], v[56:59], off offset:320
	v_accvgpr_read_b32 v100, a68
	v_accvgpr_read_b32 v101, a69
	v_accvgpr_read_b32 v102, a70
	v_accvgpr_read_b32 v103, a71
	s_waitcnt vmcnt(23)
	v_pk_fma_f32 v[60:61], v[100:101], v[28:29], v[60:61]
	v_pk_fma_f32 v[62:63], v[102:103], v[30:31], v[62:63]
	global_store_dwordx4 v[150:151], v[60:63], off offset:384
	v_accvgpr_read_b32 v100, a64
	v_accvgpr_read_b32 v101, a65
	v_accvgpr_read_b32 v102, a66
	v_accvgpr_read_b32 v103, a67
	s_waitcnt vmcnt(23)
	v_pk_fma_f32 v[64:65], v[100:101], v[32:33], v[64:65]
	v_pk_fma_f32 v[66:67], v[102:103], v[34:35], v[66:67]
	global_store_dwordx4 v[150:151], v[64:67], off offset:448
	v_accvgpr_read_b32 v100, a12
	v_accvgpr_read_b32 v101, a13
	v_accvgpr_read_b32 v102, a14
	v_accvgpr_read_b32 v103, a15
	s_waitcnt vmcnt(15)
	v_pk_fma_f32 v[68:69], v[100:101], v[4:5], v[68:69]
	v_pk_fma_f32 v[70:71], v[102:103], v[6:7], v[70:71]
	global_store_dwordx4 v[104:105], v[68:71], off
	v_accvgpr_read_b32 v100, a8
	v_accvgpr_read_b32 v101, a9
	v_accvgpr_read_b32 v102, a10
	v_accvgpr_read_b32 v103, a11
	s_waitcnt vmcnt(15)
	v_pk_fma_f32 v[72:73], v[100:101], v[8:9], v[72:73]
	v_pk_fma_f32 v[74:75], v[102:103], v[10:11], v[74:75]
	global_store_dwordx4 v[104:105], v[72:75], off offset:64
	v_accvgpr_read_b32 v100, a4
	v_accvgpr_read_b32 v101, a5
	v_accvgpr_read_b32 v102, a6
	v_accvgpr_read_b32 v103, a7
	s_waitcnt vmcnt(15)
	v_pk_fma_f32 v[76:77], v[100:101], v[12:13], v[76:77]
	v_pk_fma_f32 v[78:79], v[102:103], v[14:15], v[78:79]
	global_store_dwordx4 v[104:105], v[76:79], off offset:128
	v_accvgpr_read_b32 v100, a0
	v_accvgpr_read_b32 v101, a1
	v_accvgpr_read_b32 v102, a2
	v_accvgpr_read_b32 v103, a3
	s_waitcnt vmcnt(15)
	v_pk_fma_f32 v[80:81], v[100:101], v[16:17], v[80:81]
	v_pk_fma_f32 v[82:83], v[102:103], v[18:19], v[82:83]
	global_store_dwordx4 v[104:105], v[80:83], off offset:192
	v_accvgpr_read_b32 v100, a44
	v_accvgpr_read_b32 v101, a45
	v_accvgpr_read_b32 v102, a46
	v_accvgpr_read_b32 v103, a47
	s_waitcnt vmcnt(15)
	v_pk_fma_f32 v[84:85], v[100:101], v[20:21], v[84:85]
	v_pk_fma_f32 v[86:87], v[102:103], v[22:23], v[86:87]
	global_store_dwordx4 v[104:105], v[84:87], off offset:256
	v_accvgpr_read_b32 v100, a40
	v_accvgpr_read_b32 v101, a41
	v_accvgpr_read_b32 v102, a42
	v_accvgpr_read_b32 v103, a43
	s_waitcnt vmcnt(15)
	v_pk_fma_f32 v[88:89], v[100:101], v[24:25], v[88:89]
	v_pk_fma_f32 v[90:91], v[102:103], v[26:27], v[90:91]
	global_store_dwordx4 v[104:105], v[88:91], off offset:320
	v_accvgpr_read_b32 v100, a36
	v_accvgpr_read_b32 v101, a37
	v_accvgpr_read_b32 v102, a38
	v_accvgpr_read_b32 v103, a39
	s_waitcnt vmcnt(15)
	v_pk_fma_f32 v[92:93], v[100:101], v[28:29], v[92:93]
	v_pk_fma_f32 v[94:95], v[102:103], v[30:31], v[94:95]
	global_store_dwordx4 v[104:105], v[92:95], off offset:384
	v_accvgpr_read_b32 v100, a32
	v_accvgpr_read_b32 v101, a33
	v_accvgpr_read_b32 v102, a34
	v_accvgpr_read_b32 v103, a35
	s_waitcnt vmcnt(15)
	v_pk_fma_f32 v[96:97], v[100:101], v[32:33], v[96:97]
	v_pk_fma_f32 v[98:99], v[102:103], v[34:35], v[98:99]
	global_store_dwordx4 v[104:105], v[96:99], off offset:448
	s_add_i32 s49, s49, s2
	s_cmpk_lt_i32 s49, 0x200
	s_cbranch_scc0 .LBB0_2162

; #define LD_AF(dst, ks_) _Pragma("unroll") for (int i = 0; i < 8; ++i) dst[i] = *(const h8*)(sA + i * 16 * G_LD + (ks_) * 32)
; #define LD_BF(dst, ks_, nh_) _Pragma("unroll") for (int i = 0; i < 4; ++i) dst[i] = *(const h8*)(sB + ((nh_) * 4 + i) * 16 * G_LD + (ks_) * 32)
; #define MMA_BLK(afx, bfx, nh_) _Pragma("unroll") for (int mi = 0; mi < 8; ++mi) _Pragma("unroll") for (int ni = 0; ni < 4; ++ni) mfma16_acc(acc[mi][(nh_) * 4 + ni], bfx[ni], afx[mi])
; template <class Epi>
; __device__ __forceinline__ void gemm_run(const GemmArgs g, Epi epi, char* smem) {
;     ...
;       const hf* sA = sbase + (kt & 1) * G_STAGE + (wm * 128 + fr) * G_LD + fqs;
;       const hf* sB = sbase + (kt & 1) * G_STAGE + (256 + wn * 128 + fr) * G_LD + fqs;
;       hf* st = sbase + ((kt + 1) & 1) * G_STAGE;
;       h8 afA[8], afB[8], bfA[4], bfB[4];
;     ...
;       LD_AF(afA, 0); LD_BF(bfA, 0, 0);
;       if (kt + 1 < nk) {
; #pragma unroll
;         for (int i = 0; i < 8; ++i) *(u4*)(st + (lr + 32 * i) * G_LD + lcw) = ra[i];
;       }
;       __builtin_amdgcn_sched_barrier(0);
;       LD_BF(bfB, 0, 1);
;       MMA_BLK(afA, bfA, 0);
;       __builtin_amdgcn_sched_barrier(0);
;       if (kt + 1 < nk) {
; #pragma unroll
;         for (int i = 0; i < 8; ++i) *(u4*)(st + (256 + lr + 32 * i) * G_LD + lcw) = rb[i];
;       }
;       LD_AF(afB, 1); LD_BF(bfA, 1, 0);
;       MMA_BLK(afA, bfB, 1);
;       __builtin_amdgcn_sched_barrier(0);
;       if (kt + 2 < nk) {
;         const int ko = (kt + 2) * 64;
; #pragma unroll
;         for (int i = 0; i < 8; ++i) { ra[i] = __builtin_amdgcn_raw_buffer_load_b128(Ars, aoff, i * astep + ko * 2, 0); rb[i] = __builtin_amdgcn_raw_buffer_load_b128(Brs, boff, i * bstep + ko * 2, 0); }
;       }
;       LD_BF(bfB, 1, 1);
;       MMA_BLK(afB, bfA, 0);
;       __builtin_amdgcn_sched_barrier(0);
;       MMA_BLK(afB, bfB, 1);
.LBB0_2214:
	ds_read_b128 v[0:3], v134 offset:36864
	ds_read_b128 v[4:7], v134 offset:39168
	ds_read_b128 v[8:11], v134 offset:41472
	ds_read_b128 v[12:15], v134 offset:43776
	ds_read_b128 v[16:19], v135
	ds_read_b128 v[20:23], v135 offset:2304
	ds_read_b128 v[24:27], v135 offset:4608
	ds_read_b128 v[28:31], v135 offset:6912
	ds_read_b128 v[32:35], v135 offset:9216
	ds_read_b128 v[36:39], v135 offset:11520
	ds_read_b128 v[40:43], v135 offset:13824
	ds_read_b128 v[44:47], v135 offset:16128
	ds_read_b128 v[48:51], v134 offset:46080
	ds_read_b128 v[52:55], v134 offset:48384
	ds_read_b128 v[56:59], v134 offset:50688
	ds_read_b128 v[60:63], v134 offset:52992
	s_waitcnt lgkmcnt(11)
	v_mfma_f32_16x16x32_f16 a[208:211], v[0:3], v[16:19], a[208:211]
	v_mfma_f32_16x16x32_f16 a[200:203], v[4:7], v[16:19], a[200:203]
	v_mfma_f32_16x16x32_f16 a[196:199], v[8:11], v[16:19], a[196:199]
	v_mfma_f32_16x16x32_f16 a[192:195], v[12:15], v[16:19], a[192:195]
	s_waitcnt lgkmcnt(10)
	v_mfma_f32_16x16x32_f16 a[188:191], v[0:3], v[20:23], a[188:191]
	v_mfma_f32_16x16x32_f16 a[184:187], v[4:7], v[20:23], a[184:187]
	v_mfma_f32_16x16x32_f16 a[180:183], v[8:11], v[20:23], a[180:183]
	v_mfma_f32_16x16x32_f16 a[176:179], v[12:15], v[20:23], a[176:179]
	s_waitcnt lgkmcnt(9)
	v_mfma_f32_16x16x32_f16 a[156:159], v[0:3], v[24:27], a[156:159]
	v_mfma_f32_16x16x32_f16 a[152:155], v[4:7], v[24:27], a[152:155]
	v_mfma_f32_16x16x32_f16 a[148:151], v[8:11], v[24:27], a[148:151]
	v_mfma_f32_16x16x32_f16 a[144:147], v[12:15], v[24:27], a[144:147]
	s_waitcnt lgkmcnt(8)
	v_mfma_f32_16x16x32_f16 a[124:127], v[0:3], v[28:31], a[124:127]
	v_mfma_f32_16x16x32_f16 a[120:123], v[4:7], v[28:31], a[120:123]
	v_mfma_f32_16x16x32_f16 a[116:119], v[8:11], v[28:31], a[116:119]
	v_mfma_f32_16x16x32_f16 a[112:115], v[12:15], v[28:31], a[112:115]
	s_waitcnt lgkmcnt(7)
	v_mfma_f32_16x16x32_f16 a[92:95], v[0:3], v[32:35], a[92:95]
	v_mfma_f32_16x16x32_f16 a[88:91], v[4:7], v[32:35], a[88:91]
	v_mfma_f32_16x16x32_f16 a[84:87], v[8:11], v[32:35], a[84:87]
	v_mfma_f32_16x16x32_f16 a[80:83], v[12:15], v[32:35], a[80:83]
	s_waitcnt lgkmcnt(6)
	v_mfma_f32_16x16x32_f16 a[60:63], v[0:3], v[36:39], a[60:63]
	v_mfma_f32_16x16x32_f16 a[56:59], v[4:7], v[36:39], a[56:59]
	v_mfma_f32_16x16x32_f16 a[52:55], v[8:11], v[36:39], a[52:55]
	v_mfma_f32_16x16x32_f16 a[48:51], v[12:15], v[36:39], a[48:51]
	s_waitcnt lgkmcnt(5)
	v_mfma_f32_16x16x32_f16 a[28:31], v[0:3], v[40:43], a[28:31]
	v_mfma_f32_16x16x32_f16 a[24:27], v[4:7], v[40:43], a[24:27]
	v_mfma_f32_16x16x32_f16 a[20:23], v[8:11], v[40:43], a[20:23]
	v_mfma_f32_16x16x32_f16 a[16:19], v[12:15], v[40:43], a[16:19]
	s_waitcnt lgkmcnt(4)
	v_mfma_f32_16x16x32_f16 a[12:15], v[0:3], v[44:47], a[12:15]
	v_mfma_f32_16x16x32_f16 a[8:11], v[4:7], v[44:47], a[8:11]
	v_mfma_f32_16x16x32_f16 a[4:7], v[8:11], v[44:47], a[4:7]
	v_mfma_f32_16x16x32_f16 a[0:3], v[12:15], v[44:47], a[0:3]
	s_waitcnt lgkmcnt(3)
	v_mfma_f32_16x16x32_f16 a[172:175], v[48:51], v[28:31], a[172:175]
	s_waitcnt lgkmcnt(2)
	v_mfma_f32_16x16x32_f16 a[168:171], v[52:55], v[28:31], a[168:171]
	s_waitcnt lgkmcnt(1)
	v_mfma_f32_16x16x32_f16 a[164:167], v[56:59], v[28:31], a[164:167]
	s_waitcnt lgkmcnt(0)
	v_mfma_f32_16x16x32_f16 a[160:163], v[60:63], v[28:31], a[160:163]
	ds_read_b128 v[12:15], v134 offset:36928
	ds_read_b128 v[28:31], v134 offset:39232
	ds_read_b128 v[74:77], v134 offset:41536
	ds_read_b128 v[78:81], v134 offset:43840
	ds_read_b128 v[90:93], v135 offset:64
	s_waitcnt vmcnt(15)
	ds_read_b128 v[94:97], v135 offset:2368
	s_waitcnt vmcnt(8)
	ds_read_b128 v[138:141], v135 offset:4672
	s_waitcnt vmcnt(6)
	ds_read_b128 v[142:145], v135 offset:6976
	s_waitcnt vmcnt(3)
	ds_read_b128 v[146:149], v135 offset:9280
	ds_read_b128 v[8:11], v135 offset:11584
	ds_read_b128 v[4:7], v135 offset:13888
	ds_read_b128 v[0:3], v135 offset:16192
	v_mfma_f32_16x16x32_f16 a[240:243], v[48:51], v[16:19], a[240:243]
	v_mfma_f32_16x16x32_f16 a[252:255], v[52:55], v[16:19], a[252:255]
	v_mfma_f32_16x16x32_f16 a[248:251], v[56:59], v[16:19], a[248:251]
	v_mfma_f32_16x16x32_f16 a[244:247], v[60:63], v[16:19], a[244:247]
	v_mfma_f32_16x16x32_f16 a[236:239], v[48:51], v[20:23], a[236:239]
	v_mfma_f32_16x16x32_f16 a[232:235], v[52:55], v[20:23], a[232:235]
	v_mfma_f32_16x16x32_f16 a[228:231], v[56:59], v[20:23], a[228:231]
	v_mfma_f32_16x16x32_f16 a[224:227], v[60:63], v[20:23], a[224:227]
	v_mfma_f32_16x16x32_f16 a[220:223], v[48:51], v[24:27], a[220:223]
	v_mfma_f32_16x16x32_f16 a[216:219], v[52:55], v[24:27], a[216:219]
	v_mfma_f32_16x16x32_f16 a[212:215], v[56:59], v[24:27], a[212:215]
	v_mfma_f32_16x16x32_f16 a[204:207], v[60:63], v[24:27], a[204:207]
	v_mfma_f32_16x16x32_f16 a[140:143], v[48:51], v[32:35], a[140:143]
	v_mfma_f32_16x16x32_f16 a[136:139], v[52:55], v[32:35], a[136:139]
	v_mfma_f32_16x16x32_f16 a[132:135], v[56:59], v[32:35], a[132:135]
	v_mfma_f32_16x16x32_f16 a[128:131], v[60:63], v[32:35], a[128:131]
	v_mfma_f32_16x16x32_f16 a[108:111], v[48:51], v[36:39], a[108:111]
	v_mfma_f32_16x16x32_f16 a[104:107], v[52:55], v[36:39], a[104:107]
	v_mfma_f32_16x16x32_f16 a[100:103], v[56:59], v[36:39], a[100:103]
	v_mfma_f32_16x16x32_f16 a[96:99], v[60:63], v[36:39], a[96:99]
	v_mfma_f32_16x16x32_f16 a[76:79], v[48:51], v[40:43], a[76:79]
	v_mfma_f32_16x16x32_f16 a[72:75], v[52:55], v[40:43], a[72:75]
	v_mfma_f32_16x16x32_f16 a[68:71], v[56:59], v[40:43], a[68:71]
	v_mfma_f32_16x16x32_f16 a[64:67], v[60:63], v[40:43], a[64:67]
	v_mfma_f32_16x16x32_f16 a[44:47], v[48:51], v[44:47], a[44:47]
	v_mfma_f32_16x16x32_f16 a[40:43], v[52:55], v[44:47], a[40:43]
	v_mfma_f32_16x16x32_f16 a[36:39], v[56:59], v[44:47], a[36:39]
	v_mfma_f32_16x16x32_f16 a[32:35], v[60:63], v[44:47], a[32:35]
	ds_read_b128 v[150:153], v134 offset:46144
	s_waitcnt vmcnt(2)
; #define LD_AF(dst, ks_) _Pragma("unroll") for (int i = 0; i < 8; ++i) dst[i] = *(const h8*)(sA + i * 16 * G_LD + (ks_) * 32)
; #define LD_BF(dst, ks_, nh_) _Pragma("unroll") for (int i = 0; i < 4; ++i) dst[i] = *(const h8*)(sB + ((nh_) * 4 + i) * 16 * G_LD + (ks_) * 32)
; #define MMA_BLK(afx, bfx, nh_) _Pragma("unroll") for (int mi = 0; mi < 8; ++mi) _Pragma("unroll") for (int ni = 0; ni < 4; ++ni) mfma16_acc(acc[mi][(nh_) * 4 + ni], bfx[ni], afx[mi])
; template <class Epi>
; __device__ __forceinline__ void gemm_run(const GemmArgs g, Epi epi, char* smem) {
;     ...
;       LD_AF(afB, 1); LD_BF(bfA, 1, 0);
;       MMA_BLK(afA, bfB, 1);
;       __builtin_amdgcn_sched_barrier(0);
;       if (kt + 2 < nk) {
;         const int ko = (kt + 2) * 64;
; #pragma unroll
;         for (int i = 0; i < 8; ++i) { ra[i] = __builtin_amdgcn_raw_buffer_load_b128(Ars, aoff, i * astep + ko * 2, 0); rb[i] = __builtin_amdgcn_raw_buffer_load_b128(Brs, boff, i * bstep + ko * 2, 0); }
;       }
;       LD_BF(bfB, 1, 1);
;       MMA_BLK(afB, bfA, 0);
;       __builtin_amdgcn_sched_barrier(0);
;       MMA_BLK(afB, bfB, 1);
	ds_read_b128 v[154:157], v134 offset:48448
	ds_read_b128 v[158:161], v134 offset:50752
	s_waitcnt vmcnt(1)
	ds_read_b128 v[162:165], v134 offset:53056
	s_waitcnt lgkmcnt(11)
	v_mfma_f32_16x16x32_f16 a[208:211], v[12:15], v[90:93], a[208:211]
	v_mfma_f32_16x16x32_f16 a[200:203], v[28:31], v[90:93], a[200:203]
	v_mfma_f32_16x16x32_f16 a[196:199], v[74:77], v[90:93], a[196:199]
	v_mfma_f32_16x16x32_f16 a[192:195], v[78:81], v[90:93], a[192:195]
	s_waitcnt lgkmcnt(10)
	v_mfma_f32_16x16x32_f16 a[188:191], v[12:15], v[94:97], a[188:191]
	v_mfma_f32_16x16x32_f16 a[184:187], v[28:31], v[94:97], a[184:187]
	v_mfma_f32_16x16x32_f16 a[180:183], v[74:77], v[94:97], a[180:183]
	v_mfma_f32_16x16x32_f16 a[176:179], v[78:81], v[94:97], a[176:179]
	s_waitcnt lgkmcnt(9)
	v_mfma_f32_16x16x32_f16 a[156:159], v[12:15], v[138:141], a[156:159]
	v_mfma_f32_16x16x32_f16 a[152:155], v[28:31], v[138:141], a[152:155]
	v_mfma_f32_16x16x32_f16 a[148:151], v[74:77], v[138:141], a[148:151]
	v_mfma_f32_16x16x32_f16 a[144:147], v[78:81], v[138:141], a[144:147]
	s_waitcnt lgkmcnt(8)
	v_mfma_f32_16x16x32_f16 a[124:127], v[12:15], v[142:145], a[124:127]
	v_mfma_f32_16x16x32_f16 a[120:123], v[28:31], v[142:145], a[120:123]
	v_mfma_f32_16x16x32_f16 a[116:119], v[74:77], v[142:145], a[116:119]
	v_mfma_f32_16x16x32_f16 a[112:115], v[78:81], v[142:145], a[112:115]
	s_waitcnt lgkmcnt(7)
	v_mfma_f32_16x16x32_f16 a[92:95], v[12:15], v[146:149], a[92:95]
	v_mfma_f32_16x16x32_f16 a[88:91], v[28:31], v[146:149], a[88:91]
	v_mfma_f32_16x16x32_f16 a[84:87], v[74:77], v[146:149], a[84:87]
	v_mfma_f32_16x16x32_f16 a[80:83], v[78:81], v[146:149], a[80:83]
	v_accvgpr_read_b32 v121, a211
	v_accvgpr_read_b32 v120, a210
	v_accvgpr_read_b32 v119, a203
	v_accvgpr_read_b32 v118, a202
	v_accvgpr_read_b32 v117, a199
	v_accvgpr_read_b32 v116, a198
	v_accvgpr_read_b32 v115, a195
	v_accvgpr_read_b32 v114, a194
	v_accvgpr_read_b32 v105, a191
	v_accvgpr_read_b32 v104, a190
	v_accvgpr_read_b32 v103, a187
	v_accvgpr_read_b32 v102, a186
	v_accvgpr_read_b32 v101, a183
	v_accvgpr_read_b32 v100, a182
	v_accvgpr_read_b32 v99, a179
	v_accvgpr_read_b32 v98, a178
	v_accvgpr_read_b32 v89, a159
	v_accvgpr_read_b32 v88, a158
	v_accvgpr_read_b32 v87, a155
	v_accvgpr_read_b32 v86, a154
	v_accvgpr_read_b32 v85, a151
	v_accvgpr_read_b32 v84, a150
	v_accvgpr_read_b32 v83, a147
	v_accvgpr_read_b32 v82, a146
	v_accvgpr_read_b32 v73, a127
	v_accvgpr_read_b32 v72, a126
	v_accvgpr_read_b32 v71, a123
	v_accvgpr_read_b32 v70, a122
	v_accvgpr_read_b32 v69, a119
	v_accvgpr_read_b32 v68, a118
	v_accvgpr_read_b32 v67, a115
	v_accvgpr_read_b32 v66, a114
	v_accvgpr_read_b32 v57, a95
	v_accvgpr_read_b32 v56, a94
	v_accvgpr_read_b32 v55, a91
	v_accvgpr_read_b32 v54, a90
	v_accvgpr_read_b32 v53, a87
	v_accvgpr_read_b32 v52, a86
	v_accvgpr_read_b32 v51, a83
	v_accvgpr_read_b32 v50, a82
	s_waitcnt lgkmcnt(6)
	v_mfma_f32_16x16x32_f16 a[60:63], v[12:15], v[8:11], a[60:63]
	v_mfma_f32_16x16x32_f16 a[56:59], v[28:31], v[8:11], a[56:59]
	v_mfma_f32_16x16x32_f16 a[52:55], v[74:77], v[8:11], a[52:55]
	v_mfma_f32_16x16x32_f16 a[48:51], v[78:81], v[8:11], a[48:51]
	s_waitcnt lgkmcnt(5)
	v_mfma_f32_16x16x32_f16 a[28:31], v[12:15], v[4:7], a[28:31]
	v_mfma_f32_16x16x32_f16 a[24:27], v[28:31], v[4:7], a[24:27]
	v_mfma_f32_16x16x32_f16 a[20:23], v[74:77], v[4:7], a[20:23]
	v_mfma_f32_16x16x32_f16 a[16:19], v[78:81], v[4:7], a[16:19]
	s_waitcnt lgkmcnt(4)
	v_mfma_f32_16x16x32_f16 a[12:15], v[12:15], v[0:3], a[12:15]
	v_mfma_f32_16x16x32_f16 a[8:11], v[28:31], v[0:3], a[8:11]
	v_mfma_f32_16x16x32_f16 a[4:7], v[74:77], v[0:3], a[4:7]
	v_mfma_f32_16x16x32_f16 a[0:3], v[78:81], v[0:3], a[0:3]
	v_accvgpr_read_b32 v41, a63
	v_accvgpr_read_b32 v40, a62
	v_accvgpr_read_b32 v39, a59
	v_accvgpr_read_b32 v38, a58
	v_accvgpr_read_b32 v37, a55
	v_accvgpr_read_b32 v36, a54
	v_accvgpr_read_b32 v35, a51
	v_accvgpr_read_b32 v34, a50
	v_accvgpr_read_b32 v27, a31
	v_accvgpr_read_b32 v26, a30
	v_accvgpr_read_b32 v25, a27
	v_accvgpr_read_b32 v24, a26
	v_accvgpr_read_b32 v23, a23
	v_accvgpr_read_b32 v22, a22
	v_accvgpr_read_b32 v21, a19
	v_accvgpr_read_b32 v20, a18
	v_accvgpr_read_b32 v19, a15
	v_accvgpr_read_b32 v18, a14
	v_accvgpr_read_b32 v17, a11
	v_accvgpr_read_b32 v16, a10
	v_accvgpr_read_b32 v15, a7
	v_accvgpr_read_b32 v14, a6
	v_accvgpr_read_b32 v13, a3
	v_accvgpr_read_b32 v12, a2
	s_waitcnt lgkmcnt(3)
	v_mfma_f32_16x16x32_f16 a[240:243], v[150:153], v[90:93], a[240:243]
	s_waitcnt lgkmcnt(2)
	v_mfma_f32_16x16x32_f16 a[252:255], v[154:157], v[90:93], a[252:255]
	s_waitcnt lgkmcnt(1)
	v_mfma_f32_16x16x32_f16 a[248:251], v[158:161], v[90:93], a[248:251]
	s_waitcnt lgkmcnt(0)
	v_mfma_f32_16x16x32_f16 a[244:247], v[162:165], v[90:93], a[244:247]
	v_mfma_f32_16x16x32_f16 a[236:239], v[150:153], v[94:97], a[236:239]
	v_mfma_f32_16x16x32_f16 a[232:235], v[154:157], v[94:97], a[232:235]
	v_mfma_f32_16x16x32_f16 a[228:231], v[158:161], v[94:97], a[228:231]
	v_mfma_f32_16x16x32_f16 a[224:227], v[162:165], v[94:97], a[224:227]
	v_mfma_f32_16x16x32_f16 a[220:223], v[150:153], v[138:141], a[220:223]
	v_mfma_f32_16x16x32_f16 a[216:219], v[154:157], v[138:141], a[216:219]
	v_mfma_f32_16x16x32_f16 a[212:215], v[158:161], v[138:141], a[212:215]
	v_mfma_f32_16x16x32_f16 a[204:207], v[162:165], v[138:141], a[204:207]
	v_mfma_f32_16x16x32_f16 a[172:175], v[150:153], v[142:145], a[172:175]
	v_mfma_f32_16x16x32_f16 a[168:171], v[154:157], v[142:145], a[168:171]
	v_mfma_f32_16x16x32_f16 a[164:167], v[158:161], v[142:145], a[164:167]
	v_mfma_f32_16x16x32_f16 a[160:163], v[162:165], v[142:145], a[160:163]
	v_mfma_f32_16x16x32_f16 a[140:143], v[150:153], v[146:149], a[140:143]
	v_mfma_f32_16x16x32_f16 a[136:139], v[154:157], v[146:149], a[136:139]
	v_mfma_f32_16x16x32_f16 a[132:135], v[158:161], v[146:149], a[132:135]
	v_mfma_f32_16x16x32_f16 a[128:131], v[162:165], v[146:149], a[128:131]
	s_waitcnt vmcnt(0)
; #define MMA_BLK(afx, bfx, nh_) _Pragma("unroll") for (int mi = 0; mi < 8; ++mi) _Pragma("unroll") for (int ni = 0; ni < 4; ++ni) mfma16_acc(acc[mi][(nh_) * 4 + ni], bfx[ni], afx[mi])
; template <class Epi>
; __device__ __forceinline__ void gemm_run(const GemmArgs g, Epi epi, char* smem) {
;     ...
;       MMA_BLK(afB, bfA, 0);
;       __builtin_amdgcn_sched_barrier(0);
;       MMA_BLK(afB, bfB, 1);
	v_accvgpr_read_b32 v167, a243
	v_accvgpr_read_b32 v166, a242
	v_accvgpr_read_b32 v169, a255
	v_accvgpr_read_b32 v168, a254
	v_accvgpr_read_b32 v125, a251
	v_accvgpr_read_b32 v124, a250
	v_accvgpr_read_b32 v123, a247
	v_accvgpr_read_b32 v122, a246
	v_accvgpr_read_b32 v113, a239
	v_accvgpr_read_b32 v112, a238
	v_accvgpr_read_b32 v111, a235
	v_accvgpr_read_b32 v110, a234
	v_accvgpr_read_b32 v109, a231
	v_accvgpr_read_b32 v108, a230
	v_accvgpr_read_b32 v107, a227
	v_accvgpr_read_b32 v106, a226
	v_accvgpr_read_b32 v97, a223
	v_accvgpr_read_b32 v96, a222
	v_accvgpr_read_b32 v95, a219
	v_accvgpr_read_b32 v94, a218
	v_accvgpr_read_b32 v93, a215
	v_accvgpr_read_b32 v92, a214
	v_accvgpr_read_b32 v91, a207
	v_accvgpr_read_b32 v90, a206
	v_accvgpr_read_b32 v81, a175
	v_accvgpr_read_b32 v80, a174
	v_accvgpr_read_b32 v79, a171
	v_accvgpr_read_b32 v78, a170
	v_accvgpr_read_b32 v77, a167
	v_accvgpr_read_b32 v76, a166
	v_accvgpr_read_b32 v75, a163
	v_accvgpr_read_b32 v74, a162
	v_accvgpr_read_b32 v65, a143
	v_accvgpr_read_b32 v64, a142
	v_accvgpr_read_b32 v63, a139
	v_accvgpr_read_b32 v62, a138
	v_accvgpr_read_b32 v61, a135
	v_accvgpr_read_b32 v60, a134
	v_accvgpr_read_b32 v59, a131
	v_accvgpr_read_b32 v58, a130
	v_mfma_f32_16x16x32_f16 a[108:111], v[150:153], v[8:11], a[108:111]
	v_mfma_f32_16x16x32_f16 a[104:107], v[154:157], v[8:11], a[104:107]
	v_mfma_f32_16x16x32_f16 a[100:103], v[158:161], v[8:11], a[100:103]
	v_mfma_f32_16x16x32_f16 a[96:99], v[162:165], v[8:11], a[96:99]
	v_mfma_f32_16x16x32_f16 a[76:79], v[150:153], v[4:7], a[76:79]
	v_mfma_f32_16x16x32_f16 a[72:75], v[154:157], v[4:7], a[72:75]
	v_mfma_f32_16x16x32_f16 a[68:71], v[158:161], v[4:7], a[68:71]
	v_mfma_f32_16x16x32_f16 a[64:67], v[162:165], v[4:7], a[64:67]
	v_mfma_f32_16x16x32_f16 a[44:47], v[150:153], v[0:3], a[44:47]
	v_mfma_f32_16x16x32_f16 a[40:43], v[154:157], v[0:3], a[40:43]
	v_mfma_f32_16x16x32_f16 a[36:39], v[158:161], v[0:3], a[36:39]
	v_mfma_f32_16x16x32_f16 a[32:35], v[162:165], v[0:3], a[32:35]
	s_nop 0
	v_lshl_add_u32 v138, s35, 8, v128
	v_add_u32_e32 v140, 0x8000, v138
	v_min_i32_e32 v3, 0x8000, v140
	v_or_b32_e32 v2, s36, v131
	v_ashrrev_i32_e32 v3, 13, v3
	v_ashrrev_i32_e32 v141, 31, v140
	v_mul_hi_i32_i24_e32 v143, 0xc000, v3
	v_mul_i32_i24_e32 v142, 0xc000, v3
	v_ashrrev_i32_e32 v3, 31, v2
	v_lshlrev_b64 v[140:141], 13, v[140:141]
	v_lshlrev_b64 v[2:3], 2, v[2:3]
	v_lshl_add_u64 v[140:141], s[28:29], 0, v[140:141]
	v_lshl_add_u64 v[142:143], s[16:17], 0, v[142:143]
	v_lshl_add_u64 v[150:151], v[140:141], 0, v[2:3]
	s_barrier
	v_lshl_add_u64 v[148:149], v[142:143], 0, v[2:3]
	global_load_dwordx4 v[4:7], v[148:149], off
	global_load_dwordx4 v[8:11], v[148:149], off offset:64
	global_load_dwordx4 v[12:15], v[148:149], off offset:128
	global_load_dwordx4 v[16:19], v[148:149], off offset:192
	global_load_dwordx4 v[20:23], v[148:149], off offset:256
	global_load_dwordx4 v[24:27], v[148:149], off offset:320
	global_load_dwordx4 v[28:31], v[148:149], off offset:384
	global_load_dwordx4 v[32:35], v[148:149], off offset:448
	global_load_dwordx4 v[36:39], v[150:151], off
	global_load_dwordx4 v[40:43], v[150:151], off offset:64
	global_load_dwordx4 v[44:47], v[150:151], off offset:128
	global_load_dwordx4 v[48:51], v[150:151], off offset:192
	global_load_dwordx4 v[52:55], v[150:151], off offset:256
	global_load_dwordx4 v[56:59], v[150:151], off offset:320
	global_load_dwordx4 v[60:63], v[150:151], off offset:384
	global_load_dwordx4 v[64:67], v[150:151], off offset:448
	v_mov_b32_e32 v106, 0x20000
	v_mov_b32_e32 v107, 0
	v_lshl_add_u64 v[104:105], v[150:151], 0, v[106:107]
	v_mov_b32_e32 v106, 0x40000
	global_load_dwordx4 v[68:71], v[104:105], off
	global_load_dwordx4 v[72:75], v[104:105], off offset:64
	global_load_dwordx4 v[76:79], v[104:105], off offset:128
	global_load_dwordx4 v[80:83], v[104:105], off offset:192
	global_load_dwordx4 v[84:87], v[104:105], off offset:256
	global_load_dwordx4 v[88:91], v[104:105], off offset:320
	global_load_dwordx4 v[92:95], v[104:105], off offset:384
	global_load_dwordx4 v[96:99], v[104:105], off offset:448
	v_accvgpr_read_b32 v100, a208
	v_accvgpr_read_b32 v101, a209
	v_accvgpr_read_b32 v102, a210
	v_accvgpr_read_b32 v103, a211
	s_waitcnt vmcnt(15)
	v_pk_fma_f32 v[36:37], v[100:101], v[4:5], v[36:37]
	v_pk_fma_f32 v[38:39], v[102:103], v[6:7], v[38:39]
	global_store_dwordx4 v[150:151], v[36:39], off
	v_accvgpr_read_b32 v100, a200
	v_accvgpr_read_b32 v101, a201
	v_accvgpr_read_b32 v102, a202
	v_accvgpr_read_b32 v103, a203
	s_waitcnt vmcnt(15)
	v_pk_fma_f32 v[40:41], v[100:101], v[8:9], v[40:41]
	v_pk_fma_f32 v[42:43], v[102:103], v[10:11], v[42:43]
	global_store_dwordx4 v[150:151], v[40:43], off offset:64
	v_accvgpr_read_b32 v100, a196
	v_accvgpr_read_b32 v101, a197
	v_accvgpr_read_b32 v102, a198
	v_accvgpr_read_b32 v103, a199
	s_waitcnt vmcnt(15)
	v_pk_fma_f32 v[44:45], v[100:101], v[12:13], v[44:45]
	v_pk_fma_f32 v[46:47], v[102:103], v[14:15], v[46:47]
	global_store_dwordx4 v[150:151], v[44:47], off offset:128
	v_accvgpr_read_b32 v100, a192
	v_accvgpr_read_b32 v101, a193
	v_accvgpr_read_b32 v102, a194
	v_accvgpr_read_b32 v103, a195
	s_waitcnt vmcnt(15)
	v_pk_fma_f32 v[48:49], v[100:101], v[16:17], v[48:49]
	v_pk_fma_f32 v[50:51], v[102:103], v[18:19], v[50:51]
	global_store_dwordx4 v[150:151], v[48:51], off offset:192
	v_accvgpr_read_b32 v100, a240
	v_accvgpr_read_b32 v101, a241
	v_accvgpr_read_b32 v102, a242
	v_accvgpr_read_b32 v103, a243
	s_waitcnt vmcnt(15)
	v_pk_fma_f32 v[52:53], v[100:101], v[20:21], v[52:53]
	v_pk_fma_f32 v[54:55], v[102:103], v[22:23], v[54:55]
	global_store_dwordx4 v[150:151], v[52:55], off offset:256
	v_accvgpr_read_b32 v100, a252
	v_accvgpr_read_b32 v101, a253
	v_accvgpr_read_b32 v102, a254
	v_accvgpr_read_b32 v103, a255
	s_waitcnt vmcnt(15)
	v_pk_fma_f32 v[56:57], v[100:101], v[24:25], v[56:57]
	v_pk_fma_f32 v[58:59], v[102:103], v[26:27], v[58:59]
	global_store_dwordx4 v[150:151], v[56:59], off offset:320
	v_accvgpr_read_b32 v100, a248
	v_accvgpr_read_b32 v101, a249
	v_accvgpr_read_b32 v102, a250
	v_accvgpr_read_b32 v103, a251
	s_waitcnt vmcnt(15)
	v_pk_fma_f32 v[60:61], v[100:101], v[28:29], v[60:61]
	v_pk_fma_f32 v[62:63], v[102:103], v[30:31], v[62:63]
	global_store_dwordx4 v[150:151], v[60:63], off offset:384
	v_accvgpr_read_b32 v100, a244
	v_accvgpr_read_b32 v101, a245
	v_accvgpr_read_b32 v102, a246
	v_accvgpr_read_b32 v103, a247
	s_waitcnt vmcnt(15)
	v_pk_fma_f32 v[64:65], v[100:101], v[32:33], v[64:65]
	v_pk_fma_f32 v[66:67], v[102:103], v[34:35], v[66:67]
	global_store_dwordx4 v[150:151], v[64:67], off offset:448
	v_lshl_add_u64 v[150:151], v[150:151], 0, v[106:107]
	s_nop 1
	global_load_dwordx4 v[36:39], v[150:151], off
	global_load_dwordx4 v[40:43], v[150:151], off offset:64
	global_load_dwordx4 v[44:47], v[150:151], off offset:128
	global_load_dwordx4 v[48:51], v[150:151], off offset:192
	global_load_dwordx4 v[52:55], v[150:151], off offset:256
	global_load_dwordx4 v[56:59], v[150:151], off offset:320
	global_load_dwordx4 v[60:63], v[150:151], off offset:384
	global_load_dwordx4 v[64:67], v[150:151], off offset:448
	v_accvgpr_read_b32 v100, a188
	v_accvgpr_read_b32 v101, a189
	v_accvgpr_read_b32 v102, a190
	v_accvgpr_read_b32 v103, a191
	s_waitcnt vmcnt(23)
	v_pk_fma_f32 v[68:69], v[100:101], v[4:5], v[68:69]
	v_pk_fma_f32 v[70:71], v[102:103], v[6:7], v[70:71]
	global_store_dwordx4 v[104:105], v[68:71], off
	v_accvgpr_read_b32 v100, a184
	v_accvgpr_read_b32 v101, a185
	v_accvgpr_read_b32 v102, a186
	v_accvgpr_read_b32 v103, a187
	s_waitcnt vmcnt(23)
	v_pk_fma_f32 v[72:73], v[100:101], v[8:9], v[72:73]
	v_pk_fma_f32 v[74:75], v[102:103], v[10:11], v[74:75]
	global_store_dwordx4 v[104:105], v[72:75], off offset:64
	v_accvgpr_read_b32 v100, a180
	v_accvgpr_read_b32 v101, a181
	v_accvgpr_read_b32 v102, a182
	v_accvgpr_read_b32 v103, a183
	s_waitcnt vmcnt(23)
	v_pk_fma_f32 v[76:77], v[100:101], v[12:13], v[76:77]
	v_pk_fma_f32 v[78:79], v[102:103], v[14:15], v[78:79]
	global_store_dwordx4 v[104:105], v[76:79], off offset:128
	v_accvgpr_read_b32 v100, a176
	v_accvgpr_read_b32 v101, a177
	v_accvgpr_read_b32 v102, a178
	v_accvgpr_read_b32 v103, a179
	s_waitcnt vmcnt(23)
	v_pk_fma_f32 v[80:81], v[100:101], v[16:17], v[80:81]
	v_pk_fma_f32 v[82:83], v[102:103], v[18:19], v[82:83]
	global_store_dwordx4 v[104:105], v[80:83], off offset:192
	v_accvgpr_read_b32 v100, a236
	v_accvgpr_read_b32 v101, a237
	v_accvgpr_read_b32 v102, a238
	v_accvgpr_read_b32 v103, a239
	s_waitcnt vmcnt(23)
	v_pk_fma_f32 v[84:85], v[100:101], v[20:21], v[84:85]
	v_pk_fma_f32 v[86:87], v[102:103], v[22:23], v[86:87]
	global_store_dwordx4 v[104:105], v[84:87], off offset:256
	v_accvgpr_read_b32 v100, a232
	v_accvgpr_read_b32 v101, a233
	v_accvgpr_read_b32 v102, a234
	v_accvgpr_read_b32 v103, a235
	s_waitcnt vmcnt(23)
	v_pk_fma_f32 v[88:89], v[100:101], v[24:25], v[88:89]
	v_pk_fma_f32 v[90:91], v[102:103], v[26:27], v[90:91]
	global_store_dwordx4 v[104:105], v[88:91], off offset:320
	v_accvgpr_read_b32 v100, a228
	v_accvgpr_read_b32 v101, a229
	v_accvgpr_read_b32 v102, a230
	v_accvgpr_read_b32 v103, a231
	s_waitcnt vmcnt(23)
	v_pk_fma_f32 v[92:93], v[100:101], v[28:29], v[92:93]
	v_pk_fma_f32 v[94:95], v[102:103], v[30:31], v[94:95]
	global_store_dwordx4 v[104:105], v[92:95], off offset:384
	v_accvgpr_read_b32 v100, a224
	v_accvgpr_read_b32 v101, a225
	v_accvgpr_read_b32 v102, a226
	v_accvgpr_read_b32 v103, a227
	s_waitcnt vmcnt(23)
	v_pk_fma_f32 v[96:97], v[100:101], v[32:33], v[96:97]
	v_pk_fma_f32 v[98:99], v[102:103], v[34:35], v[98:99]
	global_store_dwordx4 v[104:105], v[96:99], off offset:448
	v_lshl_add_u64 v[104:105], v[104:105], 0, v[106:107]
	s_nop 1
	global_load_dwordx4 v[68:71], v[104:105], off
	global_load_dwordx4 v[72:75], v[104:105], off offset:64
	global_load_dwordx4 v[76:79], v[104:105], off offset:128
	global_load_dwordx4 v[80:83], v[104:105], off offset:192
	global_load_dwordx4 v[84:87], v[104:105], off offset:256
	global_load_dwordx4 v[88:91], v[104:105], off offset:320
	global_load_dwordx4 v[92:95], v[104:105], off offset:384
	global_load_dwordx4 v[96:99], v[104:105], off offset:448
	v_accvgpr_read_b32 v100, a156
	v_accvgpr_read_b32 v101, a157
	v_accvgpr_read_b32 v102, a158
	v_accvgpr_read_b32 v103, a159
	s_waitcnt vmcnt(23)
	v_pk_fma_f32 v[36:37], v[100:101], v[4:5], v[36:37]
	v_pk_fma_f32 v[38:39], v[102:103], v[6:7], v[38:39]
	global_store_dwordx4 v[150:151], v[36:39], off
	v_accvgpr_read_b32 v100, a152
	v_accvgpr_read_b32 v101, a153
	v_accvgpr_read_b32 v102, a154
	v_accvgpr_read_b32 v103, a155
	s_waitcnt vmcnt(23)
	v_pk_fma_f32 v[40:41], v[100:101], v[8:9], v[40:41]
	v_pk_fma_f32 v[42:43], v[102:103], v[10:11], v[42:43]
	global_store_dwordx4 v[150:151], v[40:43], off offset:64
	v_accvgpr_read_b32 v100, a148
	v_accvgpr_read_b32 v101, a149
	v_accvgpr_read_b32 v102, a150
	v_accvgpr_read_b32 v103, a151
	s_waitcnt vmcnt(23)
	v_pk_fma_f32 v[44:45], v[100:101], v[12:13], v[44:45]
	v_pk_fma_f32 v[46:47], v[102:103], v[14:15], v[46:47]
	global_store_dwordx4 v[150:151], v[44:47], off offset:128
	v_accvgpr_read_b32 v100, a144
	v_accvgpr_read_b32 v101, a145
	v_accvgpr_read_b32 v102, a146
	v_accvgpr_read_b32 v103, a147
	s_waitcnt vmcnt(23)
	v_pk_fma_f32 v[48:49], v[100:101], v[16:17], v[48:49]
	v_pk_fma_f32 v[50:51], v[102:103], v[18:19], v[50:51]
	global_store_dwordx4 v[150:151], v[48:51], off offset:192
	v_accvgpr_read_b32 v100, a220
	v_accvgpr_read_b32 v101, a221
	v_accvgpr_read_b32 v102, a222
	v_accvgpr_read_b32 v103, a223
	s_waitcnt vmcnt(23)
	v_pk_fma_f32 v[52:53], v[100:101], v[20:21], v[52:53]
	v_pk_fma_f32 v[54:55], v[102:103], v[22:23], v[54:55]
	global_store_dwordx4 v[150:151], v[52:55], off offset:256
	v_accvgpr_read_b32 v100, a216
	v_accvgpr_read_b32 v101, a217
	v_accvgpr_read_b32 v102, a218
	v_accvgpr_read_b32 v103, a219
	s_waitcnt vmcnt(23)
	v_pk_fma_f32 v[56:57], v[100:101], v[24:25], v[56:57]
	v_pk_fma_f32 v[58:59], v[102:103], v[26:27], v[58:59]
	global_store_dwordx4 v[150:151], v[56:59], off offset:320
	v_accvgpr_read_b32 v100, a212
	v_accvgpr_read_b32 v101, a213
	v_accvgpr_read_b32 v102, a214
	v_accvgpr_read_b32 v103, a215
	s_waitcnt vmcnt(23)
	v_pk_fma_f32 v[60:61], v[100:101], v[28:29], v[60:61]
	v_pk_fma_f32 v[62:63], v[102:103], v[30:31], v[62:63]
	global_store_dwordx4 v[150:151], v[60:63], off offset:384
	v_accvgpr_read_b32 v100, a204
	v_accvgpr_read_b32 v101, a205
	v_accvgpr_read_b32 v102, a206
	v_accvgpr_read_b32 v103, a207
	s_waitcnt vmcnt(23)
	v_pk_fma_f32 v[64:65], v[100:101], v[32:33], v[64:65]
	v_pk_fma_f32 v[66:67], v[102:103], v[34:35], v[66:67]
	global_store_dwordx4 v[150:151], v[64:67], off offset:448
	v_lshl_add_u64 v[150:151], v[150:151], 0, v[106:107]
	s_nop 1
	global_load_dwordx4 v[36:39], v[150:151], off
	global_load_dwordx4 v[40:43], v[150:151], off offset:64
	global_load_dwordx4 v[44:47], v[150:151], off offset:128
	global_load_dwordx4 v[48:51], v[150:151], off offset:192
	global_load_dwordx4 v[52:55], v[150:151], off offset:256
	global_load_dwordx4 v[56:59], v[150:151], off offset:320
	global_load_dwordx4 v[60:63], v[150:151], off offset:384
	global_load_dwordx4 v[64:67], v[150:151], off offset:448
	v_accvgpr_read_b32 v100, a124
	v_accvgpr_read_b32 v101, a125
	v_accvgpr_read_b32 v102, a126
	v_accvgpr_read_b32 v103, a127
	s_waitcnt vmcnt(23)
	v_pk_fma_f32 v[68:69], v[100:101], v[4:5], v[68:69]
	v_pk_fma_f32 v[70:71], v[102:103], v[6:7], v[70:71]
	global_store_dwordx4 v[104:105], v[68:71], off
	v_accvgpr_read_b32 v100, a120
	v_accvgpr_read_b32 v101, a121
	v_accvgpr_read_b32 v102, a122
	v_accvgpr_read_b32 v103, a123
	s_waitcnt vmcnt(23)
	v_pk_fma_f32 v[72:73], v[100:101], v[8:9], v[72:73]
	v_pk_fma_f32 v[74:75], v[102:103], v[10:11], v[74:75]
	global_store_dwordx4 v[104:105], v[72:75], off offset:64
	v_accvgpr_read_b32 v100, a116
	v_accvgpr_read_b32 v101, a117
	v_accvgpr_read_b32 v102, a118
	v_accvgpr_read_b32 v103, a119
	s_waitcnt vmcnt(23)
	v_pk_fma_f32 v[76:77], v[100:101], v[12:13], v[76:77]
	v_pk_fma_f32 v[78:79], v[102:103], v[14:15], v[78:79]
	global_store_dwordx4 v[104:105], v[76:79], off offset:128
	v_accvgpr_read_b32 v100, a112
	v_accvgpr_read_b32 v101, a113
	v_accvgpr_read_b32 v102, a114
	v_accvgpr_read_b32 v103, a115
	s_waitcnt vmcnt(23)
	v_pk_fma_f32 v[80:81], v[100:101], v[16:17], v[80:81]
	v_pk_fma_f32 v[82:83], v[102:103], v[18:19], v[82:83]
	global_store_dwordx4 v[104:105], v[80:83], off offset:192
	v_accvgpr_read_b32 v100, a172
	v_accvgpr_read_b32 v101, a173
	v_accvgpr_read_b32 v102, a174
	v_accvgpr_read_b32 v103, a175
	s_waitcnt vmcnt(23)
	v_pk_fma_f32 v[84:85], v[100:101], v[20:21], v[84:85]
	v_pk_fma_f32 v[86:87], v[102:103], v[22:23], v[86:87]
	global_store_dwordx4 v[104:105], v[84:87], off offset:256
	v_accvgpr_read_b32 v100, a168
	v_accvgpr_read_b32 v101, a169
	v_accvgpr_read_b32 v102, a170
	v_accvgpr_read_b32 v103, a171
	s_waitcnt vmcnt(23)
	v_pk_fma_f32 v[88:89], v[100:101], v[24:25], v[88:89]
	v_pk_fma_f32 v[90:91], v[102:103], v[26:27], v[90:91]
	global_store_dwordx4 v[104:105], v[88:91], off offset:320
	v_accvgpr_read_b32 v100, a164
	v_accvgpr_read_b32 v101, a165
	v_accvgpr_read_b32 v102, a166
	v_accvgpr_read_b32 v103, a167
	s_waitcnt vmcnt(23)
	v_pk_fma_f32 v[92:93], v[100:101], v[28:29], v[92:93]
	v_pk_fma_f32 v[94:95], v[102:103], v[30:31], v[94:95]
	global_store_dwordx4 v[104:105], v[92:95], off offset:384
	v_accvgpr_read_b32 v100, a160
	v_accvgpr_read_b32 v101, a161
	v_accvgpr_read_b32 v102, a162
	v_accvgpr_read_b32 v103, a163
	s_waitcnt vmcnt(23)
	v_pk_fma_f32 v[96:97], v[100:101], v[32:33], v[96:97]
	v_pk_fma_f32 v[98:99], v[102:103], v[34:35], v[98:99]
	global_store_dwordx4 v[104:105], v[96:99], off offset:448
	v_lshl_add_u64 v[104:105], v[104:105], 0, v[106:107]
	s_nop 1
	global_load_dwordx4 v[68:71], v[104:105], off
	global_load_dwordx4 v[72:75], v[104:105], off offset:64
	global_load_dwordx4 v[76:79], v[104:105], off offset:128
	global_load_dwordx4 v[80:83], v[104:105], off offset:192
	global_load_dwordx4 v[84:87], v[104:105], off offset:256
	global_load_dwordx4 v[88:91], v[104:105], off offset:320
	global_load_dwordx4 v[92:95], v[104:105], off offset:384
	global_load_dwordx4 v[96:99], v[104:105], off offset:448
	v_accvgpr_read_b32 v100, a92
	v_accvgpr_read_b32 v101, a93
	v_accvgpr_read_b32 v102, a94
	v_accvgpr_read_b32 v103, a95
	s_waitcnt vmcnt(23)
	v_pk_fma_f32 v[36:37], v[100:101], v[4:5], v[36:37]
	v_pk_fma_f32 v[38:39], v[102:103], v[6:7], v[38:39]
	global_store_dwordx4 v[150:151], v[36:39], off
	v_accvgpr_read_b32 v100, a88
	v_accvgpr_read_b32 v101, a89
	v_accvgpr_read_b32 v102, a90
	v_accvgpr_read_b32 v103, a91
	s_waitcnt vmcnt(23)
	v_pk_fma_f32 v[40:41], v[100:101], v[8:9], v[40:41]
	v_pk_fma_f32 v[42:43], v[102:103], v[10:11], v[42:43]
	global_store_dwordx4 v[150:151], v[40:43], off offset:64
	v_accvgpr_read_b32 v100, a84
	v_accvgpr_read_b32 v101, a85
	v_accvgpr_read_b32 v102, a86
	v_accvgpr_read_b32 v103, a87
	s_waitcnt vmcnt(23)
	v_pk_fma_f32 v[44:45], v[100:101], v[12:13], v[44:45]
	v_pk_fma_f32 v[46:47], v[102:103], v[14:15], v[46:47]
	global_store_dwordx4 v[150:151], v[44:47], off offset:128
	v_accvgpr_read_b32 v100, a80
	v_accvgpr_read_b32 v101, a81
	v_accvgpr_read_b32 v102, a82
	v_accvgpr_read_b32 v103, a83
	s_waitcnt vmcnt(23)
	v_pk_fma_f32 v[48:49], v[100:101], v[16:17], v[48:49]
	v_pk_fma_f32 v[50:51], v[102:103], v[18:19], v[50:51]
	global_store_dwordx4 v[150:151], v[48:51], off offset:192
	v_accvgpr_read_b32 v100, a140
	v_accvgpr_read_b32 v101, a141
	v_accvgpr_read_b32 v102, a142
	v_accvgpr_read_b32 v103, a143
	s_waitcnt vmcnt(23)
	v_pk_fma_f32 v[52:53], v[100:101], v[20:21], v[52:53]
	v_pk_fma_f32 v[54:55], v[102:103], v[22:23], v[54:55]
	global_store_dwordx4 v[150:151], v[52:55], off offset:256
	v_accvgpr_read_b32 v100, a136
	v_accvgpr_read_b32 v101, a137
	v_accvgpr_read_b32 v102, a138
	v_accvgpr_read_b32 v103, a139
	s_waitcnt vmcnt(23)
	v_pk_fma_f32 v[56:57], v[100:101], v[24:25], v[56:57]
	v_pk_fma_f32 v[58:59], v[102:103], v[26:27], v[58:59]
	global_store_dwordx4 v[150:151], v[56:59], off offset:320
	v_accvgpr_read_b32 v100, a132
	v_accvgpr_read_b32 v101, a133
	v_accvgpr_read_b32 v102, a134
	v_accvgpr_read_b32 v103, a135
	s_waitcnt vmcnt(23)
	v_pk_fma_f32 v[60:61], v[100:101], v[28:29], v[60:61]
	v_pk_fma_f32 v[62:63], v[102:103], v[30:31], v[62:63]
	global_store_dwordx4 v[150:151], v[60:63], off offset:384
	v_accvgpr_read_b32 v100, a128
	v_accvgpr_read_b32 v101, a129
	v_accvgpr_read_b32 v102, a130
	v_accvgpr_read_b32 v103, a131
	s_waitcnt vmcnt(23)
	v_pk_fma_f32 v[64:65], v[100:101], v[32:33], v[64:65]
	v_pk_fma_f32 v[66:67], v[102:103], v[34:35], v[66:67]
	global_store_dwordx4 v[150:151], v[64:67], off offset:448
	v_lshl_add_u64 v[150:151], v[150:151], 0, v[106:107]
	s_nop 1
	global_load_dwordx4 v[36:39], v[150:151], off
	global_load_dwordx4 v[40:43], v[150:151], off offset:64
	global_load_dwordx4 v[44:47], v[150:151], off offset:128
	global_load_dwordx4 v[48:51], v[150:151], off offset:192
	global_load_dwordx4 v[52:55], v[150:151], off offset:256
	global_load_dwordx4 v[56:59], v[150:151], off offset:320
	global_load_dwordx4 v[60:63], v[150:151], off offset:384
	global_load_dwordx4 v[64:67], v[150:151], off offset:448
	v_accvgpr_read_b32 v100, a60
	v_accvgpr_read_b32 v101, a61
	v_accvgpr_read_b32 v102, a62
	v_accvgpr_read_b32 v103, a63
	s_waitcnt vmcnt(23)
	v_pk_fma_f32 v[68:69], v[100:101], v[4:5], v[68:69]
	v_pk_fma_f32 v[70:71], v[102:103], v[6:7], v[70:71]
	global_store_dwordx4 v[104:105], v[68:71], off
	v_accvgpr_read_b32 v100, a56
	v_accvgpr_read_b32 v101, a57
	v_accvgpr_read_b32 v102, a58
	v_accvgpr_read_b32 v103, a59
	s_waitcnt vmcnt(23)
	v_pk_fma_f32 v[72:73], v[100:101], v[8:9], v[72:73]
	v_pk_fma_f32 v[74:75], v[102:103], v[10:11], v[74:75]
	global_store_dwordx4 v[104:105], v[72:75], off offset:64
	v_accvgpr_read_b32 v100, a52
	v_accvgpr_read_b32 v101, a53
	v_accvgpr_read_b32 v102, a54
	v_accvgpr_read_b32 v103, a55
	s_waitcnt vmcnt(23)
	v_pk_fma_f32 v[76:77], v[100:101], v[12:13], v[76:77]
	v_pk_fma_f32 v[78:79], v[102:103], v[14:15], v[78:79]
	global_store_dwordx4 v[104:105], v[76:79], off offset:128
	v_accvgpr_read_b32 v100, a48
	v_accvgpr_read_b32 v101, a49
	v_accvgpr_read_b32 v102, a50
	v_accvgpr_read_b32 v103, a51
	s_waitcnt vmcnt(23)
	v_pk_fma_f32 v[80:81], v[100:101], v[16:17], v[80:81]
	v_pk_fma_f32 v[82:83], v[102:103], v[18:19], v[82:83]
	global_store_dwordx4 v[104:105], v[80:83], off offset:192
	v_accvgpr_read_b32 v100, a108
	v_accvgpr_read_b32 v101, a109
	v_accvgpr_read_b32 v102, a110
	v_accvgpr_read_b32 v103, a111
	s_waitcnt vmcnt(23)
	v_pk_fma_f32 v[84:85], v[100:101], v[20:21], v[84:85]
	v_pk_fma_f32 v[86:87], v[102:103], v[22:23], v[86:87]
	global_store_dwordx4 v[104:105], v[84:87], off offset:256
	v_accvgpr_read_b32 v100, a104
	v_accvgpr_read_b32 v101, a105
	v_accvgpr_read_b32 v102, a106
	v_accvgpr_read_b32 v103, a107
	s_waitcnt vmcnt(23)
	v_pk_fma_f32 v[88:89], v[100:101], v[24:25], v[88:89]
	v_pk_fma_f32 v[90:91], v[102:103], v[26:27], v[90:91]
	global_store_dwordx4 v[104:105], v[88:91], off offset:320
	v_accvgpr_read_b32 v100, a100
	v_accvgpr_read_b32 v101, a101
	v_accvgpr_read_b32 v102, a102
	v_accvgpr_read_b32 v103, a103
	s_waitcnt vmcnt(23)
	v_pk_fma_f32 v[92:93], v[100:101], v[28:29], v[92:93]
	v_pk_fma_f32 v[94:95], v[102:103], v[30:31], v[94:95]
	global_store_dwordx4 v[104:105], v[92:95], off offset:384
	v_accvgpr_read_b32 v100, a96
	v_accvgpr_read_b32 v101, a97
	v_accvgpr_read_b32 v102, a98
	v_accvgpr_read_b32 v103, a99
	s_waitcnt vmcnt(23)
	v_pk_fma_f32 v[96:97], v[100:101], v[32:33], v[96:97]
	v_pk_fma_f32 v[98:99], v[102:103], v[34:35], v[98:99]
	global_store_dwordx4 v[104:105], v[96:99], off offset:448
	v_lshl_add_u64 v[104:105], v[104:105], 0, v[106:107]
	s_nop 1
	global_load_dwordx4 v[68:71], v[104:105], off
	global_load_dwordx4 v[72:75], v[104:105], off offset:64
	global_load_dwordx4 v[76:79], v[104:105], off offset:128
	global_load_dwordx4 v[80:83], v[104:105], off offset:192
	global_load_dwordx4 v[84:87], v[104:105], off offset:256
	global_load_dwordx4 v[88:91], v[104:105], off offset:320
	global_load_dwordx4 v[92:95], v[104:105], off offset:384
	global_load_dwordx4 v[96:99], v[104:105], off offset:448
	v_accvgpr_read_b32 v100, a28
	v_accvgpr_read_b32 v101, a29
	v_accvgpr_read_b32 v102, a30
	v_accvgpr_read_b32 v103, a31
	s_waitcnt vmcnt(23)
; template <class Epi>
; __device__ __forceinline__ void gemm_run(const GemmArgs g, Epi epi, char* smem) {
;     ...
;   for (int tile = blockIdx.x; tile < total; tile += gridDim.x) {
	v_pk_fma_f32 v[36:37], v[100:101], v[4:5], v[36:37]
	v_pk_fma_f32 v[38:39], v[102:103], v[6:7], v[38:39]
	global_store_dwordx4 v[150:151], v[36:39], off
	v_accvgpr_read_b32 v100, a24
	v_accvgpr_read_b32 v101, a25
	v_accvgpr_read_b32 v102, a26
	v_accvgpr_read_b32 v103, a27
	s_waitcnt vmcnt(23)
	v_pk_fma_f32 v[40:41], v[100:101], v[8:9], v[40:41]
	v_pk_fma_f32 v[42:43], v[102:103], v[10:11], v[42:43]
	global_store_dwordx4 v[150:151], v[40:43], off offset:64
	v_accvgpr_read_b32 v100, a20
	v_accvgpr_read_b32 v101, a21
	v_accvgpr_read_b32 v102, a22
	v_accvgpr_read_b32 v103, a23
	s_waitcnt vmcnt(23)
	v_pk_fma_f32 v[44:45], v[100:101], v[12:13], v[44:45]
	v_pk_fma_f32 v[46:47], v[102:103], v[14:15], v[46:47]
	global_store_dwordx4 v[150:151], v[44:47], off offset:128
	v_accvgpr_read_b32 v100, a16
	v_accvgpr_read_b32 v101, a17
	v_accvgpr_read_b32 v102, a18
	v_accvgpr_read_b32 v103, a19
	s_waitcnt vmcnt(23)
	v_pk_fma_f32 v[48:49], v[100:101], v[16:17], v[48:49]
	v_pk_fma_f32 v[50:51], v[102:103], v[18:19], v[50:51]
	global_store_dwordx4 v[150:151], v[48:51], off offset:192
	v_accvgpr_read_b32 v100, a76
	v_accvgpr_read_b32 v101, a77
	v_accvgpr_read_b32 v102, a78
	v_accvgpr_read_b32 v103, a79
	s_waitcnt vmcnt(23)
	v_pk_fma_f32 v[52:53], v[100:101], v[20:21], v[52:53]
	v_pk_fma_f32 v[54:55], v[102:103], v[22:23], v[54:55]
	global_store_dwordx4 v[150:151], v[52:55], off offset:256
	v_accvgpr_read_b32 v100, a72
	v_accvgpr_read_b32 v101, a73
	v_accvgpr_read_b32 v102, a74
	v_accvgpr_read_b32 v103, a75
	s_waitcnt vmcnt(23)
	v_pk_fma_f32 v[56:57], v[100:101], v[24:25], v[56:57]
	v_pk_fma_f32 v[58:59], v[102:103], v[26:27], v[58:59]
	global_store_dwordx4 v[150:151], v[56:59], off offset:320
	v_accvgpr_read_b32 v100, a68
	v_accvgpr_read_b32 v101, a69
	v_accvgpr_read_b32 v102, a70
	v_accvgpr_read_b32 v103, a71
	s_waitcnt vmcnt(23)
	v_pk_fma_f32 v[60:61], v[100:101], v[28:29], v[60:61]
	v_pk_fma_f32 v[62:63], v[102:103], v[30:31], v[62:63]
	global_store_dwordx4 v[150:151], v[60:63], off offset:384
	v_accvgpr_read_b32 v100, a64
	v_accvgpr_read_b32 v101, a65
	v_accvgpr_read_b32 v102, a66
	v_accvgpr_read_b32 v103, a67
	s_waitcnt vmcnt(23)
	v_pk_fma_f32 v[64:65], v[100:101], v[32:33], v[64:65]
	v_pk_fma_f32 v[66:67], v[102:103], v[34:35], v[66:67]
	global_store_dwordx4 v[150:151], v[64:67], off offset:448
	v_accvgpr_read_b32 v100, a12
	v_accvgpr_read_b32 v101, a13
	v_accvgpr_read_b32 v102, a14
	v_accvgpr_read_b32 v103, a15
	s_waitcnt vmcnt(15)
	v_pk_fma_f32 v[68:69], v[100:101], v[4:5], v[68:69]
	v_pk_fma_f32 v[70:71], v[102:103], v[6:7], v[70:71]
	global_store_dwordx4 v[104:105], v[68:71], off
	v_accvgpr_read_b32 v100, a8
	v_accvgpr_read_b32 v101, a9
	v_accvgpr_read_b32 v102, a10
	v_accvgpr_read_b32 v103, a11
	s_waitcnt vmcnt(15)
	v_pk_fma_f32 v[72:73], v[100:101], v[8:9], v[72:73]
	v_pk_fma_f32 v[74:75], v[102:103], v[10:11], v[74:75]
	global_store_dwordx4 v[104:105], v[72:75], off offset:64
	v_accvgpr_read_b32 v100, a4
	v_accvgpr_read_b32 v101, a5
	v_accvgpr_read_b32 v102, a6
	v_accvgpr_read_b32 v103, a7
	s_waitcnt vmcnt(15)
	v_pk_fma_f32 v[76:77], v[100:101], v[12:13], v[76:77]
	v_pk_fma_f32 v[78:79], v[102:103], v[14:15], v[78:79]
	global_store_dwordx4 v[104:105], v[76:79], off offset:128
	v_accvgpr_read_b32 v100, a0
	v_accvgpr_read_b32 v101, a1
	v_accvgpr_read_b32 v102, a2
	v_accvgpr_read_b32 v103, a3
	s_waitcnt vmcnt(15)
	v_pk_fma_f32 v[80:81], v[100:101], v[16:17], v[80:81]
	v_pk_fma_f32 v[82:83], v[102:103], v[18:19], v[82:83]
	global_store_dwordx4 v[104:105], v[80:83], off offset:192
	v_accvgpr_read_b32 v100, a44
	v_accvgpr_read_b32 v101, a45
	v_accvgpr_read_b32 v102, a46
	v_accvgpr_read_b32 v103, a47
	s_waitcnt vmcnt(15)
	v_pk_fma_f32 v[84:85], v[100:101], v[20:21], v[84:85]
	v_pk_fma_f32 v[86:87], v[102:103], v[22:23], v[86:87]
	global_store_dwordx4 v[104:105], v[84:87], off offset:256
	v_accvgpr_read_b32 v100, a40
	v_accvgpr_read_b32 v101, a41
	v_accvgpr_read_b32 v102, a42
	v_accvgpr_read_b32 v103, a43
	s_waitcnt vmcnt(15)
	v_pk_fma_f32 v[88:89], v[100:101], v[24:25], v[88:89]
	v_pk_fma_f32 v[90:91], v[102:103], v[26:27], v[90:91]
	global_store_dwordx4 v[104:105], v[88:91], off offset:320
	v_accvgpr_read_b32 v100, a36
	v_accvgpr_read_b32 v101, a37
	v_accvgpr_read_b32 v102, a38
	v_accvgpr_read_b32 v103, a39
	s_waitcnt vmcnt(15)
	v_pk_fma_f32 v[92:93], v[100:101], v[28:29], v[92:93]
	v_pk_fma_f32 v[94:95], v[102:103], v[30:31], v[94:95]
	global_store_dwordx4 v[104:105], v[92:95], off offset:384
	v_accvgpr_read_b32 v100, a32
	v_accvgpr_read_b32 v101, a33
	v_accvgpr_read_b32 v102, a34
	v_accvgpr_read_b32 v103, a35
	s_waitcnt vmcnt(15)
	v_pk_fma_f32 v[96:97], v[100:101], v[32:33], v[96:97]
	v_pk_fma_f32 v[98:99], v[102:103], v[34:35], v[98:99]
	global_store_dwordx4 v[104:105], v[96:99], off offset:448
	s_add_i32 s63, s63, s2
	s_cmpk_lt_i32 s63, 0x200
	s_cbranch_scc0 .LBB0_2219
